# early barrier + next-k-tile LDS fragment prefetch in 16x16x32 gates/wout/fnetw loops (barrier moved before last 8 MFMAs of each k-tile)
# speedup vs baseline: 1.0137x; 1.0020x over previous
.LBB0_749:
	s_and_b32 s3, s2, 0xffff
	s_mul_i32 s3, s3, 0xaaab
	s_lshr_b32 s3, s3, 18
	s_mul_i32 s10, s3, 6
	s_sub_i32 s2, s2, s10
	s_and_b32 s2, s2, 0xffff
	s_add_i32 s2, s6, s2
	s_lshl_b32 s10, s2, 7
	v_or_b32_e32 v2, s10, v91
	v_lshlrev_b32_e32 v66, 11, v2
	v_lshl_add_u64 v[74:75], v[68:69], 0, v[66:67]
	v_add_lshl_u32 v66, s10, v92, 11
	s_add_i32 s3, s8, s3
	v_lshl_add_u64 v[76:77], v[68:69], 0, v[66:67]
	v_add_lshl_u32 v66, s10, v93, 11
	s_lshl_b32 s11, s3, 7
	v_lshl_add_u64 v[78:79], v[68:69], 0, v[66:67]
	v_add_lshl_u32 v66, s10, v94, 11
	v_lshl_add_u64 v[80:81], v[68:69], 0, v[66:67]
	v_or_b32_e32 v66, s11, v91
	v_lshlrev_b64 v[2:3], 11, v[66:67]
	v_add_u32_e32 v66, s11, v92
	v_lshl_add_u64 v[82:83], v[70:71], 0, v[2:3]
	v_lshlrev_b64 v[2:3], 11, v[66:67]
	v_add_u32_e32 v66, s11, v93
	v_lshl_add_u64 v[84:85], v[70:71], 0, v[2:3]
	v_lshlrev_b64 v[2:3], 11, v[66:67]
	v_add_u32_e32 v66, s11, v94
	v_lshl_add_u64 v[86:87], v[70:71], 0, v[2:3]
	v_lshlrev_b64 v[2:3], 11, v[66:67]
	v_lshl_add_u64 v[88:89], v[70:71], 0, v[2:3]
	global_load_dwordx4 v[2:5], v[74:75], off
	global_load_dwordx4 v[6:9], v[76:77], off
	global_load_dwordx4 v[10:13], v[78:79], off
	global_load_dwordx4 v[14:17], v[80:81], off
	global_load_dwordx4 v[18:21], v[82:83], off
	global_load_dwordx4 v[22:25], v[84:85], off
	global_load_dwordx4 v[26:29], v[86:87], off
	global_load_dwordx4 v[30:33], v[88:89], off
	global_load_dwordx4 v[102:105], v[74:75], off offset:128
	global_load_dwordx4 v[106:109], v[76:77], off offset:128
	global_load_dwordx4 v[110:113], v[78:79], off offset:128
	global_load_dwordx4 v[114:117], v[80:81], off offset:128
	global_load_dwordx4 v[118:121], v[82:83], off offset:128
	global_load_dwordx4 v[122:125], v[84:85], off offset:128
	global_load_dwordx4 v[126:129], v[86:87], off offset:128
	global_load_dwordx4 v[136:139], v[88:89], off offset:128
	s_waitcnt vmcnt(15)
	ds_write_b128 v98, v[2:5]
	s_waitcnt vmcnt(14)
	ds_write_b128 v98, v[6:9] offset:4608
	s_waitcnt vmcnt(13)
	ds_write_b128 v98, v[10:13] offset:9216
	s_waitcnt vmcnt(12)
	ds_write_b128 v98, v[14:17] offset:13824
	s_waitcnt vmcnt(11)
	ds_write_b128 v98, v[18:21] offset:36864
	s_waitcnt vmcnt(10)
	ds_write_b128 v98, v[22:25] offset:41472
	s_waitcnt vmcnt(9)
	ds_write_b128 v98, v[26:29] offset:46080
	s_waitcnt vmcnt(8)
	ds_write_b128 v98, v[30:33] offset:50688
	s_waitcnt lgkmcnt(0)
	s_barrier
	global_load_dwordx4 v[140:143], v[74:75], off offset:256
	global_load_dwordx4 v[144:147], v[76:77], off offset:256
	global_load_dwordx4 v[148:151], v[78:79], off offset:256
	global_load_dwordx4 v[152:155], v[80:81], off offset:256
	global_load_dwordx4 v[156:159], v[82:83], off offset:256
	global_load_dwordx4 v[160:163], v[84:85], off offset:256
	global_load_dwordx4 v[164:167], v[86:87], off offset:256
	global_load_dwordx4 v[168:171], v[88:89], off offset:256
	v_and_b32_e32 v246, 15, v1
	v_add_u32_e32 v246, 4, v246
	v_bfe_u32 v246, v246, 3, 1
	v_bfe_u32 v249, v1, 4, 2
	v_xor_b32_e32 v246, v246, v249
	v_bfe_u32 v249, v1, 5, 1
	v_sub_u32_e32 v246, v246, v249
	v_lshlrev_b32_e32 v246, 4, v246
	v_bfe_u32 v249, v1, 4, 1
	v_mul_u32_u24_e32 v249, 0x900, v249
	v_sub_u32_e32 v246, v246, v249
	v_add_u32_e32 v244, v246, v96
	v_add_u32_e32 v245, v246, v97
	ds_read_b128 v[212:215], v245 offset:36864
	ds_read_b128 v[196:199], v244
	ds_read_b128 v[216:219], v245 offset:39168
	ds_read_b128 v[220:223], v245 offset:41472
	ds_read_b128 v[224:227], v245 offset:43776
	ds_read_b128 v[200:203], v244 offset:2304
	ds_read_b128 v[204:207], v244 offset:4608
	ds_read_b128 v[208:211], v244 offset:6912
	s_waitcnt lgkmcnt(6)
	v_mfma_f32_16x16x32_bf16 v[50:53], v[196:199], v[212:215], 0
	ds_read_b128 v[228:231], v245 offset:36928
	s_waitcnt lgkmcnt(6)
	v_mfma_f32_16x16x32_bf16 v[54:57], v[196:199], v[216:219], 0
	ds_read_b128 v[232:235], v245 offset:39232
	s_waitcnt lgkmcnt(6)
	v_mfma_f32_16x16x32_bf16 v[18:21], v[196:199], v[220:223], 0
	ds_read_b128 v[236:239], v245 offset:41536
	s_waitcnt lgkmcnt(6)
	v_mfma_f32_16x16x32_bf16 v[22:25], v[196:199], v[224:227], 0
	ds_read_b128 v[240:243], v245 offset:43840
	ds_read_b128 v[196:199], v244 offset:64
	s_waitcnt lgkmcnt(7)
	v_mfma_f32_16x16x32_bf16 v[58:61], v[200:203], v[212:215], 0
	v_mfma_f32_16x16x32_bf16 v[62:65], v[200:203], v[216:219], 0
	v_mfma_f32_16x16x32_bf16 v[26:29], v[200:203], v[220:223], 0
	v_mfma_f32_16x16x32_bf16 v[30:33], v[200:203], v[224:227], 0
	ds_read_b128 v[200:203], v244 offset:2368
	s_waitcnt lgkmcnt(7)
	v_mfma_f32_16x16x32_bf16 v[34:37], v[204:207], v[212:215], 0
	v_mfma_f32_16x16x32_bf16 v[38:41], v[204:207], v[216:219], 0
	v_mfma_f32_16x16x32_bf16 v[2:5], v[204:207], v[220:223], 0
	v_mfma_f32_16x16x32_bf16 v[6:9], v[204:207], v[224:227], 0
	ds_read_b128 v[204:207], v244 offset:4672
	s_waitcnt vmcnt(15)
	ds_write_b128 v98, v[102:105] offset:18432
	s_waitcnt vmcnt(14)
	ds_write_b128 v98, v[106:109] offset:23040
	s_waitcnt lgkmcnt(9)
	v_mfma_f32_16x16x32_bf16 v[42:45], v[208:211], v[212:215], 0
	v_mfma_f32_16x16x32_bf16 v[46:49], v[208:211], v[216:219], 0
	v_mfma_f32_16x16x32_bf16 v[10:13], v[208:211], v[220:223], 0
	v_mfma_f32_16x16x32_bf16 v[14:17], v[208:211], v[224:227], 0
	ds_read_b128 v[208:211], v244 offset:6976
	s_waitcnt vmcnt(13)
	ds_write_b128 v98, v[110:113] offset:27648
	s_waitcnt vmcnt(12)
	ds_write_b128 v98, v[114:117] offset:32256
	s_waitcnt lgkmcnt(7)
	v_mfma_f32_16x16x32_bf16 v[50:53], v[196:199], v[228:231], v[50:53]
	v_mfma_f32_16x16x32_bf16 v[54:57], v[196:199], v[232:235], v[54:57]
	v_mfma_f32_16x16x32_bf16 v[18:21], v[196:199], v[236:239], v[18:21]
	v_mfma_f32_16x16x32_bf16 v[22:25], v[196:199], v[240:243], v[22:25]
	s_waitcnt vmcnt(11)
	ds_write_b128 v98, v[118:121] offset:55296
	s_waitcnt vmcnt(10)
	ds_write_b128 v98, v[122:125] offset:59904
	s_waitcnt lgkmcnt(8)
	v_mfma_f32_16x16x32_bf16 v[58:61], v[200:203], v[228:231], v[58:61]
	v_mfma_f32_16x16x32_bf16 v[62:65], v[200:203], v[232:235], v[62:65]
	v_mfma_f32_16x16x32_bf16 v[26:29], v[200:203], v[236:239], v[26:29]
	v_mfma_f32_16x16x32_bf16 v[30:33], v[200:203], v[240:243], v[30:33]
	s_waitcnt vmcnt(9)
	ds_write_b128 v98, v[126:129] offset:64512
	s_waitcnt vmcnt(8)
	ds_write_b128 v99, v[136:139] offset:32256
	s_waitcnt lgkmcnt(0)
	s_barrier
	ds_read_b128 v[212:215], v245 offset:55296
	ds_read_b128 v[196:199], v244 offset:18432
	ds_read_b128 v[216:219], v245 offset:57600
	ds_read_b128 v[220:223], v245 offset:59904
	ds_read_b128 v[224:227], v245 offset:62208
	ds_read_b128 v[200:203], v244 offset:20736
	v_mfma_f32_16x16x32_bf16 v[34:37], v[204:207], v[228:231], v[34:37]
	v_mfma_f32_16x16x32_bf16 v[38:41], v[204:207], v[232:235], v[38:41]
	v_mfma_f32_16x16x32_bf16 v[2:5], v[204:207], v[236:239], v[2:5]
	v_mfma_f32_16x16x32_bf16 v[6:9], v[204:207], v[240:243], v[6:9]
	ds_read_b128 v[204:207], v244 offset:23040
	v_mfma_f32_16x16x32_bf16 v[42:45], v[208:211], v[228:231], v[42:45]
	v_mfma_f32_16x16x32_bf16 v[46:49], v[208:211], v[232:235], v[46:49]
	v_mfma_f32_16x16x32_bf16 v[10:13], v[208:211], v[236:239], v[10:13]
	v_mfma_f32_16x16x32_bf16 v[14:17], v[208:211], v[240:243], v[14:17]
	ds_read_b128 v[208:211], v244 offset:25344
	global_load_dwordx4 v[102:105], v[74:75], off offset:384
	global_load_dwordx4 v[106:109], v[76:77], off offset:384
	global_load_dwordx4 v[110:113], v[78:79], off offset:384
	global_load_dwordx4 v[114:117], v[80:81], off offset:384
	global_load_dwordx4 v[118:121], v[82:83], off offset:384
	global_load_dwordx4 v[122:125], v[84:85], off offset:384
	global_load_dwordx4 v[126:129], v[86:87], off offset:384
	global_load_dwordx4 v[136:139], v[88:89], off offset:384
	s_waitcnt lgkmcnt(6)
	v_mfma_f32_16x16x32_bf16 v[50:53], v[196:199], v[212:215], v[50:53]
	ds_read_b128 v[228:231], v245 offset:55360
	s_waitcnt lgkmcnt(6)
	v_mfma_f32_16x16x32_bf16 v[54:57], v[196:199], v[216:219], v[54:57]
	ds_read_b128 v[232:235], v245 offset:57664
	s_waitcnt lgkmcnt(6)
	v_mfma_f32_16x16x32_bf16 v[18:21], v[196:199], v[220:223], v[18:21]
	ds_read_b128 v[236:239], v245 offset:59968
	s_waitcnt lgkmcnt(6)
	v_mfma_f32_16x16x32_bf16 v[22:25], v[196:199], v[224:227], v[22:25]
	ds_read_b128 v[240:243], v245 offset:62272
	ds_read_b128 v[196:199], v244 offset:18496
	s_waitcnt lgkmcnt(7)
	v_mfma_f32_16x16x32_bf16 v[58:61], v[200:203], v[212:215], v[58:61]
	v_mfma_f32_16x16x32_bf16 v[62:65], v[200:203], v[216:219], v[62:65]
	v_mfma_f32_16x16x32_bf16 v[26:29], v[200:203], v[220:223], v[26:29]
	v_mfma_f32_16x16x32_bf16 v[30:33], v[200:203], v[224:227], v[30:33]
	ds_read_b128 v[200:203], v244 offset:20800
	s_waitcnt lgkmcnt(7)
	v_mfma_f32_16x16x32_bf16 v[34:37], v[204:207], v[212:215], v[34:37]
	v_mfma_f32_16x16x32_bf16 v[38:41], v[204:207], v[216:219], v[38:41]
	v_mfma_f32_16x16x32_bf16 v[2:5], v[204:207], v[220:223], v[2:5]
	v_mfma_f32_16x16x32_bf16 v[6:9], v[204:207], v[224:227], v[6:9]
	ds_read_b128 v[204:207], v244 offset:23104
	s_waitcnt vmcnt(15)
	ds_write_b128 v98, v[140:143]
	s_waitcnt vmcnt(14)
	ds_write_b128 v98, v[144:147] offset:4608
	s_waitcnt lgkmcnt(9)
	v_mfma_f32_16x16x32_bf16 v[42:45], v[208:211], v[212:215], v[42:45]
	v_mfma_f32_16x16x32_bf16 v[46:49], v[208:211], v[216:219], v[46:49]
	v_mfma_f32_16x16x32_bf16 v[10:13], v[208:211], v[220:223], v[10:13]
	v_mfma_f32_16x16x32_bf16 v[14:17], v[208:211], v[224:227], v[14:17]
	ds_read_b128 v[208:211], v244 offset:25408
	s_waitcnt vmcnt(13)
	ds_write_b128 v98, v[148:151] offset:9216
	s_waitcnt vmcnt(12)
	ds_write_b128 v98, v[152:155] offset:13824
	s_waitcnt lgkmcnt(7)
	v_mfma_f32_16x16x32_bf16 v[50:53], v[196:199], v[228:231], v[50:53]
	v_mfma_f32_16x16x32_bf16 v[54:57], v[196:199], v[232:235], v[54:57]
	v_mfma_f32_16x16x32_bf16 v[18:21], v[196:199], v[236:239], v[18:21]
	v_mfma_f32_16x16x32_bf16 v[22:25], v[196:199], v[240:243], v[22:25]
	s_waitcnt vmcnt(11)
	ds_write_b128 v98, v[156:159] offset:36864
	s_waitcnt vmcnt(10)
	ds_write_b128 v98, v[160:163] offset:41472
	s_waitcnt lgkmcnt(8)
	v_mfma_f32_16x16x32_bf16 v[58:61], v[200:203], v[228:231], v[58:61]
	v_mfma_f32_16x16x32_bf16 v[62:65], v[200:203], v[232:235], v[62:65]
	v_mfma_f32_16x16x32_bf16 v[26:29], v[200:203], v[236:239], v[26:29]
	v_mfma_f32_16x16x32_bf16 v[30:33], v[200:203], v[240:243], v[30:33]
	s_waitcnt vmcnt(9)
	ds_write_b128 v98, v[164:167] offset:46080
	s_waitcnt vmcnt(8)
	ds_write_b128 v98, v[168:171] offset:50688
	s_waitcnt lgkmcnt(0)
	s_barrier
	ds_read_b128 v[212:215], v245 offset:36864
	ds_read_b128 v[196:199], v244
	ds_read_b128 v[216:219], v245 offset:39168
	ds_read_b128 v[220:223], v245 offset:41472
	ds_read_b128 v[224:227], v245 offset:43776
	ds_read_b128 v[200:203], v244 offset:2304
	v_mfma_f32_16x16x32_bf16 v[34:37], v[204:207], v[228:231], v[34:37]
	v_mfma_f32_16x16x32_bf16 v[38:41], v[204:207], v[232:235], v[38:41]
	v_mfma_f32_16x16x32_bf16 v[2:5], v[204:207], v[236:239], v[2:5]
	v_mfma_f32_16x16x32_bf16 v[6:9], v[204:207], v[240:243], v[6:9]
	ds_read_b128 v[204:207], v244 offset:4608
	v_mfma_f32_16x16x32_bf16 v[42:45], v[208:211], v[228:231], v[42:45]
	v_mfma_f32_16x16x32_bf16 v[46:49], v[208:211], v[232:235], v[46:49]
	v_mfma_f32_16x16x32_bf16 v[10:13], v[208:211], v[236:239], v[10:13]
	v_mfma_f32_16x16x32_bf16 v[14:17], v[208:211], v[240:243], v[14:17]
	ds_read_b128 v[208:211], v244 offset:6912
	global_load_dwordx4 v[140:143], v[74:75], off offset:512
	global_load_dwordx4 v[144:147], v[76:77], off offset:512
	global_load_dwordx4 v[148:151], v[78:79], off offset:512
	global_load_dwordx4 v[152:155], v[80:81], off offset:512
	global_load_dwordx4 v[156:159], v[82:83], off offset:512
	global_load_dwordx4 v[160:163], v[84:85], off offset:512
	global_load_dwordx4 v[164:167], v[86:87], off offset:512
	global_load_dwordx4 v[168:171], v[88:89], off offset:512
	s_waitcnt lgkmcnt(6)
	v_mfma_f32_16x16x32_bf16 v[50:53], v[196:199], v[212:215], v[50:53]
	ds_read_b128 v[228:231], v245 offset:36928
	s_waitcnt lgkmcnt(6)
	v_mfma_f32_16x16x32_bf16 v[54:57], v[196:199], v[216:219], v[54:57]
	ds_read_b128 v[232:235], v245 offset:39232
	s_waitcnt lgkmcnt(6)
	v_mfma_f32_16x16x32_bf16 v[18:21], v[196:199], v[220:223], v[18:21]
	ds_read_b128 v[236:239], v245 offset:41536
	s_waitcnt lgkmcnt(6)
	v_mfma_f32_16x16x32_bf16 v[22:25], v[196:199], v[224:227], v[22:25]
	ds_read_b128 v[240:243], v245 offset:43840
	ds_read_b128 v[196:199], v244 offset:64
	s_waitcnt lgkmcnt(7)
	v_mfma_f32_16x16x32_bf16 v[58:61], v[200:203], v[212:215], v[58:61]
	v_mfma_f32_16x16x32_bf16 v[62:65], v[200:203], v[216:219], v[62:65]
	v_mfma_f32_16x16x32_bf16 v[26:29], v[200:203], v[220:223], v[26:29]
	v_mfma_f32_16x16x32_bf16 v[30:33], v[200:203], v[224:227], v[30:33]
	ds_read_b128 v[200:203], v244 offset:2368
	s_waitcnt lgkmcnt(7)
	v_mfma_f32_16x16x32_bf16 v[34:37], v[204:207], v[212:215], v[34:37]
	v_mfma_f32_16x16x32_bf16 v[38:41], v[204:207], v[216:219], v[38:41]
	v_mfma_f32_16x16x32_bf16 v[2:5], v[204:207], v[220:223], v[2:5]
	v_mfma_f32_16x16x32_bf16 v[6:9], v[204:207], v[224:227], v[6:9]
	ds_read_b128 v[204:207], v244 offset:4672
	s_waitcnt vmcnt(15)
	ds_write_b128 v98, v[102:105] offset:18432
	s_waitcnt vmcnt(14)
	ds_write_b128 v98, v[106:109] offset:23040
	s_waitcnt lgkmcnt(9)
	v_mfma_f32_16x16x32_bf16 v[42:45], v[208:211], v[212:215], v[42:45]
	v_mfma_f32_16x16x32_bf16 v[46:49], v[208:211], v[216:219], v[46:49]
	v_mfma_f32_16x16x32_bf16 v[10:13], v[208:211], v[220:223], v[10:13]
	v_mfma_f32_16x16x32_bf16 v[14:17], v[208:211], v[224:227], v[14:17]
	ds_read_b128 v[208:211], v244 offset:6976
	s_waitcnt vmcnt(13)
	ds_write_b128 v98, v[110:113] offset:27648
	s_waitcnt vmcnt(12)
	ds_write_b128 v98, v[114:117] offset:32256
	s_waitcnt lgkmcnt(7)
	v_mfma_f32_16x16x32_bf16 v[50:53], v[196:199], v[228:231], v[50:53]
	v_mfma_f32_16x16x32_bf16 v[54:57], v[196:199], v[232:235], v[54:57]
	v_mfma_f32_16x16x32_bf16 v[18:21], v[196:199], v[236:239], v[18:21]
	v_mfma_f32_16x16x32_bf16 v[22:25], v[196:199], v[240:243], v[22:25]
	s_waitcnt vmcnt(11)
	ds_write_b128 v98, v[118:121] offset:55296
	s_waitcnt vmcnt(10)
	ds_write_b128 v98, v[122:125] offset:59904
	s_waitcnt lgkmcnt(8)
	v_mfma_f32_16x16x32_bf16 v[58:61], v[200:203], v[228:231], v[58:61]
	v_mfma_f32_16x16x32_bf16 v[62:65], v[200:203], v[232:235], v[62:65]
	v_mfma_f32_16x16x32_bf16 v[26:29], v[200:203], v[236:239], v[26:29]
	v_mfma_f32_16x16x32_bf16 v[30:33], v[200:203], v[240:243], v[30:33]
	s_waitcnt vmcnt(9)
	ds_write_b128 v98, v[126:129] offset:64512
	s_waitcnt vmcnt(8)
	ds_write_b128 v99, v[136:139] offset:32256
	s_waitcnt lgkmcnt(0)
	s_barrier
	ds_read_b128 v[212:215], v245 offset:55296
	ds_read_b128 v[196:199], v244 offset:18432
	ds_read_b128 v[216:219], v245 offset:57600
	ds_read_b128 v[220:223], v245 offset:59904
	ds_read_b128 v[224:227], v245 offset:62208
	ds_read_b128 v[200:203], v244 offset:20736
	v_mfma_f32_16x16x32_bf16 v[34:37], v[204:207], v[228:231], v[34:37]
	v_mfma_f32_16x16x32_bf16 v[38:41], v[204:207], v[232:235], v[38:41]
	v_mfma_f32_16x16x32_bf16 v[2:5], v[204:207], v[236:239], v[2:5]
	v_mfma_f32_16x16x32_bf16 v[6:9], v[204:207], v[240:243], v[6:9]
	ds_read_b128 v[204:207], v244 offset:23040
	v_mfma_f32_16x16x32_bf16 v[42:45], v[208:211], v[228:231], v[42:45]
	v_mfma_f32_16x16x32_bf16 v[46:49], v[208:211], v[232:235], v[46:49]
	v_mfma_f32_16x16x32_bf16 v[10:13], v[208:211], v[236:239], v[10:13]
	v_mfma_f32_16x16x32_bf16 v[14:17], v[208:211], v[240:243], v[14:17]
	ds_read_b128 v[208:211], v244 offset:25344
	global_load_dwordx4 v[102:105], v[74:75], off offset:640
	global_load_dwordx4 v[106:109], v[76:77], off offset:640
	global_load_dwordx4 v[110:113], v[78:79], off offset:640
	global_load_dwordx4 v[114:117], v[80:81], off offset:640
	global_load_dwordx4 v[118:121], v[82:83], off offset:640
	global_load_dwordx4 v[122:125], v[84:85], off offset:640
	global_load_dwordx4 v[126:129], v[86:87], off offset:640
	global_load_dwordx4 v[136:139], v[88:89], off offset:640
	s_waitcnt lgkmcnt(6)
	v_mfma_f32_16x16x32_bf16 v[50:53], v[196:199], v[212:215], v[50:53]
	ds_read_b128 v[228:231], v245 offset:55360
	s_waitcnt lgkmcnt(6)
	v_mfma_f32_16x16x32_bf16 v[54:57], v[196:199], v[216:219], v[54:57]
	ds_read_b128 v[232:235], v245 offset:57664
	s_waitcnt lgkmcnt(6)
	v_mfma_f32_16x16x32_bf16 v[18:21], v[196:199], v[220:223], v[18:21]
	ds_read_b128 v[236:239], v245 offset:59968
	s_waitcnt lgkmcnt(6)
	v_mfma_f32_16x16x32_bf16 v[22:25], v[196:199], v[224:227], v[22:25]
	ds_read_b128 v[240:243], v245 offset:62272
	ds_read_b128 v[196:199], v244 offset:18496
	s_waitcnt lgkmcnt(7)
	v_mfma_f32_16x16x32_bf16 v[58:61], v[200:203], v[212:215], v[58:61]
	v_mfma_f32_16x16x32_bf16 v[62:65], v[200:203], v[216:219], v[62:65]
	v_mfma_f32_16x16x32_bf16 v[26:29], v[200:203], v[220:223], v[26:29]
	v_mfma_f32_16x16x32_bf16 v[30:33], v[200:203], v[224:227], v[30:33]
	ds_read_b128 v[200:203], v244 offset:20800
	s_waitcnt lgkmcnt(7)
	v_mfma_f32_16x16x32_bf16 v[34:37], v[204:207], v[212:215], v[34:37]
	v_mfma_f32_16x16x32_bf16 v[38:41], v[204:207], v[216:219], v[38:41]
	v_mfma_f32_16x16x32_bf16 v[2:5], v[204:207], v[220:223], v[2:5]
	v_mfma_f32_16x16x32_bf16 v[6:9], v[204:207], v[224:227], v[6:9]
	ds_read_b128 v[204:207], v244 offset:23104
	s_waitcnt vmcnt(15)
	ds_write_b128 v98, v[140:143]
	s_waitcnt vmcnt(14)
	ds_write_b128 v98, v[144:147] offset:4608
	s_waitcnt lgkmcnt(9)
	v_mfma_f32_16x16x32_bf16 v[42:45], v[208:211], v[212:215], v[42:45]
	v_mfma_f32_16x16x32_bf16 v[46:49], v[208:211], v[216:219], v[46:49]
	v_mfma_f32_16x16x32_bf16 v[10:13], v[208:211], v[220:223], v[10:13]
	v_mfma_f32_16x16x32_bf16 v[14:17], v[208:211], v[224:227], v[14:17]
	ds_read_b128 v[208:211], v244 offset:25408
	s_waitcnt vmcnt(13)
	ds_write_b128 v98, v[148:151] offset:9216
	s_waitcnt vmcnt(12)
	ds_write_b128 v98, v[152:155] offset:13824
	s_waitcnt lgkmcnt(7)
	v_mfma_f32_16x16x32_bf16 v[50:53], v[196:199], v[228:231], v[50:53]
	v_mfma_f32_16x16x32_bf16 v[54:57], v[196:199], v[232:235], v[54:57]
	v_mfma_f32_16x16x32_bf16 v[18:21], v[196:199], v[236:239], v[18:21]
	v_mfma_f32_16x16x32_bf16 v[22:25], v[196:199], v[240:243], v[22:25]
	s_waitcnt vmcnt(11)
	ds_write_b128 v98, v[156:159] offset:36864
	s_waitcnt vmcnt(10)
	ds_write_b128 v98, v[160:163] offset:41472
	s_waitcnt lgkmcnt(8)
	v_mfma_f32_16x16x32_bf16 v[58:61], v[200:203], v[228:231], v[58:61]
	v_mfma_f32_16x16x32_bf16 v[62:65], v[200:203], v[232:235], v[62:65]
	v_mfma_f32_16x16x32_bf16 v[26:29], v[200:203], v[236:239], v[26:29]
	v_mfma_f32_16x16x32_bf16 v[30:33], v[200:203], v[240:243], v[30:33]
	s_waitcnt vmcnt(9)
	ds_write_b128 v98, v[164:167] offset:46080
	s_waitcnt vmcnt(8)
	ds_write_b128 v98, v[168:171] offset:50688
	s_waitcnt lgkmcnt(0)
	s_barrier
	ds_read_b128 v[212:215], v245 offset:36864
	ds_read_b128 v[196:199], v244
	ds_read_b128 v[216:219], v245 offset:39168
	ds_read_b128 v[220:223], v245 offset:41472
	ds_read_b128 v[224:227], v245 offset:43776
	ds_read_b128 v[200:203], v244 offset:2304
	v_mfma_f32_16x16x32_bf16 v[34:37], v[204:207], v[228:231], v[34:37]
	v_mfma_f32_16x16x32_bf16 v[38:41], v[204:207], v[232:235], v[38:41]
	v_mfma_f32_16x16x32_bf16 v[2:5], v[204:207], v[236:239], v[2:5]
	v_mfma_f32_16x16x32_bf16 v[6:9], v[204:207], v[240:243], v[6:9]
	ds_read_b128 v[204:207], v244 offset:4608
	v_mfma_f32_16x16x32_bf16 v[42:45], v[208:211], v[228:231], v[42:45]
	v_mfma_f32_16x16x32_bf16 v[46:49], v[208:211], v[232:235], v[46:49]
	v_mfma_f32_16x16x32_bf16 v[10:13], v[208:211], v[236:239], v[10:13]
	v_mfma_f32_16x16x32_bf16 v[14:17], v[208:211], v[240:243], v[14:17]
	ds_read_b128 v[208:211], v244 offset:6912
	global_load_dwordx4 v[140:143], v[74:75], off offset:768
	global_load_dwordx4 v[144:147], v[76:77], off offset:768
	global_load_dwordx4 v[148:151], v[78:79], off offset:768
	global_load_dwordx4 v[152:155], v[80:81], off offset:768
	global_load_dwordx4 v[156:159], v[82:83], off offset:768
	global_load_dwordx4 v[160:163], v[84:85], off offset:768
	global_load_dwordx4 v[164:167], v[86:87], off offset:768
	global_load_dwordx4 v[168:171], v[88:89], off offset:768
	s_waitcnt lgkmcnt(6)
	v_mfma_f32_16x16x32_bf16 v[50:53], v[196:199], v[212:215], v[50:53]
	ds_read_b128 v[228:231], v245 offset:36928
	s_waitcnt lgkmcnt(6)
	v_mfma_f32_16x16x32_bf16 v[54:57], v[196:199], v[216:219], v[54:57]
	ds_read_b128 v[232:235], v245 offset:39232
	s_waitcnt lgkmcnt(6)
	v_mfma_f32_16x16x32_bf16 v[18:21], v[196:199], v[220:223], v[18:21]
	ds_read_b128 v[236:239], v245 offset:41536
	s_waitcnt lgkmcnt(6)
	v_mfma_f32_16x16x32_bf16 v[22:25], v[196:199], v[224:227], v[22:25]
	ds_read_b128 v[240:243], v245 offset:43840
	ds_read_b128 v[196:199], v244 offset:64
	s_waitcnt lgkmcnt(7)
	v_mfma_f32_16x16x32_bf16 v[58:61], v[200:203], v[212:215], v[58:61]
	v_mfma_f32_16x16x32_bf16 v[62:65], v[200:203], v[216:219], v[62:65]
	v_mfma_f32_16x16x32_bf16 v[26:29], v[200:203], v[220:223], v[26:29]
	v_mfma_f32_16x16x32_bf16 v[30:33], v[200:203], v[224:227], v[30:33]
	ds_read_b128 v[200:203], v244 offset:2368
	s_waitcnt lgkmcnt(7)
	v_mfma_f32_16x16x32_bf16 v[34:37], v[204:207], v[212:215], v[34:37]
	v_mfma_f32_16x16x32_bf16 v[38:41], v[204:207], v[216:219], v[38:41]
	v_mfma_f32_16x16x32_bf16 v[2:5], v[204:207], v[220:223], v[2:5]
	v_mfma_f32_16x16x32_bf16 v[6:9], v[204:207], v[224:227], v[6:9]
	ds_read_b128 v[204:207], v244 offset:4672
	s_waitcnt vmcnt(15)
	ds_write_b128 v98, v[102:105] offset:18432
	s_waitcnt vmcnt(14)
	ds_write_b128 v98, v[106:109] offset:23040
	s_waitcnt lgkmcnt(9)
	v_mfma_f32_16x16x32_bf16 v[42:45], v[208:211], v[212:215], v[42:45]
	v_mfma_f32_16x16x32_bf16 v[46:49], v[208:211], v[216:219], v[46:49]
	v_mfma_f32_16x16x32_bf16 v[10:13], v[208:211], v[220:223], v[10:13]
	v_mfma_f32_16x16x32_bf16 v[14:17], v[208:211], v[224:227], v[14:17]
	ds_read_b128 v[208:211], v244 offset:6976
	s_waitcnt vmcnt(13)
	ds_write_b128 v98, v[110:113] offset:27648
	s_waitcnt vmcnt(12)
	ds_write_b128 v98, v[114:117] offset:32256
	s_waitcnt lgkmcnt(7)
	v_mfma_f32_16x16x32_bf16 v[50:53], v[196:199], v[228:231], v[50:53]
	v_mfma_f32_16x16x32_bf16 v[54:57], v[196:199], v[232:235], v[54:57]
	v_mfma_f32_16x16x32_bf16 v[18:21], v[196:199], v[236:239], v[18:21]
	v_mfma_f32_16x16x32_bf16 v[22:25], v[196:199], v[240:243], v[22:25]
	s_waitcnt vmcnt(11)
	ds_write_b128 v98, v[118:121] offset:55296
	s_waitcnt vmcnt(10)
	ds_write_b128 v98, v[122:125] offset:59904
	s_waitcnt lgkmcnt(8)
	v_mfma_f32_16x16x32_bf16 v[58:61], v[200:203], v[228:231], v[58:61]
	v_mfma_f32_16x16x32_bf16 v[62:65], v[200:203], v[232:235], v[62:65]
	v_mfma_f32_16x16x32_bf16 v[26:29], v[200:203], v[236:239], v[26:29]
	v_mfma_f32_16x16x32_bf16 v[30:33], v[200:203], v[240:243], v[30:33]
	s_waitcnt vmcnt(9)
	ds_write_b128 v98, v[126:129] offset:64512
	s_waitcnt vmcnt(8)
	ds_write_b128 v99, v[136:139] offset:32256
	s_waitcnt lgkmcnt(0)
	s_barrier
	ds_read_b128 v[212:215], v245 offset:55296
	ds_read_b128 v[196:199], v244 offset:18432
	ds_read_b128 v[216:219], v245 offset:57600
	ds_read_b128 v[220:223], v245 offset:59904
	ds_read_b128 v[224:227], v245 offset:62208
	ds_read_b128 v[200:203], v244 offset:20736
	v_mfma_f32_16x16x32_bf16 v[34:37], v[204:207], v[228:231], v[34:37]
	v_mfma_f32_16x16x32_bf16 v[38:41], v[204:207], v[232:235], v[38:41]
	v_mfma_f32_16x16x32_bf16 v[2:5], v[204:207], v[236:239], v[2:5]
	v_mfma_f32_16x16x32_bf16 v[6:9], v[204:207], v[240:243], v[6:9]
	ds_read_b128 v[204:207], v244 offset:23040
	v_mfma_f32_16x16x32_bf16 v[42:45], v[208:211], v[228:231], v[42:45]
	v_mfma_f32_16x16x32_bf16 v[46:49], v[208:211], v[232:235], v[46:49]
	v_mfma_f32_16x16x32_bf16 v[10:13], v[208:211], v[236:239], v[10:13]
	v_mfma_f32_16x16x32_bf16 v[14:17], v[208:211], v[240:243], v[14:17]
	ds_read_b128 v[208:211], v244 offset:25344
	global_load_dwordx4 v[102:105], v[74:75], off offset:896
	global_load_dwordx4 v[106:109], v[76:77], off offset:896
	global_load_dwordx4 v[110:113], v[78:79], off offset:896
	global_load_dwordx4 v[114:117], v[80:81], off offset:896
	global_load_dwordx4 v[118:121], v[82:83], off offset:896
	global_load_dwordx4 v[122:125], v[84:85], off offset:896
	global_load_dwordx4 v[126:129], v[86:87], off offset:896
	global_load_dwordx4 v[136:139], v[88:89], off offset:896
	s_waitcnt lgkmcnt(6)
	v_mfma_f32_16x16x32_bf16 v[50:53], v[196:199], v[212:215], v[50:53]
	ds_read_b128 v[228:231], v245 offset:55360
	s_waitcnt lgkmcnt(6)
	v_mfma_f32_16x16x32_bf16 v[54:57], v[196:199], v[216:219], v[54:57]
	ds_read_b128 v[232:235], v245 offset:57664
	s_waitcnt lgkmcnt(6)
	v_mfma_f32_16x16x32_bf16 v[18:21], v[196:199], v[220:223], v[18:21]
	ds_read_b128 v[236:239], v245 offset:59968
	s_waitcnt lgkmcnt(6)
	v_mfma_f32_16x16x32_bf16 v[22:25], v[196:199], v[224:227], v[22:25]
	ds_read_b128 v[240:243], v245 offset:62272
	ds_read_b128 v[196:199], v244 offset:18496
	s_waitcnt lgkmcnt(7)
	v_mfma_f32_16x16x32_bf16 v[58:61], v[200:203], v[212:215], v[58:61]
	v_mfma_f32_16x16x32_bf16 v[62:65], v[200:203], v[216:219], v[62:65]
	v_mfma_f32_16x16x32_bf16 v[26:29], v[200:203], v[220:223], v[26:29]
	v_mfma_f32_16x16x32_bf16 v[30:33], v[200:203], v[224:227], v[30:33]
	ds_read_b128 v[200:203], v244 offset:20800
	s_waitcnt lgkmcnt(7)
	v_mfma_f32_16x16x32_bf16 v[34:37], v[204:207], v[212:215], v[34:37]
	v_mfma_f32_16x16x32_bf16 v[38:41], v[204:207], v[216:219], v[38:41]
	v_mfma_f32_16x16x32_bf16 v[2:5], v[204:207], v[220:223], v[2:5]
	v_mfma_f32_16x16x32_bf16 v[6:9], v[204:207], v[224:227], v[6:9]
	ds_read_b128 v[204:207], v244 offset:23104
	s_waitcnt vmcnt(15)
	ds_write_b128 v98, v[140:143]
	s_waitcnt vmcnt(14)
	ds_write_b128 v98, v[144:147] offset:4608
	s_waitcnt lgkmcnt(9)
	v_mfma_f32_16x16x32_bf16 v[42:45], v[208:211], v[212:215], v[42:45]
	v_mfma_f32_16x16x32_bf16 v[46:49], v[208:211], v[216:219], v[46:49]
	v_mfma_f32_16x16x32_bf16 v[10:13], v[208:211], v[220:223], v[10:13]
	v_mfma_f32_16x16x32_bf16 v[14:17], v[208:211], v[224:227], v[14:17]
	ds_read_b128 v[208:211], v244 offset:25408
	s_waitcnt vmcnt(13)
	ds_write_b128 v98, v[148:151] offset:9216
	s_waitcnt vmcnt(12)
	ds_write_b128 v98, v[152:155] offset:13824
	s_waitcnt lgkmcnt(7)
	v_mfma_f32_16x16x32_bf16 v[50:53], v[196:199], v[228:231], v[50:53]
	v_mfma_f32_16x16x32_bf16 v[54:57], v[196:199], v[232:235], v[54:57]
	v_mfma_f32_16x16x32_bf16 v[18:21], v[196:199], v[236:239], v[18:21]
	v_mfma_f32_16x16x32_bf16 v[22:25], v[196:199], v[240:243], v[22:25]
	s_waitcnt vmcnt(11)
	ds_write_b128 v98, v[156:159] offset:36864
	s_waitcnt vmcnt(10)
	ds_write_b128 v98, v[160:163] offset:41472
	s_waitcnt lgkmcnt(8)
	v_mfma_f32_16x16x32_bf16 v[58:61], v[200:203], v[228:231], v[58:61]
	v_mfma_f32_16x16x32_bf16 v[62:65], v[200:203], v[232:235], v[62:65]
	v_mfma_f32_16x16x32_bf16 v[26:29], v[200:203], v[236:239], v[26:29]
	v_mfma_f32_16x16x32_bf16 v[30:33], v[200:203], v[240:243], v[30:33]
	s_waitcnt vmcnt(9)
	ds_write_b128 v98, v[164:167] offset:46080
	s_waitcnt vmcnt(8)
	ds_write_b128 v98, v[168:171] offset:50688
	s_waitcnt lgkmcnt(0)
	s_barrier
	ds_read_b128 v[212:215], v245 offset:36864
	ds_read_b128 v[196:199], v244
	ds_read_b128 v[216:219], v245 offset:39168
	ds_read_b128 v[220:223], v245 offset:41472
	ds_read_b128 v[224:227], v245 offset:43776
	ds_read_b128 v[200:203], v244 offset:2304
	v_mfma_f32_16x16x32_bf16 v[34:37], v[204:207], v[228:231], v[34:37]
	v_mfma_f32_16x16x32_bf16 v[38:41], v[204:207], v[232:235], v[38:41]
	v_mfma_f32_16x16x32_bf16 v[2:5], v[204:207], v[236:239], v[2:5]
	v_mfma_f32_16x16x32_bf16 v[6:9], v[204:207], v[240:243], v[6:9]
	ds_read_b128 v[204:207], v244 offset:4608
	v_mfma_f32_16x16x32_bf16 v[42:45], v[208:211], v[228:231], v[42:45]
	v_mfma_f32_16x16x32_bf16 v[46:49], v[208:211], v[232:235], v[46:49]
	v_mfma_f32_16x16x32_bf16 v[10:13], v[208:211], v[236:239], v[10:13]
	v_mfma_f32_16x16x32_bf16 v[14:17], v[208:211], v[240:243], v[14:17]
	ds_read_b128 v[208:211], v244 offset:6912
	global_load_dwordx4 v[140:143], v[74:75], off offset:1024
	global_load_dwordx4 v[144:147], v[76:77], off offset:1024
	global_load_dwordx4 v[148:151], v[78:79], off offset:1024
	global_load_dwordx4 v[152:155], v[80:81], off offset:1024
	global_load_dwordx4 v[156:159], v[82:83], off offset:1024
	global_load_dwordx4 v[160:163], v[84:85], off offset:1024
	global_load_dwordx4 v[164:167], v[86:87], off offset:1024
	global_load_dwordx4 v[168:171], v[88:89], off offset:1024
	s_waitcnt lgkmcnt(6)
	v_mfma_f32_16x16x32_bf16 v[50:53], v[196:199], v[212:215], v[50:53]
	ds_read_b128 v[228:231], v245 offset:36928
	s_waitcnt lgkmcnt(6)
	v_mfma_f32_16x16x32_bf16 v[54:57], v[196:199], v[216:219], v[54:57]
	ds_read_b128 v[232:235], v245 offset:39232
	s_waitcnt lgkmcnt(6)
	v_mfma_f32_16x16x32_bf16 v[18:21], v[196:199], v[220:223], v[18:21]
	ds_read_b128 v[236:239], v245 offset:41536
	s_waitcnt lgkmcnt(6)
	v_mfma_f32_16x16x32_bf16 v[22:25], v[196:199], v[224:227], v[22:25]
	ds_read_b128 v[240:243], v245 offset:43840
	ds_read_b128 v[196:199], v244 offset:64
	s_waitcnt lgkmcnt(7)
	v_mfma_f32_16x16x32_bf16 v[58:61], v[200:203], v[212:215], v[58:61]
	v_mfma_f32_16x16x32_bf16 v[62:65], v[200:203], v[216:219], v[62:65]
	v_mfma_f32_16x16x32_bf16 v[26:29], v[200:203], v[220:223], v[26:29]
	v_mfma_f32_16x16x32_bf16 v[30:33], v[200:203], v[224:227], v[30:33]
	ds_read_b128 v[200:203], v244 offset:2368
	s_waitcnt lgkmcnt(7)
	v_mfma_f32_16x16x32_bf16 v[34:37], v[204:207], v[212:215], v[34:37]
	v_mfma_f32_16x16x32_bf16 v[38:41], v[204:207], v[216:219], v[38:41]
	v_mfma_f32_16x16x32_bf16 v[2:5], v[204:207], v[220:223], v[2:5]
	v_mfma_f32_16x16x32_bf16 v[6:9], v[204:207], v[224:227], v[6:9]
	ds_read_b128 v[204:207], v244 offset:4672
	s_waitcnt vmcnt(15)
	ds_write_b128 v98, v[102:105] offset:18432
	s_waitcnt vmcnt(14)
	ds_write_b128 v98, v[106:109] offset:23040
	s_waitcnt lgkmcnt(9)
	v_mfma_f32_16x16x32_bf16 v[42:45], v[208:211], v[212:215], v[42:45]
	v_mfma_f32_16x16x32_bf16 v[46:49], v[208:211], v[216:219], v[46:49]
	v_mfma_f32_16x16x32_bf16 v[10:13], v[208:211], v[220:223], v[10:13]
	v_mfma_f32_16x16x32_bf16 v[14:17], v[208:211], v[224:227], v[14:17]
	ds_read_b128 v[208:211], v244 offset:6976
	s_waitcnt vmcnt(13)
	ds_write_b128 v98, v[110:113] offset:27648
	s_waitcnt vmcnt(12)
	ds_write_b128 v98, v[114:117] offset:32256
	s_waitcnt lgkmcnt(7)
	v_mfma_f32_16x16x32_bf16 v[50:53], v[196:199], v[228:231], v[50:53]
	v_mfma_f32_16x16x32_bf16 v[54:57], v[196:199], v[232:235], v[54:57]
	v_mfma_f32_16x16x32_bf16 v[18:21], v[196:199], v[236:239], v[18:21]
	v_mfma_f32_16x16x32_bf16 v[22:25], v[196:199], v[240:243], v[22:25]
	s_waitcnt vmcnt(11)
	ds_write_b128 v98, v[118:121] offset:55296
	s_waitcnt vmcnt(10)
	ds_write_b128 v98, v[122:125] offset:59904
	s_waitcnt lgkmcnt(8)
	v_mfma_f32_16x16x32_bf16 v[58:61], v[200:203], v[228:231], v[58:61]
	v_mfma_f32_16x16x32_bf16 v[62:65], v[200:203], v[232:235], v[62:65]
	v_mfma_f32_16x16x32_bf16 v[26:29], v[200:203], v[236:239], v[26:29]
	v_mfma_f32_16x16x32_bf16 v[30:33], v[200:203], v[240:243], v[30:33]
	s_waitcnt vmcnt(9)
	ds_write_b128 v98, v[126:129] offset:64512
	s_waitcnt vmcnt(8)
	ds_write_b128 v99, v[136:139] offset:32256
	s_waitcnt lgkmcnt(0)
	s_barrier
	ds_read_b128 v[212:215], v245 offset:55296
	ds_read_b128 v[196:199], v244 offset:18432
	ds_read_b128 v[216:219], v245 offset:57600
	ds_read_b128 v[220:223], v245 offset:59904
	ds_read_b128 v[224:227], v245 offset:62208
	ds_read_b128 v[200:203], v244 offset:20736
	v_mfma_f32_16x16x32_bf16 v[34:37], v[204:207], v[228:231], v[34:37]
	v_mfma_f32_16x16x32_bf16 v[38:41], v[204:207], v[232:235], v[38:41]
	v_mfma_f32_16x16x32_bf16 v[2:5], v[204:207], v[236:239], v[2:5]
	v_mfma_f32_16x16x32_bf16 v[6:9], v[204:207], v[240:243], v[6:9]
	ds_read_b128 v[204:207], v244 offset:23040
	v_mfma_f32_16x16x32_bf16 v[42:45], v[208:211], v[228:231], v[42:45]
	v_mfma_f32_16x16x32_bf16 v[46:49], v[208:211], v[232:235], v[46:49]
	v_mfma_f32_16x16x32_bf16 v[10:13], v[208:211], v[236:239], v[10:13]
	v_mfma_f32_16x16x32_bf16 v[14:17], v[208:211], v[240:243], v[14:17]
	ds_read_b128 v[208:211], v244 offset:25344
	global_load_dwordx4 v[102:105], v[74:75], off offset:1152
	global_load_dwordx4 v[106:109], v[76:77], off offset:1152
	global_load_dwordx4 v[110:113], v[78:79], off offset:1152
	global_load_dwordx4 v[114:117], v[80:81], off offset:1152
	global_load_dwordx4 v[118:121], v[82:83], off offset:1152
	global_load_dwordx4 v[122:125], v[84:85], off offset:1152
	global_load_dwordx4 v[126:129], v[86:87], off offset:1152
	global_load_dwordx4 v[136:139], v[88:89], off offset:1152
	s_waitcnt lgkmcnt(6)
	v_mfma_f32_16x16x32_bf16 v[50:53], v[196:199], v[212:215], v[50:53]
	ds_read_b128 v[228:231], v245 offset:55360
	s_waitcnt lgkmcnt(6)
	v_mfma_f32_16x16x32_bf16 v[54:57], v[196:199], v[216:219], v[54:57]
	ds_read_b128 v[232:235], v245 offset:57664
	s_waitcnt lgkmcnt(6)
	v_mfma_f32_16x16x32_bf16 v[18:21], v[196:199], v[220:223], v[18:21]
	ds_read_b128 v[236:239], v245 offset:59968
	s_waitcnt lgkmcnt(6)
	v_mfma_f32_16x16x32_bf16 v[22:25], v[196:199], v[224:227], v[22:25]
	ds_read_b128 v[240:243], v245 offset:62272
	ds_read_b128 v[196:199], v244 offset:18496
	s_waitcnt lgkmcnt(7)
	v_mfma_f32_16x16x32_bf16 v[58:61], v[200:203], v[212:215], v[58:61]
	v_mfma_f32_16x16x32_bf16 v[62:65], v[200:203], v[216:219], v[62:65]
	v_mfma_f32_16x16x32_bf16 v[26:29], v[200:203], v[220:223], v[26:29]
	v_mfma_f32_16x16x32_bf16 v[30:33], v[200:203], v[224:227], v[30:33]
	ds_read_b128 v[200:203], v244 offset:20800
	s_waitcnt lgkmcnt(7)
	v_mfma_f32_16x16x32_bf16 v[34:37], v[204:207], v[212:215], v[34:37]
	v_mfma_f32_16x16x32_bf16 v[38:41], v[204:207], v[216:219], v[38:41]
	v_mfma_f32_16x16x32_bf16 v[2:5], v[204:207], v[220:223], v[2:5]
	v_mfma_f32_16x16x32_bf16 v[6:9], v[204:207], v[224:227], v[6:9]
	ds_read_b128 v[204:207], v244 offset:23104
	s_waitcnt vmcnt(15)
	ds_write_b128 v98, v[140:143]
	s_waitcnt vmcnt(14)
	ds_write_b128 v98, v[144:147] offset:4608
	s_waitcnt lgkmcnt(9)
	v_mfma_f32_16x16x32_bf16 v[42:45], v[208:211], v[212:215], v[42:45]
	v_mfma_f32_16x16x32_bf16 v[46:49], v[208:211], v[216:219], v[46:49]
	v_mfma_f32_16x16x32_bf16 v[10:13], v[208:211], v[220:223], v[10:13]
	v_mfma_f32_16x16x32_bf16 v[14:17], v[208:211], v[224:227], v[14:17]
	ds_read_b128 v[208:211], v244 offset:25408
	s_waitcnt vmcnt(13)
	ds_write_b128 v98, v[148:151] offset:9216
	s_waitcnt vmcnt(12)
	ds_write_b128 v98, v[152:155] offset:13824
	s_waitcnt lgkmcnt(7)
	v_mfma_f32_16x16x32_bf16 v[50:53], v[196:199], v[228:231], v[50:53]
	v_mfma_f32_16x16x32_bf16 v[54:57], v[196:199], v[232:235], v[54:57]
	v_mfma_f32_16x16x32_bf16 v[18:21], v[196:199], v[236:239], v[18:21]
	v_mfma_f32_16x16x32_bf16 v[22:25], v[196:199], v[240:243], v[22:25]
	s_waitcnt vmcnt(11)
	ds_write_b128 v98, v[156:159] offset:36864
	s_waitcnt vmcnt(10)
	ds_write_b128 v98, v[160:163] offset:41472
	s_waitcnt lgkmcnt(8)
	v_mfma_f32_16x16x32_bf16 v[58:61], v[200:203], v[228:231], v[58:61]
	v_mfma_f32_16x16x32_bf16 v[62:65], v[200:203], v[232:235], v[62:65]
	v_mfma_f32_16x16x32_bf16 v[26:29], v[200:203], v[236:239], v[26:29]
	v_mfma_f32_16x16x32_bf16 v[30:33], v[200:203], v[240:243], v[30:33]
	s_waitcnt vmcnt(9)
	ds_write_b128 v98, v[164:167] offset:46080
	s_waitcnt vmcnt(8)
	ds_write_b128 v98, v[168:171] offset:50688
	s_waitcnt lgkmcnt(0)
	s_barrier
	ds_read_b128 v[212:215], v245 offset:36864
	ds_read_b128 v[196:199], v244
	ds_read_b128 v[216:219], v245 offset:39168
	ds_read_b128 v[220:223], v245 offset:41472
	ds_read_b128 v[224:227], v245 offset:43776
	ds_read_b128 v[200:203], v244 offset:2304
	v_mfma_f32_16x16x32_bf16 v[34:37], v[204:207], v[228:231], v[34:37]
	v_mfma_f32_16x16x32_bf16 v[38:41], v[204:207], v[232:235], v[38:41]
	v_mfma_f32_16x16x32_bf16 v[2:5], v[204:207], v[236:239], v[2:5]
	v_mfma_f32_16x16x32_bf16 v[6:9], v[204:207], v[240:243], v[6:9]
	ds_read_b128 v[204:207], v244 offset:4608
	v_mfma_f32_16x16x32_bf16 v[42:45], v[208:211], v[228:231], v[42:45]
	v_mfma_f32_16x16x32_bf16 v[46:49], v[208:211], v[232:235], v[46:49]
	v_mfma_f32_16x16x32_bf16 v[10:13], v[208:211], v[236:239], v[10:13]
	v_mfma_f32_16x16x32_bf16 v[14:17], v[208:211], v[240:243], v[14:17]
	ds_read_b128 v[208:211], v244 offset:6912
	global_load_dwordx4 v[140:143], v[74:75], off offset:1280
	global_load_dwordx4 v[144:147], v[76:77], off offset:1280
	global_load_dwordx4 v[148:151], v[78:79], off offset:1280
	global_load_dwordx4 v[152:155], v[80:81], off offset:1280
	global_load_dwordx4 v[156:159], v[82:83], off offset:1280
	global_load_dwordx4 v[160:163], v[84:85], off offset:1280
	global_load_dwordx4 v[164:167], v[86:87], off offset:1280
	global_load_dwordx4 v[168:171], v[88:89], off offset:1280
	s_waitcnt lgkmcnt(6)
	v_mfma_f32_16x16x32_bf16 v[50:53], v[196:199], v[212:215], v[50:53]
	ds_read_b128 v[228:231], v245 offset:36928
	s_waitcnt lgkmcnt(6)
	v_mfma_f32_16x16x32_bf16 v[54:57], v[196:199], v[216:219], v[54:57]
	ds_read_b128 v[232:235], v245 offset:39232
	s_waitcnt lgkmcnt(6)
	v_mfma_f32_16x16x32_bf16 v[18:21], v[196:199], v[220:223], v[18:21]
	ds_read_b128 v[236:239], v245 offset:41536
	s_waitcnt lgkmcnt(6)
	v_mfma_f32_16x16x32_bf16 v[22:25], v[196:199], v[224:227], v[22:25]
	ds_read_b128 v[240:243], v245 offset:43840
	ds_read_b128 v[196:199], v244 offset:64
	s_waitcnt lgkmcnt(7)
	v_mfma_f32_16x16x32_bf16 v[58:61], v[200:203], v[212:215], v[58:61]
	v_mfma_f32_16x16x32_bf16 v[62:65], v[200:203], v[216:219], v[62:65]
	v_mfma_f32_16x16x32_bf16 v[26:29], v[200:203], v[220:223], v[26:29]
	v_mfma_f32_16x16x32_bf16 v[30:33], v[200:203], v[224:227], v[30:33]
	ds_read_b128 v[200:203], v244 offset:2368
	s_waitcnt lgkmcnt(7)
	v_mfma_f32_16x16x32_bf16 v[34:37], v[204:207], v[212:215], v[34:37]
	v_mfma_f32_16x16x32_bf16 v[38:41], v[204:207], v[216:219], v[38:41]
	v_mfma_f32_16x16x32_bf16 v[2:5], v[204:207], v[220:223], v[2:5]
	v_mfma_f32_16x16x32_bf16 v[6:9], v[204:207], v[224:227], v[6:9]
	ds_read_b128 v[204:207], v244 offset:4672
	s_waitcnt vmcnt(15)
	ds_write_b128 v98, v[102:105] offset:18432
	s_waitcnt vmcnt(14)
	ds_write_b128 v98, v[106:109] offset:23040
	s_waitcnt lgkmcnt(9)
	v_mfma_f32_16x16x32_bf16 v[42:45], v[208:211], v[212:215], v[42:45]
	v_mfma_f32_16x16x32_bf16 v[46:49], v[208:211], v[216:219], v[46:49]
	v_mfma_f32_16x16x32_bf16 v[10:13], v[208:211], v[220:223], v[10:13]
	v_mfma_f32_16x16x32_bf16 v[14:17], v[208:211], v[224:227], v[14:17]
	ds_read_b128 v[208:211], v244 offset:6976
	s_waitcnt vmcnt(13)
	ds_write_b128 v98, v[110:113] offset:27648
	s_waitcnt vmcnt(12)
	ds_write_b128 v98, v[114:117] offset:32256
	s_waitcnt lgkmcnt(7)
	v_mfma_f32_16x16x32_bf16 v[50:53], v[196:199], v[228:231], v[50:53]
	v_mfma_f32_16x16x32_bf16 v[54:57], v[196:199], v[232:235], v[54:57]
	v_mfma_f32_16x16x32_bf16 v[18:21], v[196:199], v[236:239], v[18:21]
	v_mfma_f32_16x16x32_bf16 v[22:25], v[196:199], v[240:243], v[22:25]
	s_waitcnt vmcnt(11)
	ds_write_b128 v98, v[118:121] offset:55296
	s_waitcnt vmcnt(10)
	ds_write_b128 v98, v[122:125] offset:59904
	s_waitcnt lgkmcnt(8)
	v_mfma_f32_16x16x32_bf16 v[58:61], v[200:203], v[228:231], v[58:61]
	v_mfma_f32_16x16x32_bf16 v[62:65], v[200:203], v[232:235], v[62:65]
	v_mfma_f32_16x16x32_bf16 v[26:29], v[200:203], v[236:239], v[26:29]
	v_mfma_f32_16x16x32_bf16 v[30:33], v[200:203], v[240:243], v[30:33]
	s_waitcnt vmcnt(9)
	ds_write_b128 v98, v[126:129] offset:64512
	s_waitcnt vmcnt(8)
	ds_write_b128 v99, v[136:139] offset:32256
	s_waitcnt lgkmcnt(0)
	s_barrier
	ds_read_b128 v[212:215], v245 offset:55296
	ds_read_b128 v[196:199], v244 offset:18432
	ds_read_b128 v[216:219], v245 offset:57600
	ds_read_b128 v[220:223], v245 offset:59904
	ds_read_b128 v[224:227], v245 offset:62208
	ds_read_b128 v[200:203], v244 offset:20736
	v_mfma_f32_16x16x32_bf16 v[34:37], v[204:207], v[228:231], v[34:37]
	v_mfma_f32_16x16x32_bf16 v[38:41], v[204:207], v[232:235], v[38:41]
	v_mfma_f32_16x16x32_bf16 v[2:5], v[204:207], v[236:239], v[2:5]
	v_mfma_f32_16x16x32_bf16 v[6:9], v[204:207], v[240:243], v[6:9]
	ds_read_b128 v[204:207], v244 offset:23040
	v_mfma_f32_16x16x32_bf16 v[42:45], v[208:211], v[228:231], v[42:45]
	v_mfma_f32_16x16x32_bf16 v[46:49], v[208:211], v[232:235], v[46:49]
	v_mfma_f32_16x16x32_bf16 v[10:13], v[208:211], v[236:239], v[10:13]
	v_mfma_f32_16x16x32_bf16 v[14:17], v[208:211], v[240:243], v[14:17]
	ds_read_b128 v[208:211], v244 offset:25344
	global_load_dwordx4 v[102:105], v[74:75], off offset:1408
	global_load_dwordx4 v[106:109], v[76:77], off offset:1408
	global_load_dwordx4 v[110:113], v[78:79], off offset:1408
	global_load_dwordx4 v[114:117], v[80:81], off offset:1408
	global_load_dwordx4 v[118:121], v[82:83], off offset:1408
	global_load_dwordx4 v[122:125], v[84:85], off offset:1408
	global_load_dwordx4 v[126:129], v[86:87], off offset:1408
	global_load_dwordx4 v[136:139], v[88:89], off offset:1408
	s_waitcnt lgkmcnt(6)
	v_mfma_f32_16x16x32_bf16 v[50:53], v[196:199], v[212:215], v[50:53]
	ds_read_b128 v[228:231], v245 offset:55360
	s_waitcnt lgkmcnt(6)
	v_mfma_f32_16x16x32_bf16 v[54:57], v[196:199], v[216:219], v[54:57]
	ds_read_b128 v[232:235], v245 offset:57664
	s_waitcnt lgkmcnt(6)
	v_mfma_f32_16x16x32_bf16 v[18:21], v[196:199], v[220:223], v[18:21]
	ds_read_b128 v[236:239], v245 offset:59968
	s_waitcnt lgkmcnt(6)
	v_mfma_f32_16x16x32_bf16 v[22:25], v[196:199], v[224:227], v[22:25]
	ds_read_b128 v[240:243], v245 offset:62272
	ds_read_b128 v[196:199], v244 offset:18496
	s_waitcnt lgkmcnt(7)
	v_mfma_f32_16x16x32_bf16 v[58:61], v[200:203], v[212:215], v[58:61]
	v_mfma_f32_16x16x32_bf16 v[62:65], v[200:203], v[216:219], v[62:65]
	v_mfma_f32_16x16x32_bf16 v[26:29], v[200:203], v[220:223], v[26:29]
	v_mfma_f32_16x16x32_bf16 v[30:33], v[200:203], v[224:227], v[30:33]
	ds_read_b128 v[200:203], v244 offset:20800
	s_waitcnt lgkmcnt(7)
	v_mfma_f32_16x16x32_bf16 v[34:37], v[204:207], v[212:215], v[34:37]
	v_mfma_f32_16x16x32_bf16 v[38:41], v[204:207], v[216:219], v[38:41]
	v_mfma_f32_16x16x32_bf16 v[2:5], v[204:207], v[220:223], v[2:5]
	v_mfma_f32_16x16x32_bf16 v[6:9], v[204:207], v[224:227], v[6:9]
	ds_read_b128 v[204:207], v244 offset:23104
	s_waitcnt vmcnt(15)
	ds_write_b128 v98, v[140:143]
	s_waitcnt vmcnt(14)
	ds_write_b128 v98, v[144:147] offset:4608
	s_waitcnt lgkmcnt(9)
	v_mfma_f32_16x16x32_bf16 v[42:45], v[208:211], v[212:215], v[42:45]
	v_mfma_f32_16x16x32_bf16 v[46:49], v[208:211], v[216:219], v[46:49]
	v_mfma_f32_16x16x32_bf16 v[10:13], v[208:211], v[220:223], v[10:13]
	v_mfma_f32_16x16x32_bf16 v[14:17], v[208:211], v[224:227], v[14:17]
	ds_read_b128 v[208:211], v244 offset:25408
	s_waitcnt vmcnt(13)
	ds_write_b128 v98, v[148:151] offset:9216
	s_waitcnt vmcnt(12)
	ds_write_b128 v98, v[152:155] offset:13824
	s_waitcnt lgkmcnt(7)
	v_mfma_f32_16x16x32_bf16 v[50:53], v[196:199], v[228:231], v[50:53]
	v_mfma_f32_16x16x32_bf16 v[54:57], v[196:199], v[232:235], v[54:57]
	v_mfma_f32_16x16x32_bf16 v[18:21], v[196:199], v[236:239], v[18:21]
	v_mfma_f32_16x16x32_bf16 v[22:25], v[196:199], v[240:243], v[22:25]
	s_waitcnt vmcnt(11)
	ds_write_b128 v98, v[156:159] offset:36864
	s_waitcnt vmcnt(10)
	ds_write_b128 v98, v[160:163] offset:41472
	s_waitcnt lgkmcnt(8)
	v_mfma_f32_16x16x32_bf16 v[58:61], v[200:203], v[228:231], v[58:61]
	v_mfma_f32_16x16x32_bf16 v[62:65], v[200:203], v[232:235], v[62:65]
	v_mfma_f32_16x16x32_bf16 v[26:29], v[200:203], v[236:239], v[26:29]
	v_mfma_f32_16x16x32_bf16 v[30:33], v[200:203], v[240:243], v[30:33]
	s_waitcnt vmcnt(9)
	ds_write_b128 v98, v[164:167] offset:46080
	s_waitcnt vmcnt(8)
	ds_write_b128 v98, v[168:171] offset:50688
	s_waitcnt lgkmcnt(0)
	s_barrier
	ds_read_b128 v[212:215], v245 offset:36864
	ds_read_b128 v[196:199], v244
	ds_read_b128 v[216:219], v245 offset:39168
	ds_read_b128 v[220:223], v245 offset:41472
	ds_read_b128 v[224:227], v245 offset:43776
	ds_read_b128 v[200:203], v244 offset:2304
	v_mfma_f32_16x16x32_bf16 v[34:37], v[204:207], v[228:231], v[34:37]
	v_mfma_f32_16x16x32_bf16 v[38:41], v[204:207], v[232:235], v[38:41]
	v_mfma_f32_16x16x32_bf16 v[2:5], v[204:207], v[236:239], v[2:5]
	v_mfma_f32_16x16x32_bf16 v[6:9], v[204:207], v[240:243], v[6:9]
	ds_read_b128 v[204:207], v244 offset:4608
	v_mfma_f32_16x16x32_bf16 v[42:45], v[208:211], v[228:231], v[42:45]
	v_mfma_f32_16x16x32_bf16 v[46:49], v[208:211], v[232:235], v[46:49]
	v_mfma_f32_16x16x32_bf16 v[10:13], v[208:211], v[236:239], v[10:13]
	v_mfma_f32_16x16x32_bf16 v[14:17], v[208:211], v[240:243], v[14:17]
	ds_read_b128 v[208:211], v244 offset:6912
	global_load_dwordx4 v[140:143], v[74:75], off offset:1536
	global_load_dwordx4 v[144:147], v[76:77], off offset:1536
	global_load_dwordx4 v[148:151], v[78:79], off offset:1536
	global_load_dwordx4 v[152:155], v[80:81], off offset:1536
	global_load_dwordx4 v[156:159], v[82:83], off offset:1536
	global_load_dwordx4 v[160:163], v[84:85], off offset:1536
	global_load_dwordx4 v[164:167], v[86:87], off offset:1536
	global_load_dwordx4 v[168:171], v[88:89], off offset:1536
	s_waitcnt lgkmcnt(6)
	v_mfma_f32_16x16x32_bf16 v[50:53], v[196:199], v[212:215], v[50:53]
	ds_read_b128 v[228:231], v245 offset:36928
	s_waitcnt lgkmcnt(6)
	v_mfma_f32_16x16x32_bf16 v[54:57], v[196:199], v[216:219], v[54:57]
	ds_read_b128 v[232:235], v245 offset:39232
	s_waitcnt lgkmcnt(6)
	v_mfma_f32_16x16x32_bf16 v[18:21], v[196:199], v[220:223], v[18:21]
	ds_read_b128 v[236:239], v245 offset:41536
	s_waitcnt lgkmcnt(6)
	v_mfma_f32_16x16x32_bf16 v[22:25], v[196:199], v[224:227], v[22:25]
	ds_read_b128 v[240:243], v245 offset:43840
	ds_read_b128 v[196:199], v244 offset:64
	s_waitcnt lgkmcnt(7)
	v_mfma_f32_16x16x32_bf16 v[58:61], v[200:203], v[212:215], v[58:61]
	v_mfma_f32_16x16x32_bf16 v[62:65], v[200:203], v[216:219], v[62:65]
	v_mfma_f32_16x16x32_bf16 v[26:29], v[200:203], v[220:223], v[26:29]
	v_mfma_f32_16x16x32_bf16 v[30:33], v[200:203], v[224:227], v[30:33]
	ds_read_b128 v[200:203], v244 offset:2368
	s_waitcnt lgkmcnt(7)
	v_mfma_f32_16x16x32_bf16 v[34:37], v[204:207], v[212:215], v[34:37]
	v_mfma_f32_16x16x32_bf16 v[38:41], v[204:207], v[216:219], v[38:41]
	v_mfma_f32_16x16x32_bf16 v[2:5], v[204:207], v[220:223], v[2:5]
	v_mfma_f32_16x16x32_bf16 v[6:9], v[204:207], v[224:227], v[6:9]
	ds_read_b128 v[204:207], v244 offset:4672
	s_waitcnt vmcnt(15)
	ds_write_b128 v98, v[102:105] offset:18432
	s_waitcnt vmcnt(14)
	ds_write_b128 v98, v[106:109] offset:23040
	s_waitcnt lgkmcnt(9)
	v_mfma_f32_16x16x32_bf16 v[42:45], v[208:211], v[212:215], v[42:45]
	v_mfma_f32_16x16x32_bf16 v[46:49], v[208:211], v[216:219], v[46:49]
	v_mfma_f32_16x16x32_bf16 v[10:13], v[208:211], v[220:223], v[10:13]
	v_mfma_f32_16x16x32_bf16 v[14:17], v[208:211], v[224:227], v[14:17]
	ds_read_b128 v[208:211], v244 offset:6976
	s_waitcnt vmcnt(13)
	ds_write_b128 v98, v[110:113] offset:27648
	s_waitcnt vmcnt(12)
	ds_write_b128 v98, v[114:117] offset:32256
	s_waitcnt lgkmcnt(7)
	v_mfma_f32_16x16x32_bf16 v[50:53], v[196:199], v[228:231], v[50:53]
	v_mfma_f32_16x16x32_bf16 v[54:57], v[196:199], v[232:235], v[54:57]
	v_mfma_f32_16x16x32_bf16 v[18:21], v[196:199], v[236:239], v[18:21]
	v_mfma_f32_16x16x32_bf16 v[22:25], v[196:199], v[240:243], v[22:25]
	s_waitcnt vmcnt(11)
	ds_write_b128 v98, v[118:121] offset:55296
	s_waitcnt vmcnt(10)
	ds_write_b128 v98, v[122:125] offset:59904
	s_waitcnt lgkmcnt(8)
	v_mfma_f32_16x16x32_bf16 v[58:61], v[200:203], v[228:231], v[58:61]
	v_mfma_f32_16x16x32_bf16 v[62:65], v[200:203], v[232:235], v[62:65]
	v_mfma_f32_16x16x32_bf16 v[26:29], v[200:203], v[236:239], v[26:29]
	v_mfma_f32_16x16x32_bf16 v[30:33], v[200:203], v[240:243], v[30:33]
	s_waitcnt vmcnt(9)
	ds_write_b128 v98, v[126:129] offset:64512
	s_waitcnt vmcnt(8)
	ds_write_b128 v99, v[136:139] offset:32256
	s_waitcnt lgkmcnt(0)
	s_barrier
	ds_read_b128 v[212:215], v245 offset:55296
	ds_read_b128 v[196:199], v244 offset:18432
	ds_read_b128 v[216:219], v245 offset:57600
	ds_read_b128 v[220:223], v245 offset:59904
	ds_read_b128 v[224:227], v245 offset:62208
	ds_read_b128 v[200:203], v244 offset:20736
	v_mfma_f32_16x16x32_bf16 v[34:37], v[204:207], v[228:231], v[34:37]
	v_mfma_f32_16x16x32_bf16 v[38:41], v[204:207], v[232:235], v[38:41]
	v_mfma_f32_16x16x32_bf16 v[2:5], v[204:207], v[236:239], v[2:5]
	v_mfma_f32_16x16x32_bf16 v[6:9], v[204:207], v[240:243], v[6:9]
	ds_read_b128 v[204:207], v244 offset:23040
	v_mfma_f32_16x16x32_bf16 v[42:45], v[208:211], v[228:231], v[42:45]
	v_mfma_f32_16x16x32_bf16 v[46:49], v[208:211], v[232:235], v[46:49]
	v_mfma_f32_16x16x32_bf16 v[10:13], v[208:211], v[236:239], v[10:13]
	v_mfma_f32_16x16x32_bf16 v[14:17], v[208:211], v[240:243], v[14:17]
	ds_read_b128 v[208:211], v244 offset:25344
	global_load_dwordx4 v[102:105], v[74:75], off offset:1664
	global_load_dwordx4 v[106:109], v[76:77], off offset:1664
	global_load_dwordx4 v[110:113], v[78:79], off offset:1664
	global_load_dwordx4 v[114:117], v[80:81], off offset:1664
	global_load_dwordx4 v[118:121], v[82:83], off offset:1664
	global_load_dwordx4 v[122:125], v[84:85], off offset:1664
	global_load_dwordx4 v[126:129], v[86:87], off offset:1664
	global_load_dwordx4 v[136:139], v[88:89], off offset:1664
	s_waitcnt lgkmcnt(6)
	v_mfma_f32_16x16x32_bf16 v[50:53], v[196:199], v[212:215], v[50:53]
	ds_read_b128 v[228:231], v245 offset:55360
	s_waitcnt lgkmcnt(6)
	v_mfma_f32_16x16x32_bf16 v[54:57], v[196:199], v[216:219], v[54:57]
	ds_read_b128 v[232:235], v245 offset:57664
	s_waitcnt lgkmcnt(6)
	v_mfma_f32_16x16x32_bf16 v[18:21], v[196:199], v[220:223], v[18:21]
	ds_read_b128 v[236:239], v245 offset:59968
	s_waitcnt lgkmcnt(6)
	v_mfma_f32_16x16x32_bf16 v[22:25], v[196:199], v[224:227], v[22:25]
	ds_read_b128 v[240:243], v245 offset:62272
	ds_read_b128 v[196:199], v244 offset:18496
	s_waitcnt lgkmcnt(7)
	v_mfma_f32_16x16x32_bf16 v[58:61], v[200:203], v[212:215], v[58:61]
	v_mfma_f32_16x16x32_bf16 v[62:65], v[200:203], v[216:219], v[62:65]
	v_mfma_f32_16x16x32_bf16 v[26:29], v[200:203], v[220:223], v[26:29]
	v_mfma_f32_16x16x32_bf16 v[30:33], v[200:203], v[224:227], v[30:33]
	ds_read_b128 v[200:203], v244 offset:20800
	s_waitcnt lgkmcnt(7)
	v_mfma_f32_16x16x32_bf16 v[34:37], v[204:207], v[212:215], v[34:37]
	v_mfma_f32_16x16x32_bf16 v[38:41], v[204:207], v[216:219], v[38:41]
	v_mfma_f32_16x16x32_bf16 v[2:5], v[204:207], v[220:223], v[2:5]
	v_mfma_f32_16x16x32_bf16 v[6:9], v[204:207], v[224:227], v[6:9]
	ds_read_b128 v[204:207], v244 offset:23104
	s_waitcnt vmcnt(15)
	ds_write_b128 v98, v[140:143]
	s_waitcnt vmcnt(14)
	ds_write_b128 v98, v[144:147] offset:4608
	s_waitcnt lgkmcnt(9)
	v_mfma_f32_16x16x32_bf16 v[42:45], v[208:211], v[212:215], v[42:45]
	v_mfma_f32_16x16x32_bf16 v[46:49], v[208:211], v[216:219], v[46:49]
	v_mfma_f32_16x16x32_bf16 v[10:13], v[208:211], v[220:223], v[10:13]
	v_mfma_f32_16x16x32_bf16 v[14:17], v[208:211], v[224:227], v[14:17]
	ds_read_b128 v[208:211], v244 offset:25408
	s_waitcnt vmcnt(13)
	ds_write_b128 v98, v[148:151] offset:9216
	s_waitcnt vmcnt(12)
	ds_write_b128 v98, v[152:155] offset:13824
	s_waitcnt lgkmcnt(7)
	v_mfma_f32_16x16x32_bf16 v[50:53], v[196:199], v[228:231], v[50:53]
	v_mfma_f32_16x16x32_bf16 v[54:57], v[196:199], v[232:235], v[54:57]
	v_mfma_f32_16x16x32_bf16 v[18:21], v[196:199], v[236:239], v[18:21]
	v_mfma_f32_16x16x32_bf16 v[22:25], v[196:199], v[240:243], v[22:25]
	s_waitcnt vmcnt(11)
	ds_write_b128 v98, v[156:159] offset:36864
	s_waitcnt vmcnt(10)
	ds_write_b128 v98, v[160:163] offset:41472
	s_waitcnt lgkmcnt(8)
	v_mfma_f32_16x16x32_bf16 v[58:61], v[200:203], v[228:231], v[58:61]
	v_mfma_f32_16x16x32_bf16 v[62:65], v[200:203], v[232:235], v[62:65]
	v_mfma_f32_16x16x32_bf16 v[26:29], v[200:203], v[236:239], v[26:29]
	v_mfma_f32_16x16x32_bf16 v[30:33], v[200:203], v[240:243], v[30:33]
	s_waitcnt vmcnt(9)
	ds_write_b128 v98, v[164:167] offset:46080
	s_waitcnt vmcnt(8)
	ds_write_b128 v98, v[168:171] offset:50688
	s_waitcnt lgkmcnt(0)
	s_barrier
	ds_read_b128 v[212:215], v245 offset:36864
	ds_read_b128 v[196:199], v244
	ds_read_b128 v[216:219], v245 offset:39168
	ds_read_b128 v[220:223], v245 offset:41472
	ds_read_b128 v[224:227], v245 offset:43776
	ds_read_b128 v[200:203], v244 offset:2304
	v_mfma_f32_16x16x32_bf16 v[34:37], v[204:207], v[228:231], v[34:37]
	v_mfma_f32_16x16x32_bf16 v[38:41], v[204:207], v[232:235], v[38:41]
	v_mfma_f32_16x16x32_bf16 v[2:5], v[204:207], v[236:239], v[2:5]
	v_mfma_f32_16x16x32_bf16 v[6:9], v[204:207], v[240:243], v[6:9]
	ds_read_b128 v[204:207], v244 offset:4608
	v_mfma_f32_16x16x32_bf16 v[42:45], v[208:211], v[228:231], v[42:45]
	v_mfma_f32_16x16x32_bf16 v[46:49], v[208:211], v[232:235], v[46:49]
	v_mfma_f32_16x16x32_bf16 v[10:13], v[208:211], v[236:239], v[10:13]
	v_mfma_f32_16x16x32_bf16 v[14:17], v[208:211], v[240:243], v[14:17]
	ds_read_b128 v[208:211], v244 offset:6912
	global_load_dwordx4 v[140:143], v[74:75], off offset:1792
	global_load_dwordx4 v[144:147], v[76:77], off offset:1792
	global_load_dwordx4 v[148:151], v[78:79], off offset:1792
	global_load_dwordx4 v[152:155], v[80:81], off offset:1792
	global_load_dwordx4 v[156:159], v[82:83], off offset:1792
	global_load_dwordx4 v[160:163], v[84:85], off offset:1792
	global_load_dwordx4 v[164:167], v[86:87], off offset:1792
	global_load_dwordx4 v[168:171], v[88:89], off offset:1792
	s_waitcnt lgkmcnt(6)
	v_mfma_f32_16x16x32_bf16 v[50:53], v[196:199], v[212:215], v[50:53]
	ds_read_b128 v[228:231], v245 offset:36928
	s_waitcnt lgkmcnt(6)
	v_mfma_f32_16x16x32_bf16 v[54:57], v[196:199], v[216:219], v[54:57]
	ds_read_b128 v[232:235], v245 offset:39232
	s_waitcnt lgkmcnt(6)
	v_mfma_f32_16x16x32_bf16 v[18:21], v[196:199], v[220:223], v[18:21]
	ds_read_b128 v[236:239], v245 offset:41536
	s_waitcnt lgkmcnt(6)
	v_mfma_f32_16x16x32_bf16 v[22:25], v[196:199], v[224:227], v[22:25]
	ds_read_b128 v[240:243], v245 offset:43840
	ds_read_b128 v[196:199], v244 offset:64
	s_waitcnt lgkmcnt(7)
	v_mfma_f32_16x16x32_bf16 v[58:61], v[200:203], v[212:215], v[58:61]
	v_mfma_f32_16x16x32_bf16 v[62:65], v[200:203], v[216:219], v[62:65]
	v_mfma_f32_16x16x32_bf16 v[26:29], v[200:203], v[220:223], v[26:29]
	v_mfma_f32_16x16x32_bf16 v[30:33], v[200:203], v[224:227], v[30:33]
	ds_read_b128 v[200:203], v244 offset:2368
	s_waitcnt lgkmcnt(7)
	v_mfma_f32_16x16x32_bf16 v[34:37], v[204:207], v[212:215], v[34:37]
	v_mfma_f32_16x16x32_bf16 v[38:41], v[204:207], v[216:219], v[38:41]
	v_mfma_f32_16x16x32_bf16 v[2:5], v[204:207], v[220:223], v[2:5]
	v_mfma_f32_16x16x32_bf16 v[6:9], v[204:207], v[224:227], v[6:9]
	ds_read_b128 v[204:207], v244 offset:4672
	s_waitcnt vmcnt(15)
	ds_write_b128 v98, v[102:105] offset:18432
	s_waitcnt vmcnt(14)
	ds_write_b128 v98, v[106:109] offset:23040
	s_waitcnt lgkmcnt(9)
	v_mfma_f32_16x16x32_bf16 v[42:45], v[208:211], v[212:215], v[42:45]
	v_mfma_f32_16x16x32_bf16 v[46:49], v[208:211], v[216:219], v[46:49]
	v_mfma_f32_16x16x32_bf16 v[10:13], v[208:211], v[220:223], v[10:13]
	v_mfma_f32_16x16x32_bf16 v[14:17], v[208:211], v[224:227], v[14:17]
	ds_read_b128 v[208:211], v244 offset:6976
	s_waitcnt vmcnt(13)
	ds_write_b128 v98, v[110:113] offset:27648
	s_waitcnt vmcnt(12)
	ds_write_b128 v98, v[114:117] offset:32256
	s_waitcnt lgkmcnt(7)
	v_mfma_f32_16x16x32_bf16 v[50:53], v[196:199], v[228:231], v[50:53]
	v_mfma_f32_16x16x32_bf16 v[54:57], v[196:199], v[232:235], v[54:57]
	v_mfma_f32_16x16x32_bf16 v[18:21], v[196:199], v[236:239], v[18:21]
	v_mfma_f32_16x16x32_bf16 v[22:25], v[196:199], v[240:243], v[22:25]
	s_waitcnt vmcnt(11)
	ds_write_b128 v98, v[118:121] offset:55296
	s_waitcnt vmcnt(10)
	ds_write_b128 v98, v[122:125] offset:59904
	s_waitcnt lgkmcnt(8)
	v_mfma_f32_16x16x32_bf16 v[58:61], v[200:203], v[228:231], v[58:61]
	v_mfma_f32_16x16x32_bf16 v[62:65], v[200:203], v[232:235], v[62:65]
	v_mfma_f32_16x16x32_bf16 v[26:29], v[200:203], v[236:239], v[26:29]
	v_mfma_f32_16x16x32_bf16 v[30:33], v[200:203], v[240:243], v[30:33]
	s_waitcnt vmcnt(9)
	ds_write_b128 v98, v[126:129] offset:64512
	s_waitcnt vmcnt(8)
	ds_write_b128 v99, v[136:139] offset:32256
	s_waitcnt lgkmcnt(0)
	s_barrier
	ds_read_b128 v[212:215], v245 offset:55296
	ds_read_b128 v[196:199], v244 offset:18432
	ds_read_b128 v[216:219], v245 offset:57600
	ds_read_b128 v[220:223], v245 offset:59904
	ds_read_b128 v[224:227], v245 offset:62208
	ds_read_b128 v[200:203], v244 offset:20736
	v_mfma_f32_16x16x32_bf16 v[34:37], v[204:207], v[228:231], v[34:37]
	v_mfma_f32_16x16x32_bf16 v[38:41], v[204:207], v[232:235], v[38:41]
	v_mfma_f32_16x16x32_bf16 v[2:5], v[204:207], v[236:239], v[2:5]
	v_mfma_f32_16x16x32_bf16 v[6:9], v[204:207], v[240:243], v[6:9]
	ds_read_b128 v[204:207], v244 offset:23040
	v_mfma_f32_16x16x32_bf16 v[42:45], v[208:211], v[228:231], v[42:45]
	v_mfma_f32_16x16x32_bf16 v[46:49], v[208:211], v[232:235], v[46:49]
	v_mfma_f32_16x16x32_bf16 v[10:13], v[208:211], v[236:239], v[10:13]
	v_mfma_f32_16x16x32_bf16 v[14:17], v[208:211], v[240:243], v[14:17]
	ds_read_b128 v[208:211], v244 offset:25344
	global_load_dwordx4 v[102:105], v[74:75], off offset:1920
	s_nop 0
	global_load_dwordx4 v[74:77], v[76:77], off offset:1920
	s_nop 0
	global_load_dwordx4 v[106:109], v[78:79], off offset:1920
	s_nop 0
	global_load_dwordx4 v[78:81], v[80:81], off offset:1920
	s_nop 0
	global_load_dwordx4 v[110:113], v[82:83], off offset:1920
	s_nop 0
	global_load_dwordx4 v[82:85], v[84:85], off offset:1920
	s_nop 0
	global_load_dwordx4 v[114:117], v[86:87], off offset:1920
	s_nop 0
	global_load_dwordx4 v[86:89], v[88:89], off offset:1920
	s_waitcnt lgkmcnt(6)
	v_mfma_f32_16x16x32_bf16 v[50:53], v[196:199], v[212:215], v[50:53]
	ds_read_b128 v[228:231], v245 offset:55360
	s_waitcnt lgkmcnt(6)
	v_mfma_f32_16x16x32_bf16 v[54:57], v[196:199], v[216:219], v[54:57]
	ds_read_b128 v[232:235], v245 offset:57664
	s_waitcnt lgkmcnt(6)
	v_mfma_f32_16x16x32_bf16 v[18:21], v[196:199], v[220:223], v[18:21]
	ds_read_b128 v[236:239], v245 offset:59968
	s_waitcnt lgkmcnt(6)
	v_mfma_f32_16x16x32_bf16 v[22:25], v[196:199], v[224:227], v[22:25]
	ds_read_b128 v[240:243], v245 offset:62272
	ds_read_b128 v[196:199], v244 offset:18496
	s_waitcnt lgkmcnt(7)
	v_mfma_f32_16x16x32_bf16 v[58:61], v[200:203], v[212:215], v[58:61]
	v_mfma_f32_16x16x32_bf16 v[62:65], v[200:203], v[216:219], v[62:65]
	v_mfma_f32_16x16x32_bf16 v[26:29], v[200:203], v[220:223], v[26:29]
	v_mfma_f32_16x16x32_bf16 v[30:33], v[200:203], v[224:227], v[30:33]
	ds_read_b128 v[200:203], v244 offset:20800
	s_waitcnt lgkmcnt(7)
	v_mfma_f32_16x16x32_bf16 v[34:37], v[204:207], v[212:215], v[34:37]
	v_mfma_f32_16x16x32_bf16 v[38:41], v[204:207], v[216:219], v[38:41]
	v_mfma_f32_16x16x32_bf16 v[2:5], v[204:207], v[220:223], v[2:5]
	v_mfma_f32_16x16x32_bf16 v[6:9], v[204:207], v[224:227], v[6:9]
	ds_read_b128 v[204:207], v244 offset:23104
	s_waitcnt vmcnt(15)
	ds_write_b128 v98, v[140:143]
	s_waitcnt vmcnt(14)
	ds_write_b128 v98, v[144:147] offset:4608
	s_waitcnt lgkmcnt(9)
	v_mfma_f32_16x16x32_bf16 v[42:45], v[208:211], v[212:215], v[42:45]
	v_mfma_f32_16x16x32_bf16 v[46:49], v[208:211], v[216:219], v[46:49]
	v_mfma_f32_16x16x32_bf16 v[10:13], v[208:211], v[220:223], v[10:13]
	v_mfma_f32_16x16x32_bf16 v[14:17], v[208:211], v[224:227], v[14:17]
	ds_read_b128 v[208:211], v244 offset:25408
	s_waitcnt vmcnt(13)
	ds_write_b128 v98, v[148:151] offset:9216
	s_waitcnt vmcnt(12)
	ds_write_b128 v98, v[152:155] offset:13824
	s_waitcnt lgkmcnt(7)
	v_mfma_f32_16x16x32_bf16 v[50:53], v[196:199], v[228:231], v[50:53]
	v_mfma_f32_16x16x32_bf16 v[54:57], v[196:199], v[232:235], v[54:57]
	v_mfma_f32_16x16x32_bf16 v[18:21], v[196:199], v[236:239], v[18:21]
	v_mfma_f32_16x16x32_bf16 v[22:25], v[196:199], v[240:243], v[22:25]
	s_waitcnt vmcnt(11)
	ds_write_b128 v98, v[156:159] offset:36864
	s_waitcnt vmcnt(10)
	ds_write_b128 v98, v[160:163] offset:41472
	s_waitcnt lgkmcnt(8)
	v_mfma_f32_16x16x32_bf16 v[58:61], v[200:203], v[228:231], v[58:61]
	v_mfma_f32_16x16x32_bf16 v[62:65], v[200:203], v[232:235], v[62:65]
	v_mfma_f32_16x16x32_bf16 v[26:29], v[200:203], v[236:239], v[26:29]
	v_mfma_f32_16x16x32_bf16 v[30:33], v[200:203], v[240:243], v[30:33]
	s_waitcnt vmcnt(9)
	ds_write_b128 v98, v[164:167] offset:46080
	s_waitcnt vmcnt(8)
	ds_write_b128 v98, v[168:171] offset:50688
	s_waitcnt lgkmcnt(0)
	s_barrier
	ds_read_b128 v[212:215], v245 offset:36864
	ds_read_b128 v[196:199], v244
	ds_read_b128 v[216:219], v245 offset:39168
	ds_read_b128 v[220:223], v245 offset:41472
	ds_read_b128 v[224:227], v245 offset:43776
	ds_read_b128 v[200:203], v244 offset:2304
	v_mfma_f32_16x16x32_bf16 v[34:37], v[204:207], v[228:231], v[34:37]
	v_mfma_f32_16x16x32_bf16 v[38:41], v[204:207], v[232:235], v[38:41]
	v_mfma_f32_16x16x32_bf16 v[2:5], v[204:207], v[236:239], v[2:5]
	v_mfma_f32_16x16x32_bf16 v[6:9], v[204:207], v[240:243], v[6:9]
	ds_read_b128 v[204:207], v244 offset:4608
	v_mfma_f32_16x16x32_bf16 v[42:45], v[208:211], v[228:231], v[42:45]
	v_mfma_f32_16x16x32_bf16 v[46:49], v[208:211], v[232:235], v[46:49]
	v_mfma_f32_16x16x32_bf16 v[10:13], v[208:211], v[236:239], v[10:13]
	v_mfma_f32_16x16x32_bf16 v[14:17], v[208:211], v[240:243], v[14:17]
	ds_read_b128 v[208:211], v244 offset:6912
	s_waitcnt lgkmcnt(6)
	v_mfma_f32_16x16x32_bf16 v[50:53], v[196:199], v[212:215], v[50:53]
	ds_read_b128 v[228:231], v245 offset:36928
	s_waitcnt lgkmcnt(6)
	v_mfma_f32_16x16x32_bf16 v[54:57], v[196:199], v[216:219], v[54:57]
	ds_read_b128 v[232:235], v245 offset:39232
	s_waitcnt lgkmcnt(6)
	v_mfma_f32_16x16x32_bf16 v[18:21], v[196:199], v[220:223], v[18:21]
	ds_read_b128 v[236:239], v245 offset:41536
	s_waitcnt lgkmcnt(6)
	v_mfma_f32_16x16x32_bf16 v[22:25], v[196:199], v[224:227], v[22:25]
	ds_read_b128 v[240:243], v245 offset:43840
	ds_read_b128 v[196:199], v244 offset:64
	s_waitcnt lgkmcnt(7)
	v_mfma_f32_16x16x32_bf16 v[58:61], v[200:203], v[212:215], v[58:61]
	v_mfma_f32_16x16x32_bf16 v[62:65], v[200:203], v[216:219], v[62:65]
	v_mfma_f32_16x16x32_bf16 v[26:29], v[200:203], v[220:223], v[26:29]
	v_mfma_f32_16x16x32_bf16 v[30:33], v[200:203], v[224:227], v[30:33]
	ds_read_b128 v[200:203], v244 offset:2368
	s_waitcnt lgkmcnt(7)
	v_mfma_f32_16x16x32_bf16 v[34:37], v[204:207], v[212:215], v[34:37]
	v_mfma_f32_16x16x32_bf16 v[38:41], v[204:207], v[216:219], v[38:41]
	v_mfma_f32_16x16x32_bf16 v[2:5], v[204:207], v[220:223], v[2:5]
	v_mfma_f32_16x16x32_bf16 v[6:9], v[204:207], v[224:227], v[6:9]
	ds_read_b128 v[204:207], v244 offset:4672
	s_waitcnt vmcnt(7)
	ds_write_b128 v98, v[102:105] offset:18432
	s_waitcnt vmcnt(6)
	ds_write_b128 v98, v[74:77] offset:23040
	s_waitcnt lgkmcnt(9)
	v_mfma_f32_16x16x32_bf16 v[42:45], v[208:211], v[212:215], v[42:45]
	v_mfma_f32_16x16x32_bf16 v[46:49], v[208:211], v[216:219], v[46:49]
	v_mfma_f32_16x16x32_bf16 v[10:13], v[208:211], v[220:223], v[10:13]
	v_mfma_f32_16x16x32_bf16 v[14:17], v[208:211], v[224:227], v[14:17]
	ds_read_b128 v[208:211], v244 offset:6976
	s_waitcnt vmcnt(5)
	ds_write_b128 v98, v[106:109] offset:27648
	s_waitcnt vmcnt(4)
	ds_write_b128 v98, v[78:81] offset:32256
	s_waitcnt lgkmcnt(7)
	v_mfma_f32_16x16x32_bf16 v[50:53], v[196:199], v[228:231], v[50:53]
	v_mfma_f32_16x16x32_bf16 v[54:57], v[196:199], v[232:235], v[54:57]
	v_mfma_f32_16x16x32_bf16 v[18:21], v[196:199], v[236:239], v[18:21]
	v_mfma_f32_16x16x32_bf16 v[22:25], v[196:199], v[240:243], v[22:25]
	s_waitcnt vmcnt(3)
	ds_write_b128 v98, v[110:113] offset:55296
	s_waitcnt vmcnt(2)
	ds_write_b128 v98, v[82:85] offset:59904
	s_waitcnt lgkmcnt(8)
	v_mfma_f32_16x16x32_bf16 v[58:61], v[200:203], v[228:231], v[58:61]
	v_mfma_f32_16x16x32_bf16 v[62:65], v[200:203], v[232:235], v[62:65]
	v_mfma_f32_16x16x32_bf16 v[26:29], v[200:203], v[236:239], v[26:29]
	v_mfma_f32_16x16x32_bf16 v[30:33], v[200:203], v[240:243], v[30:33]
	s_waitcnt vmcnt(1)
	ds_write_b128 v98, v[114:117] offset:64512
	s_waitcnt vmcnt(0)
	ds_write_b128 v99, v[86:89] offset:32256
	s_waitcnt lgkmcnt(0)
	s_barrier
	ds_read_b128 v[212:215], v245 offset:55296
	ds_read_b128 v[196:199], v244 offset:18432
	ds_read_b128 v[216:219], v245 offset:57600
	ds_read_b128 v[220:223], v245 offset:59904
	ds_read_b128 v[224:227], v245 offset:62208
	ds_read_b128 v[200:203], v244 offset:20736
	v_mfma_f32_16x16x32_bf16 v[34:37], v[204:207], v[228:231], v[34:37]
	v_mfma_f32_16x16x32_bf16 v[38:41], v[204:207], v[232:235], v[38:41]
	v_mfma_f32_16x16x32_bf16 v[2:5], v[204:207], v[236:239], v[2:5]
	v_mfma_f32_16x16x32_bf16 v[6:9], v[204:207], v[240:243], v[6:9]
	ds_read_b128 v[204:207], v244 offset:23040
	v_mfma_f32_16x16x32_bf16 v[42:45], v[208:211], v[228:231], v[42:45]
	v_mfma_f32_16x16x32_bf16 v[46:49], v[208:211], v[232:235], v[46:49]
	v_mfma_f32_16x16x32_bf16 v[10:13], v[208:211], v[236:239], v[10:13]
	v_mfma_f32_16x16x32_bf16 v[14:17], v[208:211], v[240:243], v[14:17]
	ds_read_b128 v[208:211], v244 offset:25344
	s_waitcnt lgkmcnt(6)
	v_mfma_f32_16x16x32_bf16 v[50:53], v[196:199], v[212:215], v[50:53]
	ds_read_b128 v[228:231], v245 offset:55360
	s_waitcnt lgkmcnt(6)
	v_mfma_f32_16x16x32_bf16 v[54:57], v[196:199], v[216:219], v[54:57]
	ds_read_b128 v[232:235], v245 offset:57664
	s_waitcnt lgkmcnt(6)
	v_mfma_f32_16x16x32_bf16 v[18:21], v[196:199], v[220:223], v[18:21]
	ds_read_b128 v[236:239], v245 offset:59968
	s_waitcnt lgkmcnt(6)
	v_mfma_f32_16x16x32_bf16 v[22:25], v[196:199], v[224:227], v[22:25]
	ds_read_b128 v[240:243], v245 offset:62272
	ds_read_b128 v[196:199], v244 offset:18496
	s_waitcnt lgkmcnt(7)
	v_mfma_f32_16x16x32_bf16 v[58:61], v[200:203], v[212:215], v[58:61]
	v_mfma_f32_16x16x32_bf16 v[62:65], v[200:203], v[216:219], v[62:65]
	v_mfma_f32_16x16x32_bf16 v[26:29], v[200:203], v[220:223], v[26:29]
	v_mfma_f32_16x16x32_bf16 v[30:33], v[200:203], v[224:227], v[30:33]
	ds_read_b128 v[200:203], v244 offset:20800
	s_waitcnt lgkmcnt(7)
	v_mfma_f32_16x16x32_bf16 v[34:37], v[204:207], v[212:215], v[34:37]
	v_mfma_f32_16x16x32_bf16 v[38:41], v[204:207], v[216:219], v[38:41]
	v_mfma_f32_16x16x32_bf16 v[2:5], v[204:207], v[220:223], v[2:5]
	v_mfma_f32_16x16x32_bf16 v[6:9], v[204:207], v[224:227], v[6:9]
	ds_read_b128 v[204:207], v244 offset:23104
	s_waitcnt lgkmcnt(7)
	v_mfma_f32_16x16x32_bf16 v[42:45], v[208:211], v[212:215], v[42:45]
	v_mfma_f32_16x16x32_bf16 v[46:49], v[208:211], v[216:219], v[46:49]
	v_mfma_f32_16x16x32_bf16 v[10:13], v[208:211], v[220:223], v[10:13]
	v_mfma_f32_16x16x32_bf16 v[14:17], v[208:211], v[224:227], v[14:17]
	ds_read_b128 v[208:211], v244 offset:25408
	s_waitcnt lgkmcnt(3)
	v_mfma_f32_16x16x32_bf16 v[50:53], v[196:199], v[228:231], v[50:53]
	v_mfma_f32_16x16x32_bf16 v[54:57], v[196:199], v[232:235], v[54:57]
	v_mfma_f32_16x16x32_bf16 v[18:21], v[196:199], v[236:239], v[18:21]
	v_mfma_f32_16x16x32_bf16 v[22:25], v[196:199], v[240:243], v[22:25]
	s_waitcnt lgkmcnt(2)
	v_mfma_f32_16x16x32_bf16 v[58:61], v[200:203], v[228:231], v[58:61]
	v_mfma_f32_16x16x32_bf16 v[62:65], v[200:203], v[232:235], v[62:65]
	v_mfma_f32_16x16x32_bf16 v[26:29], v[200:203], v[236:239], v[26:29]
	v_mfma_f32_16x16x32_bf16 v[30:33], v[200:203], v[240:243], v[30:33]
	s_lshr_b32 s14, s2, 3
	s_bfe_u32 s13, s2, 0x10002
	s_cmp_lt_i32 s14, 1
	s_mov_b64 s[2:3], -1
	s_waitcnt lgkmcnt(0)
	s_barrier
	v_mfma_f32_16x16x32_bf16 v[34:37], v[204:207], v[228:231], v[34:37]
	v_mfma_f32_16x16x32_bf16 v[38:41], v[204:207], v[232:235], v[38:41]
	v_mfma_f32_16x16x32_bf16 v[2:5], v[204:207], v[236:239], v[2:5]
	v_mfma_f32_16x16x32_bf16 v[6:9], v[204:207], v[240:243], v[6:9]
	v_mfma_f32_16x16x32_bf16 v[42:45], v[208:211], v[228:231], v[42:45]
	v_mfma_f32_16x16x32_bf16 v[46:49], v[208:211], v[232:235], v[46:49]
	v_mfma_f32_16x16x32_bf16 v[10:13], v[208:211], v[236:239], v[10:13]
	v_mfma_f32_16x16x32_bf16 v[14:17], v[208:211], v[240:243], v[14:17]
	s_nop 7
	v_permlane16_swap_b32_e32 v50, v54
	v_permlane16_swap_b32_e32 v51, v55
	v_permlane16_swap_b32_e32 v52, v56
	v_permlane16_swap_b32_e32 v53, v57
	v_permlane16_swap_b32_e32 v58, v62
	v_permlane16_swap_b32_e32 v59, v63
	v_permlane16_swap_b32_e32 v60, v64
	v_permlane16_swap_b32_e32 v61, v65
	v_permlane16_swap_b32_e32 v18, v22
	v_permlane16_swap_b32_e32 v19, v23
	v_permlane16_swap_b32_e32 v20, v24
	v_permlane16_swap_b32_e32 v21, v25
	v_permlane16_swap_b32_e32 v26, v30
	v_permlane16_swap_b32_e32 v27, v31
	v_permlane16_swap_b32_e32 v28, v32
	v_permlane16_swap_b32_e32 v29, v33
	v_permlane16_swap_b32_e32 v34, v38
	v_permlane16_swap_b32_e32 v35, v39
	v_permlane16_swap_b32_e32 v36, v40
	v_permlane16_swap_b32_e32 v37, v41
	v_permlane16_swap_b32_e32 v42, v46
	v_permlane16_swap_b32_e32 v43, v47
	v_permlane16_swap_b32_e32 v44, v48
	v_permlane16_swap_b32_e32 v45, v49
	v_permlane16_swap_b32_e32 v2, v6
	v_permlane16_swap_b32_e32 v3, v7
	v_permlane16_swap_b32_e32 v4, v8
	v_permlane16_swap_b32_e32 v5, v9
	v_permlane16_swap_b32_e32 v10, v14
	v_permlane16_swap_b32_e32 v11, v15
	v_permlane16_swap_b32_e32 v12, v16
	v_permlane16_swap_b32_e32 v13, v17
	v_permlane32_swap_b32_e32 v50, v54
	v_permlane32_swap_b32_e32 v51, v55
	v_permlane32_swap_b32_e32 v52, v56
	v_permlane32_swap_b32_e32 v53, v57
	v_permlane32_swap_b32_e32 v58, v62
	v_permlane32_swap_b32_e32 v59, v63
	v_permlane32_swap_b32_e32 v60, v64
	v_permlane32_swap_b32_e32 v61, v65
	v_permlane32_swap_b32_e32 v18, v22
	v_permlane32_swap_b32_e32 v19, v23
	v_permlane32_swap_b32_e32 v20, v24
	v_permlane32_swap_b32_e32 v21, v25
	v_permlane32_swap_b32_e32 v26, v30
	v_permlane32_swap_b32_e32 v27, v31
	v_permlane32_swap_b32_e32 v28, v32
	v_permlane32_swap_b32_e32 v29, v33
	v_permlane32_swap_b32_e32 v34, v38
	v_permlane32_swap_b32_e32 v35, v39
	v_permlane32_swap_b32_e32 v36, v40
	v_permlane32_swap_b32_e32 v37, v41
	v_permlane32_swap_b32_e32 v42, v46
	v_permlane32_swap_b32_e32 v43, v47
	v_permlane32_swap_b32_e32 v44, v48
	v_permlane32_swap_b32_e32 v45, v49
	v_permlane32_swap_b32_e32 v2, v6
	v_permlane32_swap_b32_e32 v3, v7
	v_permlane32_swap_b32_e32 v4, v8
	v_permlane32_swap_b32_e32 v5, v9
	v_permlane32_swap_b32_e32 v10, v14
	v_permlane32_swap_b32_e32 v11, v15
	v_permlane32_swap_b32_e32 v12, v16
	v_permlane32_swap_b32_e32 v13, v17
	s_cbranch_scc1 .LBB0_755
	s_and_b32 s2, 0xffff, s14
	s_cmp_lg_u32 s2, 1
	s_mov_b64 s[2:3], -1
	s_cbranch_scc0 .LBB0_752
	s_cmp_eq_u32 s13, 0
	s_cselect_b32 s12, 3, 10
	s_mov_b64 s[2:3], 0

.LBB0_828:
	s_lshr_b32 s8, s0, 2
	s_lshl_b32 s0, s0, 7
	s_and_b32 s7, s0, 0x180
	v_or_b32_e32 v2, s7, v93
	v_lshlrev_b32_e32 v74, 10, v2
	s_add_i32 s8, s8, s4
	v_lshl_add_u64 v[66:67], v[76:77], 0, v[74:75]
	v_add_lshl_u32 v74, s7, v94, 10
	s_lshl_b32 s0, s8, 7
	v_lshl_add_u64 v[68:69], v[76:77], 0, v[74:75]
	v_add_lshl_u32 v74, s7, v95, 10
	v_lshl_add_u64 v[70:71], v[76:77], 0, v[74:75]
	v_add_lshl_u32 v74, s7, v96, 10
	v_or_b32_e32 v2, s0, v93
	v_lshl_add_u64 v[72:73], v[76:77], 0, v[74:75]
	v_lshlrev_b32_e32 v74, 10, v2
	v_lshl_add_u64 v[84:85], v[78:79], 0, v[74:75]
	v_add_lshl_u32 v74, s0, v94, 10
	v_lshl_add_u64 v[86:87], v[78:79], 0, v[74:75]
	v_add_lshl_u32 v74, s0, v95, 10
	v_lshl_add_u64 v[88:89], v[78:79], 0, v[74:75]
	v_add_lshl_u32 v74, s0, v96, 10
	v_lshl_add_u64 v[90:91], v[78:79], 0, v[74:75]
	global_load_dwordx4 v[2:5], v[66:67], off
	global_load_dwordx4 v[6:9], v[68:69], off
	global_load_dwordx4 v[10:13], v[70:71], off
	global_load_dwordx4 v[14:17], v[72:73], off
	global_load_dwordx4 v[18:21], v[84:85], off
	global_load_dwordx4 v[22:25], v[86:87], off
	global_load_dwordx4 v[26:29], v[88:89], off
	global_load_dwordx4 v[30:33], v[90:91], off
	global_load_dwordx4 v[102:105], v[66:67], off offset:128
	global_load_dwordx4 v[106:109], v[68:69], off offset:128
	global_load_dwordx4 v[110:113], v[70:71], off offset:128
	global_load_dwordx4 v[114:117], v[72:73], off offset:128
	global_load_dwordx4 v[118:121], v[84:85], off offset:128
	global_load_dwordx4 v[122:125], v[86:87], off offset:128
	global_load_dwordx4 v[126:129], v[88:89], off offset:128
	global_load_dwordx4 v[136:139], v[90:91], off offset:128
	s_waitcnt vmcnt(15)
	ds_write_b128 v100, v[2:5]
	s_waitcnt vmcnt(14)
	ds_write_b128 v100, v[6:9] offset:4608
	s_waitcnt vmcnt(13)
	ds_write_b128 v100, v[10:13] offset:9216
	s_waitcnt vmcnt(12)
	ds_write_b128 v100, v[14:17] offset:13824
	s_waitcnt vmcnt(11)
	ds_write_b128 v100, v[18:21] offset:36864
	s_waitcnt vmcnt(10)
	ds_write_b128 v100, v[22:25] offset:41472
	s_waitcnt vmcnt(9)
	ds_write_b128 v100, v[26:29] offset:46080
	s_waitcnt vmcnt(8)
	ds_write_b128 v100, v[30:33] offset:50688
	s_waitcnt lgkmcnt(0)
	s_barrier
	global_load_dwordx4 v[140:143], v[66:67], off offset:256
	global_load_dwordx4 v[144:147], v[68:69], off offset:256
	global_load_dwordx4 v[148:151], v[70:71], off offset:256
	global_load_dwordx4 v[152:155], v[72:73], off offset:256
	global_load_dwordx4 v[156:159], v[84:85], off offset:256
	global_load_dwordx4 v[160:163], v[86:87], off offset:256
	global_load_dwordx4 v[164:167], v[88:89], off offset:256
	global_load_dwordx4 v[168:171], v[90:91], off offset:256
	v_and_b32_e32 v246, 15, v1
	v_add_u32_e32 v246, 4, v246
	v_bfe_u32 v246, v246, 3, 1
	v_bfe_u32 v249, v1, 4, 2
	v_xor_b32_e32 v246, v246, v249
	v_bfe_u32 v249, v1, 5, 1
	v_sub_u32_e32 v246, v246, v249
	v_lshlrev_b32_e32 v246, 4, v246
	v_bfe_u32 v249, v1, 4, 1
	v_mul_u32_u24_e32 v249, 0x900, v249
	v_sub_u32_e32 v246, v246, v249
	v_add_u32_e32 v244, v246, v98
	v_add_u32_e32 v245, v246, v99
	ds_read_b128 v[212:215], v245 offset:36864
	ds_read_b128 v[196:199], v244
	ds_read_b128 v[216:219], v245 offset:39168
	ds_read_b128 v[220:223], v245 offset:41472
	ds_read_b128 v[224:227], v245 offset:43776
	ds_read_b128 v[200:203], v244 offset:2304
	ds_read_b128 v[204:207], v244 offset:4608
	ds_read_b128 v[208:211], v244 offset:6912
	s_waitcnt lgkmcnt(6)
	v_mfma_f32_16x16x32_bf16 v[50:53], v[196:199], v[212:215], 0
	ds_read_b128 v[228:231], v245 offset:36928
	s_waitcnt lgkmcnt(6)
	v_mfma_f32_16x16x32_bf16 v[54:57], v[196:199], v[216:219], 0
	ds_read_b128 v[232:235], v245 offset:39232
	s_waitcnt lgkmcnt(6)
	v_mfma_f32_16x16x32_bf16 v[18:21], v[196:199], v[220:223], 0
	ds_read_b128 v[236:239], v245 offset:41536
	s_waitcnt lgkmcnt(6)
	v_mfma_f32_16x16x32_bf16 v[22:25], v[196:199], v[224:227], 0
	ds_read_b128 v[240:243], v245 offset:43840
	ds_read_b128 v[196:199], v244 offset:64
	s_waitcnt lgkmcnt(7)
	v_mfma_f32_16x16x32_bf16 v[58:61], v[200:203], v[212:215], 0
	v_mfma_f32_16x16x32_bf16 v[62:65], v[200:203], v[216:219], 0
	v_mfma_f32_16x16x32_bf16 v[26:29], v[200:203], v[220:223], 0
	v_mfma_f32_16x16x32_bf16 v[30:33], v[200:203], v[224:227], 0
	ds_read_b128 v[200:203], v244 offset:2368
	s_waitcnt lgkmcnt(7)
	v_mfma_f32_16x16x32_bf16 v[34:37], v[204:207], v[212:215], 0
	v_mfma_f32_16x16x32_bf16 v[38:41], v[204:207], v[216:219], 0
	v_mfma_f32_16x16x32_bf16 v[2:5], v[204:207], v[220:223], 0
	v_mfma_f32_16x16x32_bf16 v[6:9], v[204:207], v[224:227], 0
	ds_read_b128 v[204:207], v244 offset:4672
	s_waitcnt vmcnt(15)
	ds_write_b128 v100, v[102:105] offset:18432
	s_waitcnt vmcnt(14)
	ds_write_b128 v100, v[106:109] offset:23040
	s_waitcnt lgkmcnt(9)
	v_mfma_f32_16x16x32_bf16 v[42:45], v[208:211], v[212:215], 0
	v_mfma_f32_16x16x32_bf16 v[46:49], v[208:211], v[216:219], 0
	v_mfma_f32_16x16x32_bf16 v[10:13], v[208:211], v[220:223], 0
	v_mfma_f32_16x16x32_bf16 v[14:17], v[208:211], v[224:227], 0
	ds_read_b128 v[208:211], v244 offset:6976
	s_waitcnt vmcnt(13)
	ds_write_b128 v100, v[110:113] offset:27648
	s_waitcnt vmcnt(12)
	ds_write_b128 v100, v[114:117] offset:32256
	s_waitcnt lgkmcnt(7)
	v_mfma_f32_16x16x32_bf16 v[50:53], v[196:199], v[228:231], v[50:53]
	v_mfma_f32_16x16x32_bf16 v[54:57], v[196:199], v[232:235], v[54:57]
	v_mfma_f32_16x16x32_bf16 v[18:21], v[196:199], v[236:239], v[18:21]
	v_mfma_f32_16x16x32_bf16 v[22:25], v[196:199], v[240:243], v[22:25]
	s_waitcnt vmcnt(11)
	ds_write_b128 v100, v[118:121] offset:55296
	s_waitcnt vmcnt(10)
	ds_write_b128 v100, v[122:125] offset:59904
	s_waitcnt lgkmcnt(8)
	v_mfma_f32_16x16x32_bf16 v[58:61], v[200:203], v[228:231], v[58:61]
	v_mfma_f32_16x16x32_bf16 v[62:65], v[200:203], v[232:235], v[62:65]
	v_mfma_f32_16x16x32_bf16 v[26:29], v[200:203], v[236:239], v[26:29]
	v_mfma_f32_16x16x32_bf16 v[30:33], v[200:203], v[240:243], v[30:33]
	s_waitcnt vmcnt(9)
	ds_write_b128 v100, v[126:129] offset:64512
	s_waitcnt vmcnt(8)
	ds_write_b128 v101, v[136:139] offset:32256
	s_waitcnt lgkmcnt(0)
	s_barrier
	ds_read_b128 v[212:215], v245 offset:55296
	ds_read_b128 v[196:199], v244 offset:18432
	ds_read_b128 v[216:219], v245 offset:57600
	ds_read_b128 v[220:223], v245 offset:59904
	ds_read_b128 v[224:227], v245 offset:62208
	ds_read_b128 v[200:203], v244 offset:20736
	v_mfma_f32_16x16x32_bf16 v[34:37], v[204:207], v[228:231], v[34:37]
	v_mfma_f32_16x16x32_bf16 v[38:41], v[204:207], v[232:235], v[38:41]
	v_mfma_f32_16x16x32_bf16 v[2:5], v[204:207], v[236:239], v[2:5]
	v_mfma_f32_16x16x32_bf16 v[6:9], v[204:207], v[240:243], v[6:9]
	ds_read_b128 v[204:207], v244 offset:23040
	v_mfma_f32_16x16x32_bf16 v[42:45], v[208:211], v[228:231], v[42:45]
	v_mfma_f32_16x16x32_bf16 v[46:49], v[208:211], v[232:235], v[46:49]
	v_mfma_f32_16x16x32_bf16 v[10:13], v[208:211], v[236:239], v[10:13]
	v_mfma_f32_16x16x32_bf16 v[14:17], v[208:211], v[240:243], v[14:17]
	ds_read_b128 v[208:211], v244 offset:25344
	global_load_dwordx4 v[102:105], v[66:67], off offset:384
	global_load_dwordx4 v[106:109], v[68:69], off offset:384
	global_load_dwordx4 v[110:113], v[70:71], off offset:384
	global_load_dwordx4 v[114:117], v[72:73], off offset:384
	global_load_dwordx4 v[118:121], v[84:85], off offset:384
	global_load_dwordx4 v[122:125], v[86:87], off offset:384
	global_load_dwordx4 v[126:129], v[88:89], off offset:384
	global_load_dwordx4 v[136:139], v[90:91], off offset:384
	s_waitcnt lgkmcnt(6)
	v_mfma_f32_16x16x32_bf16 v[50:53], v[196:199], v[212:215], v[50:53]
	ds_read_b128 v[228:231], v245 offset:55360
	s_waitcnt lgkmcnt(6)
	v_mfma_f32_16x16x32_bf16 v[54:57], v[196:199], v[216:219], v[54:57]
	ds_read_b128 v[232:235], v245 offset:57664
	s_waitcnt lgkmcnt(6)
	v_mfma_f32_16x16x32_bf16 v[18:21], v[196:199], v[220:223], v[18:21]
	ds_read_b128 v[236:239], v245 offset:59968
	s_waitcnt lgkmcnt(6)
	v_mfma_f32_16x16x32_bf16 v[22:25], v[196:199], v[224:227], v[22:25]
	ds_read_b128 v[240:243], v245 offset:62272
	ds_read_b128 v[196:199], v244 offset:18496
	s_waitcnt lgkmcnt(7)
	v_mfma_f32_16x16x32_bf16 v[58:61], v[200:203], v[212:215], v[58:61]
	v_mfma_f32_16x16x32_bf16 v[62:65], v[200:203], v[216:219], v[62:65]
	v_mfma_f32_16x16x32_bf16 v[26:29], v[200:203], v[220:223], v[26:29]
	v_mfma_f32_16x16x32_bf16 v[30:33], v[200:203], v[224:227], v[30:33]
	ds_read_b128 v[200:203], v244 offset:20800
	s_waitcnt lgkmcnt(7)
	v_mfma_f32_16x16x32_bf16 v[34:37], v[204:207], v[212:215], v[34:37]
	v_mfma_f32_16x16x32_bf16 v[38:41], v[204:207], v[216:219], v[38:41]
	v_mfma_f32_16x16x32_bf16 v[2:5], v[204:207], v[220:223], v[2:5]
	v_mfma_f32_16x16x32_bf16 v[6:9], v[204:207], v[224:227], v[6:9]
	ds_read_b128 v[204:207], v244 offset:23104
	s_waitcnt vmcnt(15)
	ds_write_b128 v100, v[140:143]
	s_waitcnt vmcnt(14)
	ds_write_b128 v100, v[144:147] offset:4608
	s_waitcnt lgkmcnt(9)
	v_mfma_f32_16x16x32_bf16 v[42:45], v[208:211], v[212:215], v[42:45]
	v_mfma_f32_16x16x32_bf16 v[46:49], v[208:211], v[216:219], v[46:49]
	v_mfma_f32_16x16x32_bf16 v[10:13], v[208:211], v[220:223], v[10:13]
	v_mfma_f32_16x16x32_bf16 v[14:17], v[208:211], v[224:227], v[14:17]
	ds_read_b128 v[208:211], v244 offset:25408
	s_waitcnt vmcnt(13)
	ds_write_b128 v100, v[148:151] offset:9216
	s_waitcnt vmcnt(12)
	ds_write_b128 v100, v[152:155] offset:13824
	s_waitcnt lgkmcnt(7)
	v_mfma_f32_16x16x32_bf16 v[50:53], v[196:199], v[228:231], v[50:53]
	v_mfma_f32_16x16x32_bf16 v[54:57], v[196:199], v[232:235], v[54:57]
	v_mfma_f32_16x16x32_bf16 v[18:21], v[196:199], v[236:239], v[18:21]
	v_mfma_f32_16x16x32_bf16 v[22:25], v[196:199], v[240:243], v[22:25]
	s_waitcnt vmcnt(11)
	ds_write_b128 v100, v[156:159] offset:36864
	s_waitcnt vmcnt(10)
	ds_write_b128 v100, v[160:163] offset:41472
	s_waitcnt lgkmcnt(8)
	v_mfma_f32_16x16x32_bf16 v[58:61], v[200:203], v[228:231], v[58:61]
	v_mfma_f32_16x16x32_bf16 v[62:65], v[200:203], v[232:235], v[62:65]
	v_mfma_f32_16x16x32_bf16 v[26:29], v[200:203], v[236:239], v[26:29]
	v_mfma_f32_16x16x32_bf16 v[30:33], v[200:203], v[240:243], v[30:33]
	s_waitcnt vmcnt(9)
	ds_write_b128 v100, v[164:167] offset:46080
	s_waitcnt vmcnt(8)
	ds_write_b128 v100, v[168:171] offset:50688
	s_waitcnt lgkmcnt(0)
	s_barrier
	ds_read_b128 v[212:215], v245 offset:36864
	ds_read_b128 v[196:199], v244
	ds_read_b128 v[216:219], v245 offset:39168
	ds_read_b128 v[220:223], v245 offset:41472
	ds_read_b128 v[224:227], v245 offset:43776
	ds_read_b128 v[200:203], v244 offset:2304
	v_mfma_f32_16x16x32_bf16 v[34:37], v[204:207], v[228:231], v[34:37]
	v_mfma_f32_16x16x32_bf16 v[38:41], v[204:207], v[232:235], v[38:41]
	v_mfma_f32_16x16x32_bf16 v[2:5], v[204:207], v[236:239], v[2:5]
	v_mfma_f32_16x16x32_bf16 v[6:9], v[204:207], v[240:243], v[6:9]
	ds_read_b128 v[204:207], v244 offset:4608
	v_mfma_f32_16x16x32_bf16 v[42:45], v[208:211], v[228:231], v[42:45]
	v_mfma_f32_16x16x32_bf16 v[46:49], v[208:211], v[232:235], v[46:49]
	v_mfma_f32_16x16x32_bf16 v[10:13], v[208:211], v[236:239], v[10:13]
	v_mfma_f32_16x16x32_bf16 v[14:17], v[208:211], v[240:243], v[14:17]
	ds_read_b128 v[208:211], v244 offset:6912
	global_load_dwordx4 v[140:143], v[66:67], off offset:512
	global_load_dwordx4 v[144:147], v[68:69], off offset:512
	global_load_dwordx4 v[148:151], v[70:71], off offset:512
	global_load_dwordx4 v[152:155], v[72:73], off offset:512
	global_load_dwordx4 v[156:159], v[84:85], off offset:512
	global_load_dwordx4 v[160:163], v[86:87], off offset:512
	global_load_dwordx4 v[164:167], v[88:89], off offset:512
	global_load_dwordx4 v[168:171], v[90:91], off offset:512
	s_waitcnt lgkmcnt(6)
	v_mfma_f32_16x16x32_bf16 v[50:53], v[196:199], v[212:215], v[50:53]
	ds_read_b128 v[228:231], v245 offset:36928
	s_waitcnt lgkmcnt(6)
	v_mfma_f32_16x16x32_bf16 v[54:57], v[196:199], v[216:219], v[54:57]
	ds_read_b128 v[232:235], v245 offset:39232
	s_waitcnt lgkmcnt(6)
	v_mfma_f32_16x16x32_bf16 v[18:21], v[196:199], v[220:223], v[18:21]
	ds_read_b128 v[236:239], v245 offset:41536
	s_waitcnt lgkmcnt(6)
	v_mfma_f32_16x16x32_bf16 v[22:25], v[196:199], v[224:227], v[22:25]
	ds_read_b128 v[240:243], v245 offset:43840
	ds_read_b128 v[196:199], v244 offset:64
	s_waitcnt lgkmcnt(7)
	v_mfma_f32_16x16x32_bf16 v[58:61], v[200:203], v[212:215], v[58:61]
	v_mfma_f32_16x16x32_bf16 v[62:65], v[200:203], v[216:219], v[62:65]
	v_mfma_f32_16x16x32_bf16 v[26:29], v[200:203], v[220:223], v[26:29]
	v_mfma_f32_16x16x32_bf16 v[30:33], v[200:203], v[224:227], v[30:33]
	ds_read_b128 v[200:203], v244 offset:2368
	s_waitcnt lgkmcnt(7)
	v_mfma_f32_16x16x32_bf16 v[34:37], v[204:207], v[212:215], v[34:37]
	v_mfma_f32_16x16x32_bf16 v[38:41], v[204:207], v[216:219], v[38:41]
	v_mfma_f32_16x16x32_bf16 v[2:5], v[204:207], v[220:223], v[2:5]
	v_mfma_f32_16x16x32_bf16 v[6:9], v[204:207], v[224:227], v[6:9]
	ds_read_b128 v[204:207], v244 offset:4672
	s_waitcnt vmcnt(15)
	ds_write_b128 v100, v[102:105] offset:18432
	s_waitcnt vmcnt(14)
	ds_write_b128 v100, v[106:109] offset:23040
	s_waitcnt lgkmcnt(9)
	v_mfma_f32_16x16x32_bf16 v[42:45], v[208:211], v[212:215], v[42:45]
	v_mfma_f32_16x16x32_bf16 v[46:49], v[208:211], v[216:219], v[46:49]
	v_mfma_f32_16x16x32_bf16 v[10:13], v[208:211], v[220:223], v[10:13]
	v_mfma_f32_16x16x32_bf16 v[14:17], v[208:211], v[224:227], v[14:17]
	ds_read_b128 v[208:211], v244 offset:6976
	s_waitcnt vmcnt(13)
	ds_write_b128 v100, v[110:113] offset:27648
	s_waitcnt vmcnt(12)
	ds_write_b128 v100, v[114:117] offset:32256
	s_waitcnt lgkmcnt(7)
	v_mfma_f32_16x16x32_bf16 v[50:53], v[196:199], v[228:231], v[50:53]
	v_mfma_f32_16x16x32_bf16 v[54:57], v[196:199], v[232:235], v[54:57]
	v_mfma_f32_16x16x32_bf16 v[18:21], v[196:199], v[236:239], v[18:21]
	v_mfma_f32_16x16x32_bf16 v[22:25], v[196:199], v[240:243], v[22:25]
	s_waitcnt vmcnt(11)
	ds_write_b128 v100, v[118:121] offset:55296
	s_waitcnt vmcnt(10)
	ds_write_b128 v100, v[122:125] offset:59904
	s_waitcnt lgkmcnt(8)
	v_mfma_f32_16x16x32_bf16 v[58:61], v[200:203], v[228:231], v[58:61]
	v_mfma_f32_16x16x32_bf16 v[62:65], v[200:203], v[232:235], v[62:65]
	v_mfma_f32_16x16x32_bf16 v[26:29], v[200:203], v[236:239], v[26:29]
	v_mfma_f32_16x16x32_bf16 v[30:33], v[200:203], v[240:243], v[30:33]
	s_waitcnt vmcnt(9)
	ds_write_b128 v100, v[126:129] offset:64512
	s_waitcnt vmcnt(8)
	ds_write_b128 v101, v[136:139] offset:32256
	s_waitcnt lgkmcnt(0)
	s_barrier
	ds_read_b128 v[212:215], v245 offset:55296
	ds_read_b128 v[196:199], v244 offset:18432
	ds_read_b128 v[216:219], v245 offset:57600
	ds_read_b128 v[220:223], v245 offset:59904
	ds_read_b128 v[224:227], v245 offset:62208
	ds_read_b128 v[200:203], v244 offset:20736
	v_mfma_f32_16x16x32_bf16 v[34:37], v[204:207], v[228:231], v[34:37]
	v_mfma_f32_16x16x32_bf16 v[38:41], v[204:207], v[232:235], v[38:41]
	v_mfma_f32_16x16x32_bf16 v[2:5], v[204:207], v[236:239], v[2:5]
	v_mfma_f32_16x16x32_bf16 v[6:9], v[204:207], v[240:243], v[6:9]
	ds_read_b128 v[204:207], v244 offset:23040
	v_mfma_f32_16x16x32_bf16 v[42:45], v[208:211], v[228:231], v[42:45]
	v_mfma_f32_16x16x32_bf16 v[46:49], v[208:211], v[232:235], v[46:49]
	v_mfma_f32_16x16x32_bf16 v[10:13], v[208:211], v[236:239], v[10:13]
	v_mfma_f32_16x16x32_bf16 v[14:17], v[208:211], v[240:243], v[14:17]
	ds_read_b128 v[208:211], v244 offset:25344
	global_load_dwordx4 v[102:105], v[66:67], off offset:640
	global_load_dwordx4 v[106:109], v[68:69], off offset:640
	global_load_dwordx4 v[110:113], v[70:71], off offset:640
	global_load_dwordx4 v[114:117], v[72:73], off offset:640
	global_load_dwordx4 v[118:121], v[84:85], off offset:640
	global_load_dwordx4 v[122:125], v[86:87], off offset:640
	global_load_dwordx4 v[126:129], v[88:89], off offset:640
	global_load_dwordx4 v[136:139], v[90:91], off offset:640
	s_waitcnt lgkmcnt(6)
	v_mfma_f32_16x16x32_bf16 v[50:53], v[196:199], v[212:215], v[50:53]
	ds_read_b128 v[228:231], v245 offset:55360
	s_waitcnt lgkmcnt(6)
	v_mfma_f32_16x16x32_bf16 v[54:57], v[196:199], v[216:219], v[54:57]
	ds_read_b128 v[232:235], v245 offset:57664
	s_waitcnt lgkmcnt(6)
	v_mfma_f32_16x16x32_bf16 v[18:21], v[196:199], v[220:223], v[18:21]
	ds_read_b128 v[236:239], v245 offset:59968
	s_waitcnt lgkmcnt(6)
	v_mfma_f32_16x16x32_bf16 v[22:25], v[196:199], v[224:227], v[22:25]
	ds_read_b128 v[240:243], v245 offset:62272
	ds_read_b128 v[196:199], v244 offset:18496
	s_waitcnt lgkmcnt(7)
	v_mfma_f32_16x16x32_bf16 v[58:61], v[200:203], v[212:215], v[58:61]
	v_mfma_f32_16x16x32_bf16 v[62:65], v[200:203], v[216:219], v[62:65]
	v_mfma_f32_16x16x32_bf16 v[26:29], v[200:203], v[220:223], v[26:29]
	v_mfma_f32_16x16x32_bf16 v[30:33], v[200:203], v[224:227], v[30:33]
	ds_read_b128 v[200:203], v244 offset:20800
	s_waitcnt lgkmcnt(7)
	v_mfma_f32_16x16x32_bf16 v[34:37], v[204:207], v[212:215], v[34:37]
	v_mfma_f32_16x16x32_bf16 v[38:41], v[204:207], v[216:219], v[38:41]
	v_mfma_f32_16x16x32_bf16 v[2:5], v[204:207], v[220:223], v[2:5]
	v_mfma_f32_16x16x32_bf16 v[6:9], v[204:207], v[224:227], v[6:9]
	ds_read_b128 v[204:207], v244 offset:23104
	s_waitcnt vmcnt(15)
	ds_write_b128 v100, v[140:143]
	s_waitcnt vmcnt(14)
	ds_write_b128 v100, v[144:147] offset:4608
	s_waitcnt lgkmcnt(9)
	v_mfma_f32_16x16x32_bf16 v[42:45], v[208:211], v[212:215], v[42:45]
	v_mfma_f32_16x16x32_bf16 v[46:49], v[208:211], v[216:219], v[46:49]
	v_mfma_f32_16x16x32_bf16 v[10:13], v[208:211], v[220:223], v[10:13]
	v_mfma_f32_16x16x32_bf16 v[14:17], v[208:211], v[224:227], v[14:17]
	ds_read_b128 v[208:211], v244 offset:25408
	s_waitcnt vmcnt(13)
	ds_write_b128 v100, v[148:151] offset:9216
	s_waitcnt vmcnt(12)
	ds_write_b128 v100, v[152:155] offset:13824
	s_waitcnt lgkmcnt(7)
	v_mfma_f32_16x16x32_bf16 v[50:53], v[196:199], v[228:231], v[50:53]
	v_mfma_f32_16x16x32_bf16 v[54:57], v[196:199], v[232:235], v[54:57]
	v_mfma_f32_16x16x32_bf16 v[18:21], v[196:199], v[236:239], v[18:21]
	v_mfma_f32_16x16x32_bf16 v[22:25], v[196:199], v[240:243], v[22:25]
	s_waitcnt vmcnt(11)
	ds_write_b128 v100, v[156:159] offset:36864
	s_waitcnt vmcnt(10)
	ds_write_b128 v100, v[160:163] offset:41472
	s_waitcnt lgkmcnt(8)
	v_mfma_f32_16x16x32_bf16 v[58:61], v[200:203], v[228:231], v[58:61]
	v_mfma_f32_16x16x32_bf16 v[62:65], v[200:203], v[232:235], v[62:65]
	v_mfma_f32_16x16x32_bf16 v[26:29], v[200:203], v[236:239], v[26:29]
	v_mfma_f32_16x16x32_bf16 v[30:33], v[200:203], v[240:243], v[30:33]
	s_waitcnt vmcnt(9)
	ds_write_b128 v100, v[164:167] offset:46080
	s_waitcnt vmcnt(8)
	ds_write_b128 v100, v[168:171] offset:50688
	s_waitcnt lgkmcnt(0)
	s_barrier
	ds_read_b128 v[212:215], v245 offset:36864
	ds_read_b128 v[196:199], v244
	ds_read_b128 v[216:219], v245 offset:39168
	ds_read_b128 v[220:223], v245 offset:41472
	ds_read_b128 v[224:227], v245 offset:43776
	ds_read_b128 v[200:203], v244 offset:2304
	v_mfma_f32_16x16x32_bf16 v[34:37], v[204:207], v[228:231], v[34:37]
	v_mfma_f32_16x16x32_bf16 v[38:41], v[204:207], v[232:235], v[38:41]
	v_mfma_f32_16x16x32_bf16 v[2:5], v[204:207], v[236:239], v[2:5]
	v_mfma_f32_16x16x32_bf16 v[6:9], v[204:207], v[240:243], v[6:9]
	ds_read_b128 v[204:207], v244 offset:4608
	v_mfma_f32_16x16x32_bf16 v[42:45], v[208:211], v[228:231], v[42:45]
	v_mfma_f32_16x16x32_bf16 v[46:49], v[208:211], v[232:235], v[46:49]
	v_mfma_f32_16x16x32_bf16 v[10:13], v[208:211], v[236:239], v[10:13]
	v_mfma_f32_16x16x32_bf16 v[14:17], v[208:211], v[240:243], v[14:17]
	ds_read_b128 v[208:211], v244 offset:6912
	global_load_dwordx4 v[140:143], v[66:67], off offset:768
	global_load_dwordx4 v[144:147], v[68:69], off offset:768
	global_load_dwordx4 v[148:151], v[70:71], off offset:768
	global_load_dwordx4 v[152:155], v[72:73], off offset:768
	global_load_dwordx4 v[156:159], v[84:85], off offset:768
	global_load_dwordx4 v[160:163], v[86:87], off offset:768
	global_load_dwordx4 v[164:167], v[88:89], off offset:768
	global_load_dwordx4 v[168:171], v[90:91], off offset:768
	s_waitcnt lgkmcnt(6)
	v_mfma_f32_16x16x32_bf16 v[50:53], v[196:199], v[212:215], v[50:53]
	ds_read_b128 v[228:231], v245 offset:36928
	s_waitcnt lgkmcnt(6)
	v_mfma_f32_16x16x32_bf16 v[54:57], v[196:199], v[216:219], v[54:57]
	ds_read_b128 v[232:235], v245 offset:39232
	s_waitcnt lgkmcnt(6)
	v_mfma_f32_16x16x32_bf16 v[18:21], v[196:199], v[220:223], v[18:21]
	ds_read_b128 v[236:239], v245 offset:41536
	s_waitcnt lgkmcnt(6)
	v_mfma_f32_16x16x32_bf16 v[22:25], v[196:199], v[224:227], v[22:25]
	ds_read_b128 v[240:243], v245 offset:43840
	ds_read_b128 v[196:199], v244 offset:64
	s_waitcnt lgkmcnt(7)
	v_mfma_f32_16x16x32_bf16 v[58:61], v[200:203], v[212:215], v[58:61]
	v_mfma_f32_16x16x32_bf16 v[62:65], v[200:203], v[216:219], v[62:65]
	v_mfma_f32_16x16x32_bf16 v[26:29], v[200:203], v[220:223], v[26:29]
	v_mfma_f32_16x16x32_bf16 v[30:33], v[200:203], v[224:227], v[30:33]
	ds_read_b128 v[200:203], v244 offset:2368
	s_waitcnt lgkmcnt(7)
	v_mfma_f32_16x16x32_bf16 v[34:37], v[204:207], v[212:215], v[34:37]
	v_mfma_f32_16x16x32_bf16 v[38:41], v[204:207], v[216:219], v[38:41]
	v_mfma_f32_16x16x32_bf16 v[2:5], v[204:207], v[220:223], v[2:5]
	v_mfma_f32_16x16x32_bf16 v[6:9], v[204:207], v[224:227], v[6:9]
	ds_read_b128 v[204:207], v244 offset:4672
	s_waitcnt vmcnt(15)
	ds_write_b128 v100, v[102:105] offset:18432
	s_waitcnt vmcnt(14)
	ds_write_b128 v100, v[106:109] offset:23040
	s_waitcnt lgkmcnt(9)
	v_mfma_f32_16x16x32_bf16 v[42:45], v[208:211], v[212:215], v[42:45]
	v_mfma_f32_16x16x32_bf16 v[46:49], v[208:211], v[216:219], v[46:49]
	v_mfma_f32_16x16x32_bf16 v[10:13], v[208:211], v[220:223], v[10:13]
	v_mfma_f32_16x16x32_bf16 v[14:17], v[208:211], v[224:227], v[14:17]
	ds_read_b128 v[208:211], v244 offset:6976
	s_waitcnt vmcnt(13)
	ds_write_b128 v100, v[110:113] offset:27648
	s_waitcnt vmcnt(12)
	ds_write_b128 v100, v[114:117] offset:32256
	s_waitcnt lgkmcnt(7)
	v_mfma_f32_16x16x32_bf16 v[50:53], v[196:199], v[228:231], v[50:53]
	v_mfma_f32_16x16x32_bf16 v[54:57], v[196:199], v[232:235], v[54:57]
	v_mfma_f32_16x16x32_bf16 v[18:21], v[196:199], v[236:239], v[18:21]
	v_mfma_f32_16x16x32_bf16 v[22:25], v[196:199], v[240:243], v[22:25]
	s_waitcnt vmcnt(11)
	ds_write_b128 v100, v[118:121] offset:55296
	s_waitcnt vmcnt(10)
	ds_write_b128 v100, v[122:125] offset:59904
	s_waitcnt lgkmcnt(8)
	v_mfma_f32_16x16x32_bf16 v[58:61], v[200:203], v[228:231], v[58:61]
	v_mfma_f32_16x16x32_bf16 v[62:65], v[200:203], v[232:235], v[62:65]
	v_mfma_f32_16x16x32_bf16 v[26:29], v[200:203], v[236:239], v[26:29]
	v_mfma_f32_16x16x32_bf16 v[30:33], v[200:203], v[240:243], v[30:33]
	s_waitcnt vmcnt(9)
	ds_write_b128 v100, v[126:129] offset:64512
	s_waitcnt vmcnt(8)
	ds_write_b128 v101, v[136:139] offset:32256
	s_waitcnt lgkmcnt(0)
	s_barrier
	ds_read_b128 v[212:215], v245 offset:55296
	ds_read_b128 v[196:199], v244 offset:18432
	ds_read_b128 v[216:219], v245 offset:57600
	ds_read_b128 v[220:223], v245 offset:59904
	ds_read_b128 v[224:227], v245 offset:62208
	ds_read_b128 v[200:203], v244 offset:20736
	v_mfma_f32_16x16x32_bf16 v[34:37], v[204:207], v[228:231], v[34:37]
	v_mfma_f32_16x16x32_bf16 v[38:41], v[204:207], v[232:235], v[38:41]
	v_mfma_f32_16x16x32_bf16 v[2:5], v[204:207], v[236:239], v[2:5]
	v_mfma_f32_16x16x32_bf16 v[6:9], v[204:207], v[240:243], v[6:9]
	ds_read_b128 v[204:207], v244 offset:23040
	v_mfma_f32_16x16x32_bf16 v[42:45], v[208:211], v[228:231], v[42:45]
	v_mfma_f32_16x16x32_bf16 v[46:49], v[208:211], v[232:235], v[46:49]
	v_mfma_f32_16x16x32_bf16 v[10:13], v[208:211], v[236:239], v[10:13]
	v_mfma_f32_16x16x32_bf16 v[14:17], v[208:211], v[240:243], v[14:17]
	ds_read_b128 v[208:211], v244 offset:25344
	global_load_dwordx4 v[102:105], v[66:67], off offset:896
	s_nop 0
	global_load_dwordx4 v[66:69], v[68:69], off offset:896
	s_nop 0
	global_load_dwordx4 v[106:109], v[70:71], off offset:896
	s_nop 0
	global_load_dwordx4 v[70:73], v[72:73], off offset:896
	s_nop 0
	global_load_dwordx4 v[110:113], v[84:85], off offset:896
	s_nop 0
	global_load_dwordx4 v[84:87], v[86:87], off offset:896
	s_nop 0
	global_load_dwordx4 v[114:117], v[88:89], off offset:896
	s_nop 0
	global_load_dwordx4 v[88:91], v[90:91], off offset:896
	s_waitcnt lgkmcnt(6)
	v_mfma_f32_16x16x32_bf16 v[50:53], v[196:199], v[212:215], v[50:53]
	ds_read_b128 v[228:231], v245 offset:55360
	s_waitcnt lgkmcnt(6)
	v_mfma_f32_16x16x32_bf16 v[54:57], v[196:199], v[216:219], v[54:57]
	ds_read_b128 v[232:235], v245 offset:57664
	s_waitcnt lgkmcnt(6)
	v_mfma_f32_16x16x32_bf16 v[18:21], v[196:199], v[220:223], v[18:21]
	ds_read_b128 v[236:239], v245 offset:59968
	s_waitcnt lgkmcnt(6)
	v_mfma_f32_16x16x32_bf16 v[22:25], v[196:199], v[224:227], v[22:25]
	ds_read_b128 v[240:243], v245 offset:62272
	ds_read_b128 v[196:199], v244 offset:18496
	s_waitcnt lgkmcnt(7)
	v_mfma_f32_16x16x32_bf16 v[58:61], v[200:203], v[212:215], v[58:61]
	v_mfma_f32_16x16x32_bf16 v[62:65], v[200:203], v[216:219], v[62:65]
	v_mfma_f32_16x16x32_bf16 v[26:29], v[200:203], v[220:223], v[26:29]
	v_mfma_f32_16x16x32_bf16 v[30:33], v[200:203], v[224:227], v[30:33]
	ds_read_b128 v[200:203], v244 offset:20800
	s_waitcnt lgkmcnt(7)
	v_mfma_f32_16x16x32_bf16 v[34:37], v[204:207], v[212:215], v[34:37]
	v_mfma_f32_16x16x32_bf16 v[38:41], v[204:207], v[216:219], v[38:41]
	v_mfma_f32_16x16x32_bf16 v[2:5], v[204:207], v[220:223], v[2:5]
	v_mfma_f32_16x16x32_bf16 v[6:9], v[204:207], v[224:227], v[6:9]
	ds_read_b128 v[204:207], v244 offset:23104
	s_waitcnt vmcnt(15)
	ds_write_b128 v100, v[140:143]
	s_waitcnt vmcnt(14)
	ds_write_b128 v100, v[144:147] offset:4608
	s_waitcnt lgkmcnt(9)
	v_mfma_f32_16x16x32_bf16 v[42:45], v[208:211], v[212:215], v[42:45]
	v_mfma_f32_16x16x32_bf16 v[46:49], v[208:211], v[216:219], v[46:49]
	v_mfma_f32_16x16x32_bf16 v[10:13], v[208:211], v[220:223], v[10:13]
	v_mfma_f32_16x16x32_bf16 v[14:17], v[208:211], v[224:227], v[14:17]
	ds_read_b128 v[208:211], v244 offset:25408
	s_waitcnt vmcnt(13)
	ds_write_b128 v100, v[148:151] offset:9216
	s_waitcnt vmcnt(12)
	ds_write_b128 v100, v[152:155] offset:13824
	s_waitcnt lgkmcnt(7)
	v_mfma_f32_16x16x32_bf16 v[50:53], v[196:199], v[228:231], v[50:53]
	v_mfma_f32_16x16x32_bf16 v[54:57], v[196:199], v[232:235], v[54:57]
	v_mfma_f32_16x16x32_bf16 v[18:21], v[196:199], v[236:239], v[18:21]
	v_mfma_f32_16x16x32_bf16 v[22:25], v[196:199], v[240:243], v[22:25]
	s_waitcnt vmcnt(11)
	ds_write_b128 v100, v[156:159] offset:36864
	s_waitcnt vmcnt(10)
	ds_write_b128 v100, v[160:163] offset:41472
	s_waitcnt lgkmcnt(8)
	v_mfma_f32_16x16x32_bf16 v[58:61], v[200:203], v[228:231], v[58:61]
	v_mfma_f32_16x16x32_bf16 v[62:65], v[200:203], v[232:235], v[62:65]
	v_mfma_f32_16x16x32_bf16 v[26:29], v[200:203], v[236:239], v[26:29]
	v_mfma_f32_16x16x32_bf16 v[30:33], v[200:203], v[240:243], v[30:33]
	s_waitcnt vmcnt(9)
	ds_write_b128 v100, v[164:167] offset:46080
	s_waitcnt vmcnt(8)
	ds_write_b128 v100, v[168:171] offset:50688
	s_waitcnt lgkmcnt(0)
	s_barrier
	ds_read_b128 v[212:215], v245 offset:36864
	ds_read_b128 v[196:199], v244
	ds_read_b128 v[216:219], v245 offset:39168
	ds_read_b128 v[220:223], v245 offset:41472
	ds_read_b128 v[224:227], v245 offset:43776
	ds_read_b128 v[200:203], v244 offset:2304
	v_mfma_f32_16x16x32_bf16 v[34:37], v[204:207], v[228:231], v[34:37]
	v_mfma_f32_16x16x32_bf16 v[38:41], v[204:207], v[232:235], v[38:41]
	v_mfma_f32_16x16x32_bf16 v[2:5], v[204:207], v[236:239], v[2:5]
	v_mfma_f32_16x16x32_bf16 v[6:9], v[204:207], v[240:243], v[6:9]
	ds_read_b128 v[204:207], v244 offset:4608
	v_mfma_f32_16x16x32_bf16 v[42:45], v[208:211], v[228:231], v[42:45]
	v_mfma_f32_16x16x32_bf16 v[46:49], v[208:211], v[232:235], v[46:49]
	v_mfma_f32_16x16x32_bf16 v[10:13], v[208:211], v[236:239], v[10:13]
	v_mfma_f32_16x16x32_bf16 v[14:17], v[208:211], v[240:243], v[14:17]
	ds_read_b128 v[208:211], v244 offset:6912
	s_waitcnt lgkmcnt(6)
	v_mfma_f32_16x16x32_bf16 v[50:53], v[196:199], v[212:215], v[50:53]
	ds_read_b128 v[228:231], v245 offset:36928
	s_waitcnt lgkmcnt(6)
	v_mfma_f32_16x16x32_bf16 v[54:57], v[196:199], v[216:219], v[54:57]
	ds_read_b128 v[232:235], v245 offset:39232
	s_waitcnt lgkmcnt(6)
	v_mfma_f32_16x16x32_bf16 v[18:21], v[196:199], v[220:223], v[18:21]
	ds_read_b128 v[236:239], v245 offset:41536
	s_waitcnt lgkmcnt(6)
	v_mfma_f32_16x16x32_bf16 v[22:25], v[196:199], v[224:227], v[22:25]
	ds_read_b128 v[240:243], v245 offset:43840
	ds_read_b128 v[196:199], v244 offset:64
	s_waitcnt lgkmcnt(7)
	v_mfma_f32_16x16x32_bf16 v[58:61], v[200:203], v[212:215], v[58:61]
	v_mfma_f32_16x16x32_bf16 v[62:65], v[200:203], v[216:219], v[62:65]
	v_mfma_f32_16x16x32_bf16 v[26:29], v[200:203], v[220:223], v[26:29]
	v_mfma_f32_16x16x32_bf16 v[30:33], v[200:203], v[224:227], v[30:33]
	ds_read_b128 v[200:203], v244 offset:2368
	s_waitcnt lgkmcnt(7)
	v_mfma_f32_16x16x32_bf16 v[34:37], v[204:207], v[212:215], v[34:37]
	v_mfma_f32_16x16x32_bf16 v[38:41], v[204:207], v[216:219], v[38:41]
	v_mfma_f32_16x16x32_bf16 v[2:5], v[204:207], v[220:223], v[2:5]
	v_mfma_f32_16x16x32_bf16 v[6:9], v[204:207], v[224:227], v[6:9]
	ds_read_b128 v[204:207], v244 offset:4672
	s_waitcnt vmcnt(7)
	ds_write_b128 v100, v[102:105] offset:18432
	s_waitcnt vmcnt(6)
	ds_write_b128 v100, v[66:69] offset:23040
	s_waitcnt lgkmcnt(9)
	v_mfma_f32_16x16x32_bf16 v[42:45], v[208:211], v[212:215], v[42:45]
	v_mfma_f32_16x16x32_bf16 v[46:49], v[208:211], v[216:219], v[46:49]
	v_mfma_f32_16x16x32_bf16 v[10:13], v[208:211], v[220:223], v[10:13]
	v_mfma_f32_16x16x32_bf16 v[14:17], v[208:211], v[224:227], v[14:17]
	ds_read_b128 v[208:211], v244 offset:6976
	s_waitcnt vmcnt(5)
	ds_write_b128 v100, v[106:109] offset:27648
	s_waitcnt vmcnt(4)
	ds_write_b128 v100, v[70:73] offset:32256
	s_waitcnt lgkmcnt(7)
	v_mfma_f32_16x16x32_bf16 v[50:53], v[196:199], v[228:231], v[50:53]
	v_mfma_f32_16x16x32_bf16 v[54:57], v[196:199], v[232:235], v[54:57]
	v_mfma_f32_16x16x32_bf16 v[18:21], v[196:199], v[236:239], v[18:21]
	v_mfma_f32_16x16x32_bf16 v[22:25], v[196:199], v[240:243], v[22:25]
	s_waitcnt vmcnt(3)
	ds_write_b128 v100, v[110:113] offset:55296
	s_waitcnt vmcnt(2)
	ds_write_b128 v100, v[84:87] offset:59904
	s_waitcnt lgkmcnt(8)
	v_mfma_f32_16x16x32_bf16 v[58:61], v[200:203], v[228:231], v[58:61]
	v_mfma_f32_16x16x32_bf16 v[62:65], v[200:203], v[232:235], v[62:65]
	v_mfma_f32_16x16x32_bf16 v[26:29], v[200:203], v[236:239], v[26:29]
	v_mfma_f32_16x16x32_bf16 v[30:33], v[200:203], v[240:243], v[30:33]
	s_waitcnt vmcnt(1)
	ds_write_b128 v100, v[114:117] offset:64512
	s_waitcnt vmcnt(0)
	ds_write_b128 v101, v[88:91] offset:32256
	s_waitcnt lgkmcnt(0)
	s_barrier
	ds_read_b128 v[212:215], v245 offset:55296
	ds_read_b128 v[196:199], v244 offset:18432
	ds_read_b128 v[216:219], v245 offset:57600
	ds_read_b128 v[220:223], v245 offset:59904
	ds_read_b128 v[224:227], v245 offset:62208
	ds_read_b128 v[200:203], v244 offset:20736
	v_mfma_f32_16x16x32_bf16 v[34:37], v[204:207], v[228:231], v[34:37]
	v_mfma_f32_16x16x32_bf16 v[38:41], v[204:207], v[232:235], v[38:41]
	v_mfma_f32_16x16x32_bf16 v[2:5], v[204:207], v[236:239], v[2:5]
	v_mfma_f32_16x16x32_bf16 v[6:9], v[204:207], v[240:243], v[6:9]
	ds_read_b128 v[204:207], v244 offset:23040
	v_mfma_f32_16x16x32_bf16 v[42:45], v[208:211], v[228:231], v[42:45]
	v_mfma_f32_16x16x32_bf16 v[46:49], v[208:211], v[232:235], v[46:49]
	v_mfma_f32_16x16x32_bf16 v[10:13], v[208:211], v[236:239], v[10:13]
	v_mfma_f32_16x16x32_bf16 v[14:17], v[208:211], v[240:243], v[14:17]
	ds_read_b128 v[208:211], v244 offset:25344
	s_waitcnt lgkmcnt(6)
	v_mfma_f32_16x16x32_bf16 v[50:53], v[196:199], v[212:215], v[50:53]
	ds_read_b128 v[228:231], v245 offset:55360
	s_waitcnt lgkmcnt(6)
	v_mfma_f32_16x16x32_bf16 v[54:57], v[196:199], v[216:219], v[54:57]
	ds_read_b128 v[232:235], v245 offset:57664
	s_waitcnt lgkmcnt(6)
	v_mfma_f32_16x16x32_bf16 v[18:21], v[196:199], v[220:223], v[18:21]
	ds_read_b128 v[236:239], v245 offset:59968
	s_waitcnt lgkmcnt(6)
	v_mfma_f32_16x16x32_bf16 v[22:25], v[196:199], v[224:227], v[22:25]
	ds_read_b128 v[240:243], v245 offset:62272
	ds_read_b128 v[196:199], v244 offset:18496
	s_waitcnt lgkmcnt(7)
	v_mfma_f32_16x16x32_bf16 v[58:61], v[200:203], v[212:215], v[58:61]
	v_mfma_f32_16x16x32_bf16 v[62:65], v[200:203], v[216:219], v[62:65]
	v_mfma_f32_16x16x32_bf16 v[26:29], v[200:203], v[220:223], v[26:29]
	v_mfma_f32_16x16x32_bf16 v[30:33], v[200:203], v[224:227], v[30:33]
	ds_read_b128 v[200:203], v244 offset:20800
	s_waitcnt lgkmcnt(7)
	v_mfma_f32_16x16x32_bf16 v[34:37], v[204:207], v[212:215], v[34:37]
	v_mfma_f32_16x16x32_bf16 v[38:41], v[204:207], v[216:219], v[38:41]
	v_mfma_f32_16x16x32_bf16 v[2:5], v[204:207], v[220:223], v[2:5]
	v_mfma_f32_16x16x32_bf16 v[6:9], v[204:207], v[224:227], v[6:9]
	ds_read_b128 v[204:207], v244 offset:23104
	s_waitcnt lgkmcnt(7)
	v_mfma_f32_16x16x32_bf16 v[42:45], v[208:211], v[212:215], v[42:45]
	v_mfma_f32_16x16x32_bf16 v[46:49], v[208:211], v[216:219], v[46:49]
	v_mfma_f32_16x16x32_bf16 v[10:13], v[208:211], v[220:223], v[10:13]
	v_mfma_f32_16x16x32_bf16 v[14:17], v[208:211], v[224:227], v[14:17]
	ds_read_b128 v[208:211], v244 offset:25408
	s_waitcnt lgkmcnt(3)
	v_mfma_f32_16x16x32_bf16 v[50:53], v[196:199], v[228:231], v[50:53]
	v_mfma_f32_16x16x32_bf16 v[54:57], v[196:199], v[232:235], v[54:57]
	v_mfma_f32_16x16x32_bf16 v[18:21], v[196:199], v[236:239], v[18:21]
	v_mfma_f32_16x16x32_bf16 v[22:25], v[196:199], v[240:243], v[22:25]
	s_waitcnt lgkmcnt(2)
	v_mfma_f32_16x16x32_bf16 v[58:61], v[200:203], v[228:231], v[58:61]
	v_mfma_f32_16x16x32_bf16 v[62:65], v[200:203], v[232:235], v[62:65]
	v_mfma_f32_16x16x32_bf16 v[26:29], v[200:203], v[236:239], v[26:29]
	v_mfma_f32_16x16x32_bf16 v[30:33], v[200:203], v[240:243], v[30:33]
	s_add_i32 s6, s6, 1
	s_add_i32 s5, s5, s3
	v_or_b32_e32 v70, s0, v92
	s_lshl_b32 s0, s7, 1
	v_lshl_add_u64 v[110:111], v[80:81], 0, s[0:1]
	v_lshlrev_b32_e32 v74, 10, v70
	v_lshl_add_u64 v[112:113], v[110:111], 0, v[74:75]
	s_waitcnt lgkmcnt(0)
	s_barrier
	v_mfma_f32_16x16x32_bf16 v[34:37], v[204:207], v[228:231], v[34:37]
	v_mfma_f32_16x16x32_bf16 v[38:41], v[204:207], v[232:235], v[38:41]
	v_mfma_f32_16x16x32_bf16 v[2:5], v[204:207], v[236:239], v[2:5]
	v_mfma_f32_16x16x32_bf16 v[6:9], v[204:207], v[240:243], v[6:9]
	v_mfma_f32_16x16x32_bf16 v[42:45], v[208:211], v[228:231], v[42:45]
	v_mfma_f32_16x16x32_bf16 v[46:49], v[208:211], v[232:235], v[46:49]
	v_mfma_f32_16x16x32_bf16 v[10:13], v[208:211], v[236:239], v[10:13]
	v_mfma_f32_16x16x32_bf16 v[14:17], v[208:211], v[240:243], v[14:17]
	s_nop 7
	v_permlane16_swap_b32_e32 v50, v54
	v_permlane16_swap_b32_e32 v51, v55
	v_permlane16_swap_b32_e32 v52, v56
	v_permlane16_swap_b32_e32 v53, v57
	v_permlane16_swap_b32_e32 v58, v62
	v_permlane16_swap_b32_e32 v59, v63
	v_permlane16_swap_b32_e32 v60, v64
	v_permlane16_swap_b32_e32 v61, v65
	v_permlane16_swap_b32_e32 v18, v22
	v_permlane16_swap_b32_e32 v19, v23
	v_permlane16_swap_b32_e32 v20, v24
	v_permlane16_swap_b32_e32 v21, v25
	v_permlane16_swap_b32_e32 v26, v30
	v_permlane16_swap_b32_e32 v27, v31
	v_permlane16_swap_b32_e32 v28, v32
	v_permlane16_swap_b32_e32 v29, v33
	v_permlane16_swap_b32_e32 v34, v38
	v_permlane16_swap_b32_e32 v35, v39
	v_permlane16_swap_b32_e32 v36, v40
	v_permlane16_swap_b32_e32 v37, v41
	v_permlane16_swap_b32_e32 v42, v46
	v_permlane16_swap_b32_e32 v43, v47
	v_permlane16_swap_b32_e32 v44, v48
	v_permlane16_swap_b32_e32 v45, v49
	v_permlane16_swap_b32_e32 v2, v6
	v_permlane16_swap_b32_e32 v3, v7
	v_permlane16_swap_b32_e32 v4, v8
	v_permlane16_swap_b32_e32 v5, v9
	v_permlane16_swap_b32_e32 v10, v14
	v_permlane16_swap_b32_e32 v11, v15
	v_permlane16_swap_b32_e32 v12, v16
	v_permlane16_swap_b32_e32 v13, v17
	v_permlane32_swap_b32_e32 v50, v54
	v_permlane32_swap_b32_e32 v51, v55
	v_permlane32_swap_b32_e32 v52, v56
	v_permlane32_swap_b32_e32 v53, v57
	v_permlane32_swap_b32_e32 v58, v62
	v_permlane32_swap_b32_e32 v59, v63
	v_permlane32_swap_b32_e32 v60, v64
	v_permlane32_swap_b32_e32 v61, v65
	v_permlane32_swap_b32_e32 v18, v22
	v_permlane32_swap_b32_e32 v19, v23
	v_permlane32_swap_b32_e32 v20, v24
	v_permlane32_swap_b32_e32 v21, v25
	v_permlane32_swap_b32_e32 v26, v30
	v_permlane32_swap_b32_e32 v27, v31
	v_permlane32_swap_b32_e32 v28, v32
	v_permlane32_swap_b32_e32 v29, v33
	v_permlane32_swap_b32_e32 v34, v38
	v_permlane32_swap_b32_e32 v35, v39
	v_permlane32_swap_b32_e32 v36, v40
	v_permlane32_swap_b32_e32 v37, v41
	v_permlane32_swap_b32_e32 v42, v46
	v_permlane32_swap_b32_e32 v43, v47
	v_permlane32_swap_b32_e32 v44, v48
	v_permlane32_swap_b32_e32 v45, v49
	v_permlane32_swap_b32_e32 v2, v6
	v_permlane32_swap_b32_e32 v3, v7
	v_permlane32_swap_b32_e32 v4, v8
	v_permlane32_swap_b32_e32 v5, v9
	v_permlane32_swap_b32_e32 v10, v14
	v_permlane32_swap_b32_e32 v11, v15
	v_permlane32_swap_b32_e32 v12, v16
	v_permlane32_swap_b32_e32 v13, v17
	global_load_dwordx4 v[106:109], v[112:113], off
	s_mul_i32 s0, s6, s3
	s_add_i32 s0, s0, s2
	s_cmp_lt_u32 s5, 48
	global_load_dwordx4 v[88:91], v[112:113], off offset:32
	global_load_dwordx4 v[70:73], v[112:113], off offset:64
	s_waitcnt vmcnt(2)
	v_mov_b32_e32 v86, v108
	global_load_dwordx4 v[66:69], v[112:113], off offset:96
	v_permlane32_swap_b32_e32 v106, v86
	v_mov_b32_e32 v102, v109
	s_nop 1
	v_permlane32_swap_b32_e32 v107, v102
	s_waitcnt vmcnt(2)
	v_mov_b32_e32 v108, v90
	v_mov_b32_e32 v109, v91
	s_nop 0
	v_permlane32_swap_b32_e32 v88, v108
	v_permlane32_swap_b32_e32 v89, v109
	s_waitcnt vmcnt(1)
	v_mov_b32_e32 v112, v72
	v_mov_b32_e32 v113, v73
	v_lshlrev_b32_e32 v72, 16, v106
	v_and_b32_e32 v73, 0xffff0000, v106
	v_pk_mul_f32 v[72:73], v[50:51], v[72:73]
	v_lshlrev_b32_e32 v50, 16, v107
	v_and_b32_e32 v51, 0xffff0000, v107
	v_pk_mul_f32 v[84:85], v[52:53], v[50:51]
	v_lshlrev_b32_e32 v50, 16, v86
	v_and_b32_e32 v51, 0xffff0000, v86
	v_pk_mul_f32 v[86:87], v[54:55], v[50:51]
	v_lshlrev_b32_e32 v54, 16, v102
	v_and_b32_e32 v55, 0xffff0000, v102
	v_pk_mul_f32 v[102:103], v[56:57], v[54:55]
	v_cvt_pk_bf16_f32 v55, v84, v85
	v_cvt_pk_bf16_f32 v56, v86, v87
	v_cvt_pk_bf16_f32 v57, v102, v103
	v_cvt_pk_bf16_f32 v54, v72, v73
	v_add_lshl_u32 v72, s7, v97, 1
	v_mov_b32_e32 v73, v75
	v_permlane32_swap_b32_e32 v54, v56
	v_permlane32_swap_b32_e32 v55, v57
	v_lshlrev_b32_e32 v106, 16, v88
	v_and_b32_e32 v107, 0xffff0000, v88
	v_lshlrev_b32_e32 v88, 16, v89
	v_and_b32_e32 v89, 0xffff0000, v89
	v_pk_mul_f32 v[60:61], v[60:61], v[88:89]
	v_lshlrev_b32_e32 v88, 16, v108
	v_and_b32_e32 v89, 0xffff0000, v108
	v_pk_mul_f32 v[62:63], v[62:63], v[88:89]
	v_lshlrev_b32_e32 v88, 16, v109
	v_and_b32_e32 v89, 0xffff0000, v109
	v_pk_mul_f32 v[58:59], v[58:59], v[106:107]
	v_pk_mul_f32 v[64:65], v[64:65], v[88:89]
	v_cvt_pk_bf16_f32 v58, v58, v59
	v_cvt_pk_bf16_f32 v59, v60, v61
	v_cvt_pk_bf16_f32 v60, v62, v63
	v_cvt_pk_bf16_f32 v61, v64, v65
	v_permlane32_swap_b32_e32 v70, v112
	v_permlane32_swap_b32_e32 v58, v60
	v_permlane32_swap_b32_e32 v59, v61
	v_permlane32_swap_b32_e32 v71, v113
	s_waitcnt vmcnt(0)
	v_mov_b32_e32 v114, v68
	v_mov_b32_e32 v115, v69
	v_lshl_add_u64 v[68:69], v[82:83], 0, v[74:75]
	v_or_b32_e32 v74, 0x8000, v74
	v_lshl_add_u64 v[90:91], v[110:111], 0, v[74:75]
	global_load_dwordx4 v[50:53], v[90:91], off
	global_load_dwordx4 v[84:87], v[90:91], off offset:32
	global_load_dwordx4 v[102:105], v[90:91], off offset:64
	v_lshl_add_u64 v[68:69], v[68:69], 0, v[72:73]
	global_store_dwordx4 v[68:69], v[54:57], off
	global_load_dwordx4 v[54:57], v[90:91], off offset:96
	v_permlane32_swap_b32_e32 v66, v114
	global_store_dwordx4 v[68:69], v[58:61], off offset:32
	v_permlane32_swap_b32_e32 v67, v115
	s_nop 0
	v_lshlrev_b32_e32 v58, 16, v70
	v_and_b32_e32 v59, 0xffff0000, v70
	v_pk_mul_f32 v[34:35], v[34:35], v[58:59]
	v_lshlrev_b32_e32 v58, 16, v71
	v_and_b32_e32 v59, 0xffff0000, v71
	v_pk_mul_f32 v[36:37], v[36:37], v[58:59]
	v_lshlrev_b32_e32 v58, 16, v112
	v_and_b32_e32 v59, 0xffff0000, v112
	v_pk_mul_f32 v[38:39], v[38:39], v[58:59]
	v_lshlrev_b32_e32 v58, 16, v113
	v_and_b32_e32 v59, 0xffff0000, v113
	v_pk_mul_f32 v[40:41], v[40:41], v[58:59]
	v_cvt_pk_bf16_f32 v34, v34, v35
	v_cvt_pk_bf16_f32 v35, v36, v37
	v_cvt_pk_bf16_f32 v36, v38, v39
	v_cvt_pk_bf16_f32 v37, v40, v41
	s_nop 0
	v_permlane32_swap_b32_e32 v34, v36
	v_permlane32_swap_b32_e32 v35, v37
	global_store_dwordx4 v[68:69], v[34:37], off offset:64
	v_lshlrev_b32_e32 v38, 16, v114
	v_and_b32_e32 v39, 0xffff0000, v114
	v_lshlrev_b32_e32 v34, 16, v66
	v_and_b32_e32 v35, 0xffff0000, v66
	v_lshlrev_b32_e32 v36, 16, v67
	v_and_b32_e32 v37, 0xffff0000, v67
	v_lshlrev_b32_e32 v40, 16, v115
	v_and_b32_e32 v41, 0xffff0000, v115
	v_pk_mul_f32 v[34:35], v[42:43], v[34:35]
	v_pk_mul_f32 v[36:37], v[44:45], v[36:37]
	v_pk_mul_f32 v[38:39], v[46:47], v[38:39]
	v_pk_mul_f32 v[40:41], v[48:49], v[40:41]
	v_cvt_pk_bf16_f32 v34, v34, v35
	v_cvt_pk_bf16_f32 v35, v36, v37
	v_cvt_pk_bf16_f32 v36, v38, v39
	v_cvt_pk_bf16_f32 v37, v40, v41
	s_nop 0
	v_permlane32_swap_b32_e32 v34, v36
	v_permlane32_swap_b32_e32 v35, v37
	global_store_dwordx4 v[68:69], v[34:37], off offset:96
	s_waitcnt vmcnt(7)
	v_mov_b32_e32 v38, v52
	s_nop 1
	v_permlane32_swap_b32_e32 v50, v38
	v_mov_b32_e32 v39, v53
	s_nop 1
	v_permlane32_swap_b32_e32 v51, v39
	v_lshlrev_b32_e32 v36, 16, v50
	v_and_b32_e32 v37, 0xffff0000, v50
	v_pk_mul_f32 v[18:19], v[18:19], v[36:37]
	v_lshlrev_b32_e32 v36, 16, v51
	v_and_b32_e32 v37, 0xffff0000, v51
	v_pk_mul_f32 v[20:21], v[20:21], v[36:37]
	v_lshlrev_b32_e32 v36, 16, v38
	v_and_b32_e32 v37, 0xffff0000, v38
	v_pk_mul_f32 v[22:23], v[22:23], v[36:37]
	v_lshlrev_b32_e32 v36, 16, v39
	v_and_b32_e32 v37, 0xffff0000, v39
	v_pk_mul_f32 v[24:25], v[24:25], v[36:37]
	s_waitcnt vmcnt(6)
	v_mov_b32_e32 v40, v86
	v_lshl_add_u64 v[34:35], v[82:83], 0, v[74:75]
	v_cvt_pk_bf16_f32 v18, v18, v19
	v_cvt_pk_bf16_f32 v19, v20, v21
	v_cvt_pk_bf16_f32 v20, v22, v23
	v_cvt_pk_bf16_f32 v21, v24, v25
	v_permlane32_swap_b32_e32 v84, v40
	v_mov_b32_e32 v41, v87
	v_permlane32_swap_b32_e32 v18, v20
	v_permlane32_swap_b32_e32 v19, v21
	v_lshl_add_u64 v[22:23], v[34:35], 0, v[72:73]
	v_permlane32_swap_b32_e32 v85, v41
	global_store_dwordx4 v[22:23], v[18:21], off
	v_lshlrev_b32_e32 v24, 16, v40
	v_and_b32_e32 v25, 0xffff0000, v40
	v_lshlrev_b32_e32 v18, 16, v84
	v_and_b32_e32 v19, 0xffff0000, v84
	v_pk_mul_f32 v[18:19], v[26:27], v[18:19]
	v_lshlrev_b32_e32 v20, 16, v85
	v_and_b32_e32 v21, 0xffff0000, v85
	v_lshlrev_b32_e32 v26, 16, v41
	v_and_b32_e32 v27, 0xffff0000, v41
	v_pk_mul_f32 v[20:21], v[28:29], v[20:21]
	v_pk_mul_f32 v[24:25], v[30:31], v[24:25]
	v_pk_mul_f32 v[26:27], v[32:33], v[26:27]
	s_waitcnt vmcnt(6)
	v_mov_b32_e32 v42, v104
	v_cvt_pk_bf16_f32 v18, v18, v19
	v_cvt_pk_bf16_f32 v19, v20, v21
	v_cvt_pk_bf16_f32 v20, v24, v25
	v_cvt_pk_bf16_f32 v21, v26, v27
	v_permlane32_swap_b32_e32 v102, v42
	v_mov_b32_e32 v43, v105
	v_permlane32_swap_b32_e32 v18, v20
	v_permlane32_swap_b32_e32 v19, v21
	v_permlane32_swap_b32_e32 v103, v43
	global_store_dwordx4 v[22:23], v[18:21], off offset:32
	s_waitcnt vmcnt(5)
	v_mov_b32_e32 v44, v56
	v_mov_b32_e32 v45, v57
	v_lshlrev_b32_e32 v18, 16, v102
	v_and_b32_e32 v19, 0xffff0000, v102
	v_pk_mul_f32 v[2:3], v[2:3], v[18:19]
	v_lshlrev_b32_e32 v18, 16, v103
	v_and_b32_e32 v19, 0xffff0000, v103
	v_pk_mul_f32 v[4:5], v[4:5], v[18:19]
	v_lshlrev_b32_e32 v18, 16, v42
	v_and_b32_e32 v19, 0xffff0000, v42
	v_pk_mul_f32 v[6:7], v[6:7], v[18:19]
	v_lshlrev_b32_e32 v18, 16, v43
	v_and_b32_e32 v19, 0xffff0000, v43
	v_pk_mul_f32 v[8:9], v[8:9], v[18:19]
	v_cvt_pk_bf16_f32 v2, v2, v3
	v_cvt_pk_bf16_f32 v3, v4, v5
	v_cvt_pk_bf16_f32 v4, v6, v7
	v_cvt_pk_bf16_f32 v5, v8, v9
	v_permlane32_swap_b32_e32 v54, v44
	v_permlane32_swap_b32_e32 v55, v45
	v_permlane32_swap_b32_e32 v2, v4
	v_permlane32_swap_b32_e32 v3, v5
	global_store_dwordx4 v[22:23], v[2:5], off offset:64
	v_lshlrev_b32_e32 v6, 16, v44
	v_and_b32_e32 v7, 0xffff0000, v44
	v_lshlrev_b32_e32 v2, 16, v54
	v_and_b32_e32 v3, 0xffff0000, v54
	v_lshlrev_b32_e32 v4, 16, v55
	v_and_b32_e32 v5, 0xffff0000, v55
	v_lshlrev_b32_e32 v8, 16, v45
	v_and_b32_e32 v9, 0xffff0000, v45
	v_pk_mul_f32 v[2:3], v[10:11], v[2:3]
	v_pk_mul_f32 v[4:5], v[12:13], v[4:5]
	v_pk_mul_f32 v[6:7], v[14:15], v[6:7]
	v_pk_mul_f32 v[8:9], v[16:17], v[8:9]
	v_cvt_pk_bf16_f32 v2, v2, v3
	v_cvt_pk_bf16_f32 v3, v4, v5
	v_cvt_pk_bf16_f32 v4, v6, v7
	v_cvt_pk_bf16_f32 v5, v8, v9
	s_nop 0
	v_permlane32_swap_b32_e32 v2, v4
	v_permlane32_swap_b32_e32 v3, v5
	global_store_dwordx4 v[22:23], v[2:5], off offset:96
	s_cbranch_scc1 .LBB0_828

.LBB0_979:
	s_lshr_b32 s0, s2, 2
	s_and_b32 s2, s2, 3
	s_or_b32 s2, s2, s8
	s_lshl_b32 s2, s2, 7
	v_or_b32_e32 v2, s2, v89
	v_lshlrev_b32_e32 v66, 11, v2
	s_add_i32 s0, s0, s9
	v_lshl_add_u64 v[72:73], v[68:69], 0, v[66:67]
	v_add_lshl_u32 v66, s2, v90, 11
	s_lshl_b32 s3, s0, 7
	v_lshl_add_u64 v[74:75], v[68:69], 0, v[66:67]
	v_add_lshl_u32 v66, s2, v91, 11
	v_lshl_add_u64 v[76:77], v[68:69], 0, v[66:67]
	v_add_lshl_u32 v66, s2, v92, 11
	v_or_b32_e32 v2, s3, v89
	v_lshl_add_u64 v[78:79], v[68:69], 0, v[66:67]
	v_lshlrev_b32_e32 v66, 11, v2
	v_lshl_add_u64 v[80:81], v[70:71], 0, v[66:67]
	v_add_lshl_u32 v66, s3, v90, 11
	v_lshl_add_u64 v[82:83], v[70:71], 0, v[66:67]
	v_add_lshl_u32 v66, s3, v91, 11
	v_lshl_add_u64 v[84:85], v[70:71], 0, v[66:67]
	v_add_lshl_u32 v66, s3, v92, 11
	v_lshl_add_u64 v[86:87], v[70:71], 0, v[66:67]
	global_load_dwordx4 v[2:5], v[72:73], off
	global_load_dwordx4 v[6:9], v[74:75], off
	global_load_dwordx4 v[10:13], v[76:77], off
	global_load_dwordx4 v[14:17], v[78:79], off
	global_load_dwordx4 v[18:21], v[80:81], off
	global_load_dwordx4 v[22:25], v[82:83], off
	global_load_dwordx4 v[26:29], v[84:85], off
	global_load_dwordx4 v[30:33], v[86:87], off
	global_load_dwordx4 v[98:101], v[72:73], off offset:128
	global_load_dwordx4 v[102:105], v[74:75], off offset:128
	global_load_dwordx4 v[106:109], v[76:77], off offset:128
	global_load_dwordx4 v[110:113], v[78:79], off offset:128
	global_load_dwordx4 v[114:117], v[80:81], off offset:128
	global_load_dwordx4 v[118:121], v[82:83], off offset:128
	global_load_dwordx4 v[122:125], v[84:85], off offset:128
	global_load_dwordx4 v[126:129], v[86:87], off offset:128
	s_waitcnt vmcnt(15)
	ds_write_b128 v95, v[2:5]
	s_waitcnt vmcnt(14)
	ds_write_b128 v95, v[6:9] offset:4608
	s_waitcnt vmcnt(13)
	ds_write_b128 v95, v[10:13] offset:9216
	s_waitcnt vmcnt(12)
	ds_write_b128 v95, v[14:17] offset:13824
	s_waitcnt vmcnt(11)
	ds_write_b128 v95, v[18:21] offset:36864
	s_waitcnt vmcnt(10)
	ds_write_b128 v95, v[22:25] offset:41472
	s_waitcnt vmcnt(9)
	ds_write_b128 v95, v[26:29] offset:46080
	s_waitcnt vmcnt(8)
	ds_write_b128 v95, v[30:33] offset:50688
	s_waitcnt lgkmcnt(0)
	s_barrier
	global_load_dwordx4 v[136:139], v[72:73], off offset:256
	global_load_dwordx4 v[140:143], v[74:75], off offset:256
	global_load_dwordx4 v[144:147], v[76:77], off offset:256
	global_load_dwordx4 v[148:151], v[78:79], off offset:256
	global_load_dwordx4 v[152:155], v[80:81], off offset:256
	global_load_dwordx4 v[156:159], v[82:83], off offset:256
	global_load_dwordx4 v[160:163], v[84:85], off offset:256
	global_load_dwordx4 v[164:167], v[86:87], off offset:256
	v_and_b32_e32 v246, 15, v1
	v_add_u32_e32 v246, 4, v246
	v_bfe_u32 v246, v246, 3, 1
	v_bfe_u32 v249, v1, 4, 2
	v_xor_b32_e32 v246, v246, v249
	v_bfe_u32 v249, v1, 5, 1
	v_sub_u32_e32 v246, v246, v249
	v_lshlrev_b32_e32 v246, 4, v246
	v_bfe_u32 v249, v1, 4, 1
	v_mul_u32_u24_e32 v249, 0x900, v249
	v_sub_u32_e32 v246, v246, v249
	v_add_u32_e32 v244, v246, v93
	v_add_u32_e32 v245, v246, v94
	ds_read_b128 v[212:215], v245 offset:36864
	ds_read_b128 v[196:199], v244
	ds_read_b128 v[216:219], v245 offset:39168
	ds_read_b128 v[220:223], v245 offset:41472
	ds_read_b128 v[224:227], v245 offset:43776
	ds_read_b128 v[200:203], v244 offset:2304
	ds_read_b128 v[204:207], v244 offset:4608
	ds_read_b128 v[208:211], v244 offset:6912
	s_waitcnt lgkmcnt(6)
	v_mfma_f32_16x16x32_bf16 v[34:37], v[196:199], v[212:215], 0
	ds_read_b128 v[228:231], v245 offset:36928
	s_waitcnt lgkmcnt(6)
	v_mfma_f32_16x16x32_bf16 v[38:41], v[196:199], v[216:219], 0
	ds_read_b128 v[232:235], v245 offset:39232
	s_waitcnt lgkmcnt(6)
	v_mfma_f32_16x16x32_bf16 v[2:5], v[196:199], v[220:223], 0
	ds_read_b128 v[236:239], v245 offset:41536
	s_waitcnt lgkmcnt(6)
	v_mfma_f32_16x16x32_bf16 v[6:9], v[196:199], v[224:227], 0
	ds_read_b128 v[240:243], v245 offset:43840
	ds_read_b128 v[196:199], v244 offset:64
	s_waitcnt lgkmcnt(7)
	v_mfma_f32_16x16x32_bf16 v[42:45], v[200:203], v[212:215], 0
	v_mfma_f32_16x16x32_bf16 v[46:49], v[200:203], v[216:219], 0
	v_mfma_f32_16x16x32_bf16 v[10:13], v[200:203], v[220:223], 0
	v_mfma_f32_16x16x32_bf16 v[14:17], v[200:203], v[224:227], 0
	ds_read_b128 v[200:203], v244 offset:2368
	s_waitcnt lgkmcnt(7)
	v_mfma_f32_16x16x32_bf16 v[50:53], v[204:207], v[212:215], 0
	v_mfma_f32_16x16x32_bf16 v[54:57], v[204:207], v[216:219], 0
	v_mfma_f32_16x16x32_bf16 v[18:21], v[204:207], v[220:223], 0
	v_mfma_f32_16x16x32_bf16 v[22:25], v[204:207], v[224:227], 0
	ds_read_b128 v[204:207], v244 offset:4672
	s_waitcnt vmcnt(15)
	ds_write_b128 v95, v[98:101] offset:18432
	s_waitcnt vmcnt(14)
	ds_write_b128 v95, v[102:105] offset:23040
	s_waitcnt lgkmcnt(9)
	v_mfma_f32_16x16x32_bf16 v[58:61], v[208:211], v[212:215], 0
	v_mfma_f32_16x16x32_bf16 v[62:65], v[208:211], v[216:219], 0
	v_mfma_f32_16x16x32_bf16 v[26:29], v[208:211], v[220:223], 0
	v_mfma_f32_16x16x32_bf16 v[30:33], v[208:211], v[224:227], 0
	ds_read_b128 v[208:211], v244 offset:6976
	s_waitcnt vmcnt(13)
	ds_write_b128 v95, v[106:109] offset:27648
	s_waitcnt vmcnt(12)
	ds_write_b128 v95, v[110:113] offset:32256
	s_waitcnt lgkmcnt(7)
	v_mfma_f32_16x16x32_bf16 v[34:37], v[196:199], v[228:231], v[34:37]
	v_mfma_f32_16x16x32_bf16 v[38:41], v[196:199], v[232:235], v[38:41]
	v_mfma_f32_16x16x32_bf16 v[2:5], v[196:199], v[236:239], v[2:5]
	v_mfma_f32_16x16x32_bf16 v[6:9], v[196:199], v[240:243], v[6:9]
	s_waitcnt vmcnt(11)
	ds_write_b128 v95, v[114:117] offset:55296
	s_waitcnt vmcnt(10)
	ds_write_b128 v95, v[118:121] offset:59904
	s_waitcnt lgkmcnt(8)
	v_mfma_f32_16x16x32_bf16 v[42:45], v[200:203], v[228:231], v[42:45]
	v_mfma_f32_16x16x32_bf16 v[46:49], v[200:203], v[232:235], v[46:49]
	v_mfma_f32_16x16x32_bf16 v[10:13], v[200:203], v[236:239], v[10:13]
	v_mfma_f32_16x16x32_bf16 v[14:17], v[200:203], v[240:243], v[14:17]
	s_waitcnt vmcnt(9)
	ds_write_b128 v95, v[122:125] offset:64512
	s_waitcnt vmcnt(8)
	ds_write_b128 v96, v[126:129] offset:32256
	s_waitcnt lgkmcnt(0)
	s_barrier
	ds_read_b128 v[212:215], v245 offset:55296
	ds_read_b128 v[196:199], v244 offset:18432
	ds_read_b128 v[216:219], v245 offset:57600
	ds_read_b128 v[220:223], v245 offset:59904
	ds_read_b128 v[224:227], v245 offset:62208
	ds_read_b128 v[200:203], v244 offset:20736
	v_mfma_f32_16x16x32_bf16 v[50:53], v[204:207], v[228:231], v[50:53]
	v_mfma_f32_16x16x32_bf16 v[54:57], v[204:207], v[232:235], v[54:57]
	v_mfma_f32_16x16x32_bf16 v[18:21], v[204:207], v[236:239], v[18:21]
	v_mfma_f32_16x16x32_bf16 v[22:25], v[204:207], v[240:243], v[22:25]
	ds_read_b128 v[204:207], v244 offset:23040
	v_mfma_f32_16x16x32_bf16 v[58:61], v[208:211], v[228:231], v[58:61]
	v_mfma_f32_16x16x32_bf16 v[62:65], v[208:211], v[232:235], v[62:65]
	v_mfma_f32_16x16x32_bf16 v[26:29], v[208:211], v[236:239], v[26:29]
	v_mfma_f32_16x16x32_bf16 v[30:33], v[208:211], v[240:243], v[30:33]
	ds_read_b128 v[208:211], v244 offset:25344
	global_load_dwordx4 v[98:101], v[72:73], off offset:384
	global_load_dwordx4 v[102:105], v[74:75], off offset:384
	global_load_dwordx4 v[106:109], v[76:77], off offset:384
	global_load_dwordx4 v[110:113], v[78:79], off offset:384
	global_load_dwordx4 v[114:117], v[80:81], off offset:384
	global_load_dwordx4 v[118:121], v[82:83], off offset:384
	global_load_dwordx4 v[122:125], v[84:85], off offset:384
	global_load_dwordx4 v[126:129], v[86:87], off offset:384
	s_waitcnt lgkmcnt(6)
	v_mfma_f32_16x16x32_bf16 v[34:37], v[196:199], v[212:215], v[34:37]
	ds_read_b128 v[228:231], v245 offset:55360
	s_waitcnt lgkmcnt(6)
	v_mfma_f32_16x16x32_bf16 v[38:41], v[196:199], v[216:219], v[38:41]
	ds_read_b128 v[232:235], v245 offset:57664
	s_waitcnt lgkmcnt(6)
	v_mfma_f32_16x16x32_bf16 v[2:5], v[196:199], v[220:223], v[2:5]
	ds_read_b128 v[236:239], v245 offset:59968
	s_waitcnt lgkmcnt(6)
	v_mfma_f32_16x16x32_bf16 v[6:9], v[196:199], v[224:227], v[6:9]
	ds_read_b128 v[240:243], v245 offset:62272
	ds_read_b128 v[196:199], v244 offset:18496
	s_waitcnt lgkmcnt(7)
	v_mfma_f32_16x16x32_bf16 v[42:45], v[200:203], v[212:215], v[42:45]
	v_mfma_f32_16x16x32_bf16 v[46:49], v[200:203], v[216:219], v[46:49]
	v_mfma_f32_16x16x32_bf16 v[10:13], v[200:203], v[220:223], v[10:13]
	v_mfma_f32_16x16x32_bf16 v[14:17], v[200:203], v[224:227], v[14:17]
	ds_read_b128 v[200:203], v244 offset:20800
	s_waitcnt lgkmcnt(7)
	v_mfma_f32_16x16x32_bf16 v[50:53], v[204:207], v[212:215], v[50:53]
	v_mfma_f32_16x16x32_bf16 v[54:57], v[204:207], v[216:219], v[54:57]
	v_mfma_f32_16x16x32_bf16 v[18:21], v[204:207], v[220:223], v[18:21]
	v_mfma_f32_16x16x32_bf16 v[22:25], v[204:207], v[224:227], v[22:25]
	ds_read_b128 v[204:207], v244 offset:23104
	s_waitcnt vmcnt(15)
	ds_write_b128 v95, v[136:139]
	s_waitcnt vmcnt(14)
	ds_write_b128 v95, v[140:143] offset:4608
	s_waitcnt lgkmcnt(9)
	v_mfma_f32_16x16x32_bf16 v[58:61], v[208:211], v[212:215], v[58:61]
	v_mfma_f32_16x16x32_bf16 v[62:65], v[208:211], v[216:219], v[62:65]
	v_mfma_f32_16x16x32_bf16 v[26:29], v[208:211], v[220:223], v[26:29]
	v_mfma_f32_16x16x32_bf16 v[30:33], v[208:211], v[224:227], v[30:33]
	ds_read_b128 v[208:211], v244 offset:25408
	s_waitcnt vmcnt(13)
	ds_write_b128 v95, v[144:147] offset:9216
	s_waitcnt vmcnt(12)
	ds_write_b128 v95, v[148:151] offset:13824
	s_waitcnt lgkmcnt(7)
	v_mfma_f32_16x16x32_bf16 v[34:37], v[196:199], v[228:231], v[34:37]
	v_mfma_f32_16x16x32_bf16 v[38:41], v[196:199], v[232:235], v[38:41]
	v_mfma_f32_16x16x32_bf16 v[2:5], v[196:199], v[236:239], v[2:5]
	v_mfma_f32_16x16x32_bf16 v[6:9], v[196:199], v[240:243], v[6:9]
	s_waitcnt vmcnt(11)
	ds_write_b128 v95, v[152:155] offset:36864
	s_waitcnt vmcnt(10)
	ds_write_b128 v95, v[156:159] offset:41472
	s_waitcnt lgkmcnt(8)
	v_mfma_f32_16x16x32_bf16 v[42:45], v[200:203], v[228:231], v[42:45]
	v_mfma_f32_16x16x32_bf16 v[46:49], v[200:203], v[232:235], v[46:49]
	v_mfma_f32_16x16x32_bf16 v[10:13], v[200:203], v[236:239], v[10:13]
	v_mfma_f32_16x16x32_bf16 v[14:17], v[200:203], v[240:243], v[14:17]
	s_waitcnt vmcnt(9)
	ds_write_b128 v95, v[160:163] offset:46080
	s_waitcnt vmcnt(8)
	ds_write_b128 v95, v[164:167] offset:50688
	s_waitcnt lgkmcnt(0)
	s_barrier
	ds_read_b128 v[212:215], v245 offset:36864
	ds_read_b128 v[196:199], v244
	ds_read_b128 v[216:219], v245 offset:39168
	ds_read_b128 v[220:223], v245 offset:41472
	ds_read_b128 v[224:227], v245 offset:43776
	ds_read_b128 v[200:203], v244 offset:2304
	v_mfma_f32_16x16x32_bf16 v[50:53], v[204:207], v[228:231], v[50:53]
	v_mfma_f32_16x16x32_bf16 v[54:57], v[204:207], v[232:235], v[54:57]
	v_mfma_f32_16x16x32_bf16 v[18:21], v[204:207], v[236:239], v[18:21]
	v_mfma_f32_16x16x32_bf16 v[22:25], v[204:207], v[240:243], v[22:25]
	ds_read_b128 v[204:207], v244 offset:4608
	v_mfma_f32_16x16x32_bf16 v[58:61], v[208:211], v[228:231], v[58:61]
	v_mfma_f32_16x16x32_bf16 v[62:65], v[208:211], v[232:235], v[62:65]
	v_mfma_f32_16x16x32_bf16 v[26:29], v[208:211], v[236:239], v[26:29]
	v_mfma_f32_16x16x32_bf16 v[30:33], v[208:211], v[240:243], v[30:33]
	ds_read_b128 v[208:211], v244 offset:6912
	global_load_dwordx4 v[136:139], v[72:73], off offset:512
	global_load_dwordx4 v[140:143], v[74:75], off offset:512
	global_load_dwordx4 v[144:147], v[76:77], off offset:512
	global_load_dwordx4 v[148:151], v[78:79], off offset:512
	global_load_dwordx4 v[152:155], v[80:81], off offset:512
	global_load_dwordx4 v[156:159], v[82:83], off offset:512
	global_load_dwordx4 v[160:163], v[84:85], off offset:512
	global_load_dwordx4 v[164:167], v[86:87], off offset:512
	s_waitcnt lgkmcnt(6)
	v_mfma_f32_16x16x32_bf16 v[34:37], v[196:199], v[212:215], v[34:37]
	ds_read_b128 v[228:231], v245 offset:36928
	s_waitcnt lgkmcnt(6)
	v_mfma_f32_16x16x32_bf16 v[38:41], v[196:199], v[216:219], v[38:41]
	ds_read_b128 v[232:235], v245 offset:39232
	s_waitcnt lgkmcnt(6)
	v_mfma_f32_16x16x32_bf16 v[2:5], v[196:199], v[220:223], v[2:5]
	ds_read_b128 v[236:239], v245 offset:41536
	s_waitcnt lgkmcnt(6)
	v_mfma_f32_16x16x32_bf16 v[6:9], v[196:199], v[224:227], v[6:9]
	ds_read_b128 v[240:243], v245 offset:43840
	ds_read_b128 v[196:199], v244 offset:64
	s_waitcnt lgkmcnt(7)
	v_mfma_f32_16x16x32_bf16 v[42:45], v[200:203], v[212:215], v[42:45]
	v_mfma_f32_16x16x32_bf16 v[46:49], v[200:203], v[216:219], v[46:49]
	v_mfma_f32_16x16x32_bf16 v[10:13], v[200:203], v[220:223], v[10:13]
	v_mfma_f32_16x16x32_bf16 v[14:17], v[200:203], v[224:227], v[14:17]
	ds_read_b128 v[200:203], v244 offset:2368
	s_waitcnt lgkmcnt(7)
	v_mfma_f32_16x16x32_bf16 v[50:53], v[204:207], v[212:215], v[50:53]
	v_mfma_f32_16x16x32_bf16 v[54:57], v[204:207], v[216:219], v[54:57]
	v_mfma_f32_16x16x32_bf16 v[18:21], v[204:207], v[220:223], v[18:21]
	v_mfma_f32_16x16x32_bf16 v[22:25], v[204:207], v[224:227], v[22:25]
	ds_read_b128 v[204:207], v244 offset:4672
	s_waitcnt vmcnt(15)
	ds_write_b128 v95, v[98:101] offset:18432
	s_waitcnt vmcnt(14)
	ds_write_b128 v95, v[102:105] offset:23040
	s_waitcnt lgkmcnt(9)
	v_mfma_f32_16x16x32_bf16 v[58:61], v[208:211], v[212:215], v[58:61]
	v_mfma_f32_16x16x32_bf16 v[62:65], v[208:211], v[216:219], v[62:65]
	v_mfma_f32_16x16x32_bf16 v[26:29], v[208:211], v[220:223], v[26:29]
	v_mfma_f32_16x16x32_bf16 v[30:33], v[208:211], v[224:227], v[30:33]
	ds_read_b128 v[208:211], v244 offset:6976
	s_waitcnt vmcnt(13)
	ds_write_b128 v95, v[106:109] offset:27648
	s_waitcnt vmcnt(12)
	ds_write_b128 v95, v[110:113] offset:32256
	s_waitcnt lgkmcnt(7)
	v_mfma_f32_16x16x32_bf16 v[34:37], v[196:199], v[228:231], v[34:37]
	v_mfma_f32_16x16x32_bf16 v[38:41], v[196:199], v[232:235], v[38:41]
	v_mfma_f32_16x16x32_bf16 v[2:5], v[196:199], v[236:239], v[2:5]
	v_mfma_f32_16x16x32_bf16 v[6:9], v[196:199], v[240:243], v[6:9]
	s_waitcnt vmcnt(11)
	ds_write_b128 v95, v[114:117] offset:55296
	s_waitcnt vmcnt(10)
	ds_write_b128 v95, v[118:121] offset:59904
	s_waitcnt lgkmcnt(8)
	v_mfma_f32_16x16x32_bf16 v[42:45], v[200:203], v[228:231], v[42:45]
	v_mfma_f32_16x16x32_bf16 v[46:49], v[200:203], v[232:235], v[46:49]
	v_mfma_f32_16x16x32_bf16 v[10:13], v[200:203], v[236:239], v[10:13]
	v_mfma_f32_16x16x32_bf16 v[14:17], v[200:203], v[240:243], v[14:17]
	s_waitcnt vmcnt(9)
	ds_write_b128 v95, v[122:125] offset:64512
	s_waitcnt vmcnt(8)
	ds_write_b128 v96, v[126:129] offset:32256
	s_waitcnt lgkmcnt(0)
	s_barrier
	ds_read_b128 v[212:215], v245 offset:55296
	ds_read_b128 v[196:199], v244 offset:18432
	ds_read_b128 v[216:219], v245 offset:57600
	ds_read_b128 v[220:223], v245 offset:59904
	ds_read_b128 v[224:227], v245 offset:62208
	ds_read_b128 v[200:203], v244 offset:20736
	v_mfma_f32_16x16x32_bf16 v[50:53], v[204:207], v[228:231], v[50:53]
	v_mfma_f32_16x16x32_bf16 v[54:57], v[204:207], v[232:235], v[54:57]
	v_mfma_f32_16x16x32_bf16 v[18:21], v[204:207], v[236:239], v[18:21]
	v_mfma_f32_16x16x32_bf16 v[22:25], v[204:207], v[240:243], v[22:25]
	ds_read_b128 v[204:207], v244 offset:23040
	v_mfma_f32_16x16x32_bf16 v[58:61], v[208:211], v[228:231], v[58:61]
	v_mfma_f32_16x16x32_bf16 v[62:65], v[208:211], v[232:235], v[62:65]
	v_mfma_f32_16x16x32_bf16 v[26:29], v[208:211], v[236:239], v[26:29]
	v_mfma_f32_16x16x32_bf16 v[30:33], v[208:211], v[240:243], v[30:33]
	ds_read_b128 v[208:211], v244 offset:25344
	global_load_dwordx4 v[98:101], v[72:73], off offset:640
	global_load_dwordx4 v[102:105], v[74:75], off offset:640
	global_load_dwordx4 v[106:109], v[76:77], off offset:640
	global_load_dwordx4 v[110:113], v[78:79], off offset:640
	global_load_dwordx4 v[114:117], v[80:81], off offset:640
	global_load_dwordx4 v[118:121], v[82:83], off offset:640
	global_load_dwordx4 v[122:125], v[84:85], off offset:640
	global_load_dwordx4 v[126:129], v[86:87], off offset:640
	s_waitcnt lgkmcnt(6)
	v_mfma_f32_16x16x32_bf16 v[34:37], v[196:199], v[212:215], v[34:37]
	ds_read_b128 v[228:231], v245 offset:55360
	s_waitcnt lgkmcnt(6)
	v_mfma_f32_16x16x32_bf16 v[38:41], v[196:199], v[216:219], v[38:41]
	ds_read_b128 v[232:235], v245 offset:57664
	s_waitcnt lgkmcnt(6)
	v_mfma_f32_16x16x32_bf16 v[2:5], v[196:199], v[220:223], v[2:5]
	ds_read_b128 v[236:239], v245 offset:59968
	s_waitcnt lgkmcnt(6)
	v_mfma_f32_16x16x32_bf16 v[6:9], v[196:199], v[224:227], v[6:9]
	ds_read_b128 v[240:243], v245 offset:62272
	ds_read_b128 v[196:199], v244 offset:18496
	s_waitcnt lgkmcnt(7)
	v_mfma_f32_16x16x32_bf16 v[42:45], v[200:203], v[212:215], v[42:45]
	v_mfma_f32_16x16x32_bf16 v[46:49], v[200:203], v[216:219], v[46:49]
	v_mfma_f32_16x16x32_bf16 v[10:13], v[200:203], v[220:223], v[10:13]
	v_mfma_f32_16x16x32_bf16 v[14:17], v[200:203], v[224:227], v[14:17]
	ds_read_b128 v[200:203], v244 offset:20800
	s_waitcnt lgkmcnt(7)
	v_mfma_f32_16x16x32_bf16 v[50:53], v[204:207], v[212:215], v[50:53]
	v_mfma_f32_16x16x32_bf16 v[54:57], v[204:207], v[216:219], v[54:57]
	v_mfma_f32_16x16x32_bf16 v[18:21], v[204:207], v[220:223], v[18:21]
	v_mfma_f32_16x16x32_bf16 v[22:25], v[204:207], v[224:227], v[22:25]
	ds_read_b128 v[204:207], v244 offset:23104
	s_waitcnt vmcnt(15)
	ds_write_b128 v95, v[136:139]
	s_waitcnt vmcnt(14)
	ds_write_b128 v95, v[140:143] offset:4608
	s_waitcnt lgkmcnt(9)
	v_mfma_f32_16x16x32_bf16 v[58:61], v[208:211], v[212:215], v[58:61]
	v_mfma_f32_16x16x32_bf16 v[62:65], v[208:211], v[216:219], v[62:65]
	v_mfma_f32_16x16x32_bf16 v[26:29], v[208:211], v[220:223], v[26:29]
	v_mfma_f32_16x16x32_bf16 v[30:33], v[208:211], v[224:227], v[30:33]
	ds_read_b128 v[208:211], v244 offset:25408
	s_waitcnt vmcnt(13)
	ds_write_b128 v95, v[144:147] offset:9216
	s_waitcnt vmcnt(12)
	ds_write_b128 v95, v[148:151] offset:13824
	s_waitcnt lgkmcnt(7)
	v_mfma_f32_16x16x32_bf16 v[34:37], v[196:199], v[228:231], v[34:37]
	v_mfma_f32_16x16x32_bf16 v[38:41], v[196:199], v[232:235], v[38:41]
	v_mfma_f32_16x16x32_bf16 v[2:5], v[196:199], v[236:239], v[2:5]
	v_mfma_f32_16x16x32_bf16 v[6:9], v[196:199], v[240:243], v[6:9]
	s_waitcnt vmcnt(11)
	ds_write_b128 v95, v[152:155] offset:36864
	s_waitcnt vmcnt(10)
	ds_write_b128 v95, v[156:159] offset:41472
	s_waitcnt lgkmcnt(8)
	v_mfma_f32_16x16x32_bf16 v[42:45], v[200:203], v[228:231], v[42:45]
	v_mfma_f32_16x16x32_bf16 v[46:49], v[200:203], v[232:235], v[46:49]
	v_mfma_f32_16x16x32_bf16 v[10:13], v[200:203], v[236:239], v[10:13]
	v_mfma_f32_16x16x32_bf16 v[14:17], v[200:203], v[240:243], v[14:17]
	s_waitcnt vmcnt(9)
	ds_write_b128 v95, v[160:163] offset:46080
	s_waitcnt vmcnt(8)
	ds_write_b128 v95, v[164:167] offset:50688
	s_waitcnt lgkmcnt(0)
	s_barrier
	ds_read_b128 v[212:215], v245 offset:36864
	ds_read_b128 v[196:199], v244
	ds_read_b128 v[216:219], v245 offset:39168
	ds_read_b128 v[220:223], v245 offset:41472
	ds_read_b128 v[224:227], v245 offset:43776
	ds_read_b128 v[200:203], v244 offset:2304
	v_mfma_f32_16x16x32_bf16 v[50:53], v[204:207], v[228:231], v[50:53]
	v_mfma_f32_16x16x32_bf16 v[54:57], v[204:207], v[232:235], v[54:57]
	v_mfma_f32_16x16x32_bf16 v[18:21], v[204:207], v[236:239], v[18:21]
	v_mfma_f32_16x16x32_bf16 v[22:25], v[204:207], v[240:243], v[22:25]
	ds_read_b128 v[204:207], v244 offset:4608
	v_mfma_f32_16x16x32_bf16 v[58:61], v[208:211], v[228:231], v[58:61]
	v_mfma_f32_16x16x32_bf16 v[62:65], v[208:211], v[232:235], v[62:65]
	v_mfma_f32_16x16x32_bf16 v[26:29], v[208:211], v[236:239], v[26:29]
	v_mfma_f32_16x16x32_bf16 v[30:33], v[208:211], v[240:243], v[30:33]
	ds_read_b128 v[208:211], v244 offset:6912
	global_load_dwordx4 v[136:139], v[72:73], off offset:768
	global_load_dwordx4 v[140:143], v[74:75], off offset:768
	global_load_dwordx4 v[144:147], v[76:77], off offset:768
	global_load_dwordx4 v[148:151], v[78:79], off offset:768
	global_load_dwordx4 v[152:155], v[80:81], off offset:768
	global_load_dwordx4 v[156:159], v[82:83], off offset:768
	global_load_dwordx4 v[160:163], v[84:85], off offset:768
	global_load_dwordx4 v[164:167], v[86:87], off offset:768
	s_waitcnt lgkmcnt(6)
	v_mfma_f32_16x16x32_bf16 v[34:37], v[196:199], v[212:215], v[34:37]
	ds_read_b128 v[228:231], v245 offset:36928
	s_waitcnt lgkmcnt(6)
	v_mfma_f32_16x16x32_bf16 v[38:41], v[196:199], v[216:219], v[38:41]
	ds_read_b128 v[232:235], v245 offset:39232
	s_waitcnt lgkmcnt(6)
	v_mfma_f32_16x16x32_bf16 v[2:5], v[196:199], v[220:223], v[2:5]
	ds_read_b128 v[236:239], v245 offset:41536
	s_waitcnt lgkmcnt(6)
	v_mfma_f32_16x16x32_bf16 v[6:9], v[196:199], v[224:227], v[6:9]
	ds_read_b128 v[240:243], v245 offset:43840
	ds_read_b128 v[196:199], v244 offset:64
	s_waitcnt lgkmcnt(7)
	v_mfma_f32_16x16x32_bf16 v[42:45], v[200:203], v[212:215], v[42:45]
	v_mfma_f32_16x16x32_bf16 v[46:49], v[200:203], v[216:219], v[46:49]
	v_mfma_f32_16x16x32_bf16 v[10:13], v[200:203], v[220:223], v[10:13]
	v_mfma_f32_16x16x32_bf16 v[14:17], v[200:203], v[224:227], v[14:17]
	ds_read_b128 v[200:203], v244 offset:2368
	s_waitcnt lgkmcnt(7)
	v_mfma_f32_16x16x32_bf16 v[50:53], v[204:207], v[212:215], v[50:53]
	v_mfma_f32_16x16x32_bf16 v[54:57], v[204:207], v[216:219], v[54:57]
	v_mfma_f32_16x16x32_bf16 v[18:21], v[204:207], v[220:223], v[18:21]
	v_mfma_f32_16x16x32_bf16 v[22:25], v[204:207], v[224:227], v[22:25]
	ds_read_b128 v[204:207], v244 offset:4672
	s_waitcnt vmcnt(15)
	ds_write_b128 v95, v[98:101] offset:18432
	s_waitcnt vmcnt(14)
	ds_write_b128 v95, v[102:105] offset:23040
	s_waitcnt lgkmcnt(9)
	v_mfma_f32_16x16x32_bf16 v[58:61], v[208:211], v[212:215], v[58:61]
	v_mfma_f32_16x16x32_bf16 v[62:65], v[208:211], v[216:219], v[62:65]
	v_mfma_f32_16x16x32_bf16 v[26:29], v[208:211], v[220:223], v[26:29]
	v_mfma_f32_16x16x32_bf16 v[30:33], v[208:211], v[224:227], v[30:33]
	ds_read_b128 v[208:211], v244 offset:6976
	s_waitcnt vmcnt(13)
	ds_write_b128 v95, v[106:109] offset:27648
	s_waitcnt vmcnt(12)
	ds_write_b128 v95, v[110:113] offset:32256
	s_waitcnt lgkmcnt(7)
	v_mfma_f32_16x16x32_bf16 v[34:37], v[196:199], v[228:231], v[34:37]
	v_mfma_f32_16x16x32_bf16 v[38:41], v[196:199], v[232:235], v[38:41]
	v_mfma_f32_16x16x32_bf16 v[2:5], v[196:199], v[236:239], v[2:5]
	v_mfma_f32_16x16x32_bf16 v[6:9], v[196:199], v[240:243], v[6:9]
	s_waitcnt vmcnt(11)
	ds_write_b128 v95, v[114:117] offset:55296
	s_waitcnt vmcnt(10)
	ds_write_b128 v95, v[118:121] offset:59904
	s_waitcnt lgkmcnt(8)
	v_mfma_f32_16x16x32_bf16 v[42:45], v[200:203], v[228:231], v[42:45]
	v_mfma_f32_16x16x32_bf16 v[46:49], v[200:203], v[232:235], v[46:49]
	v_mfma_f32_16x16x32_bf16 v[10:13], v[200:203], v[236:239], v[10:13]
	v_mfma_f32_16x16x32_bf16 v[14:17], v[200:203], v[240:243], v[14:17]
	s_waitcnt vmcnt(9)
	ds_write_b128 v95, v[122:125] offset:64512
	s_waitcnt vmcnt(8)
	ds_write_b128 v96, v[126:129] offset:32256
	s_waitcnt lgkmcnt(0)
	s_barrier
	ds_read_b128 v[212:215], v245 offset:55296
	ds_read_b128 v[196:199], v244 offset:18432
	ds_read_b128 v[216:219], v245 offset:57600
	ds_read_b128 v[220:223], v245 offset:59904
	ds_read_b128 v[224:227], v245 offset:62208
	ds_read_b128 v[200:203], v244 offset:20736
	v_mfma_f32_16x16x32_bf16 v[50:53], v[204:207], v[228:231], v[50:53]
	v_mfma_f32_16x16x32_bf16 v[54:57], v[204:207], v[232:235], v[54:57]
	v_mfma_f32_16x16x32_bf16 v[18:21], v[204:207], v[236:239], v[18:21]
	v_mfma_f32_16x16x32_bf16 v[22:25], v[204:207], v[240:243], v[22:25]
	ds_read_b128 v[204:207], v244 offset:23040
	v_mfma_f32_16x16x32_bf16 v[58:61], v[208:211], v[228:231], v[58:61]
	v_mfma_f32_16x16x32_bf16 v[62:65], v[208:211], v[232:235], v[62:65]
	v_mfma_f32_16x16x32_bf16 v[26:29], v[208:211], v[236:239], v[26:29]
	v_mfma_f32_16x16x32_bf16 v[30:33], v[208:211], v[240:243], v[30:33]
	ds_read_b128 v[208:211], v244 offset:25344
	global_load_dwordx4 v[98:101], v[72:73], off offset:896
	global_load_dwordx4 v[102:105], v[74:75], off offset:896
	global_load_dwordx4 v[106:109], v[76:77], off offset:896
	global_load_dwordx4 v[110:113], v[78:79], off offset:896
	global_load_dwordx4 v[114:117], v[80:81], off offset:896
	global_load_dwordx4 v[118:121], v[82:83], off offset:896
	global_load_dwordx4 v[122:125], v[84:85], off offset:896
	global_load_dwordx4 v[126:129], v[86:87], off offset:896
	s_waitcnt lgkmcnt(6)
	v_mfma_f32_16x16x32_bf16 v[34:37], v[196:199], v[212:215], v[34:37]
	ds_read_b128 v[228:231], v245 offset:55360
	s_waitcnt lgkmcnt(6)
	v_mfma_f32_16x16x32_bf16 v[38:41], v[196:199], v[216:219], v[38:41]
	ds_read_b128 v[232:235], v245 offset:57664
	s_waitcnt lgkmcnt(6)
	v_mfma_f32_16x16x32_bf16 v[2:5], v[196:199], v[220:223], v[2:5]
	ds_read_b128 v[236:239], v245 offset:59968
	s_waitcnt lgkmcnt(6)
	v_mfma_f32_16x16x32_bf16 v[6:9], v[196:199], v[224:227], v[6:9]
	ds_read_b128 v[240:243], v245 offset:62272
	ds_read_b128 v[196:199], v244 offset:18496
	s_waitcnt lgkmcnt(7)
	v_mfma_f32_16x16x32_bf16 v[42:45], v[200:203], v[212:215], v[42:45]
	v_mfma_f32_16x16x32_bf16 v[46:49], v[200:203], v[216:219], v[46:49]
	v_mfma_f32_16x16x32_bf16 v[10:13], v[200:203], v[220:223], v[10:13]
	v_mfma_f32_16x16x32_bf16 v[14:17], v[200:203], v[224:227], v[14:17]
	ds_read_b128 v[200:203], v244 offset:20800
	s_waitcnt lgkmcnt(7)
	v_mfma_f32_16x16x32_bf16 v[50:53], v[204:207], v[212:215], v[50:53]
	v_mfma_f32_16x16x32_bf16 v[54:57], v[204:207], v[216:219], v[54:57]
	v_mfma_f32_16x16x32_bf16 v[18:21], v[204:207], v[220:223], v[18:21]
	v_mfma_f32_16x16x32_bf16 v[22:25], v[204:207], v[224:227], v[22:25]
	ds_read_b128 v[204:207], v244 offset:23104
	s_waitcnt vmcnt(15)
	ds_write_b128 v95, v[136:139]
	s_waitcnt vmcnt(14)
	ds_write_b128 v95, v[140:143] offset:4608
	s_waitcnt lgkmcnt(9)
	v_mfma_f32_16x16x32_bf16 v[58:61], v[208:211], v[212:215], v[58:61]
	v_mfma_f32_16x16x32_bf16 v[62:65], v[208:211], v[216:219], v[62:65]
	v_mfma_f32_16x16x32_bf16 v[26:29], v[208:211], v[220:223], v[26:29]
	v_mfma_f32_16x16x32_bf16 v[30:33], v[208:211], v[224:227], v[30:33]
	ds_read_b128 v[208:211], v244 offset:25408
	s_waitcnt vmcnt(13)
	ds_write_b128 v95, v[144:147] offset:9216
	s_waitcnt vmcnt(12)
	ds_write_b128 v95, v[148:151] offset:13824
	s_waitcnt lgkmcnt(7)
	v_mfma_f32_16x16x32_bf16 v[34:37], v[196:199], v[228:231], v[34:37]
	v_mfma_f32_16x16x32_bf16 v[38:41], v[196:199], v[232:235], v[38:41]
	v_mfma_f32_16x16x32_bf16 v[2:5], v[196:199], v[236:239], v[2:5]
	v_mfma_f32_16x16x32_bf16 v[6:9], v[196:199], v[240:243], v[6:9]
	s_waitcnt vmcnt(11)
	ds_write_b128 v95, v[152:155] offset:36864
	s_waitcnt vmcnt(10)
	ds_write_b128 v95, v[156:159] offset:41472
	s_waitcnt lgkmcnt(8)
	v_mfma_f32_16x16x32_bf16 v[42:45], v[200:203], v[228:231], v[42:45]
	v_mfma_f32_16x16x32_bf16 v[46:49], v[200:203], v[232:235], v[46:49]
	v_mfma_f32_16x16x32_bf16 v[10:13], v[200:203], v[236:239], v[10:13]
	v_mfma_f32_16x16x32_bf16 v[14:17], v[200:203], v[240:243], v[14:17]
	s_waitcnt vmcnt(9)
	ds_write_b128 v95, v[160:163] offset:46080
	s_waitcnt vmcnt(8)
	ds_write_b128 v95, v[164:167] offset:50688
	s_waitcnt lgkmcnt(0)
	s_barrier
	ds_read_b128 v[212:215], v245 offset:36864
	ds_read_b128 v[196:199], v244
	ds_read_b128 v[216:219], v245 offset:39168
	ds_read_b128 v[220:223], v245 offset:41472
	ds_read_b128 v[224:227], v245 offset:43776
	ds_read_b128 v[200:203], v244 offset:2304
	v_mfma_f32_16x16x32_bf16 v[50:53], v[204:207], v[228:231], v[50:53]
	v_mfma_f32_16x16x32_bf16 v[54:57], v[204:207], v[232:235], v[54:57]
	v_mfma_f32_16x16x32_bf16 v[18:21], v[204:207], v[236:239], v[18:21]
	v_mfma_f32_16x16x32_bf16 v[22:25], v[204:207], v[240:243], v[22:25]
	ds_read_b128 v[204:207], v244 offset:4608
	v_mfma_f32_16x16x32_bf16 v[58:61], v[208:211], v[228:231], v[58:61]
	v_mfma_f32_16x16x32_bf16 v[62:65], v[208:211], v[232:235], v[62:65]
	v_mfma_f32_16x16x32_bf16 v[26:29], v[208:211], v[236:239], v[26:29]
	v_mfma_f32_16x16x32_bf16 v[30:33], v[208:211], v[240:243], v[30:33]
	ds_read_b128 v[208:211], v244 offset:6912
	global_load_dwordx4 v[136:139], v[72:73], off offset:1024
	global_load_dwordx4 v[140:143], v[74:75], off offset:1024
	global_load_dwordx4 v[144:147], v[76:77], off offset:1024
	global_load_dwordx4 v[148:151], v[78:79], off offset:1024
	global_load_dwordx4 v[152:155], v[80:81], off offset:1024
	global_load_dwordx4 v[156:159], v[82:83], off offset:1024
	global_load_dwordx4 v[160:163], v[84:85], off offset:1024
	global_load_dwordx4 v[164:167], v[86:87], off offset:1024
	s_waitcnt lgkmcnt(6)
	v_mfma_f32_16x16x32_bf16 v[34:37], v[196:199], v[212:215], v[34:37]
	ds_read_b128 v[228:231], v245 offset:36928
	s_waitcnt lgkmcnt(6)
	v_mfma_f32_16x16x32_bf16 v[38:41], v[196:199], v[216:219], v[38:41]
	ds_read_b128 v[232:235], v245 offset:39232
	s_waitcnt lgkmcnt(6)
	v_mfma_f32_16x16x32_bf16 v[2:5], v[196:199], v[220:223], v[2:5]
	ds_read_b128 v[236:239], v245 offset:41536
	s_waitcnt lgkmcnt(6)
	v_mfma_f32_16x16x32_bf16 v[6:9], v[196:199], v[224:227], v[6:9]
	ds_read_b128 v[240:243], v245 offset:43840
	ds_read_b128 v[196:199], v244 offset:64
	s_waitcnt lgkmcnt(7)
	v_mfma_f32_16x16x32_bf16 v[42:45], v[200:203], v[212:215], v[42:45]
	v_mfma_f32_16x16x32_bf16 v[46:49], v[200:203], v[216:219], v[46:49]
	v_mfma_f32_16x16x32_bf16 v[10:13], v[200:203], v[220:223], v[10:13]
	v_mfma_f32_16x16x32_bf16 v[14:17], v[200:203], v[224:227], v[14:17]
	ds_read_b128 v[200:203], v244 offset:2368
	s_waitcnt lgkmcnt(7)
	v_mfma_f32_16x16x32_bf16 v[50:53], v[204:207], v[212:215], v[50:53]
	v_mfma_f32_16x16x32_bf16 v[54:57], v[204:207], v[216:219], v[54:57]
	v_mfma_f32_16x16x32_bf16 v[18:21], v[204:207], v[220:223], v[18:21]
	v_mfma_f32_16x16x32_bf16 v[22:25], v[204:207], v[224:227], v[22:25]
	ds_read_b128 v[204:207], v244 offset:4672
	s_waitcnt vmcnt(15)
	ds_write_b128 v95, v[98:101] offset:18432
	s_waitcnt vmcnt(14)
	ds_write_b128 v95, v[102:105] offset:23040
	s_waitcnt lgkmcnt(9)
	v_mfma_f32_16x16x32_bf16 v[58:61], v[208:211], v[212:215], v[58:61]
	v_mfma_f32_16x16x32_bf16 v[62:65], v[208:211], v[216:219], v[62:65]
	v_mfma_f32_16x16x32_bf16 v[26:29], v[208:211], v[220:223], v[26:29]
	v_mfma_f32_16x16x32_bf16 v[30:33], v[208:211], v[224:227], v[30:33]
	ds_read_b128 v[208:211], v244 offset:6976
	s_waitcnt vmcnt(13)
	ds_write_b128 v95, v[106:109] offset:27648
	s_waitcnt vmcnt(12)
	ds_write_b128 v95, v[110:113] offset:32256
	s_waitcnt lgkmcnt(7)
	v_mfma_f32_16x16x32_bf16 v[34:37], v[196:199], v[228:231], v[34:37]
	v_mfma_f32_16x16x32_bf16 v[38:41], v[196:199], v[232:235], v[38:41]
	v_mfma_f32_16x16x32_bf16 v[2:5], v[196:199], v[236:239], v[2:5]
	v_mfma_f32_16x16x32_bf16 v[6:9], v[196:199], v[240:243], v[6:9]
	s_waitcnt vmcnt(11)
	ds_write_b128 v95, v[114:117] offset:55296
	s_waitcnt vmcnt(10)
	ds_write_b128 v95, v[118:121] offset:59904
	s_waitcnt lgkmcnt(8)
	v_mfma_f32_16x16x32_bf16 v[42:45], v[200:203], v[228:231], v[42:45]
	v_mfma_f32_16x16x32_bf16 v[46:49], v[200:203], v[232:235], v[46:49]
	v_mfma_f32_16x16x32_bf16 v[10:13], v[200:203], v[236:239], v[10:13]
	v_mfma_f32_16x16x32_bf16 v[14:17], v[200:203], v[240:243], v[14:17]
	s_waitcnt vmcnt(9)
	ds_write_b128 v95, v[122:125] offset:64512
	s_waitcnt vmcnt(8)
	ds_write_b128 v96, v[126:129] offset:32256
	s_waitcnt lgkmcnt(0)
	s_barrier
	ds_read_b128 v[212:215], v245 offset:55296
	ds_read_b128 v[196:199], v244 offset:18432
	ds_read_b128 v[216:219], v245 offset:57600
	ds_read_b128 v[220:223], v245 offset:59904
	ds_read_b128 v[224:227], v245 offset:62208
	ds_read_b128 v[200:203], v244 offset:20736
	v_mfma_f32_16x16x32_bf16 v[50:53], v[204:207], v[228:231], v[50:53]
	v_mfma_f32_16x16x32_bf16 v[54:57], v[204:207], v[232:235], v[54:57]
	v_mfma_f32_16x16x32_bf16 v[18:21], v[204:207], v[236:239], v[18:21]
	v_mfma_f32_16x16x32_bf16 v[22:25], v[204:207], v[240:243], v[22:25]
	ds_read_b128 v[204:207], v244 offset:23040
	v_mfma_f32_16x16x32_bf16 v[58:61], v[208:211], v[228:231], v[58:61]
	v_mfma_f32_16x16x32_bf16 v[62:65], v[208:211], v[232:235], v[62:65]
	v_mfma_f32_16x16x32_bf16 v[26:29], v[208:211], v[236:239], v[26:29]
	v_mfma_f32_16x16x32_bf16 v[30:33], v[208:211], v[240:243], v[30:33]
	ds_read_b128 v[208:211], v244 offset:25344
	global_load_dwordx4 v[98:101], v[72:73], off offset:1152
	global_load_dwordx4 v[102:105], v[74:75], off offset:1152
	global_load_dwordx4 v[106:109], v[76:77], off offset:1152
	global_load_dwordx4 v[110:113], v[78:79], off offset:1152
	global_load_dwordx4 v[114:117], v[80:81], off offset:1152
	global_load_dwordx4 v[118:121], v[82:83], off offset:1152
	global_load_dwordx4 v[122:125], v[84:85], off offset:1152
	global_load_dwordx4 v[126:129], v[86:87], off offset:1152
	s_waitcnt lgkmcnt(6)
	v_mfma_f32_16x16x32_bf16 v[34:37], v[196:199], v[212:215], v[34:37]
	ds_read_b128 v[228:231], v245 offset:55360
	s_waitcnt lgkmcnt(6)
	v_mfma_f32_16x16x32_bf16 v[38:41], v[196:199], v[216:219], v[38:41]
	ds_read_b128 v[232:235], v245 offset:57664
	s_waitcnt lgkmcnt(6)
	v_mfma_f32_16x16x32_bf16 v[2:5], v[196:199], v[220:223], v[2:5]
	ds_read_b128 v[236:239], v245 offset:59968
	s_waitcnt lgkmcnt(6)
	v_mfma_f32_16x16x32_bf16 v[6:9], v[196:199], v[224:227], v[6:9]
	ds_read_b128 v[240:243], v245 offset:62272
	ds_read_b128 v[196:199], v244 offset:18496
	s_waitcnt lgkmcnt(7)
	v_mfma_f32_16x16x32_bf16 v[42:45], v[200:203], v[212:215], v[42:45]
	v_mfma_f32_16x16x32_bf16 v[46:49], v[200:203], v[216:219], v[46:49]
	v_mfma_f32_16x16x32_bf16 v[10:13], v[200:203], v[220:223], v[10:13]
	v_mfma_f32_16x16x32_bf16 v[14:17], v[200:203], v[224:227], v[14:17]
	ds_read_b128 v[200:203], v244 offset:20800
	s_waitcnt lgkmcnt(7)
	v_mfma_f32_16x16x32_bf16 v[50:53], v[204:207], v[212:215], v[50:53]
	v_mfma_f32_16x16x32_bf16 v[54:57], v[204:207], v[216:219], v[54:57]
	v_mfma_f32_16x16x32_bf16 v[18:21], v[204:207], v[220:223], v[18:21]
	v_mfma_f32_16x16x32_bf16 v[22:25], v[204:207], v[224:227], v[22:25]
	ds_read_b128 v[204:207], v244 offset:23104
	s_waitcnt vmcnt(15)
	ds_write_b128 v95, v[136:139]
	s_waitcnt vmcnt(14)
	ds_write_b128 v95, v[140:143] offset:4608
	s_waitcnt lgkmcnt(9)
	v_mfma_f32_16x16x32_bf16 v[58:61], v[208:211], v[212:215], v[58:61]
	v_mfma_f32_16x16x32_bf16 v[62:65], v[208:211], v[216:219], v[62:65]
	v_mfma_f32_16x16x32_bf16 v[26:29], v[208:211], v[220:223], v[26:29]
	v_mfma_f32_16x16x32_bf16 v[30:33], v[208:211], v[224:227], v[30:33]
	ds_read_b128 v[208:211], v244 offset:25408
	s_waitcnt vmcnt(13)
	ds_write_b128 v95, v[144:147] offset:9216
	s_waitcnt vmcnt(12)
	ds_write_b128 v95, v[148:151] offset:13824
	s_waitcnt lgkmcnt(7)
	v_mfma_f32_16x16x32_bf16 v[34:37], v[196:199], v[228:231], v[34:37]
	v_mfma_f32_16x16x32_bf16 v[38:41], v[196:199], v[232:235], v[38:41]
	v_mfma_f32_16x16x32_bf16 v[2:5], v[196:199], v[236:239], v[2:5]
	v_mfma_f32_16x16x32_bf16 v[6:9], v[196:199], v[240:243], v[6:9]
	s_waitcnt vmcnt(11)
	ds_write_b128 v95, v[152:155] offset:36864
	s_waitcnt vmcnt(10)
	ds_write_b128 v95, v[156:159] offset:41472
	s_waitcnt lgkmcnt(8)
	v_mfma_f32_16x16x32_bf16 v[42:45], v[200:203], v[228:231], v[42:45]
	v_mfma_f32_16x16x32_bf16 v[46:49], v[200:203], v[232:235], v[46:49]
	v_mfma_f32_16x16x32_bf16 v[10:13], v[200:203], v[236:239], v[10:13]
	v_mfma_f32_16x16x32_bf16 v[14:17], v[200:203], v[240:243], v[14:17]
	s_waitcnt vmcnt(9)
	ds_write_b128 v95, v[160:163] offset:46080
	s_waitcnt vmcnt(8)
	ds_write_b128 v95, v[164:167] offset:50688
	s_waitcnt lgkmcnt(0)
	s_barrier
	ds_read_b128 v[212:215], v245 offset:36864
	ds_read_b128 v[196:199], v244
	ds_read_b128 v[216:219], v245 offset:39168
	ds_read_b128 v[220:223], v245 offset:41472
	ds_read_b128 v[224:227], v245 offset:43776
	ds_read_b128 v[200:203], v244 offset:2304
	v_mfma_f32_16x16x32_bf16 v[50:53], v[204:207], v[228:231], v[50:53]
	v_mfma_f32_16x16x32_bf16 v[54:57], v[204:207], v[232:235], v[54:57]
	v_mfma_f32_16x16x32_bf16 v[18:21], v[204:207], v[236:239], v[18:21]
	v_mfma_f32_16x16x32_bf16 v[22:25], v[204:207], v[240:243], v[22:25]
	ds_read_b128 v[204:207], v244 offset:4608
	v_mfma_f32_16x16x32_bf16 v[58:61], v[208:211], v[228:231], v[58:61]
	v_mfma_f32_16x16x32_bf16 v[62:65], v[208:211], v[232:235], v[62:65]
	v_mfma_f32_16x16x32_bf16 v[26:29], v[208:211], v[236:239], v[26:29]
	v_mfma_f32_16x16x32_bf16 v[30:33], v[208:211], v[240:243], v[30:33]
	ds_read_b128 v[208:211], v244 offset:6912
	global_load_dwordx4 v[136:139], v[72:73], off offset:1280
	global_load_dwordx4 v[140:143], v[74:75], off offset:1280
	global_load_dwordx4 v[144:147], v[76:77], off offset:1280
	global_load_dwordx4 v[148:151], v[78:79], off offset:1280
	global_load_dwordx4 v[152:155], v[80:81], off offset:1280
	global_load_dwordx4 v[156:159], v[82:83], off offset:1280
	global_load_dwordx4 v[160:163], v[84:85], off offset:1280
	global_load_dwordx4 v[164:167], v[86:87], off offset:1280
	s_waitcnt lgkmcnt(6)
	v_mfma_f32_16x16x32_bf16 v[34:37], v[196:199], v[212:215], v[34:37]
	ds_read_b128 v[228:231], v245 offset:36928
	s_waitcnt lgkmcnt(6)
	v_mfma_f32_16x16x32_bf16 v[38:41], v[196:199], v[216:219], v[38:41]
	ds_read_b128 v[232:235], v245 offset:39232
	s_waitcnt lgkmcnt(6)
	v_mfma_f32_16x16x32_bf16 v[2:5], v[196:199], v[220:223], v[2:5]
	ds_read_b128 v[236:239], v245 offset:41536
	s_waitcnt lgkmcnt(6)
	v_mfma_f32_16x16x32_bf16 v[6:9], v[196:199], v[224:227], v[6:9]
	ds_read_b128 v[240:243], v245 offset:43840
	ds_read_b128 v[196:199], v244 offset:64
	s_waitcnt lgkmcnt(7)
	v_mfma_f32_16x16x32_bf16 v[42:45], v[200:203], v[212:215], v[42:45]
	v_mfma_f32_16x16x32_bf16 v[46:49], v[200:203], v[216:219], v[46:49]
	v_mfma_f32_16x16x32_bf16 v[10:13], v[200:203], v[220:223], v[10:13]
	v_mfma_f32_16x16x32_bf16 v[14:17], v[200:203], v[224:227], v[14:17]
	ds_read_b128 v[200:203], v244 offset:2368
	s_waitcnt lgkmcnt(7)
	v_mfma_f32_16x16x32_bf16 v[50:53], v[204:207], v[212:215], v[50:53]
	v_mfma_f32_16x16x32_bf16 v[54:57], v[204:207], v[216:219], v[54:57]
	v_mfma_f32_16x16x32_bf16 v[18:21], v[204:207], v[220:223], v[18:21]
	v_mfma_f32_16x16x32_bf16 v[22:25], v[204:207], v[224:227], v[22:25]
	ds_read_b128 v[204:207], v244 offset:4672
	s_waitcnt vmcnt(15)
	ds_write_b128 v95, v[98:101] offset:18432
	s_waitcnt vmcnt(14)
	ds_write_b128 v95, v[102:105] offset:23040
	s_waitcnt lgkmcnt(9)
	v_mfma_f32_16x16x32_bf16 v[58:61], v[208:211], v[212:215], v[58:61]
	v_mfma_f32_16x16x32_bf16 v[62:65], v[208:211], v[216:219], v[62:65]
	v_mfma_f32_16x16x32_bf16 v[26:29], v[208:211], v[220:223], v[26:29]
	v_mfma_f32_16x16x32_bf16 v[30:33], v[208:211], v[224:227], v[30:33]
	ds_read_b128 v[208:211], v244 offset:6976
	s_waitcnt vmcnt(13)
	ds_write_b128 v95, v[106:109] offset:27648
	s_waitcnt vmcnt(12)
	ds_write_b128 v95, v[110:113] offset:32256
	s_waitcnt lgkmcnt(7)
	v_mfma_f32_16x16x32_bf16 v[34:37], v[196:199], v[228:231], v[34:37]
	v_mfma_f32_16x16x32_bf16 v[38:41], v[196:199], v[232:235], v[38:41]
	v_mfma_f32_16x16x32_bf16 v[2:5], v[196:199], v[236:239], v[2:5]
	v_mfma_f32_16x16x32_bf16 v[6:9], v[196:199], v[240:243], v[6:9]
	s_waitcnt vmcnt(11)
	ds_write_b128 v95, v[114:117] offset:55296
	s_waitcnt vmcnt(10)
	ds_write_b128 v95, v[118:121] offset:59904
	s_waitcnt lgkmcnt(8)
	v_mfma_f32_16x16x32_bf16 v[42:45], v[200:203], v[228:231], v[42:45]
	v_mfma_f32_16x16x32_bf16 v[46:49], v[200:203], v[232:235], v[46:49]
	v_mfma_f32_16x16x32_bf16 v[10:13], v[200:203], v[236:239], v[10:13]
	v_mfma_f32_16x16x32_bf16 v[14:17], v[200:203], v[240:243], v[14:17]
	s_waitcnt vmcnt(9)
	ds_write_b128 v95, v[122:125] offset:64512
	s_waitcnt vmcnt(8)
	ds_write_b128 v96, v[126:129] offset:32256
	s_waitcnt lgkmcnt(0)
	s_barrier
	ds_read_b128 v[212:215], v245 offset:55296
	ds_read_b128 v[196:199], v244 offset:18432
	ds_read_b128 v[216:219], v245 offset:57600
	ds_read_b128 v[220:223], v245 offset:59904
	ds_read_b128 v[224:227], v245 offset:62208
	ds_read_b128 v[200:203], v244 offset:20736
	v_mfma_f32_16x16x32_bf16 v[50:53], v[204:207], v[228:231], v[50:53]
	v_mfma_f32_16x16x32_bf16 v[54:57], v[204:207], v[232:235], v[54:57]
	v_mfma_f32_16x16x32_bf16 v[18:21], v[204:207], v[236:239], v[18:21]
	v_mfma_f32_16x16x32_bf16 v[22:25], v[204:207], v[240:243], v[22:25]
	ds_read_b128 v[204:207], v244 offset:23040
	v_mfma_f32_16x16x32_bf16 v[58:61], v[208:211], v[228:231], v[58:61]
	v_mfma_f32_16x16x32_bf16 v[62:65], v[208:211], v[232:235], v[62:65]
	v_mfma_f32_16x16x32_bf16 v[26:29], v[208:211], v[236:239], v[26:29]
	v_mfma_f32_16x16x32_bf16 v[30:33], v[208:211], v[240:243], v[30:33]
	ds_read_b128 v[208:211], v244 offset:25344
	global_load_dwordx4 v[98:101], v[72:73], off offset:1408
	global_load_dwordx4 v[102:105], v[74:75], off offset:1408
	global_load_dwordx4 v[106:109], v[76:77], off offset:1408
	global_load_dwordx4 v[110:113], v[78:79], off offset:1408
	global_load_dwordx4 v[114:117], v[80:81], off offset:1408
	global_load_dwordx4 v[118:121], v[82:83], off offset:1408
	global_load_dwordx4 v[122:125], v[84:85], off offset:1408
	global_load_dwordx4 v[126:129], v[86:87], off offset:1408
	s_waitcnt lgkmcnt(6)
	v_mfma_f32_16x16x32_bf16 v[34:37], v[196:199], v[212:215], v[34:37]
	ds_read_b128 v[228:231], v245 offset:55360
	s_waitcnt lgkmcnt(6)
	v_mfma_f32_16x16x32_bf16 v[38:41], v[196:199], v[216:219], v[38:41]
	ds_read_b128 v[232:235], v245 offset:57664
	s_waitcnt lgkmcnt(6)
	v_mfma_f32_16x16x32_bf16 v[2:5], v[196:199], v[220:223], v[2:5]
	ds_read_b128 v[236:239], v245 offset:59968
	s_waitcnt lgkmcnt(6)
	v_mfma_f32_16x16x32_bf16 v[6:9], v[196:199], v[224:227], v[6:9]
	ds_read_b128 v[240:243], v245 offset:62272
	ds_read_b128 v[196:199], v244 offset:18496
	s_waitcnt lgkmcnt(7)
	v_mfma_f32_16x16x32_bf16 v[42:45], v[200:203], v[212:215], v[42:45]
	v_mfma_f32_16x16x32_bf16 v[46:49], v[200:203], v[216:219], v[46:49]
	v_mfma_f32_16x16x32_bf16 v[10:13], v[200:203], v[220:223], v[10:13]
	v_mfma_f32_16x16x32_bf16 v[14:17], v[200:203], v[224:227], v[14:17]
	ds_read_b128 v[200:203], v244 offset:20800
	s_waitcnt lgkmcnt(7)
	v_mfma_f32_16x16x32_bf16 v[50:53], v[204:207], v[212:215], v[50:53]
	v_mfma_f32_16x16x32_bf16 v[54:57], v[204:207], v[216:219], v[54:57]
	v_mfma_f32_16x16x32_bf16 v[18:21], v[204:207], v[220:223], v[18:21]
	v_mfma_f32_16x16x32_bf16 v[22:25], v[204:207], v[224:227], v[22:25]
	ds_read_b128 v[204:207], v244 offset:23104
	s_waitcnt vmcnt(15)
	ds_write_b128 v95, v[136:139]
	s_waitcnt vmcnt(14)
	ds_write_b128 v95, v[140:143] offset:4608
	s_waitcnt lgkmcnt(9)
	v_mfma_f32_16x16x32_bf16 v[58:61], v[208:211], v[212:215], v[58:61]
	v_mfma_f32_16x16x32_bf16 v[62:65], v[208:211], v[216:219], v[62:65]
	v_mfma_f32_16x16x32_bf16 v[26:29], v[208:211], v[220:223], v[26:29]
	v_mfma_f32_16x16x32_bf16 v[30:33], v[208:211], v[224:227], v[30:33]
	ds_read_b128 v[208:211], v244 offset:25408
	s_waitcnt vmcnt(13)
	ds_write_b128 v95, v[144:147] offset:9216
	s_waitcnt vmcnt(12)
	ds_write_b128 v95, v[148:151] offset:13824
	s_waitcnt lgkmcnt(7)
	v_mfma_f32_16x16x32_bf16 v[34:37], v[196:199], v[228:231], v[34:37]
	v_mfma_f32_16x16x32_bf16 v[38:41], v[196:199], v[232:235], v[38:41]
	v_mfma_f32_16x16x32_bf16 v[2:5], v[196:199], v[236:239], v[2:5]
	v_mfma_f32_16x16x32_bf16 v[6:9], v[196:199], v[240:243], v[6:9]
	s_waitcnt vmcnt(11)
	ds_write_b128 v95, v[152:155] offset:36864
	s_waitcnt vmcnt(10)
	ds_write_b128 v95, v[156:159] offset:41472
	s_waitcnt lgkmcnt(8)
	v_mfma_f32_16x16x32_bf16 v[42:45], v[200:203], v[228:231], v[42:45]
	v_mfma_f32_16x16x32_bf16 v[46:49], v[200:203], v[232:235], v[46:49]
	v_mfma_f32_16x16x32_bf16 v[10:13], v[200:203], v[236:239], v[10:13]
	v_mfma_f32_16x16x32_bf16 v[14:17], v[200:203], v[240:243], v[14:17]
	s_waitcnt vmcnt(9)
	ds_write_b128 v95, v[160:163] offset:46080
	s_waitcnt vmcnt(8)
	ds_write_b128 v95, v[164:167] offset:50688
	s_waitcnt lgkmcnt(0)
	s_barrier
	ds_read_b128 v[212:215], v245 offset:36864
	ds_read_b128 v[196:199], v244
	ds_read_b128 v[216:219], v245 offset:39168
	ds_read_b128 v[220:223], v245 offset:41472
	ds_read_b128 v[224:227], v245 offset:43776
	ds_read_b128 v[200:203], v244 offset:2304
	v_mfma_f32_16x16x32_bf16 v[50:53], v[204:207], v[228:231], v[50:53]
	v_mfma_f32_16x16x32_bf16 v[54:57], v[204:207], v[232:235], v[54:57]
	v_mfma_f32_16x16x32_bf16 v[18:21], v[204:207], v[236:239], v[18:21]
	v_mfma_f32_16x16x32_bf16 v[22:25], v[204:207], v[240:243], v[22:25]
	ds_read_b128 v[204:207], v244 offset:4608
	v_mfma_f32_16x16x32_bf16 v[58:61], v[208:211], v[228:231], v[58:61]
	v_mfma_f32_16x16x32_bf16 v[62:65], v[208:211], v[232:235], v[62:65]
	v_mfma_f32_16x16x32_bf16 v[26:29], v[208:211], v[236:239], v[26:29]
	v_mfma_f32_16x16x32_bf16 v[30:33], v[208:211], v[240:243], v[30:33]
	ds_read_b128 v[208:211], v244 offset:6912
	global_load_dwordx4 v[136:139], v[72:73], off offset:1536
	global_load_dwordx4 v[140:143], v[74:75], off offset:1536
	global_load_dwordx4 v[144:147], v[76:77], off offset:1536
	global_load_dwordx4 v[148:151], v[78:79], off offset:1536
	global_load_dwordx4 v[152:155], v[80:81], off offset:1536
	global_load_dwordx4 v[156:159], v[82:83], off offset:1536
	global_load_dwordx4 v[160:163], v[84:85], off offset:1536
	global_load_dwordx4 v[164:167], v[86:87], off offset:1536
	s_waitcnt lgkmcnt(6)
	v_mfma_f32_16x16x32_bf16 v[34:37], v[196:199], v[212:215], v[34:37]
	ds_read_b128 v[228:231], v245 offset:36928
	s_waitcnt lgkmcnt(6)
	v_mfma_f32_16x16x32_bf16 v[38:41], v[196:199], v[216:219], v[38:41]
	ds_read_b128 v[232:235], v245 offset:39232
	s_waitcnt lgkmcnt(6)
	v_mfma_f32_16x16x32_bf16 v[2:5], v[196:199], v[220:223], v[2:5]
	ds_read_b128 v[236:239], v245 offset:41536
	s_waitcnt lgkmcnt(6)
	v_mfma_f32_16x16x32_bf16 v[6:9], v[196:199], v[224:227], v[6:9]
	ds_read_b128 v[240:243], v245 offset:43840
	ds_read_b128 v[196:199], v244 offset:64
	s_waitcnt lgkmcnt(7)
	v_mfma_f32_16x16x32_bf16 v[42:45], v[200:203], v[212:215], v[42:45]
	v_mfma_f32_16x16x32_bf16 v[46:49], v[200:203], v[216:219], v[46:49]
	v_mfma_f32_16x16x32_bf16 v[10:13], v[200:203], v[220:223], v[10:13]
	v_mfma_f32_16x16x32_bf16 v[14:17], v[200:203], v[224:227], v[14:17]
	ds_read_b128 v[200:203], v244 offset:2368
	s_waitcnt lgkmcnt(7)
	v_mfma_f32_16x16x32_bf16 v[50:53], v[204:207], v[212:215], v[50:53]
	v_mfma_f32_16x16x32_bf16 v[54:57], v[204:207], v[216:219], v[54:57]
	v_mfma_f32_16x16x32_bf16 v[18:21], v[204:207], v[220:223], v[18:21]
	v_mfma_f32_16x16x32_bf16 v[22:25], v[204:207], v[224:227], v[22:25]
	ds_read_b128 v[204:207], v244 offset:4672
	s_waitcnt vmcnt(15)
	ds_write_b128 v95, v[98:101] offset:18432
	s_waitcnt vmcnt(14)
	ds_write_b128 v95, v[102:105] offset:23040
	s_waitcnt lgkmcnt(9)
	v_mfma_f32_16x16x32_bf16 v[58:61], v[208:211], v[212:215], v[58:61]
	v_mfma_f32_16x16x32_bf16 v[62:65], v[208:211], v[216:219], v[62:65]
	v_mfma_f32_16x16x32_bf16 v[26:29], v[208:211], v[220:223], v[26:29]
	v_mfma_f32_16x16x32_bf16 v[30:33], v[208:211], v[224:227], v[30:33]
	ds_read_b128 v[208:211], v244 offset:6976
	s_waitcnt vmcnt(13)
	ds_write_b128 v95, v[106:109] offset:27648
	s_waitcnt vmcnt(12)
	ds_write_b128 v95, v[110:113] offset:32256
	s_waitcnt lgkmcnt(7)
	v_mfma_f32_16x16x32_bf16 v[34:37], v[196:199], v[228:231], v[34:37]
	v_mfma_f32_16x16x32_bf16 v[38:41], v[196:199], v[232:235], v[38:41]
	v_mfma_f32_16x16x32_bf16 v[2:5], v[196:199], v[236:239], v[2:5]
	v_mfma_f32_16x16x32_bf16 v[6:9], v[196:199], v[240:243], v[6:9]
	s_waitcnt vmcnt(11)
	ds_write_b128 v95, v[114:117] offset:55296
	s_waitcnt vmcnt(10)
	ds_write_b128 v95, v[118:121] offset:59904
	s_waitcnt lgkmcnt(8)
	v_mfma_f32_16x16x32_bf16 v[42:45], v[200:203], v[228:231], v[42:45]
	v_mfma_f32_16x16x32_bf16 v[46:49], v[200:203], v[232:235], v[46:49]
	v_mfma_f32_16x16x32_bf16 v[10:13], v[200:203], v[236:239], v[10:13]
	v_mfma_f32_16x16x32_bf16 v[14:17], v[200:203], v[240:243], v[14:17]
	s_waitcnt vmcnt(9)
	ds_write_b128 v95, v[122:125] offset:64512
	s_waitcnt vmcnt(8)
	ds_write_b128 v96, v[126:129] offset:32256
	s_waitcnt lgkmcnt(0)
	s_barrier
	ds_read_b128 v[212:215], v245 offset:55296
	ds_read_b128 v[196:199], v244 offset:18432
	ds_read_b128 v[216:219], v245 offset:57600
	ds_read_b128 v[220:223], v245 offset:59904
	ds_read_b128 v[224:227], v245 offset:62208
	ds_read_b128 v[200:203], v244 offset:20736
	v_mfma_f32_16x16x32_bf16 v[50:53], v[204:207], v[228:231], v[50:53]
	v_mfma_f32_16x16x32_bf16 v[54:57], v[204:207], v[232:235], v[54:57]
	v_mfma_f32_16x16x32_bf16 v[18:21], v[204:207], v[236:239], v[18:21]
	v_mfma_f32_16x16x32_bf16 v[22:25], v[204:207], v[240:243], v[22:25]
	ds_read_b128 v[204:207], v244 offset:23040
	v_mfma_f32_16x16x32_bf16 v[58:61], v[208:211], v[228:231], v[58:61]
	v_mfma_f32_16x16x32_bf16 v[62:65], v[208:211], v[232:235], v[62:65]
	v_mfma_f32_16x16x32_bf16 v[26:29], v[208:211], v[236:239], v[26:29]
	v_mfma_f32_16x16x32_bf16 v[30:33], v[208:211], v[240:243], v[30:33]
	ds_read_b128 v[208:211], v244 offset:25344
	global_load_dwordx4 v[98:101], v[72:73], off offset:1664
	global_load_dwordx4 v[102:105], v[74:75], off offset:1664
	global_load_dwordx4 v[106:109], v[76:77], off offset:1664
	global_load_dwordx4 v[110:113], v[78:79], off offset:1664
	global_load_dwordx4 v[114:117], v[80:81], off offset:1664
	global_load_dwordx4 v[118:121], v[82:83], off offset:1664
	global_load_dwordx4 v[122:125], v[84:85], off offset:1664
	global_load_dwordx4 v[126:129], v[86:87], off offset:1664
	s_waitcnt lgkmcnt(6)
	v_mfma_f32_16x16x32_bf16 v[34:37], v[196:199], v[212:215], v[34:37]
	ds_read_b128 v[228:231], v245 offset:55360
	s_waitcnt lgkmcnt(6)
	v_mfma_f32_16x16x32_bf16 v[38:41], v[196:199], v[216:219], v[38:41]
	ds_read_b128 v[232:235], v245 offset:57664
	s_waitcnt lgkmcnt(6)
	v_mfma_f32_16x16x32_bf16 v[2:5], v[196:199], v[220:223], v[2:5]
	ds_read_b128 v[236:239], v245 offset:59968
	s_waitcnt lgkmcnt(6)
	v_mfma_f32_16x16x32_bf16 v[6:9], v[196:199], v[224:227], v[6:9]
	ds_read_b128 v[240:243], v245 offset:62272
	ds_read_b128 v[196:199], v244 offset:18496
	s_waitcnt lgkmcnt(7)
	v_mfma_f32_16x16x32_bf16 v[42:45], v[200:203], v[212:215], v[42:45]
	v_mfma_f32_16x16x32_bf16 v[46:49], v[200:203], v[216:219], v[46:49]
	v_mfma_f32_16x16x32_bf16 v[10:13], v[200:203], v[220:223], v[10:13]
	v_mfma_f32_16x16x32_bf16 v[14:17], v[200:203], v[224:227], v[14:17]
	ds_read_b128 v[200:203], v244 offset:20800
	s_waitcnt lgkmcnt(7)
	v_mfma_f32_16x16x32_bf16 v[50:53], v[204:207], v[212:215], v[50:53]
	v_mfma_f32_16x16x32_bf16 v[54:57], v[204:207], v[216:219], v[54:57]
	v_mfma_f32_16x16x32_bf16 v[18:21], v[204:207], v[220:223], v[18:21]
	v_mfma_f32_16x16x32_bf16 v[22:25], v[204:207], v[224:227], v[22:25]
	ds_read_b128 v[204:207], v244 offset:23104
	s_waitcnt vmcnt(15)
	ds_write_b128 v95, v[136:139]
	s_waitcnt vmcnt(14)
	ds_write_b128 v95, v[140:143] offset:4608
	s_waitcnt lgkmcnt(9)
	v_mfma_f32_16x16x32_bf16 v[58:61], v[208:211], v[212:215], v[58:61]
	v_mfma_f32_16x16x32_bf16 v[62:65], v[208:211], v[216:219], v[62:65]
	v_mfma_f32_16x16x32_bf16 v[26:29], v[208:211], v[220:223], v[26:29]
	v_mfma_f32_16x16x32_bf16 v[30:33], v[208:211], v[224:227], v[30:33]
	ds_read_b128 v[208:211], v244 offset:25408
	s_waitcnt vmcnt(13)
	ds_write_b128 v95, v[144:147] offset:9216
	s_waitcnt vmcnt(12)
	ds_write_b128 v95, v[148:151] offset:13824
	s_waitcnt lgkmcnt(7)
	v_mfma_f32_16x16x32_bf16 v[34:37], v[196:199], v[228:231], v[34:37]
	v_mfma_f32_16x16x32_bf16 v[38:41], v[196:199], v[232:235], v[38:41]
	v_mfma_f32_16x16x32_bf16 v[2:5], v[196:199], v[236:239], v[2:5]
	v_mfma_f32_16x16x32_bf16 v[6:9], v[196:199], v[240:243], v[6:9]
	s_waitcnt vmcnt(11)
	ds_write_b128 v95, v[152:155] offset:36864
	s_waitcnt vmcnt(10)
	ds_write_b128 v95, v[156:159] offset:41472
	s_waitcnt lgkmcnt(8)
	v_mfma_f32_16x16x32_bf16 v[42:45], v[200:203], v[228:231], v[42:45]
	v_mfma_f32_16x16x32_bf16 v[46:49], v[200:203], v[232:235], v[46:49]
	v_mfma_f32_16x16x32_bf16 v[10:13], v[200:203], v[236:239], v[10:13]
	v_mfma_f32_16x16x32_bf16 v[14:17], v[200:203], v[240:243], v[14:17]
	s_waitcnt vmcnt(9)
	ds_write_b128 v95, v[160:163] offset:46080
	s_waitcnt vmcnt(8)
	ds_write_b128 v95, v[164:167] offset:50688
	s_waitcnt lgkmcnt(0)
	s_barrier
	ds_read_b128 v[212:215], v245 offset:36864
	ds_read_b128 v[196:199], v244
	ds_read_b128 v[216:219], v245 offset:39168
	ds_read_b128 v[220:223], v245 offset:41472
	ds_read_b128 v[224:227], v245 offset:43776
	ds_read_b128 v[200:203], v244 offset:2304
	v_mfma_f32_16x16x32_bf16 v[50:53], v[204:207], v[228:231], v[50:53]
	v_mfma_f32_16x16x32_bf16 v[54:57], v[204:207], v[232:235], v[54:57]
	v_mfma_f32_16x16x32_bf16 v[18:21], v[204:207], v[236:239], v[18:21]
	v_mfma_f32_16x16x32_bf16 v[22:25], v[204:207], v[240:243], v[22:25]
	ds_read_b128 v[204:207], v244 offset:4608
	v_mfma_f32_16x16x32_bf16 v[58:61], v[208:211], v[228:231], v[58:61]
	v_mfma_f32_16x16x32_bf16 v[62:65], v[208:211], v[232:235], v[62:65]
	v_mfma_f32_16x16x32_bf16 v[26:29], v[208:211], v[236:239], v[26:29]
	v_mfma_f32_16x16x32_bf16 v[30:33], v[208:211], v[240:243], v[30:33]
	ds_read_b128 v[208:211], v244 offset:6912
	global_load_dwordx4 v[136:139], v[72:73], off offset:1792
	global_load_dwordx4 v[140:143], v[74:75], off offset:1792
	global_load_dwordx4 v[144:147], v[76:77], off offset:1792
	global_load_dwordx4 v[148:151], v[78:79], off offset:1792
	global_load_dwordx4 v[152:155], v[80:81], off offset:1792
	global_load_dwordx4 v[156:159], v[82:83], off offset:1792
	global_load_dwordx4 v[160:163], v[84:85], off offset:1792
	global_load_dwordx4 v[164:167], v[86:87], off offset:1792
	s_waitcnt lgkmcnt(6)
	v_mfma_f32_16x16x32_bf16 v[34:37], v[196:199], v[212:215], v[34:37]
	ds_read_b128 v[228:231], v245 offset:36928
	s_waitcnt lgkmcnt(6)
	v_mfma_f32_16x16x32_bf16 v[38:41], v[196:199], v[216:219], v[38:41]
	ds_read_b128 v[232:235], v245 offset:39232
	s_waitcnt lgkmcnt(6)
	v_mfma_f32_16x16x32_bf16 v[2:5], v[196:199], v[220:223], v[2:5]
	ds_read_b128 v[236:239], v245 offset:41536
	s_waitcnt lgkmcnt(6)
	v_mfma_f32_16x16x32_bf16 v[6:9], v[196:199], v[224:227], v[6:9]
	ds_read_b128 v[240:243], v245 offset:43840
	ds_read_b128 v[196:199], v244 offset:64
	s_waitcnt lgkmcnt(7)
	v_mfma_f32_16x16x32_bf16 v[42:45], v[200:203], v[212:215], v[42:45]
	v_mfma_f32_16x16x32_bf16 v[46:49], v[200:203], v[216:219], v[46:49]
	v_mfma_f32_16x16x32_bf16 v[10:13], v[200:203], v[220:223], v[10:13]
	v_mfma_f32_16x16x32_bf16 v[14:17], v[200:203], v[224:227], v[14:17]
	ds_read_b128 v[200:203], v244 offset:2368
	s_waitcnt lgkmcnt(7)
	v_mfma_f32_16x16x32_bf16 v[50:53], v[204:207], v[212:215], v[50:53]
	v_mfma_f32_16x16x32_bf16 v[54:57], v[204:207], v[216:219], v[54:57]
	v_mfma_f32_16x16x32_bf16 v[18:21], v[204:207], v[220:223], v[18:21]
	v_mfma_f32_16x16x32_bf16 v[22:25], v[204:207], v[224:227], v[22:25]
	ds_read_b128 v[204:207], v244 offset:4672
	s_waitcnt vmcnt(15)
	ds_write_b128 v95, v[98:101] offset:18432
	s_waitcnt vmcnt(14)
	ds_write_b128 v95, v[102:105] offset:23040
	s_waitcnt lgkmcnt(9)
	v_mfma_f32_16x16x32_bf16 v[58:61], v[208:211], v[212:215], v[58:61]
	v_mfma_f32_16x16x32_bf16 v[62:65], v[208:211], v[216:219], v[62:65]
	v_mfma_f32_16x16x32_bf16 v[26:29], v[208:211], v[220:223], v[26:29]
	v_mfma_f32_16x16x32_bf16 v[30:33], v[208:211], v[224:227], v[30:33]
	ds_read_b128 v[208:211], v244 offset:6976
	s_waitcnt vmcnt(13)
	ds_write_b128 v95, v[106:109] offset:27648
	s_waitcnt vmcnt(12)
	ds_write_b128 v95, v[110:113] offset:32256
	s_waitcnt lgkmcnt(7)
	v_mfma_f32_16x16x32_bf16 v[34:37], v[196:199], v[228:231], v[34:37]
	v_mfma_f32_16x16x32_bf16 v[38:41], v[196:199], v[232:235], v[38:41]
	v_mfma_f32_16x16x32_bf16 v[2:5], v[196:199], v[236:239], v[2:5]
	v_mfma_f32_16x16x32_bf16 v[6:9], v[196:199], v[240:243], v[6:9]
	s_waitcnt vmcnt(11)
	ds_write_b128 v95, v[114:117] offset:55296
	s_waitcnt vmcnt(10)
	ds_write_b128 v95, v[118:121] offset:59904
	s_waitcnt lgkmcnt(8)
	v_mfma_f32_16x16x32_bf16 v[42:45], v[200:203], v[228:231], v[42:45]
	v_mfma_f32_16x16x32_bf16 v[46:49], v[200:203], v[232:235], v[46:49]
	v_mfma_f32_16x16x32_bf16 v[10:13], v[200:203], v[236:239], v[10:13]
	v_mfma_f32_16x16x32_bf16 v[14:17], v[200:203], v[240:243], v[14:17]
	s_waitcnt vmcnt(9)
	ds_write_b128 v95, v[122:125] offset:64512
	s_waitcnt vmcnt(8)
	ds_write_b128 v96, v[126:129] offset:32256
	s_waitcnt lgkmcnt(0)
	s_barrier
	ds_read_b128 v[212:215], v245 offset:55296
	ds_read_b128 v[196:199], v244 offset:18432
	ds_read_b128 v[216:219], v245 offset:57600
	ds_read_b128 v[220:223], v245 offset:59904
	ds_read_b128 v[224:227], v245 offset:62208
	ds_read_b128 v[200:203], v244 offset:20736
	v_mfma_f32_16x16x32_bf16 v[50:53], v[204:207], v[228:231], v[50:53]
	v_mfma_f32_16x16x32_bf16 v[54:57], v[204:207], v[232:235], v[54:57]
	v_mfma_f32_16x16x32_bf16 v[18:21], v[204:207], v[236:239], v[18:21]
	v_mfma_f32_16x16x32_bf16 v[22:25], v[204:207], v[240:243], v[22:25]
	ds_read_b128 v[204:207], v244 offset:23040
	v_mfma_f32_16x16x32_bf16 v[58:61], v[208:211], v[228:231], v[58:61]
	v_mfma_f32_16x16x32_bf16 v[62:65], v[208:211], v[232:235], v[62:65]
	v_mfma_f32_16x16x32_bf16 v[26:29], v[208:211], v[236:239], v[26:29]
	v_mfma_f32_16x16x32_bf16 v[30:33], v[208:211], v[240:243], v[30:33]
	ds_read_b128 v[208:211], v244 offset:25344
	global_load_dwordx4 v[98:101], v[72:73], off offset:1920
	s_nop 0
	global_load_dwordx4 v[72:75], v[74:75], off offset:1920
	s_nop 0
	global_load_dwordx4 v[102:105], v[76:77], off offset:1920
	s_nop 0
	global_load_dwordx4 v[76:79], v[78:79], off offset:1920
	s_nop 0
	global_load_dwordx4 v[106:109], v[80:81], off offset:1920
	s_nop 0
	global_load_dwordx4 v[80:83], v[82:83], off offset:1920
	s_nop 0
	global_load_dwordx4 v[110:113], v[84:85], off offset:1920
	s_nop 0
	global_load_dwordx4 v[84:87], v[86:87], off offset:1920
	s_waitcnt lgkmcnt(6)
	v_mfma_f32_16x16x32_bf16 v[34:37], v[196:199], v[212:215], v[34:37]
	ds_read_b128 v[228:231], v245 offset:55360
	s_waitcnt lgkmcnt(6)
	v_mfma_f32_16x16x32_bf16 v[38:41], v[196:199], v[216:219], v[38:41]
	ds_read_b128 v[232:235], v245 offset:57664
	s_waitcnt lgkmcnt(6)
	v_mfma_f32_16x16x32_bf16 v[2:5], v[196:199], v[220:223], v[2:5]
	ds_read_b128 v[236:239], v245 offset:59968
	s_waitcnt lgkmcnt(6)
	v_mfma_f32_16x16x32_bf16 v[6:9], v[196:199], v[224:227], v[6:9]
	ds_read_b128 v[240:243], v245 offset:62272
	ds_read_b128 v[196:199], v244 offset:18496
	s_waitcnt lgkmcnt(7)
	v_mfma_f32_16x16x32_bf16 v[42:45], v[200:203], v[212:215], v[42:45]
	v_mfma_f32_16x16x32_bf16 v[46:49], v[200:203], v[216:219], v[46:49]
	v_mfma_f32_16x16x32_bf16 v[10:13], v[200:203], v[220:223], v[10:13]
	v_mfma_f32_16x16x32_bf16 v[14:17], v[200:203], v[224:227], v[14:17]
	ds_read_b128 v[200:203], v244 offset:20800
	s_waitcnt lgkmcnt(7)
	v_mfma_f32_16x16x32_bf16 v[50:53], v[204:207], v[212:215], v[50:53]
	v_mfma_f32_16x16x32_bf16 v[54:57], v[204:207], v[216:219], v[54:57]
	v_mfma_f32_16x16x32_bf16 v[18:21], v[204:207], v[220:223], v[18:21]
	v_mfma_f32_16x16x32_bf16 v[22:25], v[204:207], v[224:227], v[22:25]
	ds_read_b128 v[204:207], v244 offset:23104
	s_waitcnt vmcnt(15)
	ds_write_b128 v95, v[136:139]
	s_waitcnt vmcnt(14)
	ds_write_b128 v95, v[140:143] offset:4608
	s_waitcnt lgkmcnt(9)
	v_mfma_f32_16x16x32_bf16 v[58:61], v[208:211], v[212:215], v[58:61]
	v_mfma_f32_16x16x32_bf16 v[62:65], v[208:211], v[216:219], v[62:65]
	v_mfma_f32_16x16x32_bf16 v[26:29], v[208:211], v[220:223], v[26:29]
	v_mfma_f32_16x16x32_bf16 v[30:33], v[208:211], v[224:227], v[30:33]
	ds_read_b128 v[208:211], v244 offset:25408
	s_waitcnt vmcnt(13)
	ds_write_b128 v95, v[144:147] offset:9216
	s_waitcnt vmcnt(12)
	ds_write_b128 v95, v[148:151] offset:13824
	s_waitcnt lgkmcnt(7)
	v_mfma_f32_16x16x32_bf16 v[34:37], v[196:199], v[228:231], v[34:37]
	v_mfma_f32_16x16x32_bf16 v[38:41], v[196:199], v[232:235], v[38:41]
	v_mfma_f32_16x16x32_bf16 v[2:5], v[196:199], v[236:239], v[2:5]
	v_mfma_f32_16x16x32_bf16 v[6:9], v[196:199], v[240:243], v[6:9]
	s_waitcnt vmcnt(11)
	ds_write_b128 v95, v[152:155] offset:36864
	s_waitcnt vmcnt(10)
	ds_write_b128 v95, v[156:159] offset:41472
	s_waitcnt lgkmcnt(8)
	v_mfma_f32_16x16x32_bf16 v[42:45], v[200:203], v[228:231], v[42:45]
	v_mfma_f32_16x16x32_bf16 v[46:49], v[200:203], v[232:235], v[46:49]
	v_mfma_f32_16x16x32_bf16 v[10:13], v[200:203], v[236:239], v[10:13]
	v_mfma_f32_16x16x32_bf16 v[14:17], v[200:203], v[240:243], v[14:17]
	s_waitcnt vmcnt(9)
	ds_write_b128 v95, v[160:163] offset:46080
	s_waitcnt vmcnt(8)
	ds_write_b128 v95, v[164:167] offset:50688
	s_waitcnt lgkmcnt(0)
	s_barrier
	ds_read_b128 v[212:215], v245 offset:36864
	ds_read_b128 v[196:199], v244
	ds_read_b128 v[216:219], v245 offset:39168
	ds_read_b128 v[220:223], v245 offset:41472
	ds_read_b128 v[224:227], v245 offset:43776
	ds_read_b128 v[200:203], v244 offset:2304
	v_mfma_f32_16x16x32_bf16 v[50:53], v[204:207], v[228:231], v[50:53]
	v_mfma_f32_16x16x32_bf16 v[54:57], v[204:207], v[232:235], v[54:57]
	v_mfma_f32_16x16x32_bf16 v[18:21], v[204:207], v[236:239], v[18:21]
	v_mfma_f32_16x16x32_bf16 v[22:25], v[204:207], v[240:243], v[22:25]
	ds_read_b128 v[204:207], v244 offset:4608
	v_mfma_f32_16x16x32_bf16 v[58:61], v[208:211], v[228:231], v[58:61]
	v_mfma_f32_16x16x32_bf16 v[62:65], v[208:211], v[232:235], v[62:65]
	v_mfma_f32_16x16x32_bf16 v[26:29], v[208:211], v[236:239], v[26:29]
	v_mfma_f32_16x16x32_bf16 v[30:33], v[208:211], v[240:243], v[30:33]
	ds_read_b128 v[208:211], v244 offset:6912
	s_waitcnt lgkmcnt(6)
	v_mfma_f32_16x16x32_bf16 v[34:37], v[196:199], v[212:215], v[34:37]
	ds_read_b128 v[228:231], v245 offset:36928
	s_waitcnt lgkmcnt(6)
	v_mfma_f32_16x16x32_bf16 v[38:41], v[196:199], v[216:219], v[38:41]
	ds_read_b128 v[232:235], v245 offset:39232
	s_waitcnt lgkmcnt(6)
	v_mfma_f32_16x16x32_bf16 v[2:5], v[196:199], v[220:223], v[2:5]
	ds_read_b128 v[236:239], v245 offset:41536
	s_waitcnt lgkmcnt(6)
	v_mfma_f32_16x16x32_bf16 v[6:9], v[196:199], v[224:227], v[6:9]
	ds_read_b128 v[240:243], v245 offset:43840
	ds_read_b128 v[196:199], v244 offset:64
	s_waitcnt lgkmcnt(7)
	v_mfma_f32_16x16x32_bf16 v[42:45], v[200:203], v[212:215], v[42:45]
	v_mfma_f32_16x16x32_bf16 v[46:49], v[200:203], v[216:219], v[46:49]
	v_mfma_f32_16x16x32_bf16 v[10:13], v[200:203], v[220:223], v[10:13]
	v_mfma_f32_16x16x32_bf16 v[14:17], v[200:203], v[224:227], v[14:17]
	ds_read_b128 v[200:203], v244 offset:2368
	s_waitcnt lgkmcnt(7)
	v_mfma_f32_16x16x32_bf16 v[50:53], v[204:207], v[212:215], v[50:53]
	v_mfma_f32_16x16x32_bf16 v[54:57], v[204:207], v[216:219], v[54:57]
	v_mfma_f32_16x16x32_bf16 v[18:21], v[204:207], v[220:223], v[18:21]
	v_mfma_f32_16x16x32_bf16 v[22:25], v[204:207], v[224:227], v[22:25]
	ds_read_b128 v[204:207], v244 offset:4672
	s_waitcnt vmcnt(7)
	ds_write_b128 v95, v[98:101] offset:18432
	s_waitcnt vmcnt(6)
	ds_write_b128 v95, v[72:75] offset:23040
	s_waitcnt lgkmcnt(9)
	v_mfma_f32_16x16x32_bf16 v[58:61], v[208:211], v[212:215], v[58:61]
	v_mfma_f32_16x16x32_bf16 v[62:65], v[208:211], v[216:219], v[62:65]
	v_mfma_f32_16x16x32_bf16 v[26:29], v[208:211], v[220:223], v[26:29]
	v_mfma_f32_16x16x32_bf16 v[30:33], v[208:211], v[224:227], v[30:33]
	ds_read_b128 v[208:211], v244 offset:6976
	s_waitcnt vmcnt(5)
	ds_write_b128 v95, v[102:105] offset:27648
	s_waitcnt vmcnt(4)
	ds_write_b128 v95, v[76:79] offset:32256
	s_waitcnt lgkmcnt(7)
	v_mfma_f32_16x16x32_bf16 v[34:37], v[196:199], v[228:231], v[34:37]
	v_mfma_f32_16x16x32_bf16 v[38:41], v[196:199], v[232:235], v[38:41]
	v_mfma_f32_16x16x32_bf16 v[2:5], v[196:199], v[236:239], v[2:5]
	v_mfma_f32_16x16x32_bf16 v[6:9], v[196:199], v[240:243], v[6:9]
	s_waitcnt vmcnt(3)
	ds_write_b128 v95, v[106:109] offset:55296
	s_waitcnt vmcnt(2)
	ds_write_b128 v95, v[80:83] offset:59904
	s_waitcnt lgkmcnt(8)
	v_mfma_f32_16x16x32_bf16 v[42:45], v[200:203], v[228:231], v[42:45]
	v_mfma_f32_16x16x32_bf16 v[46:49], v[200:203], v[232:235], v[46:49]
	v_mfma_f32_16x16x32_bf16 v[10:13], v[200:203], v[236:239], v[10:13]
	v_mfma_f32_16x16x32_bf16 v[14:17], v[200:203], v[240:243], v[14:17]
	s_waitcnt vmcnt(1)
	ds_write_b128 v95, v[110:113] offset:64512
	s_waitcnt vmcnt(0)
	ds_write_b128 v96, v[84:87] offset:32256
	s_waitcnt lgkmcnt(0)
	s_barrier
	ds_read_b128 v[212:215], v245 offset:55296
	ds_read_b128 v[196:199], v244 offset:18432
	ds_read_b128 v[216:219], v245 offset:57600
	ds_read_b128 v[220:223], v245 offset:59904
	ds_read_b128 v[224:227], v245 offset:62208
	ds_read_b128 v[200:203], v244 offset:20736
	v_mfma_f32_16x16x32_bf16 v[50:53], v[204:207], v[228:231], v[50:53]
	v_mfma_f32_16x16x32_bf16 v[54:57], v[204:207], v[232:235], v[54:57]
	v_mfma_f32_16x16x32_bf16 v[18:21], v[204:207], v[236:239], v[18:21]
	v_mfma_f32_16x16x32_bf16 v[22:25], v[204:207], v[240:243], v[22:25]
	ds_read_b128 v[204:207], v244 offset:23040
	v_mfma_f32_16x16x32_bf16 v[58:61], v[208:211], v[228:231], v[58:61]
	v_mfma_f32_16x16x32_bf16 v[62:65], v[208:211], v[232:235], v[62:65]
	v_mfma_f32_16x16x32_bf16 v[26:29], v[208:211], v[236:239], v[26:29]
	v_mfma_f32_16x16x32_bf16 v[30:33], v[208:211], v[240:243], v[30:33]
	ds_read_b128 v[208:211], v244 offset:25344
	s_waitcnt lgkmcnt(6)
	v_mfma_f32_16x16x32_bf16 v[34:37], v[196:199], v[212:215], v[34:37]
	ds_read_b128 v[228:231], v245 offset:55360
	s_waitcnt lgkmcnt(6)
	v_mfma_f32_16x16x32_bf16 v[38:41], v[196:199], v[216:219], v[38:41]
	ds_read_b128 v[232:235], v245 offset:57664
	s_waitcnt lgkmcnt(6)
	v_mfma_f32_16x16x32_bf16 v[2:5], v[196:199], v[220:223], v[2:5]
	ds_read_b128 v[236:239], v245 offset:59968
	s_waitcnt lgkmcnt(6)
	v_mfma_f32_16x16x32_bf16 v[6:9], v[196:199], v[224:227], v[6:9]
	ds_read_b128 v[240:243], v245 offset:62272
	ds_read_b128 v[196:199], v244 offset:18496
	s_waitcnt lgkmcnt(7)
	v_mfma_f32_16x16x32_bf16 v[42:45], v[200:203], v[212:215], v[42:45]
	v_mfma_f32_16x16x32_bf16 v[46:49], v[200:203], v[216:219], v[46:49]
	v_mfma_f32_16x16x32_bf16 v[10:13], v[200:203], v[220:223], v[10:13]
	v_mfma_f32_16x16x32_bf16 v[14:17], v[200:203], v[224:227], v[14:17]
	ds_read_b128 v[200:203], v244 offset:20800
	s_waitcnt lgkmcnt(7)
	v_mfma_f32_16x16x32_bf16 v[50:53], v[204:207], v[212:215], v[50:53]
	v_mfma_f32_16x16x32_bf16 v[54:57], v[204:207], v[216:219], v[54:57]
	v_mfma_f32_16x16x32_bf16 v[18:21], v[204:207], v[220:223], v[18:21]
	v_mfma_f32_16x16x32_bf16 v[22:25], v[204:207], v[224:227], v[22:25]
	ds_read_b128 v[204:207], v244 offset:23104
	s_waitcnt lgkmcnt(7)
	v_mfma_f32_16x16x32_bf16 v[58:61], v[208:211], v[212:215], v[58:61]
	v_mfma_f32_16x16x32_bf16 v[62:65], v[208:211], v[216:219], v[62:65]
	v_mfma_f32_16x16x32_bf16 v[26:29], v[208:211], v[220:223], v[26:29]
	v_mfma_f32_16x16x32_bf16 v[30:33], v[208:211], v[224:227], v[30:33]
	ds_read_b128 v[208:211], v244 offset:25408
	s_waitcnt lgkmcnt(3)
	v_mfma_f32_16x16x32_bf16 v[34:37], v[196:199], v[228:231], v[34:37]
	v_mfma_f32_16x16x32_bf16 v[38:41], v[196:199], v[232:235], v[38:41]
	v_mfma_f32_16x16x32_bf16 v[2:5], v[196:199], v[236:239], v[2:5]
	v_mfma_f32_16x16x32_bf16 v[6:9], v[196:199], v[240:243], v[6:9]
	s_waitcnt lgkmcnt(2)
	v_mfma_f32_16x16x32_bf16 v[42:45], v[200:203], v[228:231], v[42:45]
	v_mfma_f32_16x16x32_bf16 v[46:49], v[200:203], v[232:235], v[46:49]
	v_mfma_f32_16x16x32_bf16 v[10:13], v[200:203], v[236:239], v[10:13]
	v_mfma_f32_16x16x32_bf16 v[14:17], v[200:203], v[240:243], v[14:17]
	v_or_b32_e32 v66, s3, v88
	s_addk_i32 s3, 0xf000
	s_lshr_b32 s3, s3, 12
	s_cmp_lt_u32 s0, 32
	s_cselect_b64 vcc, -1, 0
	s_and_b64 s[4:5], vcc, exec
	s_mul_i32 s0, s3, 0xc00
	s_cselect_b32 s5, s17, s19
	s_cselect_b32 s4, s16, s18
	s_addk_i32 s0, 0xc00
	s_and_b64 s[12:13], vcc, exec
	s_cselect_b32 s0, 0, s0
	v_add_u32_e32 v72, 0xfffff000, v66
	v_cndmask_b32_e32 v72, v72, v66, vcc
	v_mov_b32_e32 v73, v67
	v_lshlrev_b64 v[72:73], 12, v[72:73]
	v_lshl_add_u64 v[78:79], s[4:5], 0, v[72:73]
	v_add_lshl_u32 v72, s2, v97, 2
	s_lshl_b64 s[2:3], s[0:1], 2
	s_add_u32 s0, s82, s2
	s_addc_u32 s3, s83, s3
	v_mov_b32_e32 v73, v67
	s_add_u32 s2, s0, 0xe958000
	v_lshl_add_u64 v[148:149], v[78:79], 0, v[72:73]
	s_addc_u32 s3, s3, 0
	v_or_b32_e32 v156, 0xe0, v72
	v_or_b32_e32 v157, 32, v72
	v_or_b32_e32 v158, 64, v72
	v_or_b32_e32 v159, 0x60, v72
	v_or_b32_e32 v160, 0x80, v72
	v_or_b32_e32 v161, 0xa0, v72
	v_or_b32_e32 v162, 0xc0, v72
	s_waitcnt lgkmcnt(0)
	s_barrier
	v_mfma_f32_16x16x32_bf16 v[50:53], v[204:207], v[228:231], v[50:53]
	v_mfma_f32_16x16x32_bf16 v[54:57], v[204:207], v[232:235], v[54:57]
	v_mfma_f32_16x16x32_bf16 v[18:21], v[204:207], v[236:239], v[18:21]
	v_mfma_f32_16x16x32_bf16 v[22:25], v[204:207], v[240:243], v[22:25]
	v_mfma_f32_16x16x32_bf16 v[58:61], v[208:211], v[228:231], v[58:61]
	v_mfma_f32_16x16x32_bf16 v[62:65], v[208:211], v[232:235], v[62:65]
	v_mfma_f32_16x16x32_bf16 v[26:29], v[208:211], v[236:239], v[26:29]
	v_mfma_f32_16x16x32_bf16 v[30:33], v[208:211], v[240:243], v[30:33]
	s_nop 7
	v_permlane16_swap_b32_e32 v34, v38
	v_permlane16_swap_b32_e32 v35, v39
	v_permlane16_swap_b32_e32 v36, v40
	v_permlane16_swap_b32_e32 v37, v41
	v_permlane16_swap_b32_e32 v42, v46
	v_permlane16_swap_b32_e32 v43, v47
	v_permlane16_swap_b32_e32 v44, v48
	v_permlane16_swap_b32_e32 v45, v49
	v_permlane16_swap_b32_e32 v2, v6
	v_permlane16_swap_b32_e32 v3, v7
	v_permlane16_swap_b32_e32 v4, v8
	v_permlane16_swap_b32_e32 v5, v9
	v_permlane16_swap_b32_e32 v10, v14
	v_permlane16_swap_b32_e32 v11, v15
	v_permlane16_swap_b32_e32 v12, v16
	v_permlane16_swap_b32_e32 v13, v17
	v_permlane16_swap_b32_e32 v50, v54
	v_permlane16_swap_b32_e32 v51, v55
	v_permlane16_swap_b32_e32 v52, v56
	v_permlane16_swap_b32_e32 v53, v57
	v_permlane16_swap_b32_e32 v58, v62
	v_permlane16_swap_b32_e32 v59, v63
	v_permlane16_swap_b32_e32 v60, v64
	v_permlane16_swap_b32_e32 v61, v65
	v_permlane16_swap_b32_e32 v18, v22
	v_permlane16_swap_b32_e32 v19, v23
	v_permlane16_swap_b32_e32 v20, v24
	v_permlane16_swap_b32_e32 v21, v25
	v_permlane16_swap_b32_e32 v26, v30
	v_permlane16_swap_b32_e32 v27, v31
	v_permlane16_swap_b32_e32 v28, v32
	v_permlane16_swap_b32_e32 v29, v33
	v_permlane32_swap_b32_e32 v34, v38
	v_permlane32_swap_b32_e32 v35, v39
	v_permlane32_swap_b32_e32 v36, v40
	v_permlane32_swap_b32_e32 v37, v41
	v_permlane32_swap_b32_e32 v42, v46
	v_permlane32_swap_b32_e32 v43, v47
	v_permlane32_swap_b32_e32 v44, v48
	v_permlane32_swap_b32_e32 v45, v49
	v_permlane32_swap_b32_e32 v2, v6
	v_permlane32_swap_b32_e32 v3, v7
	v_permlane32_swap_b32_e32 v4, v8
	v_permlane32_swap_b32_e32 v5, v9
	v_permlane32_swap_b32_e32 v10, v14
	v_permlane32_swap_b32_e32 v11, v15
	v_permlane32_swap_b32_e32 v12, v16
	v_permlane32_swap_b32_e32 v13, v17
	v_permlane32_swap_b32_e32 v50, v54
	v_permlane32_swap_b32_e32 v51, v55
	v_permlane32_swap_b32_e32 v52, v56
	v_permlane32_swap_b32_e32 v53, v57
	v_permlane32_swap_b32_e32 v58, v62
	v_permlane32_swap_b32_e32 v59, v63
	v_permlane32_swap_b32_e32 v60, v64
	v_permlane32_swap_b32_e32 v61, v65
	v_permlane32_swap_b32_e32 v18, v22
	v_permlane32_swap_b32_e32 v19, v23
	v_permlane32_swap_b32_e32 v20, v24
	v_permlane32_swap_b32_e32 v21, v25
	v_permlane32_swap_b32_e32 v26, v30
	v_permlane32_swap_b32_e32 v27, v31
	v_permlane32_swap_b32_e32 v28, v32
	v_permlane32_swap_b32_e32 v29, v33
	global_load_dwordx4 v[102:105], v[148:149], off offset:224
	s_add_i32 s11, s11, 1
	s_mul_i32 s0, s11, s7
	s_add_i32 s10, s10, s7
	global_load_dwordx4 v[84:87], v156, s[2:3]
	global_load_dwordx4 v[78:81], v[148:149], off offset:192
	v_lshlrev_b64 v[82:83], 12, v[66:67]
	v_lshl_add_u64 v[82:83], s[80:81], 0, v[82:83]
	v_lshl_add_u64 v[82:83], v[82:83], 0, v[72:73]
	s_waitcnt vmcnt(1)
	v_pk_fma_f32 v[64:65], v[64:65], v[86:87], v[104:105]
	global_load_dwordx4 v[74:77], v162, s[2:3]
	global_load_dwordx4 v[98:101], v[148:149], off offset:160
	global_load_dwordx4 v[106:109], v161, s[2:3]
	global_load_dwordx4 v[110:113], v[148:149], off offset:128
	global_load_dwordx4 v[114:117], v160, s[2:3]
	global_load_dwordx4 v[118:121], v[148:149], off offset:96
	global_load_dwordx4 v[122:125], v159, s[2:3]
	global_load_dwordx4 v[126:129], v[148:149], off offset:64
	global_load_dwordx4 v[136:139], v158, s[2:3]
	global_load_dwordx4 v[140:143], v[148:149], off offset:32
	global_load_dwordx4 v[144:147], v157, s[2:3]
	v_or_b32_e32 v86, 32, v66
	global_load_dwordx4 v[148:151], v[148:149], off
	v_pk_fma_f32 v[62:63], v[62:63], v[84:85], v[102:103]
	global_load_dwordx4 v[152:155], v72, s[2:3]
	v_mov_b32_e32 v87, v67
	global_store_dwordx4 v[82:83], v[62:65], off offset:224
	s_waitcnt vmcnt(13)
	v_pk_fma_f32 v[58:59], v[58:59], v[74:75], v[78:79]
	v_pk_fma_f32 v[60:61], v[60:61], v[76:77], v[80:81]
	s_waitcnt vmcnt(11)
	v_pk_fma_f32 v[54:55], v[54:55], v[106:107], v[98:99]
	v_pk_fma_f32 v[56:57], v[56:57], v[108:109], v[100:101]
	s_waitcnt vmcnt(9)
	v_pk_fma_f32 v[50:51], v[50:51], v[114:115], v[110:111]
	v_pk_fma_f32 v[52:53], v[52:53], v[116:117], v[112:113]
	s_waitcnt vmcnt(7)
	v_pk_fma_f32 v[46:47], v[46:47], v[122:123], v[118:119]
	v_pk_fma_f32 v[48:49], v[48:49], v[124:125], v[120:121]
	s_waitcnt vmcnt(5)
	v_pk_fma_f32 v[42:43], v[42:43], v[136:137], v[126:127]
	v_pk_fma_f32 v[44:45], v[44:45], v[138:139], v[128:129]
	s_waitcnt vmcnt(3)
	v_pk_fma_f32 v[38:39], v[38:39], v[144:145], v[140:141]
	v_pk_fma_f32 v[40:41], v[40:41], v[146:147], v[142:143]
	global_store_dwordx4 v[82:83], v[38:41], off offset:32
	global_store_dwordx4 v[82:83], v[42:45], off offset:64
	s_waitcnt vmcnt(3)
	v_pk_fma_f32 v[34:35], v[34:35], v[152:153], v[148:149]
	v_pk_fma_f32 v[36:37], v[36:37], v[154:155], v[150:151]
	global_store_dwordx4 v[82:83], v[34:37], off
	global_store_dwordx4 v[82:83], v[46:49], off offset:96
	global_store_dwordx4 v[82:83], v[50:53], off offset:128
	v_add_u32_e32 v34, 0xfffff020, v66
	v_cndmask_b32_e32 v66, v34, v86, vcc
	v_lshlrev_b64 v[34:35], 12, v[66:67]
	v_lshl_add_u64 v[34:35], s[4:5], 0, v[34:35]
	global_store_dwordx4 v[82:83], v[54:57], off offset:160
	global_store_dwordx4 v[82:83], v[58:61], off offset:192
	v_lshl_add_u64 v[118:119], v[34:35], 0, v[72:73]
	global_load_dwordx4 v[34:37], v[118:119], off offset:224
	global_load_dwordx4 v[38:41], v156, s[2:3]
	global_load_dwordx4 v[42:45], v[118:119], off offset:192
	global_load_dwordx4 v[46:49], v162, s[2:3]
	global_load_dwordx4 v[50:53], v[118:119], off offset:160
	global_load_dwordx4 v[54:57], v161, s[2:3]
	global_load_dwordx4 v[58:61], v[118:119], off offset:128
	global_load_dwordx4 v[62:65], v160, s[2:3]
	global_load_dwordx4 v[74:77], v[118:119], off offset:96
	global_load_dwordx4 v[78:81], v159, s[2:3]
	global_load_dwordx4 v[82:85], v[118:119], off offset:64
	global_load_dwordx4 v[98:101], v158, s[2:3]
	global_load_dwordx4 v[102:105], v[118:119], off offset:32
	global_load_dwordx4 v[106:109], v157, s[2:3]
	global_load_dwordx4 v[110:113], v[118:119], off
	global_load_dwordx4 v[114:117], v72, s[2:3]
	v_lshlrev_b64 v[86:87], 12, v[86:87]
	v_lshl_add_u64 v[86:87], s[80:81], 0, v[86:87]
	s_add_i32 s2, s0, s6
	v_lshl_add_u64 v[72:73], v[86:87], 0, v[72:73]
	s_cmpk_lt_u32 s10, 0x60
	s_waitcnt vmcnt(14)
	v_pk_fma_f32 v[30:31], v[30:31], v[38:39], v[34:35]
	v_pk_fma_f32 v[32:33], v[32:33], v[40:41], v[36:37]
	s_waitcnt vmcnt(12)
	v_pk_fma_f32 v[26:27], v[26:27], v[46:47], v[42:43]
	v_pk_fma_f32 v[28:29], v[28:29], v[48:49], v[44:45]
	s_waitcnt vmcnt(10)
	v_pk_fma_f32 v[22:23], v[22:23], v[54:55], v[50:51]
	v_pk_fma_f32 v[24:25], v[24:25], v[56:57], v[52:53]
	s_waitcnt vmcnt(8)
	v_pk_fma_f32 v[18:19], v[18:19], v[62:63], v[58:59]
	v_pk_fma_f32 v[20:21], v[20:21], v[64:65], v[60:61]
	s_waitcnt vmcnt(6)
	v_pk_fma_f32 v[14:15], v[14:15], v[78:79], v[74:75]
	v_pk_fma_f32 v[16:17], v[16:17], v[80:81], v[76:77]
	s_waitcnt vmcnt(4)
	v_pk_fma_f32 v[10:11], v[10:11], v[98:99], v[82:83]
	v_pk_fma_f32 v[12:13], v[12:13], v[100:101], v[84:85]
	s_waitcnt vmcnt(2)
	v_pk_fma_f32 v[6:7], v[6:7], v[106:107], v[102:103]
	v_pk_fma_f32 v[8:9], v[8:9], v[108:109], v[104:105]
	s_waitcnt vmcnt(0)
	v_pk_fma_f32 v[2:3], v[2:3], v[114:115], v[110:111]
	v_pk_fma_f32 v[4:5], v[4:5], v[116:117], v[112:113]
	global_store_dwordx4 v[72:73], v[2:5], off
	global_store_dwordx4 v[72:73], v[6:9], off offset:32
	global_store_dwordx4 v[72:73], v[10:13], off offset:64
	global_store_dwordx4 v[72:73], v[14:17], off offset:96
	global_store_dwordx4 v[72:73], v[18:21], off offset:128
	global_store_dwordx4 v[72:73], v[22:25], off offset:160
	global_store_dwordx4 v[72:73], v[26:29], off offset:192
	global_store_dwordx4 v[72:73], v[30:33], off offset:224
	s_cbranch_scc1 .LBB0_979

.LBB0_1641:
	s_and_b32 s3, s2, 0xffff
	s_mul_i32 s3, s3, 0xaaab
	s_lshr_b32 s3, s3, 18
	s_mul_i32 s10, s3, 6
	s_sub_i32 s2, s2, s10
	s_and_b32 s2, s2, 0xffff
	s_add_i32 s2, s6, s2
	s_lshl_b32 s10, s2, 7
	v_or_b32_e32 v2, s10, v91
	v_lshlrev_b32_e32 v66, 11, v2
	v_lshl_add_u64 v[74:75], v[68:69], 0, v[66:67]
	v_add_lshl_u32 v66, s10, v92, 11
	s_add_i32 s3, s8, s3
	v_lshl_add_u64 v[76:77], v[68:69], 0, v[66:67]
	v_add_lshl_u32 v66, s10, v93, 11
	s_lshl_b32 s11, s3, 7
	v_lshl_add_u64 v[78:79], v[68:69], 0, v[66:67]
	v_add_lshl_u32 v66, s10, v94, 11
	v_lshl_add_u64 v[80:81], v[68:69], 0, v[66:67]
	v_or_b32_e32 v66, s11, v91
	v_lshlrev_b64 v[2:3], 11, v[66:67]
	v_add_u32_e32 v66, s11, v92
	v_lshl_add_u64 v[82:83], v[70:71], 0, v[2:3]
	v_lshlrev_b64 v[2:3], 11, v[66:67]
	v_add_u32_e32 v66, s11, v93
	v_lshl_add_u64 v[84:85], v[70:71], 0, v[2:3]
	v_lshlrev_b64 v[2:3], 11, v[66:67]
	v_add_u32_e32 v66, s11, v94
	v_lshl_add_u64 v[86:87], v[70:71], 0, v[2:3]
	v_lshlrev_b64 v[2:3], 11, v[66:67]
	v_lshl_add_u64 v[88:89], v[70:71], 0, v[2:3]
	global_load_dwordx4 v[2:5], v[74:75], off
	global_load_dwordx4 v[6:9], v[76:77], off
	global_load_dwordx4 v[10:13], v[78:79], off
	global_load_dwordx4 v[14:17], v[80:81], off
	global_load_dwordx4 v[18:21], v[82:83], off
	global_load_dwordx4 v[22:25], v[84:85], off
	global_load_dwordx4 v[26:29], v[86:87], off
	global_load_dwordx4 v[30:33], v[88:89], off
	global_load_dwordx4 v[102:105], v[74:75], off offset:128
	global_load_dwordx4 v[106:109], v[76:77], off offset:128
	global_load_dwordx4 v[110:113], v[78:79], off offset:128
	global_load_dwordx4 v[114:117], v[80:81], off offset:128
	global_load_dwordx4 v[118:121], v[82:83], off offset:128
	global_load_dwordx4 v[122:125], v[84:85], off offset:128
	global_load_dwordx4 v[126:129], v[86:87], off offset:128
	global_load_dwordx4 v[132:135], v[88:89], off offset:128
	s_waitcnt vmcnt(15)
	ds_write_b128 v98, v[2:5]
	s_waitcnt vmcnt(14)
	ds_write_b128 v98, v[6:9] offset:4608
	s_waitcnt vmcnt(13)
	ds_write_b128 v98, v[10:13] offset:9216
	s_waitcnt vmcnt(12)
	ds_write_b128 v98, v[14:17] offset:13824
	s_waitcnt vmcnt(11)
	ds_write_b128 v98, v[18:21] offset:36864
	s_waitcnt vmcnt(10)
	ds_write_b128 v98, v[22:25] offset:41472
	s_waitcnt vmcnt(9)
	ds_write_b128 v98, v[26:29] offset:46080
	s_waitcnt vmcnt(8)
	ds_write_b128 v98, v[30:33] offset:50688
	s_waitcnt lgkmcnt(0)
	s_barrier
	global_load_dwordx4 v[136:139], v[74:75], off offset:256
	global_load_dwordx4 v[140:143], v[76:77], off offset:256
	global_load_dwordx4 v[144:147], v[78:79], off offset:256
	global_load_dwordx4 v[148:151], v[80:81], off offset:256
	global_load_dwordx4 v[152:155], v[82:83], off offset:256
	global_load_dwordx4 v[156:159], v[84:85], off offset:256
	global_load_dwordx4 v[160:163], v[86:87], off offset:256
	global_load_dwordx4 v[164:167], v[88:89], off offset:256
	v_and_b32_e32 v246, 15, v1
	v_add_u32_e32 v246, 4, v246
	v_bfe_u32 v246, v246, 3, 1
	v_bfe_u32 v249, v1, 4, 2
	v_xor_b32_e32 v246, v246, v249
	v_bfe_u32 v249, v1, 5, 1
	v_sub_u32_e32 v246, v246, v249
	v_lshlrev_b32_e32 v246, 4, v246
	v_bfe_u32 v249, v1, 4, 1
	v_mul_u32_u24_e32 v249, 0x900, v249
	v_sub_u32_e32 v246, v246, v249
	v_add_u32_e32 v244, v246, v96
	v_add_u32_e32 v245, v246, v97
	ds_read_b128 v[212:215], v245 offset:36864
	ds_read_b128 v[196:199], v244
	ds_read_b128 v[216:219], v245 offset:39168
	ds_read_b128 v[220:223], v245 offset:41472
	ds_read_b128 v[224:227], v245 offset:43776
	ds_read_b128 v[200:203], v244 offset:2304
	ds_read_b128 v[204:207], v244 offset:4608
	ds_read_b128 v[208:211], v244 offset:6912
	s_waitcnt lgkmcnt(6)
	v_mfma_f32_16x16x32_bf16 v[50:53], v[196:199], v[212:215], 0
	ds_read_b128 v[228:231], v245 offset:36928
	s_waitcnt lgkmcnt(6)
	v_mfma_f32_16x16x32_bf16 v[54:57], v[196:199], v[216:219], 0
	ds_read_b128 v[232:235], v245 offset:39232
	s_waitcnt lgkmcnt(6)
	v_mfma_f32_16x16x32_bf16 v[18:21], v[196:199], v[220:223], 0
	ds_read_b128 v[236:239], v245 offset:41536
	s_waitcnt lgkmcnt(6)
	v_mfma_f32_16x16x32_bf16 v[22:25], v[196:199], v[224:227], 0
	ds_read_b128 v[240:243], v245 offset:43840
	ds_read_b128 v[196:199], v244 offset:64
	s_waitcnt lgkmcnt(7)
	v_mfma_f32_16x16x32_bf16 v[58:61], v[200:203], v[212:215], 0
	v_mfma_f32_16x16x32_bf16 v[62:65], v[200:203], v[216:219], 0
	v_mfma_f32_16x16x32_bf16 v[26:29], v[200:203], v[220:223], 0
	v_mfma_f32_16x16x32_bf16 v[30:33], v[200:203], v[224:227], 0
	ds_read_b128 v[200:203], v244 offset:2368
	s_waitcnt lgkmcnt(7)
	v_mfma_f32_16x16x32_bf16 v[34:37], v[204:207], v[212:215], 0
	v_mfma_f32_16x16x32_bf16 v[38:41], v[204:207], v[216:219], 0
	v_mfma_f32_16x16x32_bf16 v[2:5], v[204:207], v[220:223], 0
	v_mfma_f32_16x16x32_bf16 v[6:9], v[204:207], v[224:227], 0
	ds_read_b128 v[204:207], v244 offset:4672
	s_waitcnt vmcnt(15)
	ds_write_b128 v98, v[102:105] offset:18432
	s_waitcnt vmcnt(14)
	ds_write_b128 v98, v[106:109] offset:23040
	s_waitcnt lgkmcnt(9)
	v_mfma_f32_16x16x32_bf16 v[42:45], v[208:211], v[212:215], 0
	v_mfma_f32_16x16x32_bf16 v[46:49], v[208:211], v[216:219], 0
	v_mfma_f32_16x16x32_bf16 v[10:13], v[208:211], v[220:223], 0
	v_mfma_f32_16x16x32_bf16 v[14:17], v[208:211], v[224:227], 0
	ds_read_b128 v[208:211], v244 offset:6976
	s_waitcnt vmcnt(13)
	ds_write_b128 v98, v[110:113] offset:27648
	s_waitcnt vmcnt(12)
	ds_write_b128 v98, v[114:117] offset:32256
	s_waitcnt lgkmcnt(7)
	v_mfma_f32_16x16x32_bf16 v[50:53], v[196:199], v[228:231], v[50:53]
	v_mfma_f32_16x16x32_bf16 v[54:57], v[196:199], v[232:235], v[54:57]
	v_mfma_f32_16x16x32_bf16 v[18:21], v[196:199], v[236:239], v[18:21]
	v_mfma_f32_16x16x32_bf16 v[22:25], v[196:199], v[240:243], v[22:25]
	s_waitcnt vmcnt(11)
	ds_write_b128 v98, v[118:121] offset:55296
	s_waitcnt vmcnt(10)
	ds_write_b128 v98, v[122:125] offset:59904
	s_waitcnt lgkmcnt(8)
	v_mfma_f32_16x16x32_bf16 v[58:61], v[200:203], v[228:231], v[58:61]
	v_mfma_f32_16x16x32_bf16 v[62:65], v[200:203], v[232:235], v[62:65]
	v_mfma_f32_16x16x32_bf16 v[26:29], v[200:203], v[236:239], v[26:29]
	v_mfma_f32_16x16x32_bf16 v[30:33], v[200:203], v[240:243], v[30:33]
	s_waitcnt vmcnt(9)
	ds_write_b128 v98, v[126:129] offset:64512
	s_waitcnt vmcnt(8)
	ds_write_b128 v99, v[132:135] offset:32256
	s_waitcnt lgkmcnt(0)
	s_barrier
	ds_read_b128 v[212:215], v245 offset:55296
	ds_read_b128 v[196:199], v244 offset:18432
	ds_read_b128 v[216:219], v245 offset:57600
	ds_read_b128 v[220:223], v245 offset:59904
	ds_read_b128 v[224:227], v245 offset:62208
	ds_read_b128 v[200:203], v244 offset:20736
	v_mfma_f32_16x16x32_bf16 v[34:37], v[204:207], v[228:231], v[34:37]
	v_mfma_f32_16x16x32_bf16 v[38:41], v[204:207], v[232:235], v[38:41]
	v_mfma_f32_16x16x32_bf16 v[2:5], v[204:207], v[236:239], v[2:5]
	v_mfma_f32_16x16x32_bf16 v[6:9], v[204:207], v[240:243], v[6:9]
	ds_read_b128 v[204:207], v244 offset:23040
	v_mfma_f32_16x16x32_bf16 v[42:45], v[208:211], v[228:231], v[42:45]
	v_mfma_f32_16x16x32_bf16 v[46:49], v[208:211], v[232:235], v[46:49]
	v_mfma_f32_16x16x32_bf16 v[10:13], v[208:211], v[236:239], v[10:13]
	v_mfma_f32_16x16x32_bf16 v[14:17], v[208:211], v[240:243], v[14:17]
	ds_read_b128 v[208:211], v244 offset:25344
	global_load_dwordx4 v[102:105], v[74:75], off offset:384
	global_load_dwordx4 v[106:109], v[76:77], off offset:384
	global_load_dwordx4 v[110:113], v[78:79], off offset:384
	global_load_dwordx4 v[114:117], v[80:81], off offset:384
	global_load_dwordx4 v[118:121], v[82:83], off offset:384
	global_load_dwordx4 v[122:125], v[84:85], off offset:384
	global_load_dwordx4 v[126:129], v[86:87], off offset:384
	global_load_dwordx4 v[132:135], v[88:89], off offset:384
	s_waitcnt lgkmcnt(6)
	v_mfma_f32_16x16x32_bf16 v[50:53], v[196:199], v[212:215], v[50:53]
	ds_read_b128 v[228:231], v245 offset:55360
	s_waitcnt lgkmcnt(6)
	v_mfma_f32_16x16x32_bf16 v[54:57], v[196:199], v[216:219], v[54:57]
	ds_read_b128 v[232:235], v245 offset:57664
	s_waitcnt lgkmcnt(6)
	v_mfma_f32_16x16x32_bf16 v[18:21], v[196:199], v[220:223], v[18:21]
	ds_read_b128 v[236:239], v245 offset:59968
	s_waitcnt lgkmcnt(6)
	v_mfma_f32_16x16x32_bf16 v[22:25], v[196:199], v[224:227], v[22:25]
	ds_read_b128 v[240:243], v245 offset:62272
	ds_read_b128 v[196:199], v244 offset:18496
	s_waitcnt lgkmcnt(7)
	v_mfma_f32_16x16x32_bf16 v[58:61], v[200:203], v[212:215], v[58:61]
	v_mfma_f32_16x16x32_bf16 v[62:65], v[200:203], v[216:219], v[62:65]
	v_mfma_f32_16x16x32_bf16 v[26:29], v[200:203], v[220:223], v[26:29]
	v_mfma_f32_16x16x32_bf16 v[30:33], v[200:203], v[224:227], v[30:33]
	ds_read_b128 v[200:203], v244 offset:20800
	s_waitcnt lgkmcnt(7)
	v_mfma_f32_16x16x32_bf16 v[34:37], v[204:207], v[212:215], v[34:37]
	v_mfma_f32_16x16x32_bf16 v[38:41], v[204:207], v[216:219], v[38:41]
	v_mfma_f32_16x16x32_bf16 v[2:5], v[204:207], v[220:223], v[2:5]
	v_mfma_f32_16x16x32_bf16 v[6:9], v[204:207], v[224:227], v[6:9]
	ds_read_b128 v[204:207], v244 offset:23104
	s_waitcnt vmcnt(15)
	ds_write_b128 v98, v[136:139]
	s_waitcnt vmcnt(14)
	ds_write_b128 v98, v[140:143] offset:4608
	s_waitcnt lgkmcnt(9)
	v_mfma_f32_16x16x32_bf16 v[42:45], v[208:211], v[212:215], v[42:45]
	v_mfma_f32_16x16x32_bf16 v[46:49], v[208:211], v[216:219], v[46:49]
	v_mfma_f32_16x16x32_bf16 v[10:13], v[208:211], v[220:223], v[10:13]
	v_mfma_f32_16x16x32_bf16 v[14:17], v[208:211], v[224:227], v[14:17]
	ds_read_b128 v[208:211], v244 offset:25408
	s_waitcnt vmcnt(13)
	ds_write_b128 v98, v[144:147] offset:9216
	s_waitcnt vmcnt(12)
	ds_write_b128 v98, v[148:151] offset:13824
	s_waitcnt lgkmcnt(7)
	v_mfma_f32_16x16x32_bf16 v[50:53], v[196:199], v[228:231], v[50:53]
	v_mfma_f32_16x16x32_bf16 v[54:57], v[196:199], v[232:235], v[54:57]
	v_mfma_f32_16x16x32_bf16 v[18:21], v[196:199], v[236:239], v[18:21]
	v_mfma_f32_16x16x32_bf16 v[22:25], v[196:199], v[240:243], v[22:25]
	s_waitcnt vmcnt(11)
	ds_write_b128 v98, v[152:155] offset:36864
	s_waitcnt vmcnt(10)
	ds_write_b128 v98, v[156:159] offset:41472
	s_waitcnt lgkmcnt(8)
	v_mfma_f32_16x16x32_bf16 v[58:61], v[200:203], v[228:231], v[58:61]
	v_mfma_f32_16x16x32_bf16 v[62:65], v[200:203], v[232:235], v[62:65]
	v_mfma_f32_16x16x32_bf16 v[26:29], v[200:203], v[236:239], v[26:29]
	v_mfma_f32_16x16x32_bf16 v[30:33], v[200:203], v[240:243], v[30:33]
	s_waitcnt vmcnt(9)
	ds_write_b128 v98, v[160:163] offset:46080
	s_waitcnt vmcnt(8)
	ds_write_b128 v98, v[164:167] offset:50688
	s_waitcnt lgkmcnt(0)
	s_barrier
	ds_read_b128 v[212:215], v245 offset:36864
	ds_read_b128 v[196:199], v244
	ds_read_b128 v[216:219], v245 offset:39168
	ds_read_b128 v[220:223], v245 offset:41472
	ds_read_b128 v[224:227], v245 offset:43776
	ds_read_b128 v[200:203], v244 offset:2304
	v_mfma_f32_16x16x32_bf16 v[34:37], v[204:207], v[228:231], v[34:37]
	v_mfma_f32_16x16x32_bf16 v[38:41], v[204:207], v[232:235], v[38:41]
	v_mfma_f32_16x16x32_bf16 v[2:5], v[204:207], v[236:239], v[2:5]
	v_mfma_f32_16x16x32_bf16 v[6:9], v[204:207], v[240:243], v[6:9]
	ds_read_b128 v[204:207], v244 offset:4608
	v_mfma_f32_16x16x32_bf16 v[42:45], v[208:211], v[228:231], v[42:45]
	v_mfma_f32_16x16x32_bf16 v[46:49], v[208:211], v[232:235], v[46:49]
	v_mfma_f32_16x16x32_bf16 v[10:13], v[208:211], v[236:239], v[10:13]
	v_mfma_f32_16x16x32_bf16 v[14:17], v[208:211], v[240:243], v[14:17]
	ds_read_b128 v[208:211], v244 offset:6912
	global_load_dwordx4 v[136:139], v[74:75], off offset:512
	global_load_dwordx4 v[140:143], v[76:77], off offset:512
	global_load_dwordx4 v[144:147], v[78:79], off offset:512
	global_load_dwordx4 v[148:151], v[80:81], off offset:512
	global_load_dwordx4 v[152:155], v[82:83], off offset:512
	global_load_dwordx4 v[156:159], v[84:85], off offset:512
	global_load_dwordx4 v[160:163], v[86:87], off offset:512
	global_load_dwordx4 v[164:167], v[88:89], off offset:512
	s_waitcnt lgkmcnt(6)
	v_mfma_f32_16x16x32_bf16 v[50:53], v[196:199], v[212:215], v[50:53]
	ds_read_b128 v[228:231], v245 offset:36928
	s_waitcnt lgkmcnt(6)
	v_mfma_f32_16x16x32_bf16 v[54:57], v[196:199], v[216:219], v[54:57]
	ds_read_b128 v[232:235], v245 offset:39232
	s_waitcnt lgkmcnt(6)
	v_mfma_f32_16x16x32_bf16 v[18:21], v[196:199], v[220:223], v[18:21]
	ds_read_b128 v[236:239], v245 offset:41536
	s_waitcnt lgkmcnt(6)
	v_mfma_f32_16x16x32_bf16 v[22:25], v[196:199], v[224:227], v[22:25]
	ds_read_b128 v[240:243], v245 offset:43840
	ds_read_b128 v[196:199], v244 offset:64
	s_waitcnt lgkmcnt(7)
	v_mfma_f32_16x16x32_bf16 v[58:61], v[200:203], v[212:215], v[58:61]
	v_mfma_f32_16x16x32_bf16 v[62:65], v[200:203], v[216:219], v[62:65]
	v_mfma_f32_16x16x32_bf16 v[26:29], v[200:203], v[220:223], v[26:29]
	v_mfma_f32_16x16x32_bf16 v[30:33], v[200:203], v[224:227], v[30:33]
	ds_read_b128 v[200:203], v244 offset:2368
	s_waitcnt lgkmcnt(7)
	v_mfma_f32_16x16x32_bf16 v[34:37], v[204:207], v[212:215], v[34:37]
	v_mfma_f32_16x16x32_bf16 v[38:41], v[204:207], v[216:219], v[38:41]
	v_mfma_f32_16x16x32_bf16 v[2:5], v[204:207], v[220:223], v[2:5]
	v_mfma_f32_16x16x32_bf16 v[6:9], v[204:207], v[224:227], v[6:9]
	ds_read_b128 v[204:207], v244 offset:4672
	s_waitcnt vmcnt(15)
	ds_write_b128 v98, v[102:105] offset:18432
	s_waitcnt vmcnt(14)
	ds_write_b128 v98, v[106:109] offset:23040
	s_waitcnt lgkmcnt(9)
	v_mfma_f32_16x16x32_bf16 v[42:45], v[208:211], v[212:215], v[42:45]
	v_mfma_f32_16x16x32_bf16 v[46:49], v[208:211], v[216:219], v[46:49]
	v_mfma_f32_16x16x32_bf16 v[10:13], v[208:211], v[220:223], v[10:13]
	v_mfma_f32_16x16x32_bf16 v[14:17], v[208:211], v[224:227], v[14:17]
	ds_read_b128 v[208:211], v244 offset:6976
	s_waitcnt vmcnt(13)
	ds_write_b128 v98, v[110:113] offset:27648
	s_waitcnt vmcnt(12)
	ds_write_b128 v98, v[114:117] offset:32256
	s_waitcnt lgkmcnt(7)
	v_mfma_f32_16x16x32_bf16 v[50:53], v[196:199], v[228:231], v[50:53]
	v_mfma_f32_16x16x32_bf16 v[54:57], v[196:199], v[232:235], v[54:57]
	v_mfma_f32_16x16x32_bf16 v[18:21], v[196:199], v[236:239], v[18:21]
	v_mfma_f32_16x16x32_bf16 v[22:25], v[196:199], v[240:243], v[22:25]
	s_waitcnt vmcnt(11)
	ds_write_b128 v98, v[118:121] offset:55296
	s_waitcnt vmcnt(10)
	ds_write_b128 v98, v[122:125] offset:59904
	s_waitcnt lgkmcnt(8)
	v_mfma_f32_16x16x32_bf16 v[58:61], v[200:203], v[228:231], v[58:61]
	v_mfma_f32_16x16x32_bf16 v[62:65], v[200:203], v[232:235], v[62:65]
	v_mfma_f32_16x16x32_bf16 v[26:29], v[200:203], v[236:239], v[26:29]
	v_mfma_f32_16x16x32_bf16 v[30:33], v[200:203], v[240:243], v[30:33]
	s_waitcnt vmcnt(9)
	ds_write_b128 v98, v[126:129] offset:64512
	s_waitcnt vmcnt(8)
	ds_write_b128 v99, v[132:135] offset:32256
	s_waitcnt lgkmcnt(0)
	s_barrier
	ds_read_b128 v[212:215], v245 offset:55296
	ds_read_b128 v[196:199], v244 offset:18432
	ds_read_b128 v[216:219], v245 offset:57600
	ds_read_b128 v[220:223], v245 offset:59904
	ds_read_b128 v[224:227], v245 offset:62208
	ds_read_b128 v[200:203], v244 offset:20736
	v_mfma_f32_16x16x32_bf16 v[34:37], v[204:207], v[228:231], v[34:37]
	v_mfma_f32_16x16x32_bf16 v[38:41], v[204:207], v[232:235], v[38:41]
	v_mfma_f32_16x16x32_bf16 v[2:5], v[204:207], v[236:239], v[2:5]
	v_mfma_f32_16x16x32_bf16 v[6:9], v[204:207], v[240:243], v[6:9]
	ds_read_b128 v[204:207], v244 offset:23040
	v_mfma_f32_16x16x32_bf16 v[42:45], v[208:211], v[228:231], v[42:45]
	v_mfma_f32_16x16x32_bf16 v[46:49], v[208:211], v[232:235], v[46:49]
	v_mfma_f32_16x16x32_bf16 v[10:13], v[208:211], v[236:239], v[10:13]
	v_mfma_f32_16x16x32_bf16 v[14:17], v[208:211], v[240:243], v[14:17]
	ds_read_b128 v[208:211], v244 offset:25344
	global_load_dwordx4 v[102:105], v[74:75], off offset:640
	global_load_dwordx4 v[106:109], v[76:77], off offset:640
	global_load_dwordx4 v[110:113], v[78:79], off offset:640
	global_load_dwordx4 v[114:117], v[80:81], off offset:640
	global_load_dwordx4 v[118:121], v[82:83], off offset:640
	global_load_dwordx4 v[122:125], v[84:85], off offset:640
	global_load_dwordx4 v[126:129], v[86:87], off offset:640
	global_load_dwordx4 v[132:135], v[88:89], off offset:640
	s_waitcnt lgkmcnt(6)
	v_mfma_f32_16x16x32_bf16 v[50:53], v[196:199], v[212:215], v[50:53]
	ds_read_b128 v[228:231], v245 offset:55360
	s_waitcnt lgkmcnt(6)
	v_mfma_f32_16x16x32_bf16 v[54:57], v[196:199], v[216:219], v[54:57]
	ds_read_b128 v[232:235], v245 offset:57664
	s_waitcnt lgkmcnt(6)
	v_mfma_f32_16x16x32_bf16 v[18:21], v[196:199], v[220:223], v[18:21]
	ds_read_b128 v[236:239], v245 offset:59968
	s_waitcnt lgkmcnt(6)
	v_mfma_f32_16x16x32_bf16 v[22:25], v[196:199], v[224:227], v[22:25]
	ds_read_b128 v[240:243], v245 offset:62272
	ds_read_b128 v[196:199], v244 offset:18496
	s_waitcnt lgkmcnt(7)
	v_mfma_f32_16x16x32_bf16 v[58:61], v[200:203], v[212:215], v[58:61]
	v_mfma_f32_16x16x32_bf16 v[62:65], v[200:203], v[216:219], v[62:65]
	v_mfma_f32_16x16x32_bf16 v[26:29], v[200:203], v[220:223], v[26:29]
	v_mfma_f32_16x16x32_bf16 v[30:33], v[200:203], v[224:227], v[30:33]
	ds_read_b128 v[200:203], v244 offset:20800
	s_waitcnt lgkmcnt(7)
	v_mfma_f32_16x16x32_bf16 v[34:37], v[204:207], v[212:215], v[34:37]
	v_mfma_f32_16x16x32_bf16 v[38:41], v[204:207], v[216:219], v[38:41]
	v_mfma_f32_16x16x32_bf16 v[2:5], v[204:207], v[220:223], v[2:5]
	v_mfma_f32_16x16x32_bf16 v[6:9], v[204:207], v[224:227], v[6:9]
	ds_read_b128 v[204:207], v244 offset:23104
	s_waitcnt vmcnt(15)
	ds_write_b128 v98, v[136:139]
	s_waitcnt vmcnt(14)
	ds_write_b128 v98, v[140:143] offset:4608
	s_waitcnt lgkmcnt(9)
	v_mfma_f32_16x16x32_bf16 v[42:45], v[208:211], v[212:215], v[42:45]
	v_mfma_f32_16x16x32_bf16 v[46:49], v[208:211], v[216:219], v[46:49]
	v_mfma_f32_16x16x32_bf16 v[10:13], v[208:211], v[220:223], v[10:13]
	v_mfma_f32_16x16x32_bf16 v[14:17], v[208:211], v[224:227], v[14:17]
	ds_read_b128 v[208:211], v244 offset:25408
	s_waitcnt vmcnt(13)
	ds_write_b128 v98, v[144:147] offset:9216
	s_waitcnt vmcnt(12)
	ds_write_b128 v98, v[148:151] offset:13824
	s_waitcnt lgkmcnt(7)
	v_mfma_f32_16x16x32_bf16 v[50:53], v[196:199], v[228:231], v[50:53]
	v_mfma_f32_16x16x32_bf16 v[54:57], v[196:199], v[232:235], v[54:57]
	v_mfma_f32_16x16x32_bf16 v[18:21], v[196:199], v[236:239], v[18:21]
	v_mfma_f32_16x16x32_bf16 v[22:25], v[196:199], v[240:243], v[22:25]
	s_waitcnt vmcnt(11)
	ds_write_b128 v98, v[152:155] offset:36864
	s_waitcnt vmcnt(10)
	ds_write_b128 v98, v[156:159] offset:41472
	s_waitcnt lgkmcnt(8)
	v_mfma_f32_16x16x32_bf16 v[58:61], v[200:203], v[228:231], v[58:61]
	v_mfma_f32_16x16x32_bf16 v[62:65], v[200:203], v[232:235], v[62:65]
	v_mfma_f32_16x16x32_bf16 v[26:29], v[200:203], v[236:239], v[26:29]
	v_mfma_f32_16x16x32_bf16 v[30:33], v[200:203], v[240:243], v[30:33]
	s_waitcnt vmcnt(9)
	ds_write_b128 v98, v[160:163] offset:46080
	s_waitcnt vmcnt(8)
	ds_write_b128 v98, v[164:167] offset:50688
	s_waitcnt lgkmcnt(0)
	s_barrier
	ds_read_b128 v[212:215], v245 offset:36864
	ds_read_b128 v[196:199], v244
	ds_read_b128 v[216:219], v245 offset:39168
	ds_read_b128 v[220:223], v245 offset:41472
	ds_read_b128 v[224:227], v245 offset:43776
	ds_read_b128 v[200:203], v244 offset:2304
	v_mfma_f32_16x16x32_bf16 v[34:37], v[204:207], v[228:231], v[34:37]
	v_mfma_f32_16x16x32_bf16 v[38:41], v[204:207], v[232:235], v[38:41]
	v_mfma_f32_16x16x32_bf16 v[2:5], v[204:207], v[236:239], v[2:5]
	v_mfma_f32_16x16x32_bf16 v[6:9], v[204:207], v[240:243], v[6:9]
	ds_read_b128 v[204:207], v244 offset:4608
	v_mfma_f32_16x16x32_bf16 v[42:45], v[208:211], v[228:231], v[42:45]
	v_mfma_f32_16x16x32_bf16 v[46:49], v[208:211], v[232:235], v[46:49]
	v_mfma_f32_16x16x32_bf16 v[10:13], v[208:211], v[236:239], v[10:13]
	v_mfma_f32_16x16x32_bf16 v[14:17], v[208:211], v[240:243], v[14:17]
	ds_read_b128 v[208:211], v244 offset:6912
	global_load_dwordx4 v[136:139], v[74:75], off offset:768
	global_load_dwordx4 v[140:143], v[76:77], off offset:768
	global_load_dwordx4 v[144:147], v[78:79], off offset:768
	global_load_dwordx4 v[148:151], v[80:81], off offset:768
	global_load_dwordx4 v[152:155], v[82:83], off offset:768
	global_load_dwordx4 v[156:159], v[84:85], off offset:768
	global_load_dwordx4 v[160:163], v[86:87], off offset:768
	global_load_dwordx4 v[164:167], v[88:89], off offset:768
	s_waitcnt lgkmcnt(6)
	v_mfma_f32_16x16x32_bf16 v[50:53], v[196:199], v[212:215], v[50:53]
	ds_read_b128 v[228:231], v245 offset:36928
	s_waitcnt lgkmcnt(6)
	v_mfma_f32_16x16x32_bf16 v[54:57], v[196:199], v[216:219], v[54:57]
	ds_read_b128 v[232:235], v245 offset:39232
	s_waitcnt lgkmcnt(6)
	v_mfma_f32_16x16x32_bf16 v[18:21], v[196:199], v[220:223], v[18:21]
	ds_read_b128 v[236:239], v245 offset:41536
	s_waitcnt lgkmcnt(6)
	v_mfma_f32_16x16x32_bf16 v[22:25], v[196:199], v[224:227], v[22:25]
	ds_read_b128 v[240:243], v245 offset:43840
	ds_read_b128 v[196:199], v244 offset:64
	s_waitcnt lgkmcnt(7)
	v_mfma_f32_16x16x32_bf16 v[58:61], v[200:203], v[212:215], v[58:61]
	v_mfma_f32_16x16x32_bf16 v[62:65], v[200:203], v[216:219], v[62:65]
	v_mfma_f32_16x16x32_bf16 v[26:29], v[200:203], v[220:223], v[26:29]
	v_mfma_f32_16x16x32_bf16 v[30:33], v[200:203], v[224:227], v[30:33]
	ds_read_b128 v[200:203], v244 offset:2368
	s_waitcnt lgkmcnt(7)
	v_mfma_f32_16x16x32_bf16 v[34:37], v[204:207], v[212:215], v[34:37]
	v_mfma_f32_16x16x32_bf16 v[38:41], v[204:207], v[216:219], v[38:41]
	v_mfma_f32_16x16x32_bf16 v[2:5], v[204:207], v[220:223], v[2:5]
	v_mfma_f32_16x16x32_bf16 v[6:9], v[204:207], v[224:227], v[6:9]
	ds_read_b128 v[204:207], v244 offset:4672
	s_waitcnt vmcnt(15)
	ds_write_b128 v98, v[102:105] offset:18432
	s_waitcnt vmcnt(14)
	ds_write_b128 v98, v[106:109] offset:23040
	s_waitcnt lgkmcnt(9)
	v_mfma_f32_16x16x32_bf16 v[42:45], v[208:211], v[212:215], v[42:45]
	v_mfma_f32_16x16x32_bf16 v[46:49], v[208:211], v[216:219], v[46:49]
	v_mfma_f32_16x16x32_bf16 v[10:13], v[208:211], v[220:223], v[10:13]
	v_mfma_f32_16x16x32_bf16 v[14:17], v[208:211], v[224:227], v[14:17]
	ds_read_b128 v[208:211], v244 offset:6976
	s_waitcnt vmcnt(13)
	ds_write_b128 v98, v[110:113] offset:27648
	s_waitcnt vmcnt(12)
	ds_write_b128 v98, v[114:117] offset:32256
	s_waitcnt lgkmcnt(7)
	v_mfma_f32_16x16x32_bf16 v[50:53], v[196:199], v[228:231], v[50:53]
	v_mfma_f32_16x16x32_bf16 v[54:57], v[196:199], v[232:235], v[54:57]
	v_mfma_f32_16x16x32_bf16 v[18:21], v[196:199], v[236:239], v[18:21]
	v_mfma_f32_16x16x32_bf16 v[22:25], v[196:199], v[240:243], v[22:25]
	s_waitcnt vmcnt(11)
	ds_write_b128 v98, v[118:121] offset:55296
	s_waitcnt vmcnt(10)
	ds_write_b128 v98, v[122:125] offset:59904
	s_waitcnt lgkmcnt(8)
	v_mfma_f32_16x16x32_bf16 v[58:61], v[200:203], v[228:231], v[58:61]
	v_mfma_f32_16x16x32_bf16 v[62:65], v[200:203], v[232:235], v[62:65]
	v_mfma_f32_16x16x32_bf16 v[26:29], v[200:203], v[236:239], v[26:29]
	v_mfma_f32_16x16x32_bf16 v[30:33], v[200:203], v[240:243], v[30:33]
	s_waitcnt vmcnt(9)
	ds_write_b128 v98, v[126:129] offset:64512
	s_waitcnt vmcnt(8)
	ds_write_b128 v99, v[132:135] offset:32256
	s_waitcnt lgkmcnt(0)
	s_barrier
	ds_read_b128 v[212:215], v245 offset:55296
	ds_read_b128 v[196:199], v244 offset:18432
	ds_read_b128 v[216:219], v245 offset:57600
	ds_read_b128 v[220:223], v245 offset:59904
	ds_read_b128 v[224:227], v245 offset:62208
	ds_read_b128 v[200:203], v244 offset:20736
	v_mfma_f32_16x16x32_bf16 v[34:37], v[204:207], v[228:231], v[34:37]
	v_mfma_f32_16x16x32_bf16 v[38:41], v[204:207], v[232:235], v[38:41]
	v_mfma_f32_16x16x32_bf16 v[2:5], v[204:207], v[236:239], v[2:5]
	v_mfma_f32_16x16x32_bf16 v[6:9], v[204:207], v[240:243], v[6:9]
	ds_read_b128 v[204:207], v244 offset:23040
	v_mfma_f32_16x16x32_bf16 v[42:45], v[208:211], v[228:231], v[42:45]
	v_mfma_f32_16x16x32_bf16 v[46:49], v[208:211], v[232:235], v[46:49]
	v_mfma_f32_16x16x32_bf16 v[10:13], v[208:211], v[236:239], v[10:13]
	v_mfma_f32_16x16x32_bf16 v[14:17], v[208:211], v[240:243], v[14:17]
	ds_read_b128 v[208:211], v244 offset:25344
	global_load_dwordx4 v[102:105], v[74:75], off offset:896
	global_load_dwordx4 v[106:109], v[76:77], off offset:896
	global_load_dwordx4 v[110:113], v[78:79], off offset:896
	global_load_dwordx4 v[114:117], v[80:81], off offset:896
	global_load_dwordx4 v[118:121], v[82:83], off offset:896
	global_load_dwordx4 v[122:125], v[84:85], off offset:896
	global_load_dwordx4 v[126:129], v[86:87], off offset:896
	global_load_dwordx4 v[132:135], v[88:89], off offset:896
	s_waitcnt lgkmcnt(6)
	v_mfma_f32_16x16x32_bf16 v[50:53], v[196:199], v[212:215], v[50:53]
	ds_read_b128 v[228:231], v245 offset:55360
	s_waitcnt lgkmcnt(6)
	v_mfma_f32_16x16x32_bf16 v[54:57], v[196:199], v[216:219], v[54:57]
	ds_read_b128 v[232:235], v245 offset:57664
	s_waitcnt lgkmcnt(6)
	v_mfma_f32_16x16x32_bf16 v[18:21], v[196:199], v[220:223], v[18:21]
	ds_read_b128 v[236:239], v245 offset:59968
	s_waitcnt lgkmcnt(6)
	v_mfma_f32_16x16x32_bf16 v[22:25], v[196:199], v[224:227], v[22:25]
	ds_read_b128 v[240:243], v245 offset:62272
	ds_read_b128 v[196:199], v244 offset:18496
	s_waitcnt lgkmcnt(7)
	v_mfma_f32_16x16x32_bf16 v[58:61], v[200:203], v[212:215], v[58:61]
	v_mfma_f32_16x16x32_bf16 v[62:65], v[200:203], v[216:219], v[62:65]
	v_mfma_f32_16x16x32_bf16 v[26:29], v[200:203], v[220:223], v[26:29]
	v_mfma_f32_16x16x32_bf16 v[30:33], v[200:203], v[224:227], v[30:33]
	ds_read_b128 v[200:203], v244 offset:20800
	s_waitcnt lgkmcnt(7)
	v_mfma_f32_16x16x32_bf16 v[34:37], v[204:207], v[212:215], v[34:37]
	v_mfma_f32_16x16x32_bf16 v[38:41], v[204:207], v[216:219], v[38:41]
	v_mfma_f32_16x16x32_bf16 v[2:5], v[204:207], v[220:223], v[2:5]
	v_mfma_f32_16x16x32_bf16 v[6:9], v[204:207], v[224:227], v[6:9]
	ds_read_b128 v[204:207], v244 offset:23104
	s_waitcnt vmcnt(15)
	ds_write_b128 v98, v[136:139]
	s_waitcnt vmcnt(14)
	ds_write_b128 v98, v[140:143] offset:4608
	s_waitcnt lgkmcnt(9)
	v_mfma_f32_16x16x32_bf16 v[42:45], v[208:211], v[212:215], v[42:45]
	v_mfma_f32_16x16x32_bf16 v[46:49], v[208:211], v[216:219], v[46:49]
	v_mfma_f32_16x16x32_bf16 v[10:13], v[208:211], v[220:223], v[10:13]
	v_mfma_f32_16x16x32_bf16 v[14:17], v[208:211], v[224:227], v[14:17]
	ds_read_b128 v[208:211], v244 offset:25408
	s_waitcnt vmcnt(13)
	ds_write_b128 v98, v[144:147] offset:9216
	s_waitcnt vmcnt(12)
	ds_write_b128 v98, v[148:151] offset:13824
	s_waitcnt lgkmcnt(7)
	v_mfma_f32_16x16x32_bf16 v[50:53], v[196:199], v[228:231], v[50:53]
	v_mfma_f32_16x16x32_bf16 v[54:57], v[196:199], v[232:235], v[54:57]
	v_mfma_f32_16x16x32_bf16 v[18:21], v[196:199], v[236:239], v[18:21]
	v_mfma_f32_16x16x32_bf16 v[22:25], v[196:199], v[240:243], v[22:25]
	s_waitcnt vmcnt(11)
	ds_write_b128 v98, v[152:155] offset:36864
	s_waitcnt vmcnt(10)
	ds_write_b128 v98, v[156:159] offset:41472
	s_waitcnt lgkmcnt(8)
	v_mfma_f32_16x16x32_bf16 v[58:61], v[200:203], v[228:231], v[58:61]
	v_mfma_f32_16x16x32_bf16 v[62:65], v[200:203], v[232:235], v[62:65]
	v_mfma_f32_16x16x32_bf16 v[26:29], v[200:203], v[236:239], v[26:29]
	v_mfma_f32_16x16x32_bf16 v[30:33], v[200:203], v[240:243], v[30:33]
	s_waitcnt vmcnt(9)
	ds_write_b128 v98, v[160:163] offset:46080
	s_waitcnt vmcnt(8)
	ds_write_b128 v98, v[164:167] offset:50688
	s_waitcnt lgkmcnt(0)
	s_barrier
	ds_read_b128 v[212:215], v245 offset:36864
	ds_read_b128 v[196:199], v244
	ds_read_b128 v[216:219], v245 offset:39168
	ds_read_b128 v[220:223], v245 offset:41472
	ds_read_b128 v[224:227], v245 offset:43776
	ds_read_b128 v[200:203], v244 offset:2304
	v_mfma_f32_16x16x32_bf16 v[34:37], v[204:207], v[228:231], v[34:37]
	v_mfma_f32_16x16x32_bf16 v[38:41], v[204:207], v[232:235], v[38:41]
	v_mfma_f32_16x16x32_bf16 v[2:5], v[204:207], v[236:239], v[2:5]
	v_mfma_f32_16x16x32_bf16 v[6:9], v[204:207], v[240:243], v[6:9]
	ds_read_b128 v[204:207], v244 offset:4608
	v_mfma_f32_16x16x32_bf16 v[42:45], v[208:211], v[228:231], v[42:45]
	v_mfma_f32_16x16x32_bf16 v[46:49], v[208:211], v[232:235], v[46:49]
	v_mfma_f32_16x16x32_bf16 v[10:13], v[208:211], v[236:239], v[10:13]
	v_mfma_f32_16x16x32_bf16 v[14:17], v[208:211], v[240:243], v[14:17]
	ds_read_b128 v[208:211], v244 offset:6912
	global_load_dwordx4 v[136:139], v[74:75], off offset:1024
	global_load_dwordx4 v[140:143], v[76:77], off offset:1024
	global_load_dwordx4 v[144:147], v[78:79], off offset:1024
	global_load_dwordx4 v[148:151], v[80:81], off offset:1024
	global_load_dwordx4 v[152:155], v[82:83], off offset:1024
	global_load_dwordx4 v[156:159], v[84:85], off offset:1024
	global_load_dwordx4 v[160:163], v[86:87], off offset:1024
	global_load_dwordx4 v[164:167], v[88:89], off offset:1024
	s_waitcnt lgkmcnt(6)
	v_mfma_f32_16x16x32_bf16 v[50:53], v[196:199], v[212:215], v[50:53]
	ds_read_b128 v[228:231], v245 offset:36928
	s_waitcnt lgkmcnt(6)
	v_mfma_f32_16x16x32_bf16 v[54:57], v[196:199], v[216:219], v[54:57]
	ds_read_b128 v[232:235], v245 offset:39232
	s_waitcnt lgkmcnt(6)
	v_mfma_f32_16x16x32_bf16 v[18:21], v[196:199], v[220:223], v[18:21]
	ds_read_b128 v[236:239], v245 offset:41536
	s_waitcnt lgkmcnt(6)
	v_mfma_f32_16x16x32_bf16 v[22:25], v[196:199], v[224:227], v[22:25]
	ds_read_b128 v[240:243], v245 offset:43840
	ds_read_b128 v[196:199], v244 offset:64
	s_waitcnt lgkmcnt(7)
	v_mfma_f32_16x16x32_bf16 v[58:61], v[200:203], v[212:215], v[58:61]
	v_mfma_f32_16x16x32_bf16 v[62:65], v[200:203], v[216:219], v[62:65]
	v_mfma_f32_16x16x32_bf16 v[26:29], v[200:203], v[220:223], v[26:29]
	v_mfma_f32_16x16x32_bf16 v[30:33], v[200:203], v[224:227], v[30:33]
	ds_read_b128 v[200:203], v244 offset:2368
	s_waitcnt lgkmcnt(7)
	v_mfma_f32_16x16x32_bf16 v[34:37], v[204:207], v[212:215], v[34:37]
	v_mfma_f32_16x16x32_bf16 v[38:41], v[204:207], v[216:219], v[38:41]
	v_mfma_f32_16x16x32_bf16 v[2:5], v[204:207], v[220:223], v[2:5]
	v_mfma_f32_16x16x32_bf16 v[6:9], v[204:207], v[224:227], v[6:9]
	ds_read_b128 v[204:207], v244 offset:4672
	s_waitcnt vmcnt(15)
	ds_write_b128 v98, v[102:105] offset:18432
	s_waitcnt vmcnt(14)
	ds_write_b128 v98, v[106:109] offset:23040
	s_waitcnt lgkmcnt(9)
	v_mfma_f32_16x16x32_bf16 v[42:45], v[208:211], v[212:215], v[42:45]
	v_mfma_f32_16x16x32_bf16 v[46:49], v[208:211], v[216:219], v[46:49]
	v_mfma_f32_16x16x32_bf16 v[10:13], v[208:211], v[220:223], v[10:13]
	v_mfma_f32_16x16x32_bf16 v[14:17], v[208:211], v[224:227], v[14:17]
	ds_read_b128 v[208:211], v244 offset:6976
	s_waitcnt vmcnt(13)
	ds_write_b128 v98, v[110:113] offset:27648
	s_waitcnt vmcnt(12)
	ds_write_b128 v98, v[114:117] offset:32256
	s_waitcnt lgkmcnt(7)
	v_mfma_f32_16x16x32_bf16 v[50:53], v[196:199], v[228:231], v[50:53]
	v_mfma_f32_16x16x32_bf16 v[54:57], v[196:199], v[232:235], v[54:57]
	v_mfma_f32_16x16x32_bf16 v[18:21], v[196:199], v[236:239], v[18:21]
	v_mfma_f32_16x16x32_bf16 v[22:25], v[196:199], v[240:243], v[22:25]
	s_waitcnt vmcnt(11)
	ds_write_b128 v98, v[118:121] offset:55296
	s_waitcnt vmcnt(10)
	ds_write_b128 v98, v[122:125] offset:59904
	s_waitcnt lgkmcnt(8)
	v_mfma_f32_16x16x32_bf16 v[58:61], v[200:203], v[228:231], v[58:61]
	v_mfma_f32_16x16x32_bf16 v[62:65], v[200:203], v[232:235], v[62:65]
	v_mfma_f32_16x16x32_bf16 v[26:29], v[200:203], v[236:239], v[26:29]
	v_mfma_f32_16x16x32_bf16 v[30:33], v[200:203], v[240:243], v[30:33]
	s_waitcnt vmcnt(9)
	ds_write_b128 v98, v[126:129] offset:64512
	s_waitcnt vmcnt(8)
	ds_write_b128 v99, v[132:135] offset:32256
	s_waitcnt lgkmcnt(0)
	s_barrier
	ds_read_b128 v[212:215], v245 offset:55296
	ds_read_b128 v[196:199], v244 offset:18432
	ds_read_b128 v[216:219], v245 offset:57600
	ds_read_b128 v[220:223], v245 offset:59904
	ds_read_b128 v[224:227], v245 offset:62208
	ds_read_b128 v[200:203], v244 offset:20736
	v_mfma_f32_16x16x32_bf16 v[34:37], v[204:207], v[228:231], v[34:37]
	v_mfma_f32_16x16x32_bf16 v[38:41], v[204:207], v[232:235], v[38:41]
	v_mfma_f32_16x16x32_bf16 v[2:5], v[204:207], v[236:239], v[2:5]
	v_mfma_f32_16x16x32_bf16 v[6:9], v[204:207], v[240:243], v[6:9]
	ds_read_b128 v[204:207], v244 offset:23040
	v_mfma_f32_16x16x32_bf16 v[42:45], v[208:211], v[228:231], v[42:45]
	v_mfma_f32_16x16x32_bf16 v[46:49], v[208:211], v[232:235], v[46:49]
	v_mfma_f32_16x16x32_bf16 v[10:13], v[208:211], v[236:239], v[10:13]
	v_mfma_f32_16x16x32_bf16 v[14:17], v[208:211], v[240:243], v[14:17]
	ds_read_b128 v[208:211], v244 offset:25344
	global_load_dwordx4 v[102:105], v[74:75], off offset:1152
	global_load_dwordx4 v[106:109], v[76:77], off offset:1152
	global_load_dwordx4 v[110:113], v[78:79], off offset:1152
	global_load_dwordx4 v[114:117], v[80:81], off offset:1152
	global_load_dwordx4 v[118:121], v[82:83], off offset:1152
	global_load_dwordx4 v[122:125], v[84:85], off offset:1152
	global_load_dwordx4 v[126:129], v[86:87], off offset:1152
	global_load_dwordx4 v[132:135], v[88:89], off offset:1152
	s_waitcnt lgkmcnt(6)
	v_mfma_f32_16x16x32_bf16 v[50:53], v[196:199], v[212:215], v[50:53]
	ds_read_b128 v[228:231], v245 offset:55360
	s_waitcnt lgkmcnt(6)
	v_mfma_f32_16x16x32_bf16 v[54:57], v[196:199], v[216:219], v[54:57]
	ds_read_b128 v[232:235], v245 offset:57664
	s_waitcnt lgkmcnt(6)
	v_mfma_f32_16x16x32_bf16 v[18:21], v[196:199], v[220:223], v[18:21]
	ds_read_b128 v[236:239], v245 offset:59968
	s_waitcnt lgkmcnt(6)
	v_mfma_f32_16x16x32_bf16 v[22:25], v[196:199], v[224:227], v[22:25]
	ds_read_b128 v[240:243], v245 offset:62272
	ds_read_b128 v[196:199], v244 offset:18496
	s_waitcnt lgkmcnt(7)
	v_mfma_f32_16x16x32_bf16 v[58:61], v[200:203], v[212:215], v[58:61]
	v_mfma_f32_16x16x32_bf16 v[62:65], v[200:203], v[216:219], v[62:65]
	v_mfma_f32_16x16x32_bf16 v[26:29], v[200:203], v[220:223], v[26:29]
	v_mfma_f32_16x16x32_bf16 v[30:33], v[200:203], v[224:227], v[30:33]
	ds_read_b128 v[200:203], v244 offset:20800
	s_waitcnt lgkmcnt(7)
	v_mfma_f32_16x16x32_bf16 v[34:37], v[204:207], v[212:215], v[34:37]
	v_mfma_f32_16x16x32_bf16 v[38:41], v[204:207], v[216:219], v[38:41]
	v_mfma_f32_16x16x32_bf16 v[2:5], v[204:207], v[220:223], v[2:5]
	v_mfma_f32_16x16x32_bf16 v[6:9], v[204:207], v[224:227], v[6:9]
	ds_read_b128 v[204:207], v244 offset:23104
	s_waitcnt vmcnt(15)
	ds_write_b128 v98, v[136:139]
	s_waitcnt vmcnt(14)
	ds_write_b128 v98, v[140:143] offset:4608
	s_waitcnt lgkmcnt(9)
	v_mfma_f32_16x16x32_bf16 v[42:45], v[208:211], v[212:215], v[42:45]
	v_mfma_f32_16x16x32_bf16 v[46:49], v[208:211], v[216:219], v[46:49]
	v_mfma_f32_16x16x32_bf16 v[10:13], v[208:211], v[220:223], v[10:13]
	v_mfma_f32_16x16x32_bf16 v[14:17], v[208:211], v[224:227], v[14:17]
	ds_read_b128 v[208:211], v244 offset:25408
	s_waitcnt vmcnt(13)
	ds_write_b128 v98, v[144:147] offset:9216
	s_waitcnt vmcnt(12)
	ds_write_b128 v98, v[148:151] offset:13824
	s_waitcnt lgkmcnt(7)
	v_mfma_f32_16x16x32_bf16 v[50:53], v[196:199], v[228:231], v[50:53]
	v_mfma_f32_16x16x32_bf16 v[54:57], v[196:199], v[232:235], v[54:57]
	v_mfma_f32_16x16x32_bf16 v[18:21], v[196:199], v[236:239], v[18:21]
	v_mfma_f32_16x16x32_bf16 v[22:25], v[196:199], v[240:243], v[22:25]
	s_waitcnt vmcnt(11)
	ds_write_b128 v98, v[152:155] offset:36864
	s_waitcnt vmcnt(10)
	ds_write_b128 v98, v[156:159] offset:41472
	s_waitcnt lgkmcnt(8)
	v_mfma_f32_16x16x32_bf16 v[58:61], v[200:203], v[228:231], v[58:61]
	v_mfma_f32_16x16x32_bf16 v[62:65], v[200:203], v[232:235], v[62:65]
	v_mfma_f32_16x16x32_bf16 v[26:29], v[200:203], v[236:239], v[26:29]
	v_mfma_f32_16x16x32_bf16 v[30:33], v[200:203], v[240:243], v[30:33]
	s_waitcnt vmcnt(9)
	ds_write_b128 v98, v[160:163] offset:46080
	s_waitcnt vmcnt(8)
	ds_write_b128 v98, v[164:167] offset:50688
	s_waitcnt lgkmcnt(0)
	s_barrier
	ds_read_b128 v[212:215], v245 offset:36864
	ds_read_b128 v[196:199], v244
	ds_read_b128 v[216:219], v245 offset:39168
	ds_read_b128 v[220:223], v245 offset:41472
	ds_read_b128 v[224:227], v245 offset:43776
	ds_read_b128 v[200:203], v244 offset:2304
	v_mfma_f32_16x16x32_bf16 v[34:37], v[204:207], v[228:231], v[34:37]
	v_mfma_f32_16x16x32_bf16 v[38:41], v[204:207], v[232:235], v[38:41]
	v_mfma_f32_16x16x32_bf16 v[2:5], v[204:207], v[236:239], v[2:5]
	v_mfma_f32_16x16x32_bf16 v[6:9], v[204:207], v[240:243], v[6:9]
	ds_read_b128 v[204:207], v244 offset:4608
	v_mfma_f32_16x16x32_bf16 v[42:45], v[208:211], v[228:231], v[42:45]
	v_mfma_f32_16x16x32_bf16 v[46:49], v[208:211], v[232:235], v[46:49]
	v_mfma_f32_16x16x32_bf16 v[10:13], v[208:211], v[236:239], v[10:13]
	v_mfma_f32_16x16x32_bf16 v[14:17], v[208:211], v[240:243], v[14:17]
	ds_read_b128 v[208:211], v244 offset:6912
	global_load_dwordx4 v[136:139], v[74:75], off offset:1280
	global_load_dwordx4 v[140:143], v[76:77], off offset:1280
	global_load_dwordx4 v[144:147], v[78:79], off offset:1280
	global_load_dwordx4 v[148:151], v[80:81], off offset:1280
	global_load_dwordx4 v[152:155], v[82:83], off offset:1280
	global_load_dwordx4 v[156:159], v[84:85], off offset:1280
	global_load_dwordx4 v[160:163], v[86:87], off offset:1280
	global_load_dwordx4 v[164:167], v[88:89], off offset:1280
	s_waitcnt lgkmcnt(6)
	v_mfma_f32_16x16x32_bf16 v[50:53], v[196:199], v[212:215], v[50:53]
	ds_read_b128 v[228:231], v245 offset:36928
	s_waitcnt lgkmcnt(6)
	v_mfma_f32_16x16x32_bf16 v[54:57], v[196:199], v[216:219], v[54:57]
	ds_read_b128 v[232:235], v245 offset:39232
	s_waitcnt lgkmcnt(6)
	v_mfma_f32_16x16x32_bf16 v[18:21], v[196:199], v[220:223], v[18:21]
	ds_read_b128 v[236:239], v245 offset:41536
	s_waitcnt lgkmcnt(6)
	v_mfma_f32_16x16x32_bf16 v[22:25], v[196:199], v[224:227], v[22:25]
	ds_read_b128 v[240:243], v245 offset:43840
	ds_read_b128 v[196:199], v244 offset:64
	s_waitcnt lgkmcnt(7)
	v_mfma_f32_16x16x32_bf16 v[58:61], v[200:203], v[212:215], v[58:61]
	v_mfma_f32_16x16x32_bf16 v[62:65], v[200:203], v[216:219], v[62:65]
	v_mfma_f32_16x16x32_bf16 v[26:29], v[200:203], v[220:223], v[26:29]
	v_mfma_f32_16x16x32_bf16 v[30:33], v[200:203], v[224:227], v[30:33]
	ds_read_b128 v[200:203], v244 offset:2368
	s_waitcnt lgkmcnt(7)
	v_mfma_f32_16x16x32_bf16 v[34:37], v[204:207], v[212:215], v[34:37]
	v_mfma_f32_16x16x32_bf16 v[38:41], v[204:207], v[216:219], v[38:41]
	v_mfma_f32_16x16x32_bf16 v[2:5], v[204:207], v[220:223], v[2:5]
	v_mfma_f32_16x16x32_bf16 v[6:9], v[204:207], v[224:227], v[6:9]
	ds_read_b128 v[204:207], v244 offset:4672
	s_waitcnt vmcnt(15)
	ds_write_b128 v98, v[102:105] offset:18432
	s_waitcnt vmcnt(14)
	ds_write_b128 v98, v[106:109] offset:23040
	s_waitcnt lgkmcnt(9)
	v_mfma_f32_16x16x32_bf16 v[42:45], v[208:211], v[212:215], v[42:45]
	v_mfma_f32_16x16x32_bf16 v[46:49], v[208:211], v[216:219], v[46:49]
	v_mfma_f32_16x16x32_bf16 v[10:13], v[208:211], v[220:223], v[10:13]
	v_mfma_f32_16x16x32_bf16 v[14:17], v[208:211], v[224:227], v[14:17]
	ds_read_b128 v[208:211], v244 offset:6976
	s_waitcnt vmcnt(13)
	ds_write_b128 v98, v[110:113] offset:27648
	s_waitcnt vmcnt(12)
	ds_write_b128 v98, v[114:117] offset:32256
	s_waitcnt lgkmcnt(7)
	v_mfma_f32_16x16x32_bf16 v[50:53], v[196:199], v[228:231], v[50:53]
	v_mfma_f32_16x16x32_bf16 v[54:57], v[196:199], v[232:235], v[54:57]
	v_mfma_f32_16x16x32_bf16 v[18:21], v[196:199], v[236:239], v[18:21]
	v_mfma_f32_16x16x32_bf16 v[22:25], v[196:199], v[240:243], v[22:25]
	s_waitcnt vmcnt(11)
	ds_write_b128 v98, v[118:121] offset:55296
	s_waitcnt vmcnt(10)
	ds_write_b128 v98, v[122:125] offset:59904
	s_waitcnt lgkmcnt(8)
	v_mfma_f32_16x16x32_bf16 v[58:61], v[200:203], v[228:231], v[58:61]
	v_mfma_f32_16x16x32_bf16 v[62:65], v[200:203], v[232:235], v[62:65]
	v_mfma_f32_16x16x32_bf16 v[26:29], v[200:203], v[236:239], v[26:29]
	v_mfma_f32_16x16x32_bf16 v[30:33], v[200:203], v[240:243], v[30:33]
	s_waitcnt vmcnt(9)
	ds_write_b128 v98, v[126:129] offset:64512
	s_waitcnt vmcnt(8)
	ds_write_b128 v99, v[132:135] offset:32256
	s_waitcnt lgkmcnt(0)
	s_barrier
	ds_read_b128 v[212:215], v245 offset:55296
	ds_read_b128 v[196:199], v244 offset:18432
	ds_read_b128 v[216:219], v245 offset:57600
	ds_read_b128 v[220:223], v245 offset:59904
	ds_read_b128 v[224:227], v245 offset:62208
	ds_read_b128 v[200:203], v244 offset:20736
	v_mfma_f32_16x16x32_bf16 v[34:37], v[204:207], v[228:231], v[34:37]
	v_mfma_f32_16x16x32_bf16 v[38:41], v[204:207], v[232:235], v[38:41]
	v_mfma_f32_16x16x32_bf16 v[2:5], v[204:207], v[236:239], v[2:5]
	v_mfma_f32_16x16x32_bf16 v[6:9], v[204:207], v[240:243], v[6:9]
	ds_read_b128 v[204:207], v244 offset:23040
	v_mfma_f32_16x16x32_bf16 v[42:45], v[208:211], v[228:231], v[42:45]
	v_mfma_f32_16x16x32_bf16 v[46:49], v[208:211], v[232:235], v[46:49]
	v_mfma_f32_16x16x32_bf16 v[10:13], v[208:211], v[236:239], v[10:13]
	v_mfma_f32_16x16x32_bf16 v[14:17], v[208:211], v[240:243], v[14:17]
	ds_read_b128 v[208:211], v244 offset:25344
	global_load_dwordx4 v[102:105], v[74:75], off offset:1408
	global_load_dwordx4 v[106:109], v[76:77], off offset:1408
	global_load_dwordx4 v[110:113], v[78:79], off offset:1408
	global_load_dwordx4 v[114:117], v[80:81], off offset:1408
	global_load_dwordx4 v[118:121], v[82:83], off offset:1408
	global_load_dwordx4 v[122:125], v[84:85], off offset:1408
	global_load_dwordx4 v[126:129], v[86:87], off offset:1408
	global_load_dwordx4 v[132:135], v[88:89], off offset:1408
	s_waitcnt lgkmcnt(6)
	v_mfma_f32_16x16x32_bf16 v[50:53], v[196:199], v[212:215], v[50:53]
	ds_read_b128 v[228:231], v245 offset:55360
	s_waitcnt lgkmcnt(6)
	v_mfma_f32_16x16x32_bf16 v[54:57], v[196:199], v[216:219], v[54:57]
	ds_read_b128 v[232:235], v245 offset:57664
	s_waitcnt lgkmcnt(6)
	v_mfma_f32_16x16x32_bf16 v[18:21], v[196:199], v[220:223], v[18:21]
	ds_read_b128 v[236:239], v245 offset:59968
	s_waitcnt lgkmcnt(6)
	v_mfma_f32_16x16x32_bf16 v[22:25], v[196:199], v[224:227], v[22:25]
	ds_read_b128 v[240:243], v245 offset:62272
	ds_read_b128 v[196:199], v244 offset:18496
	s_waitcnt lgkmcnt(7)
	v_mfma_f32_16x16x32_bf16 v[58:61], v[200:203], v[212:215], v[58:61]
	v_mfma_f32_16x16x32_bf16 v[62:65], v[200:203], v[216:219], v[62:65]
	v_mfma_f32_16x16x32_bf16 v[26:29], v[200:203], v[220:223], v[26:29]
	v_mfma_f32_16x16x32_bf16 v[30:33], v[200:203], v[224:227], v[30:33]
	ds_read_b128 v[200:203], v244 offset:20800
	s_waitcnt lgkmcnt(7)
	v_mfma_f32_16x16x32_bf16 v[34:37], v[204:207], v[212:215], v[34:37]
	v_mfma_f32_16x16x32_bf16 v[38:41], v[204:207], v[216:219], v[38:41]
	v_mfma_f32_16x16x32_bf16 v[2:5], v[204:207], v[220:223], v[2:5]
	v_mfma_f32_16x16x32_bf16 v[6:9], v[204:207], v[224:227], v[6:9]
	ds_read_b128 v[204:207], v244 offset:23104
	s_waitcnt vmcnt(15)
	ds_write_b128 v98, v[136:139]
	s_waitcnt vmcnt(14)
	ds_write_b128 v98, v[140:143] offset:4608
	s_waitcnt lgkmcnt(9)
	v_mfma_f32_16x16x32_bf16 v[42:45], v[208:211], v[212:215], v[42:45]
	v_mfma_f32_16x16x32_bf16 v[46:49], v[208:211], v[216:219], v[46:49]
	v_mfma_f32_16x16x32_bf16 v[10:13], v[208:211], v[220:223], v[10:13]
	v_mfma_f32_16x16x32_bf16 v[14:17], v[208:211], v[224:227], v[14:17]
	ds_read_b128 v[208:211], v244 offset:25408
	s_waitcnt vmcnt(13)
	ds_write_b128 v98, v[144:147] offset:9216
	s_waitcnt vmcnt(12)
	ds_write_b128 v98, v[148:151] offset:13824
	s_waitcnt lgkmcnt(7)
	v_mfma_f32_16x16x32_bf16 v[50:53], v[196:199], v[228:231], v[50:53]
	v_mfma_f32_16x16x32_bf16 v[54:57], v[196:199], v[232:235], v[54:57]
	v_mfma_f32_16x16x32_bf16 v[18:21], v[196:199], v[236:239], v[18:21]
	v_mfma_f32_16x16x32_bf16 v[22:25], v[196:199], v[240:243], v[22:25]
	s_waitcnt vmcnt(11)
	ds_write_b128 v98, v[152:155] offset:36864
	s_waitcnt vmcnt(10)
	ds_write_b128 v98, v[156:159] offset:41472
	s_waitcnt lgkmcnt(8)
	v_mfma_f32_16x16x32_bf16 v[58:61], v[200:203], v[228:231], v[58:61]
	v_mfma_f32_16x16x32_bf16 v[62:65], v[200:203], v[232:235], v[62:65]
	v_mfma_f32_16x16x32_bf16 v[26:29], v[200:203], v[236:239], v[26:29]
	v_mfma_f32_16x16x32_bf16 v[30:33], v[200:203], v[240:243], v[30:33]
	s_waitcnt vmcnt(9)
	ds_write_b128 v98, v[160:163] offset:46080
	s_waitcnt vmcnt(8)
	ds_write_b128 v98, v[164:167] offset:50688
	s_waitcnt lgkmcnt(0)
	s_barrier
	ds_read_b128 v[212:215], v245 offset:36864
	ds_read_b128 v[196:199], v244
	ds_read_b128 v[216:219], v245 offset:39168
	ds_read_b128 v[220:223], v245 offset:41472
	ds_read_b128 v[224:227], v245 offset:43776
	ds_read_b128 v[200:203], v244 offset:2304
	v_mfma_f32_16x16x32_bf16 v[34:37], v[204:207], v[228:231], v[34:37]
	v_mfma_f32_16x16x32_bf16 v[38:41], v[204:207], v[232:235], v[38:41]
	v_mfma_f32_16x16x32_bf16 v[2:5], v[204:207], v[236:239], v[2:5]
	v_mfma_f32_16x16x32_bf16 v[6:9], v[204:207], v[240:243], v[6:9]
	ds_read_b128 v[204:207], v244 offset:4608
	v_mfma_f32_16x16x32_bf16 v[42:45], v[208:211], v[228:231], v[42:45]
	v_mfma_f32_16x16x32_bf16 v[46:49], v[208:211], v[232:235], v[46:49]
	v_mfma_f32_16x16x32_bf16 v[10:13], v[208:211], v[236:239], v[10:13]
	v_mfma_f32_16x16x32_bf16 v[14:17], v[208:211], v[240:243], v[14:17]
	ds_read_b128 v[208:211], v244 offset:6912
	global_load_dwordx4 v[136:139], v[74:75], off offset:1536
	global_load_dwordx4 v[140:143], v[76:77], off offset:1536
	global_load_dwordx4 v[144:147], v[78:79], off offset:1536
	global_load_dwordx4 v[148:151], v[80:81], off offset:1536
	global_load_dwordx4 v[152:155], v[82:83], off offset:1536
	global_load_dwordx4 v[156:159], v[84:85], off offset:1536
	global_load_dwordx4 v[160:163], v[86:87], off offset:1536
	global_load_dwordx4 v[164:167], v[88:89], off offset:1536
	s_waitcnt lgkmcnt(6)
	v_mfma_f32_16x16x32_bf16 v[50:53], v[196:199], v[212:215], v[50:53]
	ds_read_b128 v[228:231], v245 offset:36928
	s_waitcnt lgkmcnt(6)
	v_mfma_f32_16x16x32_bf16 v[54:57], v[196:199], v[216:219], v[54:57]
	ds_read_b128 v[232:235], v245 offset:39232
	s_waitcnt lgkmcnt(6)
	v_mfma_f32_16x16x32_bf16 v[18:21], v[196:199], v[220:223], v[18:21]
	ds_read_b128 v[236:239], v245 offset:41536
	s_waitcnt lgkmcnt(6)
	v_mfma_f32_16x16x32_bf16 v[22:25], v[196:199], v[224:227], v[22:25]
	ds_read_b128 v[240:243], v245 offset:43840
	ds_read_b128 v[196:199], v244 offset:64
	s_waitcnt lgkmcnt(7)
	v_mfma_f32_16x16x32_bf16 v[58:61], v[200:203], v[212:215], v[58:61]
	v_mfma_f32_16x16x32_bf16 v[62:65], v[200:203], v[216:219], v[62:65]
	v_mfma_f32_16x16x32_bf16 v[26:29], v[200:203], v[220:223], v[26:29]
	v_mfma_f32_16x16x32_bf16 v[30:33], v[200:203], v[224:227], v[30:33]
	ds_read_b128 v[200:203], v244 offset:2368
	s_waitcnt lgkmcnt(7)
	v_mfma_f32_16x16x32_bf16 v[34:37], v[204:207], v[212:215], v[34:37]
	v_mfma_f32_16x16x32_bf16 v[38:41], v[204:207], v[216:219], v[38:41]
	v_mfma_f32_16x16x32_bf16 v[2:5], v[204:207], v[220:223], v[2:5]
	v_mfma_f32_16x16x32_bf16 v[6:9], v[204:207], v[224:227], v[6:9]
	ds_read_b128 v[204:207], v244 offset:4672
	s_waitcnt vmcnt(15)
	ds_write_b128 v98, v[102:105] offset:18432
	s_waitcnt vmcnt(14)
	ds_write_b128 v98, v[106:109] offset:23040
	s_waitcnt lgkmcnt(9)
	v_mfma_f32_16x16x32_bf16 v[42:45], v[208:211], v[212:215], v[42:45]
	v_mfma_f32_16x16x32_bf16 v[46:49], v[208:211], v[216:219], v[46:49]
	v_mfma_f32_16x16x32_bf16 v[10:13], v[208:211], v[220:223], v[10:13]
	v_mfma_f32_16x16x32_bf16 v[14:17], v[208:211], v[224:227], v[14:17]
	ds_read_b128 v[208:211], v244 offset:6976
	s_waitcnt vmcnt(13)
	ds_write_b128 v98, v[110:113] offset:27648
	s_waitcnt vmcnt(12)
	ds_write_b128 v98, v[114:117] offset:32256
	s_waitcnt lgkmcnt(7)
	v_mfma_f32_16x16x32_bf16 v[50:53], v[196:199], v[228:231], v[50:53]
	v_mfma_f32_16x16x32_bf16 v[54:57], v[196:199], v[232:235], v[54:57]
	v_mfma_f32_16x16x32_bf16 v[18:21], v[196:199], v[236:239], v[18:21]
	v_mfma_f32_16x16x32_bf16 v[22:25], v[196:199], v[240:243], v[22:25]
	s_waitcnt vmcnt(11)
	ds_write_b128 v98, v[118:121] offset:55296
	s_waitcnt vmcnt(10)
	ds_write_b128 v98, v[122:125] offset:59904
	s_waitcnt lgkmcnt(8)
	v_mfma_f32_16x16x32_bf16 v[58:61], v[200:203], v[228:231], v[58:61]
	v_mfma_f32_16x16x32_bf16 v[62:65], v[200:203], v[232:235], v[62:65]
	v_mfma_f32_16x16x32_bf16 v[26:29], v[200:203], v[236:239], v[26:29]
	v_mfma_f32_16x16x32_bf16 v[30:33], v[200:203], v[240:243], v[30:33]
	s_waitcnt vmcnt(9)
	ds_write_b128 v98, v[126:129] offset:64512
	s_waitcnt vmcnt(8)
	ds_write_b128 v99, v[132:135] offset:32256
	s_waitcnt lgkmcnt(0)
	s_barrier
	ds_read_b128 v[212:215], v245 offset:55296
	ds_read_b128 v[196:199], v244 offset:18432
	ds_read_b128 v[216:219], v245 offset:57600
	ds_read_b128 v[220:223], v245 offset:59904
	ds_read_b128 v[224:227], v245 offset:62208
	ds_read_b128 v[200:203], v244 offset:20736
	v_mfma_f32_16x16x32_bf16 v[34:37], v[204:207], v[228:231], v[34:37]
	v_mfma_f32_16x16x32_bf16 v[38:41], v[204:207], v[232:235], v[38:41]
	v_mfma_f32_16x16x32_bf16 v[2:5], v[204:207], v[236:239], v[2:5]
	v_mfma_f32_16x16x32_bf16 v[6:9], v[204:207], v[240:243], v[6:9]
	ds_read_b128 v[204:207], v244 offset:23040
	v_mfma_f32_16x16x32_bf16 v[42:45], v[208:211], v[228:231], v[42:45]
	v_mfma_f32_16x16x32_bf16 v[46:49], v[208:211], v[232:235], v[46:49]
	v_mfma_f32_16x16x32_bf16 v[10:13], v[208:211], v[236:239], v[10:13]
	v_mfma_f32_16x16x32_bf16 v[14:17], v[208:211], v[240:243], v[14:17]
	ds_read_b128 v[208:211], v244 offset:25344
	global_load_dwordx4 v[102:105], v[74:75], off offset:1664
	global_load_dwordx4 v[106:109], v[76:77], off offset:1664
	global_load_dwordx4 v[110:113], v[78:79], off offset:1664
	global_load_dwordx4 v[114:117], v[80:81], off offset:1664
	global_load_dwordx4 v[118:121], v[82:83], off offset:1664
	global_load_dwordx4 v[122:125], v[84:85], off offset:1664
	global_load_dwordx4 v[126:129], v[86:87], off offset:1664
	global_load_dwordx4 v[132:135], v[88:89], off offset:1664
	s_waitcnt lgkmcnt(6)
	v_mfma_f32_16x16x32_bf16 v[50:53], v[196:199], v[212:215], v[50:53]
	ds_read_b128 v[228:231], v245 offset:55360
	s_waitcnt lgkmcnt(6)
	v_mfma_f32_16x16x32_bf16 v[54:57], v[196:199], v[216:219], v[54:57]
	ds_read_b128 v[232:235], v245 offset:57664
	s_waitcnt lgkmcnt(6)
	v_mfma_f32_16x16x32_bf16 v[18:21], v[196:199], v[220:223], v[18:21]
	ds_read_b128 v[236:239], v245 offset:59968
	s_waitcnt lgkmcnt(6)
	v_mfma_f32_16x16x32_bf16 v[22:25], v[196:199], v[224:227], v[22:25]
	ds_read_b128 v[240:243], v245 offset:62272
	ds_read_b128 v[196:199], v244 offset:18496
	s_waitcnt lgkmcnt(7)
	v_mfma_f32_16x16x32_bf16 v[58:61], v[200:203], v[212:215], v[58:61]
	v_mfma_f32_16x16x32_bf16 v[62:65], v[200:203], v[216:219], v[62:65]
	v_mfma_f32_16x16x32_bf16 v[26:29], v[200:203], v[220:223], v[26:29]
	v_mfma_f32_16x16x32_bf16 v[30:33], v[200:203], v[224:227], v[30:33]
	ds_read_b128 v[200:203], v244 offset:20800
	s_waitcnt lgkmcnt(7)
	v_mfma_f32_16x16x32_bf16 v[34:37], v[204:207], v[212:215], v[34:37]
	v_mfma_f32_16x16x32_bf16 v[38:41], v[204:207], v[216:219], v[38:41]
	v_mfma_f32_16x16x32_bf16 v[2:5], v[204:207], v[220:223], v[2:5]
	v_mfma_f32_16x16x32_bf16 v[6:9], v[204:207], v[224:227], v[6:9]
	ds_read_b128 v[204:207], v244 offset:23104
	s_waitcnt vmcnt(15)
	ds_write_b128 v98, v[136:139]
	s_waitcnt vmcnt(14)
	ds_write_b128 v98, v[140:143] offset:4608
	s_waitcnt lgkmcnt(9)
	v_mfma_f32_16x16x32_bf16 v[42:45], v[208:211], v[212:215], v[42:45]
	v_mfma_f32_16x16x32_bf16 v[46:49], v[208:211], v[216:219], v[46:49]
	v_mfma_f32_16x16x32_bf16 v[10:13], v[208:211], v[220:223], v[10:13]
	v_mfma_f32_16x16x32_bf16 v[14:17], v[208:211], v[224:227], v[14:17]
	ds_read_b128 v[208:211], v244 offset:25408
	s_waitcnt vmcnt(13)
	ds_write_b128 v98, v[144:147] offset:9216
	s_waitcnt vmcnt(12)
	ds_write_b128 v98, v[148:151] offset:13824
	s_waitcnt lgkmcnt(7)
	v_mfma_f32_16x16x32_bf16 v[50:53], v[196:199], v[228:231], v[50:53]
	v_mfma_f32_16x16x32_bf16 v[54:57], v[196:199], v[232:235], v[54:57]
	v_mfma_f32_16x16x32_bf16 v[18:21], v[196:199], v[236:239], v[18:21]
	v_mfma_f32_16x16x32_bf16 v[22:25], v[196:199], v[240:243], v[22:25]
	s_waitcnt vmcnt(11)
	ds_write_b128 v98, v[152:155] offset:36864
	s_waitcnt vmcnt(10)
	ds_write_b128 v98, v[156:159] offset:41472
	s_waitcnt lgkmcnt(8)
	v_mfma_f32_16x16x32_bf16 v[58:61], v[200:203], v[228:231], v[58:61]
	v_mfma_f32_16x16x32_bf16 v[62:65], v[200:203], v[232:235], v[62:65]
	v_mfma_f32_16x16x32_bf16 v[26:29], v[200:203], v[236:239], v[26:29]
	v_mfma_f32_16x16x32_bf16 v[30:33], v[200:203], v[240:243], v[30:33]
	s_waitcnt vmcnt(9)
	ds_write_b128 v98, v[160:163] offset:46080
	s_waitcnt vmcnt(8)
	ds_write_b128 v98, v[164:167] offset:50688
	s_waitcnt lgkmcnt(0)
	s_barrier
	ds_read_b128 v[212:215], v245 offset:36864
	ds_read_b128 v[196:199], v244
	ds_read_b128 v[216:219], v245 offset:39168
	ds_read_b128 v[220:223], v245 offset:41472
	ds_read_b128 v[224:227], v245 offset:43776
	ds_read_b128 v[200:203], v244 offset:2304
	v_mfma_f32_16x16x32_bf16 v[34:37], v[204:207], v[228:231], v[34:37]
	v_mfma_f32_16x16x32_bf16 v[38:41], v[204:207], v[232:235], v[38:41]
	v_mfma_f32_16x16x32_bf16 v[2:5], v[204:207], v[236:239], v[2:5]
	v_mfma_f32_16x16x32_bf16 v[6:9], v[204:207], v[240:243], v[6:9]
	ds_read_b128 v[204:207], v244 offset:4608
	v_mfma_f32_16x16x32_bf16 v[42:45], v[208:211], v[228:231], v[42:45]
	v_mfma_f32_16x16x32_bf16 v[46:49], v[208:211], v[232:235], v[46:49]
	v_mfma_f32_16x16x32_bf16 v[10:13], v[208:211], v[236:239], v[10:13]
	v_mfma_f32_16x16x32_bf16 v[14:17], v[208:211], v[240:243], v[14:17]
	ds_read_b128 v[208:211], v244 offset:6912
	global_load_dwordx4 v[136:139], v[74:75], off offset:1792
	global_load_dwordx4 v[140:143], v[76:77], off offset:1792
	global_load_dwordx4 v[144:147], v[78:79], off offset:1792
	global_load_dwordx4 v[148:151], v[80:81], off offset:1792
	global_load_dwordx4 v[152:155], v[82:83], off offset:1792
	global_load_dwordx4 v[156:159], v[84:85], off offset:1792
	global_load_dwordx4 v[160:163], v[86:87], off offset:1792
	global_load_dwordx4 v[164:167], v[88:89], off offset:1792
	s_waitcnt lgkmcnt(6)
	v_mfma_f32_16x16x32_bf16 v[50:53], v[196:199], v[212:215], v[50:53]
	ds_read_b128 v[228:231], v245 offset:36928
	s_waitcnt lgkmcnt(6)
	v_mfma_f32_16x16x32_bf16 v[54:57], v[196:199], v[216:219], v[54:57]
	ds_read_b128 v[232:235], v245 offset:39232
	s_waitcnt lgkmcnt(6)
	v_mfma_f32_16x16x32_bf16 v[18:21], v[196:199], v[220:223], v[18:21]
	ds_read_b128 v[236:239], v245 offset:41536
	s_waitcnt lgkmcnt(6)
	v_mfma_f32_16x16x32_bf16 v[22:25], v[196:199], v[224:227], v[22:25]
	ds_read_b128 v[240:243], v245 offset:43840
	ds_read_b128 v[196:199], v244 offset:64
	s_waitcnt lgkmcnt(7)
	v_mfma_f32_16x16x32_bf16 v[58:61], v[200:203], v[212:215], v[58:61]
	v_mfma_f32_16x16x32_bf16 v[62:65], v[200:203], v[216:219], v[62:65]
	v_mfma_f32_16x16x32_bf16 v[26:29], v[200:203], v[220:223], v[26:29]
	v_mfma_f32_16x16x32_bf16 v[30:33], v[200:203], v[224:227], v[30:33]
	ds_read_b128 v[200:203], v244 offset:2368
	s_waitcnt lgkmcnt(7)
	v_mfma_f32_16x16x32_bf16 v[34:37], v[204:207], v[212:215], v[34:37]
	v_mfma_f32_16x16x32_bf16 v[38:41], v[204:207], v[216:219], v[38:41]
	v_mfma_f32_16x16x32_bf16 v[2:5], v[204:207], v[220:223], v[2:5]
	v_mfma_f32_16x16x32_bf16 v[6:9], v[204:207], v[224:227], v[6:9]
	ds_read_b128 v[204:207], v244 offset:4672
	s_waitcnt vmcnt(15)
	ds_write_b128 v98, v[102:105] offset:18432
	s_waitcnt vmcnt(14)
	ds_write_b128 v98, v[106:109] offset:23040
	s_waitcnt lgkmcnt(9)
	v_mfma_f32_16x16x32_bf16 v[42:45], v[208:211], v[212:215], v[42:45]
	v_mfma_f32_16x16x32_bf16 v[46:49], v[208:211], v[216:219], v[46:49]
	v_mfma_f32_16x16x32_bf16 v[10:13], v[208:211], v[220:223], v[10:13]
	v_mfma_f32_16x16x32_bf16 v[14:17], v[208:211], v[224:227], v[14:17]
	ds_read_b128 v[208:211], v244 offset:6976
	s_waitcnt vmcnt(13)
	ds_write_b128 v98, v[110:113] offset:27648
	s_waitcnt vmcnt(12)
	ds_write_b128 v98, v[114:117] offset:32256
	s_waitcnt lgkmcnt(7)
	v_mfma_f32_16x16x32_bf16 v[50:53], v[196:199], v[228:231], v[50:53]
	v_mfma_f32_16x16x32_bf16 v[54:57], v[196:199], v[232:235], v[54:57]
	v_mfma_f32_16x16x32_bf16 v[18:21], v[196:199], v[236:239], v[18:21]
	v_mfma_f32_16x16x32_bf16 v[22:25], v[196:199], v[240:243], v[22:25]
	s_waitcnt vmcnt(11)
	ds_write_b128 v98, v[118:121] offset:55296
	s_waitcnt vmcnt(10)
	ds_write_b128 v98, v[122:125] offset:59904
	s_waitcnt lgkmcnt(8)
	v_mfma_f32_16x16x32_bf16 v[58:61], v[200:203], v[228:231], v[58:61]
	v_mfma_f32_16x16x32_bf16 v[62:65], v[200:203], v[232:235], v[62:65]
	v_mfma_f32_16x16x32_bf16 v[26:29], v[200:203], v[236:239], v[26:29]
	v_mfma_f32_16x16x32_bf16 v[30:33], v[200:203], v[240:243], v[30:33]
	s_waitcnt vmcnt(9)
	ds_write_b128 v98, v[126:129] offset:64512
	s_waitcnt vmcnt(8)
	ds_write_b128 v99, v[132:135] offset:32256
	s_waitcnt lgkmcnt(0)
	s_barrier
	ds_read_b128 v[212:215], v245 offset:55296
	ds_read_b128 v[196:199], v244 offset:18432
	ds_read_b128 v[216:219], v245 offset:57600
	ds_read_b128 v[220:223], v245 offset:59904
	ds_read_b128 v[224:227], v245 offset:62208
	ds_read_b128 v[200:203], v244 offset:20736
	v_mfma_f32_16x16x32_bf16 v[34:37], v[204:207], v[228:231], v[34:37]
	v_mfma_f32_16x16x32_bf16 v[38:41], v[204:207], v[232:235], v[38:41]
	v_mfma_f32_16x16x32_bf16 v[2:5], v[204:207], v[236:239], v[2:5]
	v_mfma_f32_16x16x32_bf16 v[6:9], v[204:207], v[240:243], v[6:9]
	ds_read_b128 v[204:207], v244 offset:23040
	v_mfma_f32_16x16x32_bf16 v[42:45], v[208:211], v[228:231], v[42:45]
	v_mfma_f32_16x16x32_bf16 v[46:49], v[208:211], v[232:235], v[46:49]
	v_mfma_f32_16x16x32_bf16 v[10:13], v[208:211], v[236:239], v[10:13]
	v_mfma_f32_16x16x32_bf16 v[14:17], v[208:211], v[240:243], v[14:17]
	ds_read_b128 v[208:211], v244 offset:25344
	global_load_dwordx4 v[102:105], v[74:75], off offset:1920
	s_nop 0
	global_load_dwordx4 v[74:77], v[76:77], off offset:1920
	s_nop 0
	global_load_dwordx4 v[106:109], v[78:79], off offset:1920
	s_nop 0
	global_load_dwordx4 v[78:81], v[80:81], off offset:1920
	s_nop 0
	global_load_dwordx4 v[110:113], v[82:83], off offset:1920
	s_nop 0
	global_load_dwordx4 v[82:85], v[84:85], off offset:1920
	s_nop 0
	global_load_dwordx4 v[114:117], v[86:87], off offset:1920
	s_nop 0
	global_load_dwordx4 v[86:89], v[88:89], off offset:1920
	s_waitcnt lgkmcnt(6)
	v_mfma_f32_16x16x32_bf16 v[50:53], v[196:199], v[212:215], v[50:53]
	ds_read_b128 v[228:231], v245 offset:55360
	s_waitcnt lgkmcnt(6)
	v_mfma_f32_16x16x32_bf16 v[54:57], v[196:199], v[216:219], v[54:57]
	ds_read_b128 v[232:235], v245 offset:57664
	s_waitcnt lgkmcnt(6)
	v_mfma_f32_16x16x32_bf16 v[18:21], v[196:199], v[220:223], v[18:21]
	ds_read_b128 v[236:239], v245 offset:59968
	s_waitcnt lgkmcnt(6)
	v_mfma_f32_16x16x32_bf16 v[22:25], v[196:199], v[224:227], v[22:25]
	ds_read_b128 v[240:243], v245 offset:62272
	ds_read_b128 v[196:199], v244 offset:18496
	s_waitcnt lgkmcnt(7)
	v_mfma_f32_16x16x32_bf16 v[58:61], v[200:203], v[212:215], v[58:61]
	v_mfma_f32_16x16x32_bf16 v[62:65], v[200:203], v[216:219], v[62:65]
	v_mfma_f32_16x16x32_bf16 v[26:29], v[200:203], v[220:223], v[26:29]
	v_mfma_f32_16x16x32_bf16 v[30:33], v[200:203], v[224:227], v[30:33]
	ds_read_b128 v[200:203], v244 offset:20800
	s_waitcnt lgkmcnt(7)
	v_mfma_f32_16x16x32_bf16 v[34:37], v[204:207], v[212:215], v[34:37]
	v_mfma_f32_16x16x32_bf16 v[38:41], v[204:207], v[216:219], v[38:41]
	v_mfma_f32_16x16x32_bf16 v[2:5], v[204:207], v[220:223], v[2:5]
	v_mfma_f32_16x16x32_bf16 v[6:9], v[204:207], v[224:227], v[6:9]
	ds_read_b128 v[204:207], v244 offset:23104
	s_waitcnt vmcnt(15)
	ds_write_b128 v98, v[136:139]
	s_waitcnt vmcnt(14)
	ds_write_b128 v98, v[140:143] offset:4608
	s_waitcnt lgkmcnt(9)
	v_mfma_f32_16x16x32_bf16 v[42:45], v[208:211], v[212:215], v[42:45]
	v_mfma_f32_16x16x32_bf16 v[46:49], v[208:211], v[216:219], v[46:49]
	v_mfma_f32_16x16x32_bf16 v[10:13], v[208:211], v[220:223], v[10:13]
	v_mfma_f32_16x16x32_bf16 v[14:17], v[208:211], v[224:227], v[14:17]
	ds_read_b128 v[208:211], v244 offset:25408
	s_waitcnt vmcnt(13)
	ds_write_b128 v98, v[144:147] offset:9216
	s_waitcnt vmcnt(12)
	ds_write_b128 v98, v[148:151] offset:13824
	s_waitcnt lgkmcnt(7)
	v_mfma_f32_16x16x32_bf16 v[50:53], v[196:199], v[228:231], v[50:53]
	v_mfma_f32_16x16x32_bf16 v[54:57], v[196:199], v[232:235], v[54:57]
	v_mfma_f32_16x16x32_bf16 v[18:21], v[196:199], v[236:239], v[18:21]
	v_mfma_f32_16x16x32_bf16 v[22:25], v[196:199], v[240:243], v[22:25]
	s_waitcnt vmcnt(11)
	ds_write_b128 v98, v[152:155] offset:36864
	s_waitcnt vmcnt(10)
	ds_write_b128 v98, v[156:159] offset:41472
	s_waitcnt lgkmcnt(8)
	v_mfma_f32_16x16x32_bf16 v[58:61], v[200:203], v[228:231], v[58:61]
	v_mfma_f32_16x16x32_bf16 v[62:65], v[200:203], v[232:235], v[62:65]
	v_mfma_f32_16x16x32_bf16 v[26:29], v[200:203], v[236:239], v[26:29]
	v_mfma_f32_16x16x32_bf16 v[30:33], v[200:203], v[240:243], v[30:33]
	s_waitcnt vmcnt(9)
	ds_write_b128 v98, v[160:163] offset:46080
	s_waitcnt vmcnt(8)
	ds_write_b128 v98, v[164:167] offset:50688
	s_waitcnt lgkmcnt(0)
	s_barrier
	ds_read_b128 v[212:215], v245 offset:36864
	ds_read_b128 v[196:199], v244
	ds_read_b128 v[216:219], v245 offset:39168
	ds_read_b128 v[220:223], v245 offset:41472
	ds_read_b128 v[224:227], v245 offset:43776
	ds_read_b128 v[200:203], v244 offset:2304
	v_mfma_f32_16x16x32_bf16 v[34:37], v[204:207], v[228:231], v[34:37]
	v_mfma_f32_16x16x32_bf16 v[38:41], v[204:207], v[232:235], v[38:41]
	v_mfma_f32_16x16x32_bf16 v[2:5], v[204:207], v[236:239], v[2:5]
	v_mfma_f32_16x16x32_bf16 v[6:9], v[204:207], v[240:243], v[6:9]
	ds_read_b128 v[204:207], v244 offset:4608
	v_mfma_f32_16x16x32_bf16 v[42:45], v[208:211], v[228:231], v[42:45]
	v_mfma_f32_16x16x32_bf16 v[46:49], v[208:211], v[232:235], v[46:49]
	v_mfma_f32_16x16x32_bf16 v[10:13], v[208:211], v[236:239], v[10:13]
	v_mfma_f32_16x16x32_bf16 v[14:17], v[208:211], v[240:243], v[14:17]
	ds_read_b128 v[208:211], v244 offset:6912
	s_waitcnt lgkmcnt(6)
	v_mfma_f32_16x16x32_bf16 v[50:53], v[196:199], v[212:215], v[50:53]
	ds_read_b128 v[228:231], v245 offset:36928
	s_waitcnt lgkmcnt(6)
	v_mfma_f32_16x16x32_bf16 v[54:57], v[196:199], v[216:219], v[54:57]
	ds_read_b128 v[232:235], v245 offset:39232
	s_waitcnt lgkmcnt(6)
	v_mfma_f32_16x16x32_bf16 v[18:21], v[196:199], v[220:223], v[18:21]
	ds_read_b128 v[236:239], v245 offset:41536
	s_waitcnt lgkmcnt(6)
	v_mfma_f32_16x16x32_bf16 v[22:25], v[196:199], v[224:227], v[22:25]
	ds_read_b128 v[240:243], v245 offset:43840
	ds_read_b128 v[196:199], v244 offset:64
	s_waitcnt lgkmcnt(7)
	v_mfma_f32_16x16x32_bf16 v[58:61], v[200:203], v[212:215], v[58:61]
	v_mfma_f32_16x16x32_bf16 v[62:65], v[200:203], v[216:219], v[62:65]
	v_mfma_f32_16x16x32_bf16 v[26:29], v[200:203], v[220:223], v[26:29]
	v_mfma_f32_16x16x32_bf16 v[30:33], v[200:203], v[224:227], v[30:33]
	ds_read_b128 v[200:203], v244 offset:2368
	s_waitcnt lgkmcnt(7)
	v_mfma_f32_16x16x32_bf16 v[34:37], v[204:207], v[212:215], v[34:37]
	v_mfma_f32_16x16x32_bf16 v[38:41], v[204:207], v[216:219], v[38:41]
	v_mfma_f32_16x16x32_bf16 v[2:5], v[204:207], v[220:223], v[2:5]
	v_mfma_f32_16x16x32_bf16 v[6:9], v[204:207], v[224:227], v[6:9]
	ds_read_b128 v[204:207], v244 offset:4672
	s_waitcnt vmcnt(7)
	ds_write_b128 v98, v[102:105] offset:18432
	s_waitcnt vmcnt(6)
	ds_write_b128 v98, v[74:77] offset:23040
	s_waitcnt lgkmcnt(9)
	v_mfma_f32_16x16x32_bf16 v[42:45], v[208:211], v[212:215], v[42:45]
	v_mfma_f32_16x16x32_bf16 v[46:49], v[208:211], v[216:219], v[46:49]
	v_mfma_f32_16x16x32_bf16 v[10:13], v[208:211], v[220:223], v[10:13]
	v_mfma_f32_16x16x32_bf16 v[14:17], v[208:211], v[224:227], v[14:17]
	ds_read_b128 v[208:211], v244 offset:6976
	s_waitcnt vmcnt(5)
	ds_write_b128 v98, v[106:109] offset:27648
	s_waitcnt vmcnt(4)
	ds_write_b128 v98, v[78:81] offset:32256
	s_waitcnt lgkmcnt(7)
	v_mfma_f32_16x16x32_bf16 v[50:53], v[196:199], v[228:231], v[50:53]
	v_mfma_f32_16x16x32_bf16 v[54:57], v[196:199], v[232:235], v[54:57]
	v_mfma_f32_16x16x32_bf16 v[18:21], v[196:199], v[236:239], v[18:21]
	v_mfma_f32_16x16x32_bf16 v[22:25], v[196:199], v[240:243], v[22:25]
	s_waitcnt vmcnt(3)
	ds_write_b128 v98, v[110:113] offset:55296
	s_waitcnt vmcnt(2)
	ds_write_b128 v98, v[82:85] offset:59904
	s_waitcnt lgkmcnt(8)
	v_mfma_f32_16x16x32_bf16 v[58:61], v[200:203], v[228:231], v[58:61]
	v_mfma_f32_16x16x32_bf16 v[62:65], v[200:203], v[232:235], v[62:65]
	v_mfma_f32_16x16x32_bf16 v[26:29], v[200:203], v[236:239], v[26:29]
	v_mfma_f32_16x16x32_bf16 v[30:33], v[200:203], v[240:243], v[30:33]
	s_waitcnt vmcnt(1)
	ds_write_b128 v98, v[114:117] offset:64512
	s_waitcnt vmcnt(0)
	ds_write_b128 v99, v[86:89] offset:32256
	s_waitcnt lgkmcnt(0)
	s_barrier
	ds_read_b128 v[212:215], v245 offset:55296
	ds_read_b128 v[196:199], v244 offset:18432
	ds_read_b128 v[216:219], v245 offset:57600
	ds_read_b128 v[220:223], v245 offset:59904
	ds_read_b128 v[224:227], v245 offset:62208
	ds_read_b128 v[200:203], v244 offset:20736
	v_mfma_f32_16x16x32_bf16 v[34:37], v[204:207], v[228:231], v[34:37]
	v_mfma_f32_16x16x32_bf16 v[38:41], v[204:207], v[232:235], v[38:41]
	v_mfma_f32_16x16x32_bf16 v[2:5], v[204:207], v[236:239], v[2:5]
	v_mfma_f32_16x16x32_bf16 v[6:9], v[204:207], v[240:243], v[6:9]
	ds_read_b128 v[204:207], v244 offset:23040
	v_mfma_f32_16x16x32_bf16 v[42:45], v[208:211], v[228:231], v[42:45]
	v_mfma_f32_16x16x32_bf16 v[46:49], v[208:211], v[232:235], v[46:49]
	v_mfma_f32_16x16x32_bf16 v[10:13], v[208:211], v[236:239], v[10:13]
	v_mfma_f32_16x16x32_bf16 v[14:17], v[208:211], v[240:243], v[14:17]
	ds_read_b128 v[208:211], v244 offset:25344
	s_waitcnt lgkmcnt(6)
	v_mfma_f32_16x16x32_bf16 v[50:53], v[196:199], v[212:215], v[50:53]
	ds_read_b128 v[228:231], v245 offset:55360
	s_waitcnt lgkmcnt(6)
	v_mfma_f32_16x16x32_bf16 v[54:57], v[196:199], v[216:219], v[54:57]
	ds_read_b128 v[232:235], v245 offset:57664
	s_waitcnt lgkmcnt(6)
	v_mfma_f32_16x16x32_bf16 v[18:21], v[196:199], v[220:223], v[18:21]
	ds_read_b128 v[236:239], v245 offset:59968
	s_waitcnt lgkmcnt(6)
	v_mfma_f32_16x16x32_bf16 v[22:25], v[196:199], v[224:227], v[22:25]
	ds_read_b128 v[240:243], v245 offset:62272
	ds_read_b128 v[196:199], v244 offset:18496
	s_waitcnt lgkmcnt(7)
	v_mfma_f32_16x16x32_bf16 v[58:61], v[200:203], v[212:215], v[58:61]
	v_mfma_f32_16x16x32_bf16 v[62:65], v[200:203], v[216:219], v[62:65]
	v_mfma_f32_16x16x32_bf16 v[26:29], v[200:203], v[220:223], v[26:29]
	v_mfma_f32_16x16x32_bf16 v[30:33], v[200:203], v[224:227], v[30:33]
	ds_read_b128 v[200:203], v244 offset:20800
	s_waitcnt lgkmcnt(7)
	v_mfma_f32_16x16x32_bf16 v[34:37], v[204:207], v[212:215], v[34:37]
	v_mfma_f32_16x16x32_bf16 v[38:41], v[204:207], v[216:219], v[38:41]
	v_mfma_f32_16x16x32_bf16 v[2:5], v[204:207], v[220:223], v[2:5]
	v_mfma_f32_16x16x32_bf16 v[6:9], v[204:207], v[224:227], v[6:9]
	ds_read_b128 v[204:207], v244 offset:23104
	s_waitcnt lgkmcnt(7)
	v_mfma_f32_16x16x32_bf16 v[42:45], v[208:211], v[212:215], v[42:45]
	v_mfma_f32_16x16x32_bf16 v[46:49], v[208:211], v[216:219], v[46:49]
	v_mfma_f32_16x16x32_bf16 v[10:13], v[208:211], v[220:223], v[10:13]
	v_mfma_f32_16x16x32_bf16 v[14:17], v[208:211], v[224:227], v[14:17]
	ds_read_b128 v[208:211], v244 offset:25408
	s_waitcnt lgkmcnt(3)
	v_mfma_f32_16x16x32_bf16 v[50:53], v[196:199], v[228:231], v[50:53]
	v_mfma_f32_16x16x32_bf16 v[54:57], v[196:199], v[232:235], v[54:57]
	v_mfma_f32_16x16x32_bf16 v[18:21], v[196:199], v[236:239], v[18:21]
	v_mfma_f32_16x16x32_bf16 v[22:25], v[196:199], v[240:243], v[22:25]
	s_waitcnt lgkmcnt(2)
	v_mfma_f32_16x16x32_bf16 v[58:61], v[200:203], v[228:231], v[58:61]
	v_mfma_f32_16x16x32_bf16 v[62:65], v[200:203], v[232:235], v[62:65]
	v_mfma_f32_16x16x32_bf16 v[26:29], v[200:203], v[236:239], v[26:29]
	v_mfma_f32_16x16x32_bf16 v[30:33], v[200:203], v[240:243], v[30:33]
	s_lshr_b32 s14, s2, 3
	s_bfe_u32 s13, s2, 0x10002
	s_cmp_lt_i32 s14, 1
	s_mov_b64 s[2:3], -1
	s_waitcnt lgkmcnt(0)
	s_barrier
	v_mfma_f32_16x16x32_bf16 v[34:37], v[204:207], v[228:231], v[34:37]
	v_mfma_f32_16x16x32_bf16 v[38:41], v[204:207], v[232:235], v[38:41]
	v_mfma_f32_16x16x32_bf16 v[2:5], v[204:207], v[236:239], v[2:5]
	v_mfma_f32_16x16x32_bf16 v[6:9], v[204:207], v[240:243], v[6:9]
	v_mfma_f32_16x16x32_bf16 v[42:45], v[208:211], v[228:231], v[42:45]
	v_mfma_f32_16x16x32_bf16 v[46:49], v[208:211], v[232:235], v[46:49]
	v_mfma_f32_16x16x32_bf16 v[10:13], v[208:211], v[236:239], v[10:13]
	v_mfma_f32_16x16x32_bf16 v[14:17], v[208:211], v[240:243], v[14:17]
	s_nop 7
	v_permlane16_swap_b32_e32 v50, v54
	v_permlane16_swap_b32_e32 v51, v55
	v_permlane16_swap_b32_e32 v52, v56
	v_permlane16_swap_b32_e32 v53, v57
	v_permlane16_swap_b32_e32 v58, v62
	v_permlane16_swap_b32_e32 v59, v63
	v_permlane16_swap_b32_e32 v60, v64
	v_permlane16_swap_b32_e32 v61, v65
	v_permlane16_swap_b32_e32 v18, v22
	v_permlane16_swap_b32_e32 v19, v23
	v_permlane16_swap_b32_e32 v20, v24
	v_permlane16_swap_b32_e32 v21, v25
	v_permlane16_swap_b32_e32 v26, v30
	v_permlane16_swap_b32_e32 v27, v31
	v_permlane16_swap_b32_e32 v28, v32
	v_permlane16_swap_b32_e32 v29, v33
	v_permlane16_swap_b32_e32 v34, v38
	v_permlane16_swap_b32_e32 v35, v39
	v_permlane16_swap_b32_e32 v36, v40
	v_permlane16_swap_b32_e32 v37, v41
	v_permlane16_swap_b32_e32 v42, v46
	v_permlane16_swap_b32_e32 v43, v47
	v_permlane16_swap_b32_e32 v44, v48
	v_permlane16_swap_b32_e32 v45, v49
	v_permlane16_swap_b32_e32 v2, v6
	v_permlane16_swap_b32_e32 v3, v7
	v_permlane16_swap_b32_e32 v4, v8
	v_permlane16_swap_b32_e32 v5, v9
	v_permlane16_swap_b32_e32 v10, v14
	v_permlane16_swap_b32_e32 v11, v15
	v_permlane16_swap_b32_e32 v12, v16
	v_permlane16_swap_b32_e32 v13, v17
	v_permlane32_swap_b32_e32 v50, v54
	v_permlane32_swap_b32_e32 v51, v55
	v_permlane32_swap_b32_e32 v52, v56
	v_permlane32_swap_b32_e32 v53, v57
	v_permlane32_swap_b32_e32 v58, v62
	v_permlane32_swap_b32_e32 v59, v63
	v_permlane32_swap_b32_e32 v60, v64
	v_permlane32_swap_b32_e32 v61, v65
	v_permlane32_swap_b32_e32 v18, v22
	v_permlane32_swap_b32_e32 v19, v23
	v_permlane32_swap_b32_e32 v20, v24
	v_permlane32_swap_b32_e32 v21, v25
	v_permlane32_swap_b32_e32 v26, v30
	v_permlane32_swap_b32_e32 v27, v31
	v_permlane32_swap_b32_e32 v28, v32
	v_permlane32_swap_b32_e32 v29, v33
	v_permlane32_swap_b32_e32 v34, v38
	v_permlane32_swap_b32_e32 v35, v39
	v_permlane32_swap_b32_e32 v36, v40
	v_permlane32_swap_b32_e32 v37, v41
	v_permlane32_swap_b32_e32 v42, v46
	v_permlane32_swap_b32_e32 v43, v47
	v_permlane32_swap_b32_e32 v44, v48
	v_permlane32_swap_b32_e32 v45, v49
	v_permlane32_swap_b32_e32 v2, v6
	v_permlane32_swap_b32_e32 v3, v7
	v_permlane32_swap_b32_e32 v4, v8
	v_permlane32_swap_b32_e32 v5, v9
	v_permlane32_swap_b32_e32 v10, v14
	v_permlane32_swap_b32_e32 v11, v15
	v_permlane32_swap_b32_e32 v12, v16
	v_permlane32_swap_b32_e32 v13, v17
	s_cbranch_scc1 .LBB0_1647
	s_and_b32 s2, 0xffff, s14
	s_cmp_lg_u32 s2, 1
	s_mov_b64 s[2:3], -1
	s_cbranch_scc0 .LBB0_1644
	s_cmp_eq_u32 s13, 0
	s_cselect_b32 s12, 3, 10
	s_mov_b64 s[2:3], 0

.LBB0_1720:
	s_lshr_b32 s8, s0, 2
	s_lshl_b32 s0, s0, 7
	s_and_b32 s7, s0, 0x180
	v_or_b32_e32 v2, s7, v93
	v_lshlrev_b32_e32 v74, 10, v2
	s_add_i32 s8, s8, s4
	v_lshl_add_u64 v[66:67], v[76:77], 0, v[74:75]
	v_add_lshl_u32 v74, s7, v94, 10
	s_lshl_b32 s0, s8, 7
	v_lshl_add_u64 v[68:69], v[76:77], 0, v[74:75]
	v_add_lshl_u32 v74, s7, v95, 10
	v_lshl_add_u64 v[70:71], v[76:77], 0, v[74:75]
	v_add_lshl_u32 v74, s7, v96, 10
	v_or_b32_e32 v2, s0, v93
	v_lshl_add_u64 v[72:73], v[76:77], 0, v[74:75]
	v_lshlrev_b32_e32 v74, 10, v2
	v_lshl_add_u64 v[84:85], v[78:79], 0, v[74:75]
	v_add_lshl_u32 v74, s0, v94, 10
	v_lshl_add_u64 v[86:87], v[78:79], 0, v[74:75]
	v_add_lshl_u32 v74, s0, v95, 10
	v_lshl_add_u64 v[88:89], v[78:79], 0, v[74:75]
	v_add_lshl_u32 v74, s0, v96, 10
	v_lshl_add_u64 v[90:91], v[78:79], 0, v[74:75]
	global_load_dwordx4 v[2:5], v[66:67], off
	global_load_dwordx4 v[6:9], v[68:69], off
	global_load_dwordx4 v[10:13], v[70:71], off
	global_load_dwordx4 v[14:17], v[72:73], off
	global_load_dwordx4 v[18:21], v[84:85], off
	global_load_dwordx4 v[22:25], v[86:87], off
	global_load_dwordx4 v[26:29], v[88:89], off
	global_load_dwordx4 v[30:33], v[90:91], off
	global_load_dwordx4 v[102:105], v[66:67], off offset:128
	global_load_dwordx4 v[106:109], v[68:69], off offset:128
	global_load_dwordx4 v[110:113], v[70:71], off offset:128
	global_load_dwordx4 v[114:117], v[72:73], off offset:128
	global_load_dwordx4 v[118:121], v[84:85], off offset:128
	global_load_dwordx4 v[122:125], v[86:87], off offset:128
	global_load_dwordx4 v[126:129], v[88:89], off offset:128
	global_load_dwordx4 v[132:135], v[90:91], off offset:128
	s_waitcnt vmcnt(15)
	ds_write_b128 v100, v[2:5]
	s_waitcnt vmcnt(14)
	ds_write_b128 v100, v[6:9] offset:4608
	s_waitcnt vmcnt(13)
	ds_write_b128 v100, v[10:13] offset:9216
	s_waitcnt vmcnt(12)
	ds_write_b128 v100, v[14:17] offset:13824
	s_waitcnt vmcnt(11)
	ds_write_b128 v100, v[18:21] offset:36864
	s_waitcnt vmcnt(10)
	ds_write_b128 v100, v[22:25] offset:41472
	s_waitcnt vmcnt(9)
	ds_write_b128 v100, v[26:29] offset:46080
	s_waitcnt vmcnt(8)
	ds_write_b128 v100, v[30:33] offset:50688
	s_waitcnt lgkmcnt(0)
	s_barrier
	global_load_dwordx4 v[136:139], v[66:67], off offset:256
	global_load_dwordx4 v[140:143], v[68:69], off offset:256
	global_load_dwordx4 v[144:147], v[70:71], off offset:256
	global_load_dwordx4 v[148:151], v[72:73], off offset:256
	global_load_dwordx4 v[152:155], v[84:85], off offset:256
	global_load_dwordx4 v[156:159], v[86:87], off offset:256
	global_load_dwordx4 v[160:163], v[88:89], off offset:256
	global_load_dwordx4 v[164:167], v[90:91], off offset:256
	v_and_b32_e32 v246, 15, v1
	v_add_u32_e32 v246, 4, v246
	v_bfe_u32 v246, v246, 3, 1
	v_bfe_u32 v249, v1, 4, 2
	v_xor_b32_e32 v246, v246, v249
	v_bfe_u32 v249, v1, 5, 1
	v_sub_u32_e32 v246, v246, v249
	v_lshlrev_b32_e32 v246, 4, v246
	v_bfe_u32 v249, v1, 4, 1
	v_mul_u32_u24_e32 v249, 0x900, v249
	v_sub_u32_e32 v246, v246, v249
	v_add_u32_e32 v244, v246, v98
	v_add_u32_e32 v245, v246, v99
	ds_read_b128 v[212:215], v245 offset:36864
	ds_read_b128 v[196:199], v244
	ds_read_b128 v[216:219], v245 offset:39168
	ds_read_b128 v[220:223], v245 offset:41472
	ds_read_b128 v[224:227], v245 offset:43776
	ds_read_b128 v[200:203], v244 offset:2304
	ds_read_b128 v[204:207], v244 offset:4608
	ds_read_b128 v[208:211], v244 offset:6912
	s_waitcnt lgkmcnt(6)
	v_mfma_f32_16x16x32_bf16 v[50:53], v[196:199], v[212:215], 0
	ds_read_b128 v[228:231], v245 offset:36928
	s_waitcnt lgkmcnt(6)
	v_mfma_f32_16x16x32_bf16 v[54:57], v[196:199], v[216:219], 0
	ds_read_b128 v[232:235], v245 offset:39232
	s_waitcnt lgkmcnt(6)
	v_mfma_f32_16x16x32_bf16 v[18:21], v[196:199], v[220:223], 0
	ds_read_b128 v[236:239], v245 offset:41536
	s_waitcnt lgkmcnt(6)
	v_mfma_f32_16x16x32_bf16 v[22:25], v[196:199], v[224:227], 0
	ds_read_b128 v[240:243], v245 offset:43840
	ds_read_b128 v[196:199], v244 offset:64
	s_waitcnt lgkmcnt(7)
	v_mfma_f32_16x16x32_bf16 v[58:61], v[200:203], v[212:215], 0
	v_mfma_f32_16x16x32_bf16 v[62:65], v[200:203], v[216:219], 0
	v_mfma_f32_16x16x32_bf16 v[26:29], v[200:203], v[220:223], 0
	v_mfma_f32_16x16x32_bf16 v[30:33], v[200:203], v[224:227], 0
	ds_read_b128 v[200:203], v244 offset:2368
	s_waitcnt lgkmcnt(7)
	v_mfma_f32_16x16x32_bf16 v[34:37], v[204:207], v[212:215], 0
	v_mfma_f32_16x16x32_bf16 v[38:41], v[204:207], v[216:219], 0
	v_mfma_f32_16x16x32_bf16 v[2:5], v[204:207], v[220:223], 0
	v_mfma_f32_16x16x32_bf16 v[6:9], v[204:207], v[224:227], 0
	ds_read_b128 v[204:207], v244 offset:4672
	s_waitcnt vmcnt(15)
	ds_write_b128 v100, v[102:105] offset:18432
	s_waitcnt vmcnt(14)
	ds_write_b128 v100, v[106:109] offset:23040
	s_waitcnt lgkmcnt(9)
	v_mfma_f32_16x16x32_bf16 v[42:45], v[208:211], v[212:215], 0
	v_mfma_f32_16x16x32_bf16 v[46:49], v[208:211], v[216:219], 0
	v_mfma_f32_16x16x32_bf16 v[10:13], v[208:211], v[220:223], 0
	v_mfma_f32_16x16x32_bf16 v[14:17], v[208:211], v[224:227], 0
	ds_read_b128 v[208:211], v244 offset:6976
	s_waitcnt vmcnt(13)
	ds_write_b128 v100, v[110:113] offset:27648
	s_waitcnt vmcnt(12)
	ds_write_b128 v100, v[114:117] offset:32256
	s_waitcnt lgkmcnt(7)
	v_mfma_f32_16x16x32_bf16 v[50:53], v[196:199], v[228:231], v[50:53]
	v_mfma_f32_16x16x32_bf16 v[54:57], v[196:199], v[232:235], v[54:57]
	v_mfma_f32_16x16x32_bf16 v[18:21], v[196:199], v[236:239], v[18:21]
	v_mfma_f32_16x16x32_bf16 v[22:25], v[196:199], v[240:243], v[22:25]
	s_waitcnt vmcnt(11)
	ds_write_b128 v100, v[118:121] offset:55296
	s_waitcnt vmcnt(10)
	ds_write_b128 v100, v[122:125] offset:59904
	s_waitcnt lgkmcnt(8)
	v_mfma_f32_16x16x32_bf16 v[58:61], v[200:203], v[228:231], v[58:61]
	v_mfma_f32_16x16x32_bf16 v[62:65], v[200:203], v[232:235], v[62:65]
	v_mfma_f32_16x16x32_bf16 v[26:29], v[200:203], v[236:239], v[26:29]
	v_mfma_f32_16x16x32_bf16 v[30:33], v[200:203], v[240:243], v[30:33]
	s_waitcnt vmcnt(9)
	ds_write_b128 v100, v[126:129] offset:64512
	s_waitcnt vmcnt(8)
	ds_write_b128 v101, v[132:135] offset:32256
	s_waitcnt lgkmcnt(0)
	s_barrier
	ds_read_b128 v[212:215], v245 offset:55296
	ds_read_b128 v[196:199], v244 offset:18432
	ds_read_b128 v[216:219], v245 offset:57600
	ds_read_b128 v[220:223], v245 offset:59904
	ds_read_b128 v[224:227], v245 offset:62208
	ds_read_b128 v[200:203], v244 offset:20736
	v_mfma_f32_16x16x32_bf16 v[34:37], v[204:207], v[228:231], v[34:37]
	v_mfma_f32_16x16x32_bf16 v[38:41], v[204:207], v[232:235], v[38:41]
	v_mfma_f32_16x16x32_bf16 v[2:5], v[204:207], v[236:239], v[2:5]
	v_mfma_f32_16x16x32_bf16 v[6:9], v[204:207], v[240:243], v[6:9]
	ds_read_b128 v[204:207], v244 offset:23040
	v_mfma_f32_16x16x32_bf16 v[42:45], v[208:211], v[228:231], v[42:45]
	v_mfma_f32_16x16x32_bf16 v[46:49], v[208:211], v[232:235], v[46:49]
	v_mfma_f32_16x16x32_bf16 v[10:13], v[208:211], v[236:239], v[10:13]
	v_mfma_f32_16x16x32_bf16 v[14:17], v[208:211], v[240:243], v[14:17]
	ds_read_b128 v[208:211], v244 offset:25344
	global_load_dwordx4 v[102:105], v[66:67], off offset:384
	global_load_dwordx4 v[106:109], v[68:69], off offset:384
	global_load_dwordx4 v[110:113], v[70:71], off offset:384
	global_load_dwordx4 v[114:117], v[72:73], off offset:384
	global_load_dwordx4 v[118:121], v[84:85], off offset:384
	global_load_dwordx4 v[122:125], v[86:87], off offset:384
	global_load_dwordx4 v[126:129], v[88:89], off offset:384
	global_load_dwordx4 v[132:135], v[90:91], off offset:384
	s_waitcnt lgkmcnt(6)
	v_mfma_f32_16x16x32_bf16 v[50:53], v[196:199], v[212:215], v[50:53]
	ds_read_b128 v[228:231], v245 offset:55360
	s_waitcnt lgkmcnt(6)
	v_mfma_f32_16x16x32_bf16 v[54:57], v[196:199], v[216:219], v[54:57]
	ds_read_b128 v[232:235], v245 offset:57664
	s_waitcnt lgkmcnt(6)
	v_mfma_f32_16x16x32_bf16 v[18:21], v[196:199], v[220:223], v[18:21]
	ds_read_b128 v[236:239], v245 offset:59968
	s_waitcnt lgkmcnt(6)
	v_mfma_f32_16x16x32_bf16 v[22:25], v[196:199], v[224:227], v[22:25]
	ds_read_b128 v[240:243], v245 offset:62272
	ds_read_b128 v[196:199], v244 offset:18496
	s_waitcnt lgkmcnt(7)
	v_mfma_f32_16x16x32_bf16 v[58:61], v[200:203], v[212:215], v[58:61]
	v_mfma_f32_16x16x32_bf16 v[62:65], v[200:203], v[216:219], v[62:65]
	v_mfma_f32_16x16x32_bf16 v[26:29], v[200:203], v[220:223], v[26:29]
	v_mfma_f32_16x16x32_bf16 v[30:33], v[200:203], v[224:227], v[30:33]
	ds_read_b128 v[200:203], v244 offset:20800
	s_waitcnt lgkmcnt(7)
	v_mfma_f32_16x16x32_bf16 v[34:37], v[204:207], v[212:215], v[34:37]
	v_mfma_f32_16x16x32_bf16 v[38:41], v[204:207], v[216:219], v[38:41]
	v_mfma_f32_16x16x32_bf16 v[2:5], v[204:207], v[220:223], v[2:5]
	v_mfma_f32_16x16x32_bf16 v[6:9], v[204:207], v[224:227], v[6:9]
	ds_read_b128 v[204:207], v244 offset:23104
	s_waitcnt vmcnt(15)
	ds_write_b128 v100, v[136:139]
	s_waitcnt vmcnt(14)
	ds_write_b128 v100, v[140:143] offset:4608
	s_waitcnt lgkmcnt(9)
	v_mfma_f32_16x16x32_bf16 v[42:45], v[208:211], v[212:215], v[42:45]
	v_mfma_f32_16x16x32_bf16 v[46:49], v[208:211], v[216:219], v[46:49]
	v_mfma_f32_16x16x32_bf16 v[10:13], v[208:211], v[220:223], v[10:13]
	v_mfma_f32_16x16x32_bf16 v[14:17], v[208:211], v[224:227], v[14:17]
	ds_read_b128 v[208:211], v244 offset:25408
	s_waitcnt vmcnt(13)
	ds_write_b128 v100, v[144:147] offset:9216
	s_waitcnt vmcnt(12)
	ds_write_b128 v100, v[148:151] offset:13824
	s_waitcnt lgkmcnt(7)
	v_mfma_f32_16x16x32_bf16 v[50:53], v[196:199], v[228:231], v[50:53]
	v_mfma_f32_16x16x32_bf16 v[54:57], v[196:199], v[232:235], v[54:57]
	v_mfma_f32_16x16x32_bf16 v[18:21], v[196:199], v[236:239], v[18:21]
	v_mfma_f32_16x16x32_bf16 v[22:25], v[196:199], v[240:243], v[22:25]
	s_waitcnt vmcnt(11)
	ds_write_b128 v100, v[152:155] offset:36864
	s_waitcnt vmcnt(10)
	ds_write_b128 v100, v[156:159] offset:41472
	s_waitcnt lgkmcnt(8)
	v_mfma_f32_16x16x32_bf16 v[58:61], v[200:203], v[228:231], v[58:61]
	v_mfma_f32_16x16x32_bf16 v[62:65], v[200:203], v[232:235], v[62:65]
	v_mfma_f32_16x16x32_bf16 v[26:29], v[200:203], v[236:239], v[26:29]
	v_mfma_f32_16x16x32_bf16 v[30:33], v[200:203], v[240:243], v[30:33]
	s_waitcnt vmcnt(9)
	ds_write_b128 v100, v[160:163] offset:46080
	s_waitcnt vmcnt(8)
	ds_write_b128 v100, v[164:167] offset:50688
	s_waitcnt lgkmcnt(0)
	s_barrier
	ds_read_b128 v[212:215], v245 offset:36864
	ds_read_b128 v[196:199], v244
	ds_read_b128 v[216:219], v245 offset:39168
	ds_read_b128 v[220:223], v245 offset:41472
	ds_read_b128 v[224:227], v245 offset:43776
	ds_read_b128 v[200:203], v244 offset:2304
	v_mfma_f32_16x16x32_bf16 v[34:37], v[204:207], v[228:231], v[34:37]
	v_mfma_f32_16x16x32_bf16 v[38:41], v[204:207], v[232:235], v[38:41]
	v_mfma_f32_16x16x32_bf16 v[2:5], v[204:207], v[236:239], v[2:5]
	v_mfma_f32_16x16x32_bf16 v[6:9], v[204:207], v[240:243], v[6:9]
	ds_read_b128 v[204:207], v244 offset:4608
	v_mfma_f32_16x16x32_bf16 v[42:45], v[208:211], v[228:231], v[42:45]
	v_mfma_f32_16x16x32_bf16 v[46:49], v[208:211], v[232:235], v[46:49]
	v_mfma_f32_16x16x32_bf16 v[10:13], v[208:211], v[236:239], v[10:13]
	v_mfma_f32_16x16x32_bf16 v[14:17], v[208:211], v[240:243], v[14:17]
	ds_read_b128 v[208:211], v244 offset:6912
	global_load_dwordx4 v[136:139], v[66:67], off offset:512
	global_load_dwordx4 v[140:143], v[68:69], off offset:512
	global_load_dwordx4 v[144:147], v[70:71], off offset:512
	global_load_dwordx4 v[148:151], v[72:73], off offset:512
	global_load_dwordx4 v[152:155], v[84:85], off offset:512
	global_load_dwordx4 v[156:159], v[86:87], off offset:512
	global_load_dwordx4 v[160:163], v[88:89], off offset:512
	global_load_dwordx4 v[164:167], v[90:91], off offset:512
	s_waitcnt lgkmcnt(6)
	v_mfma_f32_16x16x32_bf16 v[50:53], v[196:199], v[212:215], v[50:53]
	ds_read_b128 v[228:231], v245 offset:36928
	s_waitcnt lgkmcnt(6)
	v_mfma_f32_16x16x32_bf16 v[54:57], v[196:199], v[216:219], v[54:57]
	ds_read_b128 v[232:235], v245 offset:39232
	s_waitcnt lgkmcnt(6)
	v_mfma_f32_16x16x32_bf16 v[18:21], v[196:199], v[220:223], v[18:21]
	ds_read_b128 v[236:239], v245 offset:41536
	s_waitcnt lgkmcnt(6)
	v_mfma_f32_16x16x32_bf16 v[22:25], v[196:199], v[224:227], v[22:25]
	ds_read_b128 v[240:243], v245 offset:43840
	ds_read_b128 v[196:199], v244 offset:64
	s_waitcnt lgkmcnt(7)
	v_mfma_f32_16x16x32_bf16 v[58:61], v[200:203], v[212:215], v[58:61]
	v_mfma_f32_16x16x32_bf16 v[62:65], v[200:203], v[216:219], v[62:65]
	v_mfma_f32_16x16x32_bf16 v[26:29], v[200:203], v[220:223], v[26:29]
	v_mfma_f32_16x16x32_bf16 v[30:33], v[200:203], v[224:227], v[30:33]
	ds_read_b128 v[200:203], v244 offset:2368
	s_waitcnt lgkmcnt(7)
	v_mfma_f32_16x16x32_bf16 v[34:37], v[204:207], v[212:215], v[34:37]
	v_mfma_f32_16x16x32_bf16 v[38:41], v[204:207], v[216:219], v[38:41]
	v_mfma_f32_16x16x32_bf16 v[2:5], v[204:207], v[220:223], v[2:5]
	v_mfma_f32_16x16x32_bf16 v[6:9], v[204:207], v[224:227], v[6:9]
	ds_read_b128 v[204:207], v244 offset:4672
	s_waitcnt vmcnt(15)
	ds_write_b128 v100, v[102:105] offset:18432
	s_waitcnt vmcnt(14)
	ds_write_b128 v100, v[106:109] offset:23040
	s_waitcnt lgkmcnt(9)
	v_mfma_f32_16x16x32_bf16 v[42:45], v[208:211], v[212:215], v[42:45]
	v_mfma_f32_16x16x32_bf16 v[46:49], v[208:211], v[216:219], v[46:49]
	v_mfma_f32_16x16x32_bf16 v[10:13], v[208:211], v[220:223], v[10:13]
	v_mfma_f32_16x16x32_bf16 v[14:17], v[208:211], v[224:227], v[14:17]
	ds_read_b128 v[208:211], v244 offset:6976
	s_waitcnt vmcnt(13)
	ds_write_b128 v100, v[110:113] offset:27648
	s_waitcnt vmcnt(12)
	ds_write_b128 v100, v[114:117] offset:32256
	s_waitcnt lgkmcnt(7)
	v_mfma_f32_16x16x32_bf16 v[50:53], v[196:199], v[228:231], v[50:53]
	v_mfma_f32_16x16x32_bf16 v[54:57], v[196:199], v[232:235], v[54:57]
	v_mfma_f32_16x16x32_bf16 v[18:21], v[196:199], v[236:239], v[18:21]
	v_mfma_f32_16x16x32_bf16 v[22:25], v[196:199], v[240:243], v[22:25]
	s_waitcnt vmcnt(11)
	ds_write_b128 v100, v[118:121] offset:55296
	s_waitcnt vmcnt(10)
	ds_write_b128 v100, v[122:125] offset:59904
	s_waitcnt lgkmcnt(8)
	v_mfma_f32_16x16x32_bf16 v[58:61], v[200:203], v[228:231], v[58:61]
	v_mfma_f32_16x16x32_bf16 v[62:65], v[200:203], v[232:235], v[62:65]
	v_mfma_f32_16x16x32_bf16 v[26:29], v[200:203], v[236:239], v[26:29]
	v_mfma_f32_16x16x32_bf16 v[30:33], v[200:203], v[240:243], v[30:33]
	s_waitcnt vmcnt(9)
	ds_write_b128 v100, v[126:129] offset:64512
	s_waitcnt vmcnt(8)
	ds_write_b128 v101, v[132:135] offset:32256
	s_waitcnt lgkmcnt(0)
	s_barrier
	ds_read_b128 v[212:215], v245 offset:55296
	ds_read_b128 v[196:199], v244 offset:18432
	ds_read_b128 v[216:219], v245 offset:57600
	ds_read_b128 v[220:223], v245 offset:59904
	ds_read_b128 v[224:227], v245 offset:62208
	ds_read_b128 v[200:203], v244 offset:20736
	v_mfma_f32_16x16x32_bf16 v[34:37], v[204:207], v[228:231], v[34:37]
	v_mfma_f32_16x16x32_bf16 v[38:41], v[204:207], v[232:235], v[38:41]
	v_mfma_f32_16x16x32_bf16 v[2:5], v[204:207], v[236:239], v[2:5]
	v_mfma_f32_16x16x32_bf16 v[6:9], v[204:207], v[240:243], v[6:9]
	ds_read_b128 v[204:207], v244 offset:23040
	v_mfma_f32_16x16x32_bf16 v[42:45], v[208:211], v[228:231], v[42:45]
	v_mfma_f32_16x16x32_bf16 v[46:49], v[208:211], v[232:235], v[46:49]
	v_mfma_f32_16x16x32_bf16 v[10:13], v[208:211], v[236:239], v[10:13]
	v_mfma_f32_16x16x32_bf16 v[14:17], v[208:211], v[240:243], v[14:17]
	ds_read_b128 v[208:211], v244 offset:25344
	global_load_dwordx4 v[102:105], v[66:67], off offset:640
	global_load_dwordx4 v[106:109], v[68:69], off offset:640
	global_load_dwordx4 v[110:113], v[70:71], off offset:640
	global_load_dwordx4 v[114:117], v[72:73], off offset:640
	global_load_dwordx4 v[118:121], v[84:85], off offset:640
	global_load_dwordx4 v[122:125], v[86:87], off offset:640
	global_load_dwordx4 v[126:129], v[88:89], off offset:640
	global_load_dwordx4 v[132:135], v[90:91], off offset:640
	s_waitcnt lgkmcnt(6)
	v_mfma_f32_16x16x32_bf16 v[50:53], v[196:199], v[212:215], v[50:53]
	ds_read_b128 v[228:231], v245 offset:55360
	s_waitcnt lgkmcnt(6)
	v_mfma_f32_16x16x32_bf16 v[54:57], v[196:199], v[216:219], v[54:57]
	ds_read_b128 v[232:235], v245 offset:57664
	s_waitcnt lgkmcnt(6)
	v_mfma_f32_16x16x32_bf16 v[18:21], v[196:199], v[220:223], v[18:21]
	ds_read_b128 v[236:239], v245 offset:59968
	s_waitcnt lgkmcnt(6)
	v_mfma_f32_16x16x32_bf16 v[22:25], v[196:199], v[224:227], v[22:25]
	ds_read_b128 v[240:243], v245 offset:62272
	ds_read_b128 v[196:199], v244 offset:18496
	s_waitcnt lgkmcnt(7)
	v_mfma_f32_16x16x32_bf16 v[58:61], v[200:203], v[212:215], v[58:61]
	v_mfma_f32_16x16x32_bf16 v[62:65], v[200:203], v[216:219], v[62:65]
	v_mfma_f32_16x16x32_bf16 v[26:29], v[200:203], v[220:223], v[26:29]
	v_mfma_f32_16x16x32_bf16 v[30:33], v[200:203], v[224:227], v[30:33]
	ds_read_b128 v[200:203], v244 offset:20800
	s_waitcnt lgkmcnt(7)
	v_mfma_f32_16x16x32_bf16 v[34:37], v[204:207], v[212:215], v[34:37]
	v_mfma_f32_16x16x32_bf16 v[38:41], v[204:207], v[216:219], v[38:41]
	v_mfma_f32_16x16x32_bf16 v[2:5], v[204:207], v[220:223], v[2:5]
	v_mfma_f32_16x16x32_bf16 v[6:9], v[204:207], v[224:227], v[6:9]
	ds_read_b128 v[204:207], v244 offset:23104
	s_waitcnt vmcnt(15)
	ds_write_b128 v100, v[136:139]
	s_waitcnt vmcnt(14)
	ds_write_b128 v100, v[140:143] offset:4608
	s_waitcnt lgkmcnt(9)
	v_mfma_f32_16x16x32_bf16 v[42:45], v[208:211], v[212:215], v[42:45]
	v_mfma_f32_16x16x32_bf16 v[46:49], v[208:211], v[216:219], v[46:49]
	v_mfma_f32_16x16x32_bf16 v[10:13], v[208:211], v[220:223], v[10:13]
	v_mfma_f32_16x16x32_bf16 v[14:17], v[208:211], v[224:227], v[14:17]
	ds_read_b128 v[208:211], v244 offset:25408
	s_waitcnt vmcnt(13)
	ds_write_b128 v100, v[144:147] offset:9216
	s_waitcnt vmcnt(12)
	ds_write_b128 v100, v[148:151] offset:13824
	s_waitcnt lgkmcnt(7)
	v_mfma_f32_16x16x32_bf16 v[50:53], v[196:199], v[228:231], v[50:53]
	v_mfma_f32_16x16x32_bf16 v[54:57], v[196:199], v[232:235], v[54:57]
	v_mfma_f32_16x16x32_bf16 v[18:21], v[196:199], v[236:239], v[18:21]
	v_mfma_f32_16x16x32_bf16 v[22:25], v[196:199], v[240:243], v[22:25]
	s_waitcnt vmcnt(11)
	ds_write_b128 v100, v[152:155] offset:36864
	s_waitcnt vmcnt(10)
	ds_write_b128 v100, v[156:159] offset:41472
	s_waitcnt lgkmcnt(8)
	v_mfma_f32_16x16x32_bf16 v[58:61], v[200:203], v[228:231], v[58:61]
	v_mfma_f32_16x16x32_bf16 v[62:65], v[200:203], v[232:235], v[62:65]
	v_mfma_f32_16x16x32_bf16 v[26:29], v[200:203], v[236:239], v[26:29]
	v_mfma_f32_16x16x32_bf16 v[30:33], v[200:203], v[240:243], v[30:33]
	s_waitcnt vmcnt(9)
	ds_write_b128 v100, v[160:163] offset:46080
	s_waitcnt vmcnt(8)
	ds_write_b128 v100, v[164:167] offset:50688
	s_waitcnt lgkmcnt(0)
	s_barrier
	ds_read_b128 v[212:215], v245 offset:36864
	ds_read_b128 v[196:199], v244
	ds_read_b128 v[216:219], v245 offset:39168
	ds_read_b128 v[220:223], v245 offset:41472
	ds_read_b128 v[224:227], v245 offset:43776
	ds_read_b128 v[200:203], v244 offset:2304
	v_mfma_f32_16x16x32_bf16 v[34:37], v[204:207], v[228:231], v[34:37]
	v_mfma_f32_16x16x32_bf16 v[38:41], v[204:207], v[232:235], v[38:41]
	v_mfma_f32_16x16x32_bf16 v[2:5], v[204:207], v[236:239], v[2:5]
	v_mfma_f32_16x16x32_bf16 v[6:9], v[204:207], v[240:243], v[6:9]
	ds_read_b128 v[204:207], v244 offset:4608
	v_mfma_f32_16x16x32_bf16 v[42:45], v[208:211], v[228:231], v[42:45]
	v_mfma_f32_16x16x32_bf16 v[46:49], v[208:211], v[232:235], v[46:49]
	v_mfma_f32_16x16x32_bf16 v[10:13], v[208:211], v[236:239], v[10:13]
	v_mfma_f32_16x16x32_bf16 v[14:17], v[208:211], v[240:243], v[14:17]
	ds_read_b128 v[208:211], v244 offset:6912
	global_load_dwordx4 v[136:139], v[66:67], off offset:768
	global_load_dwordx4 v[140:143], v[68:69], off offset:768
	global_load_dwordx4 v[144:147], v[70:71], off offset:768
	global_load_dwordx4 v[148:151], v[72:73], off offset:768
	global_load_dwordx4 v[152:155], v[84:85], off offset:768
	global_load_dwordx4 v[156:159], v[86:87], off offset:768
	global_load_dwordx4 v[160:163], v[88:89], off offset:768
	global_load_dwordx4 v[164:167], v[90:91], off offset:768
	s_waitcnt lgkmcnt(6)
	v_mfma_f32_16x16x32_bf16 v[50:53], v[196:199], v[212:215], v[50:53]
	ds_read_b128 v[228:231], v245 offset:36928
	s_waitcnt lgkmcnt(6)
	v_mfma_f32_16x16x32_bf16 v[54:57], v[196:199], v[216:219], v[54:57]
	ds_read_b128 v[232:235], v245 offset:39232
	s_waitcnt lgkmcnt(6)
	v_mfma_f32_16x16x32_bf16 v[18:21], v[196:199], v[220:223], v[18:21]
	ds_read_b128 v[236:239], v245 offset:41536
	s_waitcnt lgkmcnt(6)
	v_mfma_f32_16x16x32_bf16 v[22:25], v[196:199], v[224:227], v[22:25]
	ds_read_b128 v[240:243], v245 offset:43840
	ds_read_b128 v[196:199], v244 offset:64
	s_waitcnt lgkmcnt(7)
	v_mfma_f32_16x16x32_bf16 v[58:61], v[200:203], v[212:215], v[58:61]
	v_mfma_f32_16x16x32_bf16 v[62:65], v[200:203], v[216:219], v[62:65]
	v_mfma_f32_16x16x32_bf16 v[26:29], v[200:203], v[220:223], v[26:29]
	v_mfma_f32_16x16x32_bf16 v[30:33], v[200:203], v[224:227], v[30:33]
	ds_read_b128 v[200:203], v244 offset:2368
	s_waitcnt lgkmcnt(7)
	v_mfma_f32_16x16x32_bf16 v[34:37], v[204:207], v[212:215], v[34:37]
	v_mfma_f32_16x16x32_bf16 v[38:41], v[204:207], v[216:219], v[38:41]
	v_mfma_f32_16x16x32_bf16 v[2:5], v[204:207], v[220:223], v[2:5]
	v_mfma_f32_16x16x32_bf16 v[6:9], v[204:207], v[224:227], v[6:9]
	ds_read_b128 v[204:207], v244 offset:4672
	s_waitcnt vmcnt(15)
	ds_write_b128 v100, v[102:105] offset:18432
	s_waitcnt vmcnt(14)
	ds_write_b128 v100, v[106:109] offset:23040
	s_waitcnt lgkmcnt(9)
	v_mfma_f32_16x16x32_bf16 v[42:45], v[208:211], v[212:215], v[42:45]
	v_mfma_f32_16x16x32_bf16 v[46:49], v[208:211], v[216:219], v[46:49]
	v_mfma_f32_16x16x32_bf16 v[10:13], v[208:211], v[220:223], v[10:13]
	v_mfma_f32_16x16x32_bf16 v[14:17], v[208:211], v[224:227], v[14:17]
	ds_read_b128 v[208:211], v244 offset:6976
	s_waitcnt vmcnt(13)
	ds_write_b128 v100, v[110:113] offset:27648
	s_waitcnt vmcnt(12)
	ds_write_b128 v100, v[114:117] offset:32256
	s_waitcnt lgkmcnt(7)
	v_mfma_f32_16x16x32_bf16 v[50:53], v[196:199], v[228:231], v[50:53]
	v_mfma_f32_16x16x32_bf16 v[54:57], v[196:199], v[232:235], v[54:57]
	v_mfma_f32_16x16x32_bf16 v[18:21], v[196:199], v[236:239], v[18:21]
	v_mfma_f32_16x16x32_bf16 v[22:25], v[196:199], v[240:243], v[22:25]
	s_waitcnt vmcnt(11)
	ds_write_b128 v100, v[118:121] offset:55296
	s_waitcnt vmcnt(10)
	ds_write_b128 v100, v[122:125] offset:59904
	s_waitcnt lgkmcnt(8)
	v_mfma_f32_16x16x32_bf16 v[58:61], v[200:203], v[228:231], v[58:61]
	v_mfma_f32_16x16x32_bf16 v[62:65], v[200:203], v[232:235], v[62:65]
	v_mfma_f32_16x16x32_bf16 v[26:29], v[200:203], v[236:239], v[26:29]
	v_mfma_f32_16x16x32_bf16 v[30:33], v[200:203], v[240:243], v[30:33]
	s_waitcnt vmcnt(9)
	ds_write_b128 v100, v[126:129] offset:64512
	s_waitcnt vmcnt(8)
	ds_write_b128 v101, v[132:135] offset:32256
	s_waitcnt lgkmcnt(0)
	s_barrier
	ds_read_b128 v[212:215], v245 offset:55296
	ds_read_b128 v[196:199], v244 offset:18432
	ds_read_b128 v[216:219], v245 offset:57600
	ds_read_b128 v[220:223], v245 offset:59904
	ds_read_b128 v[224:227], v245 offset:62208
	ds_read_b128 v[200:203], v244 offset:20736
	v_mfma_f32_16x16x32_bf16 v[34:37], v[204:207], v[228:231], v[34:37]
	v_mfma_f32_16x16x32_bf16 v[38:41], v[204:207], v[232:235], v[38:41]
	v_mfma_f32_16x16x32_bf16 v[2:5], v[204:207], v[236:239], v[2:5]
	v_mfma_f32_16x16x32_bf16 v[6:9], v[204:207], v[240:243], v[6:9]
	ds_read_b128 v[204:207], v244 offset:23040
	v_mfma_f32_16x16x32_bf16 v[42:45], v[208:211], v[228:231], v[42:45]
	v_mfma_f32_16x16x32_bf16 v[46:49], v[208:211], v[232:235], v[46:49]
	v_mfma_f32_16x16x32_bf16 v[10:13], v[208:211], v[236:239], v[10:13]
	v_mfma_f32_16x16x32_bf16 v[14:17], v[208:211], v[240:243], v[14:17]
	ds_read_b128 v[208:211], v244 offset:25344
	global_load_dwordx4 v[102:105], v[66:67], off offset:896
	s_nop 0
	global_load_dwordx4 v[66:69], v[68:69], off offset:896
	s_nop 0
	global_load_dwordx4 v[106:109], v[70:71], off offset:896
	s_nop 0
	global_load_dwordx4 v[70:73], v[72:73], off offset:896
	s_nop 0
	global_load_dwordx4 v[110:113], v[84:85], off offset:896
	s_nop 0
	global_load_dwordx4 v[84:87], v[86:87], off offset:896
	s_nop 0
	global_load_dwordx4 v[114:117], v[88:89], off offset:896
	s_nop 0
	global_load_dwordx4 v[88:91], v[90:91], off offset:896
	s_waitcnt lgkmcnt(6)
	v_mfma_f32_16x16x32_bf16 v[50:53], v[196:199], v[212:215], v[50:53]
	ds_read_b128 v[228:231], v245 offset:55360
	s_waitcnt lgkmcnt(6)
	v_mfma_f32_16x16x32_bf16 v[54:57], v[196:199], v[216:219], v[54:57]
	ds_read_b128 v[232:235], v245 offset:57664
	s_waitcnt lgkmcnt(6)
	v_mfma_f32_16x16x32_bf16 v[18:21], v[196:199], v[220:223], v[18:21]
	ds_read_b128 v[236:239], v245 offset:59968
	s_waitcnt lgkmcnt(6)
	v_mfma_f32_16x16x32_bf16 v[22:25], v[196:199], v[224:227], v[22:25]
	ds_read_b128 v[240:243], v245 offset:62272
	ds_read_b128 v[196:199], v244 offset:18496
	s_waitcnt lgkmcnt(7)
	v_mfma_f32_16x16x32_bf16 v[58:61], v[200:203], v[212:215], v[58:61]
	v_mfma_f32_16x16x32_bf16 v[62:65], v[200:203], v[216:219], v[62:65]
	v_mfma_f32_16x16x32_bf16 v[26:29], v[200:203], v[220:223], v[26:29]
	v_mfma_f32_16x16x32_bf16 v[30:33], v[200:203], v[224:227], v[30:33]
	ds_read_b128 v[200:203], v244 offset:20800
	s_waitcnt lgkmcnt(7)
	v_mfma_f32_16x16x32_bf16 v[34:37], v[204:207], v[212:215], v[34:37]
	v_mfma_f32_16x16x32_bf16 v[38:41], v[204:207], v[216:219], v[38:41]
	v_mfma_f32_16x16x32_bf16 v[2:5], v[204:207], v[220:223], v[2:5]
	v_mfma_f32_16x16x32_bf16 v[6:9], v[204:207], v[224:227], v[6:9]
	ds_read_b128 v[204:207], v244 offset:23104
	s_waitcnt vmcnt(15)
	ds_write_b128 v100, v[136:139]
	s_waitcnt vmcnt(14)
	ds_write_b128 v100, v[140:143] offset:4608
	s_waitcnt lgkmcnt(9)
	v_mfma_f32_16x16x32_bf16 v[42:45], v[208:211], v[212:215], v[42:45]
	v_mfma_f32_16x16x32_bf16 v[46:49], v[208:211], v[216:219], v[46:49]
	v_mfma_f32_16x16x32_bf16 v[10:13], v[208:211], v[220:223], v[10:13]
	v_mfma_f32_16x16x32_bf16 v[14:17], v[208:211], v[224:227], v[14:17]
	ds_read_b128 v[208:211], v244 offset:25408
	s_waitcnt vmcnt(13)
	ds_write_b128 v100, v[144:147] offset:9216
	s_waitcnt vmcnt(12)
	ds_write_b128 v100, v[148:151] offset:13824
	s_waitcnt lgkmcnt(7)
	v_mfma_f32_16x16x32_bf16 v[50:53], v[196:199], v[228:231], v[50:53]
	v_mfma_f32_16x16x32_bf16 v[54:57], v[196:199], v[232:235], v[54:57]
	v_mfma_f32_16x16x32_bf16 v[18:21], v[196:199], v[236:239], v[18:21]
	v_mfma_f32_16x16x32_bf16 v[22:25], v[196:199], v[240:243], v[22:25]
	s_waitcnt vmcnt(11)
	ds_write_b128 v100, v[152:155] offset:36864
	s_waitcnt vmcnt(10)
	ds_write_b128 v100, v[156:159] offset:41472
	s_waitcnt lgkmcnt(8)
	v_mfma_f32_16x16x32_bf16 v[58:61], v[200:203], v[228:231], v[58:61]
	v_mfma_f32_16x16x32_bf16 v[62:65], v[200:203], v[232:235], v[62:65]
	v_mfma_f32_16x16x32_bf16 v[26:29], v[200:203], v[236:239], v[26:29]
	v_mfma_f32_16x16x32_bf16 v[30:33], v[200:203], v[240:243], v[30:33]
	s_waitcnt vmcnt(9)
	ds_write_b128 v100, v[160:163] offset:46080
	s_waitcnt vmcnt(8)
	ds_write_b128 v100, v[164:167] offset:50688
	s_waitcnt lgkmcnt(0)
	s_barrier
	ds_read_b128 v[212:215], v245 offset:36864
	ds_read_b128 v[196:199], v244
	ds_read_b128 v[216:219], v245 offset:39168
	ds_read_b128 v[220:223], v245 offset:41472
	ds_read_b128 v[224:227], v245 offset:43776
	ds_read_b128 v[200:203], v244 offset:2304
	v_mfma_f32_16x16x32_bf16 v[34:37], v[204:207], v[228:231], v[34:37]
	v_mfma_f32_16x16x32_bf16 v[38:41], v[204:207], v[232:235], v[38:41]
	v_mfma_f32_16x16x32_bf16 v[2:5], v[204:207], v[236:239], v[2:5]
	v_mfma_f32_16x16x32_bf16 v[6:9], v[204:207], v[240:243], v[6:9]
	ds_read_b128 v[204:207], v244 offset:4608
	v_mfma_f32_16x16x32_bf16 v[42:45], v[208:211], v[228:231], v[42:45]
	v_mfma_f32_16x16x32_bf16 v[46:49], v[208:211], v[232:235], v[46:49]
	v_mfma_f32_16x16x32_bf16 v[10:13], v[208:211], v[236:239], v[10:13]
	v_mfma_f32_16x16x32_bf16 v[14:17], v[208:211], v[240:243], v[14:17]
	ds_read_b128 v[208:211], v244 offset:6912
	s_waitcnt lgkmcnt(6)
	v_mfma_f32_16x16x32_bf16 v[50:53], v[196:199], v[212:215], v[50:53]
	ds_read_b128 v[228:231], v245 offset:36928
	s_waitcnt lgkmcnt(6)
	v_mfma_f32_16x16x32_bf16 v[54:57], v[196:199], v[216:219], v[54:57]
	ds_read_b128 v[232:235], v245 offset:39232
	s_waitcnt lgkmcnt(6)
	v_mfma_f32_16x16x32_bf16 v[18:21], v[196:199], v[220:223], v[18:21]
	ds_read_b128 v[236:239], v245 offset:41536
	s_waitcnt lgkmcnt(6)
	v_mfma_f32_16x16x32_bf16 v[22:25], v[196:199], v[224:227], v[22:25]
	ds_read_b128 v[240:243], v245 offset:43840
	ds_read_b128 v[196:199], v244 offset:64
	s_waitcnt lgkmcnt(7)
	v_mfma_f32_16x16x32_bf16 v[58:61], v[200:203], v[212:215], v[58:61]
	v_mfma_f32_16x16x32_bf16 v[62:65], v[200:203], v[216:219], v[62:65]
	v_mfma_f32_16x16x32_bf16 v[26:29], v[200:203], v[220:223], v[26:29]
	v_mfma_f32_16x16x32_bf16 v[30:33], v[200:203], v[224:227], v[30:33]
	ds_read_b128 v[200:203], v244 offset:2368
	s_waitcnt lgkmcnt(7)
	v_mfma_f32_16x16x32_bf16 v[34:37], v[204:207], v[212:215], v[34:37]
	v_mfma_f32_16x16x32_bf16 v[38:41], v[204:207], v[216:219], v[38:41]
	v_mfma_f32_16x16x32_bf16 v[2:5], v[204:207], v[220:223], v[2:5]
	v_mfma_f32_16x16x32_bf16 v[6:9], v[204:207], v[224:227], v[6:9]
	ds_read_b128 v[204:207], v244 offset:4672
	s_waitcnt vmcnt(7)
	ds_write_b128 v100, v[102:105] offset:18432
	s_waitcnt vmcnt(6)
	ds_write_b128 v100, v[66:69] offset:23040
	s_waitcnt lgkmcnt(9)
	v_mfma_f32_16x16x32_bf16 v[42:45], v[208:211], v[212:215], v[42:45]
	v_mfma_f32_16x16x32_bf16 v[46:49], v[208:211], v[216:219], v[46:49]
	v_mfma_f32_16x16x32_bf16 v[10:13], v[208:211], v[220:223], v[10:13]
	v_mfma_f32_16x16x32_bf16 v[14:17], v[208:211], v[224:227], v[14:17]
	ds_read_b128 v[208:211], v244 offset:6976
	s_waitcnt vmcnt(5)
	ds_write_b128 v100, v[106:109] offset:27648
	s_waitcnt vmcnt(4)
	ds_write_b128 v100, v[70:73] offset:32256
	s_waitcnt lgkmcnt(7)
	v_mfma_f32_16x16x32_bf16 v[50:53], v[196:199], v[228:231], v[50:53]
	v_mfma_f32_16x16x32_bf16 v[54:57], v[196:199], v[232:235], v[54:57]
	v_mfma_f32_16x16x32_bf16 v[18:21], v[196:199], v[236:239], v[18:21]
	v_mfma_f32_16x16x32_bf16 v[22:25], v[196:199], v[240:243], v[22:25]
	s_waitcnt vmcnt(3)
	ds_write_b128 v100, v[110:113] offset:55296
	s_waitcnt vmcnt(2)
	ds_write_b128 v100, v[84:87] offset:59904
	s_waitcnt lgkmcnt(8)
	v_mfma_f32_16x16x32_bf16 v[58:61], v[200:203], v[228:231], v[58:61]
	v_mfma_f32_16x16x32_bf16 v[62:65], v[200:203], v[232:235], v[62:65]
	v_mfma_f32_16x16x32_bf16 v[26:29], v[200:203], v[236:239], v[26:29]
	v_mfma_f32_16x16x32_bf16 v[30:33], v[200:203], v[240:243], v[30:33]
	s_waitcnt vmcnt(1)
	ds_write_b128 v100, v[114:117] offset:64512
	s_waitcnt vmcnt(0)
	ds_write_b128 v101, v[88:91] offset:32256
	s_waitcnt lgkmcnt(0)
	s_barrier
	ds_read_b128 v[212:215], v245 offset:55296
	ds_read_b128 v[196:199], v244 offset:18432
	ds_read_b128 v[216:219], v245 offset:57600
	ds_read_b128 v[220:223], v245 offset:59904
	ds_read_b128 v[224:227], v245 offset:62208
	ds_read_b128 v[200:203], v244 offset:20736
	v_mfma_f32_16x16x32_bf16 v[34:37], v[204:207], v[228:231], v[34:37]
	v_mfma_f32_16x16x32_bf16 v[38:41], v[204:207], v[232:235], v[38:41]
	v_mfma_f32_16x16x32_bf16 v[2:5], v[204:207], v[236:239], v[2:5]
	v_mfma_f32_16x16x32_bf16 v[6:9], v[204:207], v[240:243], v[6:9]
	ds_read_b128 v[204:207], v244 offset:23040
	v_mfma_f32_16x16x32_bf16 v[42:45], v[208:211], v[228:231], v[42:45]
	v_mfma_f32_16x16x32_bf16 v[46:49], v[208:211], v[232:235], v[46:49]
	v_mfma_f32_16x16x32_bf16 v[10:13], v[208:211], v[236:239], v[10:13]
	v_mfma_f32_16x16x32_bf16 v[14:17], v[208:211], v[240:243], v[14:17]
	ds_read_b128 v[208:211], v244 offset:25344
	s_waitcnt lgkmcnt(6)
	v_mfma_f32_16x16x32_bf16 v[50:53], v[196:199], v[212:215], v[50:53]
	ds_read_b128 v[228:231], v245 offset:55360
	s_waitcnt lgkmcnt(6)
	v_mfma_f32_16x16x32_bf16 v[54:57], v[196:199], v[216:219], v[54:57]
	ds_read_b128 v[232:235], v245 offset:57664
	s_waitcnt lgkmcnt(6)
	v_mfma_f32_16x16x32_bf16 v[18:21], v[196:199], v[220:223], v[18:21]
	ds_read_b128 v[236:239], v245 offset:59968
	s_waitcnt lgkmcnt(6)
	v_mfma_f32_16x16x32_bf16 v[22:25], v[196:199], v[224:227], v[22:25]
	ds_read_b128 v[240:243], v245 offset:62272
	ds_read_b128 v[196:199], v244 offset:18496
	s_waitcnt lgkmcnt(7)
	v_mfma_f32_16x16x32_bf16 v[58:61], v[200:203], v[212:215], v[58:61]
	v_mfma_f32_16x16x32_bf16 v[62:65], v[200:203], v[216:219], v[62:65]
	v_mfma_f32_16x16x32_bf16 v[26:29], v[200:203], v[220:223], v[26:29]
	v_mfma_f32_16x16x32_bf16 v[30:33], v[200:203], v[224:227], v[30:33]
	ds_read_b128 v[200:203], v244 offset:20800
	s_waitcnt lgkmcnt(7)
	v_mfma_f32_16x16x32_bf16 v[34:37], v[204:207], v[212:215], v[34:37]
	v_mfma_f32_16x16x32_bf16 v[38:41], v[204:207], v[216:219], v[38:41]
	v_mfma_f32_16x16x32_bf16 v[2:5], v[204:207], v[220:223], v[2:5]
	v_mfma_f32_16x16x32_bf16 v[6:9], v[204:207], v[224:227], v[6:9]
	ds_read_b128 v[204:207], v244 offset:23104
	s_waitcnt lgkmcnt(7)
	v_mfma_f32_16x16x32_bf16 v[42:45], v[208:211], v[212:215], v[42:45]
	v_mfma_f32_16x16x32_bf16 v[46:49], v[208:211], v[216:219], v[46:49]
	v_mfma_f32_16x16x32_bf16 v[10:13], v[208:211], v[220:223], v[10:13]
	v_mfma_f32_16x16x32_bf16 v[14:17], v[208:211], v[224:227], v[14:17]
	ds_read_b128 v[208:211], v244 offset:25408
	s_waitcnt lgkmcnt(3)
	v_mfma_f32_16x16x32_bf16 v[50:53], v[196:199], v[228:231], v[50:53]
	v_mfma_f32_16x16x32_bf16 v[54:57], v[196:199], v[232:235], v[54:57]
	v_mfma_f32_16x16x32_bf16 v[18:21], v[196:199], v[236:239], v[18:21]
	v_mfma_f32_16x16x32_bf16 v[22:25], v[196:199], v[240:243], v[22:25]
	s_waitcnt lgkmcnt(2)
	v_mfma_f32_16x16x32_bf16 v[58:61], v[200:203], v[228:231], v[58:61]
	v_mfma_f32_16x16x32_bf16 v[62:65], v[200:203], v[232:235], v[62:65]
	v_mfma_f32_16x16x32_bf16 v[26:29], v[200:203], v[236:239], v[26:29]
	v_mfma_f32_16x16x32_bf16 v[30:33], v[200:203], v[240:243], v[30:33]
	s_add_i32 s6, s6, 1
	s_add_i32 s5, s5, s3
	v_or_b32_e32 v70, s0, v92
	s_lshl_b32 s0, s7, 1
	v_lshl_add_u64 v[110:111], v[80:81], 0, s[0:1]
	v_lshlrev_b32_e32 v74, 10, v70
	v_lshl_add_u64 v[112:113], v[110:111], 0, v[74:75]
	s_waitcnt lgkmcnt(0)
	s_barrier
	v_mfma_f32_16x16x32_bf16 v[34:37], v[204:207], v[228:231], v[34:37]
	v_mfma_f32_16x16x32_bf16 v[38:41], v[204:207], v[232:235], v[38:41]
	v_mfma_f32_16x16x32_bf16 v[2:5], v[204:207], v[236:239], v[2:5]
	v_mfma_f32_16x16x32_bf16 v[6:9], v[204:207], v[240:243], v[6:9]
	v_mfma_f32_16x16x32_bf16 v[42:45], v[208:211], v[228:231], v[42:45]
	v_mfma_f32_16x16x32_bf16 v[46:49], v[208:211], v[232:235], v[46:49]
	v_mfma_f32_16x16x32_bf16 v[10:13], v[208:211], v[236:239], v[10:13]
	v_mfma_f32_16x16x32_bf16 v[14:17], v[208:211], v[240:243], v[14:17]
	s_nop 7
	v_permlane16_swap_b32_e32 v50, v54
	v_permlane16_swap_b32_e32 v51, v55
	v_permlane16_swap_b32_e32 v52, v56
	v_permlane16_swap_b32_e32 v53, v57
	v_permlane16_swap_b32_e32 v58, v62
	v_permlane16_swap_b32_e32 v59, v63
	v_permlane16_swap_b32_e32 v60, v64
	v_permlane16_swap_b32_e32 v61, v65
	v_permlane16_swap_b32_e32 v18, v22
	v_permlane16_swap_b32_e32 v19, v23
	v_permlane16_swap_b32_e32 v20, v24
	v_permlane16_swap_b32_e32 v21, v25
	v_permlane16_swap_b32_e32 v26, v30
	v_permlane16_swap_b32_e32 v27, v31
	v_permlane16_swap_b32_e32 v28, v32
	v_permlane16_swap_b32_e32 v29, v33
	v_permlane16_swap_b32_e32 v34, v38
	v_permlane16_swap_b32_e32 v35, v39
	v_permlane16_swap_b32_e32 v36, v40
	v_permlane16_swap_b32_e32 v37, v41
	v_permlane16_swap_b32_e32 v42, v46
	v_permlane16_swap_b32_e32 v43, v47
	v_permlane16_swap_b32_e32 v44, v48
	v_permlane16_swap_b32_e32 v45, v49
	v_permlane16_swap_b32_e32 v2, v6
	v_permlane16_swap_b32_e32 v3, v7
	v_permlane16_swap_b32_e32 v4, v8
	v_permlane16_swap_b32_e32 v5, v9
	v_permlane16_swap_b32_e32 v10, v14
	v_permlane16_swap_b32_e32 v11, v15
	v_permlane16_swap_b32_e32 v12, v16
	v_permlane16_swap_b32_e32 v13, v17
	v_permlane32_swap_b32_e32 v50, v54
	v_permlane32_swap_b32_e32 v51, v55
	v_permlane32_swap_b32_e32 v52, v56
	v_permlane32_swap_b32_e32 v53, v57
	v_permlane32_swap_b32_e32 v58, v62
	v_permlane32_swap_b32_e32 v59, v63
	v_permlane32_swap_b32_e32 v60, v64
	v_permlane32_swap_b32_e32 v61, v65
	v_permlane32_swap_b32_e32 v18, v22
	v_permlane32_swap_b32_e32 v19, v23
	v_permlane32_swap_b32_e32 v20, v24
	v_permlane32_swap_b32_e32 v21, v25
	v_permlane32_swap_b32_e32 v26, v30
	v_permlane32_swap_b32_e32 v27, v31
	v_permlane32_swap_b32_e32 v28, v32
	v_permlane32_swap_b32_e32 v29, v33
	v_permlane32_swap_b32_e32 v34, v38
	v_permlane32_swap_b32_e32 v35, v39
	v_permlane32_swap_b32_e32 v36, v40
	v_permlane32_swap_b32_e32 v37, v41
	v_permlane32_swap_b32_e32 v42, v46
	v_permlane32_swap_b32_e32 v43, v47
	v_permlane32_swap_b32_e32 v44, v48
	v_permlane32_swap_b32_e32 v45, v49
	v_permlane32_swap_b32_e32 v2, v6
	v_permlane32_swap_b32_e32 v3, v7
	v_permlane32_swap_b32_e32 v4, v8
	v_permlane32_swap_b32_e32 v5, v9
	v_permlane32_swap_b32_e32 v10, v14
	v_permlane32_swap_b32_e32 v11, v15
	v_permlane32_swap_b32_e32 v12, v16
	v_permlane32_swap_b32_e32 v13, v17
	global_load_dwordx4 v[106:109], v[112:113], off
	s_mul_i32 s0, s6, s3
	s_add_i32 s0, s0, s2
	s_cmp_lt_u32 s5, 48
	global_load_dwordx4 v[88:91], v[112:113], off offset:32
	global_load_dwordx4 v[70:73], v[112:113], off offset:64
	s_waitcnt vmcnt(2)
	v_mov_b32_e32 v86, v108
	global_load_dwordx4 v[66:69], v[112:113], off offset:96
	v_permlane32_swap_b32_e32 v106, v86
	v_mov_b32_e32 v102, v109
	s_nop 1
	v_permlane32_swap_b32_e32 v107, v102
	s_waitcnt vmcnt(2)
	v_mov_b32_e32 v108, v90
	v_mov_b32_e32 v109, v91
	s_nop 0
	v_permlane32_swap_b32_e32 v88, v108
	v_permlane32_swap_b32_e32 v89, v109
	s_waitcnt vmcnt(1)
	v_mov_b32_e32 v112, v72
	v_mov_b32_e32 v113, v73
	v_lshlrev_b32_e32 v72, 16, v106
	v_and_b32_e32 v73, 0xffff0000, v106
	v_pk_mul_f32 v[72:73], v[50:51], v[72:73]
	v_lshlrev_b32_e32 v50, 16, v107
	v_and_b32_e32 v51, 0xffff0000, v107
	v_pk_mul_f32 v[84:85], v[52:53], v[50:51]
	v_lshlrev_b32_e32 v50, 16, v86
	v_and_b32_e32 v51, 0xffff0000, v86
	v_pk_mul_f32 v[86:87], v[54:55], v[50:51]
	v_lshlrev_b32_e32 v54, 16, v102
	v_and_b32_e32 v55, 0xffff0000, v102
	v_pk_mul_f32 v[102:103], v[56:57], v[54:55]
	v_cvt_pk_bf16_f32 v55, v84, v85
	v_cvt_pk_bf16_f32 v56, v86, v87
	v_cvt_pk_bf16_f32 v57, v102, v103
	v_cvt_pk_bf16_f32 v54, v72, v73
	v_add_lshl_u32 v72, s7, v97, 1
	v_mov_b32_e32 v73, v75
	v_permlane32_swap_b32_e32 v54, v56
	v_permlane32_swap_b32_e32 v55, v57
	v_lshlrev_b32_e32 v106, 16, v88
	v_and_b32_e32 v107, 0xffff0000, v88
	v_lshlrev_b32_e32 v88, 16, v89
	v_and_b32_e32 v89, 0xffff0000, v89
	v_pk_mul_f32 v[60:61], v[60:61], v[88:89]
	v_lshlrev_b32_e32 v88, 16, v108
	v_and_b32_e32 v89, 0xffff0000, v108
	v_pk_mul_f32 v[62:63], v[62:63], v[88:89]
	v_lshlrev_b32_e32 v88, 16, v109
	v_and_b32_e32 v89, 0xffff0000, v109
	v_pk_mul_f32 v[58:59], v[58:59], v[106:107]
	v_pk_mul_f32 v[64:65], v[64:65], v[88:89]
	v_cvt_pk_bf16_f32 v58, v58, v59
	v_cvt_pk_bf16_f32 v59, v60, v61
	v_cvt_pk_bf16_f32 v60, v62, v63
	v_cvt_pk_bf16_f32 v61, v64, v65
	v_permlane32_swap_b32_e32 v70, v112
	v_permlane32_swap_b32_e32 v58, v60
	v_permlane32_swap_b32_e32 v59, v61
	v_permlane32_swap_b32_e32 v71, v113
	s_waitcnt vmcnt(0)
	v_mov_b32_e32 v114, v68
	v_mov_b32_e32 v115, v69
	v_lshl_add_u64 v[68:69], v[82:83], 0, v[74:75]
	v_or_b32_e32 v74, 0x8000, v74
	v_lshl_add_u64 v[90:91], v[110:111], 0, v[74:75]
	global_load_dwordx4 v[50:53], v[90:91], off
	global_load_dwordx4 v[84:87], v[90:91], off offset:32
	global_load_dwordx4 v[102:105], v[90:91], off offset:64
	v_lshl_add_u64 v[68:69], v[68:69], 0, v[72:73]
	global_store_dwordx4 v[68:69], v[54:57], off
	global_load_dwordx4 v[54:57], v[90:91], off offset:96
	v_permlane32_swap_b32_e32 v66, v114
	global_store_dwordx4 v[68:69], v[58:61], off offset:32
	v_permlane32_swap_b32_e32 v67, v115
	s_nop 0
	v_lshlrev_b32_e32 v58, 16, v70
	v_and_b32_e32 v59, 0xffff0000, v70
	v_pk_mul_f32 v[34:35], v[34:35], v[58:59]
	v_lshlrev_b32_e32 v58, 16, v71
	v_and_b32_e32 v59, 0xffff0000, v71
	v_pk_mul_f32 v[36:37], v[36:37], v[58:59]
	v_lshlrev_b32_e32 v58, 16, v112
	v_and_b32_e32 v59, 0xffff0000, v112
	v_pk_mul_f32 v[38:39], v[38:39], v[58:59]
	v_lshlrev_b32_e32 v58, 16, v113
	v_and_b32_e32 v59, 0xffff0000, v113
	v_pk_mul_f32 v[40:41], v[40:41], v[58:59]
	v_cvt_pk_bf16_f32 v34, v34, v35
	v_cvt_pk_bf16_f32 v35, v36, v37
	v_cvt_pk_bf16_f32 v36, v38, v39
	v_cvt_pk_bf16_f32 v37, v40, v41
	s_nop 0
	v_permlane32_swap_b32_e32 v34, v36
	v_permlane32_swap_b32_e32 v35, v37
	global_store_dwordx4 v[68:69], v[34:37], off offset:64
	v_lshlrev_b32_e32 v38, 16, v114
	v_and_b32_e32 v39, 0xffff0000, v114
	v_lshlrev_b32_e32 v34, 16, v66
	v_and_b32_e32 v35, 0xffff0000, v66
	v_lshlrev_b32_e32 v36, 16, v67
	v_and_b32_e32 v37, 0xffff0000, v67
	v_lshlrev_b32_e32 v40, 16, v115
	v_and_b32_e32 v41, 0xffff0000, v115
	v_pk_mul_f32 v[34:35], v[42:43], v[34:35]
	v_pk_mul_f32 v[36:37], v[44:45], v[36:37]
	v_pk_mul_f32 v[38:39], v[46:47], v[38:39]
	v_pk_mul_f32 v[40:41], v[48:49], v[40:41]
	v_cvt_pk_bf16_f32 v34, v34, v35
	v_cvt_pk_bf16_f32 v35, v36, v37
	v_cvt_pk_bf16_f32 v36, v38, v39
	v_cvt_pk_bf16_f32 v37, v40, v41
	s_nop 0
	v_permlane32_swap_b32_e32 v34, v36
	v_permlane32_swap_b32_e32 v35, v37
	global_store_dwordx4 v[68:69], v[34:37], off offset:96
	s_waitcnt vmcnt(7)
	v_mov_b32_e32 v38, v52
	s_nop 1
	v_permlane32_swap_b32_e32 v50, v38
	v_mov_b32_e32 v39, v53
	s_nop 1
	v_permlane32_swap_b32_e32 v51, v39
	v_lshlrev_b32_e32 v36, 16, v50
	v_and_b32_e32 v37, 0xffff0000, v50
	v_pk_mul_f32 v[18:19], v[18:19], v[36:37]
	v_lshlrev_b32_e32 v36, 16, v51
	v_and_b32_e32 v37, 0xffff0000, v51
	v_pk_mul_f32 v[20:21], v[20:21], v[36:37]
	v_lshlrev_b32_e32 v36, 16, v38
	v_and_b32_e32 v37, 0xffff0000, v38
	v_pk_mul_f32 v[22:23], v[22:23], v[36:37]
	v_lshlrev_b32_e32 v36, 16, v39
	v_and_b32_e32 v37, 0xffff0000, v39
	v_pk_mul_f32 v[24:25], v[24:25], v[36:37]
	s_waitcnt vmcnt(6)
	v_mov_b32_e32 v40, v86
	v_lshl_add_u64 v[34:35], v[82:83], 0, v[74:75]
	v_cvt_pk_bf16_f32 v18, v18, v19
	v_cvt_pk_bf16_f32 v19, v20, v21
	v_cvt_pk_bf16_f32 v20, v22, v23
	v_cvt_pk_bf16_f32 v21, v24, v25
	v_permlane32_swap_b32_e32 v84, v40
	v_mov_b32_e32 v41, v87
	v_permlane32_swap_b32_e32 v18, v20
	v_permlane32_swap_b32_e32 v19, v21
	v_lshl_add_u64 v[22:23], v[34:35], 0, v[72:73]
	v_permlane32_swap_b32_e32 v85, v41
	global_store_dwordx4 v[22:23], v[18:21], off
	v_lshlrev_b32_e32 v24, 16, v40
	v_and_b32_e32 v25, 0xffff0000, v40
	v_lshlrev_b32_e32 v18, 16, v84
	v_and_b32_e32 v19, 0xffff0000, v84
	v_pk_mul_f32 v[18:19], v[26:27], v[18:19]
	v_lshlrev_b32_e32 v20, 16, v85
	v_and_b32_e32 v21, 0xffff0000, v85
	v_lshlrev_b32_e32 v26, 16, v41
	v_and_b32_e32 v27, 0xffff0000, v41
	v_pk_mul_f32 v[20:21], v[28:29], v[20:21]
	v_pk_mul_f32 v[24:25], v[30:31], v[24:25]
	v_pk_mul_f32 v[26:27], v[32:33], v[26:27]
	s_waitcnt vmcnt(6)
	v_mov_b32_e32 v42, v104
	v_cvt_pk_bf16_f32 v18, v18, v19
	v_cvt_pk_bf16_f32 v19, v20, v21
	v_cvt_pk_bf16_f32 v20, v24, v25
	v_cvt_pk_bf16_f32 v21, v26, v27
	v_permlane32_swap_b32_e32 v102, v42
	v_mov_b32_e32 v43, v105
	v_permlane32_swap_b32_e32 v18, v20
	v_permlane32_swap_b32_e32 v19, v21
	v_permlane32_swap_b32_e32 v103, v43
	global_store_dwordx4 v[22:23], v[18:21], off offset:32
	s_waitcnt vmcnt(5)
	v_mov_b32_e32 v44, v56
	v_mov_b32_e32 v45, v57
	v_lshlrev_b32_e32 v18, 16, v102
	v_and_b32_e32 v19, 0xffff0000, v102
	v_pk_mul_f32 v[2:3], v[2:3], v[18:19]
	v_lshlrev_b32_e32 v18, 16, v103
	v_and_b32_e32 v19, 0xffff0000, v103
	v_pk_mul_f32 v[4:5], v[4:5], v[18:19]
	v_lshlrev_b32_e32 v18, 16, v42
	v_and_b32_e32 v19, 0xffff0000, v42
	v_pk_mul_f32 v[6:7], v[6:7], v[18:19]
	v_lshlrev_b32_e32 v18, 16, v43
	v_and_b32_e32 v19, 0xffff0000, v43
	v_pk_mul_f32 v[8:9], v[8:9], v[18:19]
	v_cvt_pk_bf16_f32 v2, v2, v3
	v_cvt_pk_bf16_f32 v3, v4, v5
	v_cvt_pk_bf16_f32 v4, v6, v7
	v_cvt_pk_bf16_f32 v5, v8, v9
	v_permlane32_swap_b32_e32 v54, v44
	v_permlane32_swap_b32_e32 v55, v45
	v_permlane32_swap_b32_e32 v2, v4
	v_permlane32_swap_b32_e32 v3, v5
	global_store_dwordx4 v[22:23], v[2:5], off offset:64
	v_lshlrev_b32_e32 v6, 16, v44
	v_and_b32_e32 v7, 0xffff0000, v44
	v_lshlrev_b32_e32 v2, 16, v54
	v_and_b32_e32 v3, 0xffff0000, v54
	v_lshlrev_b32_e32 v4, 16, v55
	v_and_b32_e32 v5, 0xffff0000, v55
	v_lshlrev_b32_e32 v8, 16, v45
	v_and_b32_e32 v9, 0xffff0000, v45
	v_pk_mul_f32 v[2:3], v[10:11], v[2:3]
	v_pk_mul_f32 v[4:5], v[12:13], v[4:5]
	v_pk_mul_f32 v[6:7], v[14:15], v[6:7]
	v_pk_mul_f32 v[8:9], v[16:17], v[8:9]
	v_cvt_pk_bf16_f32 v2, v2, v3
	v_cvt_pk_bf16_f32 v3, v4, v5
	v_cvt_pk_bf16_f32 v4, v6, v7
	v_cvt_pk_bf16_f32 v5, v8, v9
	s_nop 0
	v_permlane32_swap_b32_e32 v2, v4
	v_permlane32_swap_b32_e32 v3, v5
	global_store_dwordx4 v[22:23], v[2:5], off offset:96
	s_cbranch_scc1 .LBB0_1720

.LBB0_1871:
	s_lshr_b32 s0, s4, 2
	s_and_b32 s4, s4, 3
	s_or_b32 s4, s4, s8
	s_lshl_b32 s4, s4, 7
	v_or_b32_e32 v2, s4, v89
	v_lshlrev_b32_e32 v66, 11, v2
	s_add_i32 s0, s0, s9
	v_lshl_add_u64 v[72:73], v[68:69], 0, v[66:67]
	v_add_lshl_u32 v66, s4, v90, 11
	s_lshl_b32 s5, s0, 7
	v_lshl_add_u64 v[74:75], v[68:69], 0, v[66:67]
	v_add_lshl_u32 v66, s4, v91, 11
	v_lshl_add_u64 v[76:77], v[68:69], 0, v[66:67]
	v_add_lshl_u32 v66, s4, v92, 11
	v_or_b32_e32 v2, s5, v89
	v_lshl_add_u64 v[78:79], v[68:69], 0, v[66:67]
	v_lshlrev_b32_e32 v66, 11, v2
	v_lshl_add_u64 v[80:81], v[70:71], 0, v[66:67]
	v_add_lshl_u32 v66, s5, v90, 11
	v_lshl_add_u64 v[82:83], v[70:71], 0, v[66:67]
	v_add_lshl_u32 v66, s5, v91, 11
	v_lshl_add_u64 v[84:85], v[70:71], 0, v[66:67]
	v_add_lshl_u32 v66, s5, v92, 11
	v_lshl_add_u64 v[86:87], v[70:71], 0, v[66:67]
	global_load_dwordx4 v[2:5], v[72:73], off
	global_load_dwordx4 v[6:9], v[74:75], off
	global_load_dwordx4 v[10:13], v[76:77], off
	global_load_dwordx4 v[14:17], v[78:79], off
	global_load_dwordx4 v[18:21], v[80:81], off
	global_load_dwordx4 v[22:25], v[82:83], off
	global_load_dwordx4 v[26:29], v[84:85], off
	global_load_dwordx4 v[30:33], v[86:87], off
	global_load_dwordx4 v[98:101], v[72:73], off offset:128
	global_load_dwordx4 v[102:105], v[74:75], off offset:128
	global_load_dwordx4 v[106:109], v[76:77], off offset:128
	global_load_dwordx4 v[110:113], v[78:79], off offset:128
	global_load_dwordx4 v[114:117], v[80:81], off offset:128
	global_load_dwordx4 v[118:121], v[82:83], off offset:128
	global_load_dwordx4 v[122:125], v[84:85], off offset:128
	global_load_dwordx4 v[126:129], v[86:87], off offset:128
	s_waitcnt vmcnt(15)
	ds_write_b128 v95, v[2:5]
	s_waitcnt vmcnt(14)
	ds_write_b128 v95, v[6:9] offset:4608
	s_waitcnt vmcnt(13)
	ds_write_b128 v95, v[10:13] offset:9216
	s_waitcnt vmcnt(12)
	ds_write_b128 v95, v[14:17] offset:13824
	s_waitcnt vmcnt(11)
	ds_write_b128 v95, v[18:21] offset:36864
	s_waitcnt vmcnt(10)
	ds_write_b128 v95, v[22:25] offset:41472
	s_waitcnt vmcnt(9)
	ds_write_b128 v95, v[26:29] offset:46080
	s_waitcnt vmcnt(8)
	ds_write_b128 v95, v[30:33] offset:50688
	s_waitcnt lgkmcnt(0)
	s_barrier
	global_load_dwordx4 v[132:135], v[72:73], off offset:256
	global_load_dwordx4 v[136:139], v[74:75], off offset:256
	global_load_dwordx4 v[140:143], v[76:77], off offset:256
	global_load_dwordx4 v[144:147], v[78:79], off offset:256
	global_load_dwordx4 v[148:151], v[80:81], off offset:256
	global_load_dwordx4 v[152:155], v[82:83], off offset:256
	global_load_dwordx4 v[156:159], v[84:85], off offset:256
	global_load_dwordx4 v[160:163], v[86:87], off offset:256
	v_and_b32_e32 v246, 15, v1
	v_add_u32_e32 v246, 4, v246
	v_bfe_u32 v246, v246, 3, 1
	v_bfe_u32 v249, v1, 4, 2
	v_xor_b32_e32 v246, v246, v249
	v_bfe_u32 v249, v1, 5, 1
	v_sub_u32_e32 v246, v246, v249
	v_lshlrev_b32_e32 v246, 4, v246
	v_bfe_u32 v249, v1, 4, 1
	v_mul_u32_u24_e32 v249, 0x900, v249
	v_sub_u32_e32 v246, v246, v249
	v_add_u32_e32 v244, v246, v93
	v_add_u32_e32 v245, v246, v94
	ds_read_b128 v[212:215], v245 offset:36864
	ds_read_b128 v[196:199], v244
	ds_read_b128 v[216:219], v245 offset:39168
	ds_read_b128 v[220:223], v245 offset:41472
	ds_read_b128 v[224:227], v245 offset:43776
	ds_read_b128 v[200:203], v244 offset:2304
	ds_read_b128 v[204:207], v244 offset:4608
	ds_read_b128 v[208:211], v244 offset:6912
	s_waitcnt lgkmcnt(6)
	v_mfma_f32_16x16x32_bf16 v[34:37], v[196:199], v[212:215], 0
	ds_read_b128 v[228:231], v245 offset:36928
	s_waitcnt lgkmcnt(6)
	v_mfma_f32_16x16x32_bf16 v[38:41], v[196:199], v[216:219], 0
	ds_read_b128 v[232:235], v245 offset:39232
	s_waitcnt lgkmcnt(6)
	v_mfma_f32_16x16x32_bf16 v[2:5], v[196:199], v[220:223], 0
	ds_read_b128 v[236:239], v245 offset:41536
	s_waitcnt lgkmcnt(6)
	v_mfma_f32_16x16x32_bf16 v[6:9], v[196:199], v[224:227], 0
	ds_read_b128 v[240:243], v245 offset:43840
	ds_read_b128 v[196:199], v244 offset:64
	s_waitcnt lgkmcnt(7)
	v_mfma_f32_16x16x32_bf16 v[42:45], v[200:203], v[212:215], 0
	v_mfma_f32_16x16x32_bf16 v[46:49], v[200:203], v[216:219], 0
	v_mfma_f32_16x16x32_bf16 v[10:13], v[200:203], v[220:223], 0
	v_mfma_f32_16x16x32_bf16 v[14:17], v[200:203], v[224:227], 0
	ds_read_b128 v[200:203], v244 offset:2368
	s_waitcnt lgkmcnt(7)
	v_mfma_f32_16x16x32_bf16 v[50:53], v[204:207], v[212:215], 0
	v_mfma_f32_16x16x32_bf16 v[54:57], v[204:207], v[216:219], 0
	v_mfma_f32_16x16x32_bf16 v[18:21], v[204:207], v[220:223], 0
	v_mfma_f32_16x16x32_bf16 v[22:25], v[204:207], v[224:227], 0
	ds_read_b128 v[204:207], v244 offset:4672
	s_waitcnt vmcnt(15)
	ds_write_b128 v95, v[98:101] offset:18432
	s_waitcnt vmcnt(14)
	ds_write_b128 v95, v[102:105] offset:23040
	s_waitcnt lgkmcnt(9)
	v_mfma_f32_16x16x32_bf16 v[58:61], v[208:211], v[212:215], 0
	v_mfma_f32_16x16x32_bf16 v[62:65], v[208:211], v[216:219], 0
	v_mfma_f32_16x16x32_bf16 v[26:29], v[208:211], v[220:223], 0
	v_mfma_f32_16x16x32_bf16 v[30:33], v[208:211], v[224:227], 0
	ds_read_b128 v[208:211], v244 offset:6976
	s_waitcnt vmcnt(13)
	ds_write_b128 v95, v[106:109] offset:27648
	s_waitcnt vmcnt(12)
	ds_write_b128 v95, v[110:113] offset:32256
	s_waitcnt lgkmcnt(7)
	v_mfma_f32_16x16x32_bf16 v[34:37], v[196:199], v[228:231], v[34:37]
	v_mfma_f32_16x16x32_bf16 v[38:41], v[196:199], v[232:235], v[38:41]
	v_mfma_f32_16x16x32_bf16 v[2:5], v[196:199], v[236:239], v[2:5]
	v_mfma_f32_16x16x32_bf16 v[6:9], v[196:199], v[240:243], v[6:9]
	s_waitcnt vmcnt(11)
	ds_write_b128 v95, v[114:117] offset:55296
	s_waitcnt vmcnt(10)
	ds_write_b128 v95, v[118:121] offset:59904
	s_waitcnt lgkmcnt(8)
	v_mfma_f32_16x16x32_bf16 v[42:45], v[200:203], v[228:231], v[42:45]
	v_mfma_f32_16x16x32_bf16 v[46:49], v[200:203], v[232:235], v[46:49]
	v_mfma_f32_16x16x32_bf16 v[10:13], v[200:203], v[236:239], v[10:13]
	v_mfma_f32_16x16x32_bf16 v[14:17], v[200:203], v[240:243], v[14:17]
	s_waitcnt vmcnt(9)
	ds_write_b128 v95, v[122:125] offset:64512
	s_waitcnt vmcnt(8)
	ds_write_b128 v96, v[126:129] offset:32256
	s_waitcnt lgkmcnt(0)
	s_barrier
	ds_read_b128 v[212:215], v245 offset:55296
	ds_read_b128 v[196:199], v244 offset:18432
	ds_read_b128 v[216:219], v245 offset:57600
	ds_read_b128 v[220:223], v245 offset:59904
	ds_read_b128 v[224:227], v245 offset:62208
	ds_read_b128 v[200:203], v244 offset:20736
	v_mfma_f32_16x16x32_bf16 v[50:53], v[204:207], v[228:231], v[50:53]
	v_mfma_f32_16x16x32_bf16 v[54:57], v[204:207], v[232:235], v[54:57]
	v_mfma_f32_16x16x32_bf16 v[18:21], v[204:207], v[236:239], v[18:21]
	v_mfma_f32_16x16x32_bf16 v[22:25], v[204:207], v[240:243], v[22:25]
	ds_read_b128 v[204:207], v244 offset:23040
	v_mfma_f32_16x16x32_bf16 v[58:61], v[208:211], v[228:231], v[58:61]
	v_mfma_f32_16x16x32_bf16 v[62:65], v[208:211], v[232:235], v[62:65]
	v_mfma_f32_16x16x32_bf16 v[26:29], v[208:211], v[236:239], v[26:29]
	v_mfma_f32_16x16x32_bf16 v[30:33], v[208:211], v[240:243], v[30:33]
	ds_read_b128 v[208:211], v244 offset:25344
	global_load_dwordx4 v[98:101], v[72:73], off offset:384
	global_load_dwordx4 v[102:105], v[74:75], off offset:384
	global_load_dwordx4 v[106:109], v[76:77], off offset:384
	global_load_dwordx4 v[110:113], v[78:79], off offset:384
	global_load_dwordx4 v[114:117], v[80:81], off offset:384
	global_load_dwordx4 v[118:121], v[82:83], off offset:384
	global_load_dwordx4 v[122:125], v[84:85], off offset:384
	global_load_dwordx4 v[126:129], v[86:87], off offset:384
	s_waitcnt lgkmcnt(6)
	v_mfma_f32_16x16x32_bf16 v[34:37], v[196:199], v[212:215], v[34:37]
	ds_read_b128 v[228:231], v245 offset:55360
	s_waitcnt lgkmcnt(6)
	v_mfma_f32_16x16x32_bf16 v[38:41], v[196:199], v[216:219], v[38:41]
	ds_read_b128 v[232:235], v245 offset:57664
	s_waitcnt lgkmcnt(6)
	v_mfma_f32_16x16x32_bf16 v[2:5], v[196:199], v[220:223], v[2:5]
	ds_read_b128 v[236:239], v245 offset:59968
	s_waitcnt lgkmcnt(6)
	v_mfma_f32_16x16x32_bf16 v[6:9], v[196:199], v[224:227], v[6:9]
	ds_read_b128 v[240:243], v245 offset:62272
	ds_read_b128 v[196:199], v244 offset:18496
	s_waitcnt lgkmcnt(7)
	v_mfma_f32_16x16x32_bf16 v[42:45], v[200:203], v[212:215], v[42:45]
	v_mfma_f32_16x16x32_bf16 v[46:49], v[200:203], v[216:219], v[46:49]
	v_mfma_f32_16x16x32_bf16 v[10:13], v[200:203], v[220:223], v[10:13]
	v_mfma_f32_16x16x32_bf16 v[14:17], v[200:203], v[224:227], v[14:17]
	ds_read_b128 v[200:203], v244 offset:20800
	s_waitcnt lgkmcnt(7)
	v_mfma_f32_16x16x32_bf16 v[50:53], v[204:207], v[212:215], v[50:53]
	v_mfma_f32_16x16x32_bf16 v[54:57], v[204:207], v[216:219], v[54:57]
	v_mfma_f32_16x16x32_bf16 v[18:21], v[204:207], v[220:223], v[18:21]
	v_mfma_f32_16x16x32_bf16 v[22:25], v[204:207], v[224:227], v[22:25]
	ds_read_b128 v[204:207], v244 offset:23104
	s_waitcnt vmcnt(15)
	ds_write_b128 v95, v[132:135]
	s_waitcnt vmcnt(14)
	ds_write_b128 v95, v[136:139] offset:4608
	s_waitcnt lgkmcnt(9)
	v_mfma_f32_16x16x32_bf16 v[58:61], v[208:211], v[212:215], v[58:61]
	v_mfma_f32_16x16x32_bf16 v[62:65], v[208:211], v[216:219], v[62:65]
	v_mfma_f32_16x16x32_bf16 v[26:29], v[208:211], v[220:223], v[26:29]
	v_mfma_f32_16x16x32_bf16 v[30:33], v[208:211], v[224:227], v[30:33]
	ds_read_b128 v[208:211], v244 offset:25408
	s_waitcnt vmcnt(13)
	ds_write_b128 v95, v[140:143] offset:9216
	s_waitcnt vmcnt(12)
	ds_write_b128 v95, v[144:147] offset:13824
	s_waitcnt lgkmcnt(7)
	v_mfma_f32_16x16x32_bf16 v[34:37], v[196:199], v[228:231], v[34:37]
	v_mfma_f32_16x16x32_bf16 v[38:41], v[196:199], v[232:235], v[38:41]
	v_mfma_f32_16x16x32_bf16 v[2:5], v[196:199], v[236:239], v[2:5]
	v_mfma_f32_16x16x32_bf16 v[6:9], v[196:199], v[240:243], v[6:9]
	s_waitcnt vmcnt(11)
	ds_write_b128 v95, v[148:151] offset:36864
	s_waitcnt vmcnt(10)
	ds_write_b128 v95, v[152:155] offset:41472
	s_waitcnt lgkmcnt(8)
	v_mfma_f32_16x16x32_bf16 v[42:45], v[200:203], v[228:231], v[42:45]
	v_mfma_f32_16x16x32_bf16 v[46:49], v[200:203], v[232:235], v[46:49]
	v_mfma_f32_16x16x32_bf16 v[10:13], v[200:203], v[236:239], v[10:13]
	v_mfma_f32_16x16x32_bf16 v[14:17], v[200:203], v[240:243], v[14:17]
	s_waitcnt vmcnt(9)
	ds_write_b128 v95, v[156:159] offset:46080
	s_waitcnt vmcnt(8)
	ds_write_b128 v95, v[160:163] offset:50688
	s_waitcnt lgkmcnt(0)
	s_barrier
	ds_read_b128 v[212:215], v245 offset:36864
	ds_read_b128 v[196:199], v244
	ds_read_b128 v[216:219], v245 offset:39168
	ds_read_b128 v[220:223], v245 offset:41472
	ds_read_b128 v[224:227], v245 offset:43776
	ds_read_b128 v[200:203], v244 offset:2304
	v_mfma_f32_16x16x32_bf16 v[50:53], v[204:207], v[228:231], v[50:53]
	v_mfma_f32_16x16x32_bf16 v[54:57], v[204:207], v[232:235], v[54:57]
	v_mfma_f32_16x16x32_bf16 v[18:21], v[204:207], v[236:239], v[18:21]
	v_mfma_f32_16x16x32_bf16 v[22:25], v[204:207], v[240:243], v[22:25]
	ds_read_b128 v[204:207], v244 offset:4608
	v_mfma_f32_16x16x32_bf16 v[58:61], v[208:211], v[228:231], v[58:61]
	v_mfma_f32_16x16x32_bf16 v[62:65], v[208:211], v[232:235], v[62:65]
	v_mfma_f32_16x16x32_bf16 v[26:29], v[208:211], v[236:239], v[26:29]
	v_mfma_f32_16x16x32_bf16 v[30:33], v[208:211], v[240:243], v[30:33]
	ds_read_b128 v[208:211], v244 offset:6912
	global_load_dwordx4 v[132:135], v[72:73], off offset:512
	global_load_dwordx4 v[136:139], v[74:75], off offset:512
	global_load_dwordx4 v[140:143], v[76:77], off offset:512
	global_load_dwordx4 v[144:147], v[78:79], off offset:512
	global_load_dwordx4 v[148:151], v[80:81], off offset:512
	global_load_dwordx4 v[152:155], v[82:83], off offset:512
	global_load_dwordx4 v[156:159], v[84:85], off offset:512
	global_load_dwordx4 v[160:163], v[86:87], off offset:512
	s_waitcnt lgkmcnt(6)
	v_mfma_f32_16x16x32_bf16 v[34:37], v[196:199], v[212:215], v[34:37]
	ds_read_b128 v[228:231], v245 offset:36928
	s_waitcnt lgkmcnt(6)
	v_mfma_f32_16x16x32_bf16 v[38:41], v[196:199], v[216:219], v[38:41]
	ds_read_b128 v[232:235], v245 offset:39232
	s_waitcnt lgkmcnt(6)
	v_mfma_f32_16x16x32_bf16 v[2:5], v[196:199], v[220:223], v[2:5]
	ds_read_b128 v[236:239], v245 offset:41536
	s_waitcnt lgkmcnt(6)
	v_mfma_f32_16x16x32_bf16 v[6:9], v[196:199], v[224:227], v[6:9]
	ds_read_b128 v[240:243], v245 offset:43840
	ds_read_b128 v[196:199], v244 offset:64
	s_waitcnt lgkmcnt(7)
	v_mfma_f32_16x16x32_bf16 v[42:45], v[200:203], v[212:215], v[42:45]
	v_mfma_f32_16x16x32_bf16 v[46:49], v[200:203], v[216:219], v[46:49]
	v_mfma_f32_16x16x32_bf16 v[10:13], v[200:203], v[220:223], v[10:13]
	v_mfma_f32_16x16x32_bf16 v[14:17], v[200:203], v[224:227], v[14:17]
	ds_read_b128 v[200:203], v244 offset:2368
	s_waitcnt lgkmcnt(7)
	v_mfma_f32_16x16x32_bf16 v[50:53], v[204:207], v[212:215], v[50:53]
	v_mfma_f32_16x16x32_bf16 v[54:57], v[204:207], v[216:219], v[54:57]
	v_mfma_f32_16x16x32_bf16 v[18:21], v[204:207], v[220:223], v[18:21]
	v_mfma_f32_16x16x32_bf16 v[22:25], v[204:207], v[224:227], v[22:25]
	ds_read_b128 v[204:207], v244 offset:4672
	s_waitcnt vmcnt(15)
	ds_write_b128 v95, v[98:101] offset:18432
	s_waitcnt vmcnt(14)
	ds_write_b128 v95, v[102:105] offset:23040
	s_waitcnt lgkmcnt(9)
	v_mfma_f32_16x16x32_bf16 v[58:61], v[208:211], v[212:215], v[58:61]
	v_mfma_f32_16x16x32_bf16 v[62:65], v[208:211], v[216:219], v[62:65]
	v_mfma_f32_16x16x32_bf16 v[26:29], v[208:211], v[220:223], v[26:29]
	v_mfma_f32_16x16x32_bf16 v[30:33], v[208:211], v[224:227], v[30:33]
	ds_read_b128 v[208:211], v244 offset:6976
	s_waitcnt vmcnt(13)
	ds_write_b128 v95, v[106:109] offset:27648
	s_waitcnt vmcnt(12)
	ds_write_b128 v95, v[110:113] offset:32256
	s_waitcnt lgkmcnt(7)
	v_mfma_f32_16x16x32_bf16 v[34:37], v[196:199], v[228:231], v[34:37]
	v_mfma_f32_16x16x32_bf16 v[38:41], v[196:199], v[232:235], v[38:41]
	v_mfma_f32_16x16x32_bf16 v[2:5], v[196:199], v[236:239], v[2:5]
	v_mfma_f32_16x16x32_bf16 v[6:9], v[196:199], v[240:243], v[6:9]
	s_waitcnt vmcnt(11)
	ds_write_b128 v95, v[114:117] offset:55296
	s_waitcnt vmcnt(10)
	ds_write_b128 v95, v[118:121] offset:59904
	s_waitcnt lgkmcnt(8)
	v_mfma_f32_16x16x32_bf16 v[42:45], v[200:203], v[228:231], v[42:45]
	v_mfma_f32_16x16x32_bf16 v[46:49], v[200:203], v[232:235], v[46:49]
	v_mfma_f32_16x16x32_bf16 v[10:13], v[200:203], v[236:239], v[10:13]
	v_mfma_f32_16x16x32_bf16 v[14:17], v[200:203], v[240:243], v[14:17]
	s_waitcnt vmcnt(9)
	ds_write_b128 v95, v[122:125] offset:64512
	s_waitcnt vmcnt(8)
	ds_write_b128 v96, v[126:129] offset:32256
	s_waitcnt lgkmcnt(0)
	s_barrier
	ds_read_b128 v[212:215], v245 offset:55296
	ds_read_b128 v[196:199], v244 offset:18432
	ds_read_b128 v[216:219], v245 offset:57600
	ds_read_b128 v[220:223], v245 offset:59904
	ds_read_b128 v[224:227], v245 offset:62208
	ds_read_b128 v[200:203], v244 offset:20736
	v_mfma_f32_16x16x32_bf16 v[50:53], v[204:207], v[228:231], v[50:53]
	v_mfma_f32_16x16x32_bf16 v[54:57], v[204:207], v[232:235], v[54:57]
	v_mfma_f32_16x16x32_bf16 v[18:21], v[204:207], v[236:239], v[18:21]
	v_mfma_f32_16x16x32_bf16 v[22:25], v[204:207], v[240:243], v[22:25]
	ds_read_b128 v[204:207], v244 offset:23040
	v_mfma_f32_16x16x32_bf16 v[58:61], v[208:211], v[228:231], v[58:61]
	v_mfma_f32_16x16x32_bf16 v[62:65], v[208:211], v[232:235], v[62:65]
	v_mfma_f32_16x16x32_bf16 v[26:29], v[208:211], v[236:239], v[26:29]
	v_mfma_f32_16x16x32_bf16 v[30:33], v[208:211], v[240:243], v[30:33]
	ds_read_b128 v[208:211], v244 offset:25344
	global_load_dwordx4 v[98:101], v[72:73], off offset:640
	global_load_dwordx4 v[102:105], v[74:75], off offset:640
	global_load_dwordx4 v[106:109], v[76:77], off offset:640
	global_load_dwordx4 v[110:113], v[78:79], off offset:640
	global_load_dwordx4 v[114:117], v[80:81], off offset:640
	global_load_dwordx4 v[118:121], v[82:83], off offset:640
	global_load_dwordx4 v[122:125], v[84:85], off offset:640
	global_load_dwordx4 v[126:129], v[86:87], off offset:640
	s_waitcnt lgkmcnt(6)
	v_mfma_f32_16x16x32_bf16 v[34:37], v[196:199], v[212:215], v[34:37]
	ds_read_b128 v[228:231], v245 offset:55360
	s_waitcnt lgkmcnt(6)
	v_mfma_f32_16x16x32_bf16 v[38:41], v[196:199], v[216:219], v[38:41]
	ds_read_b128 v[232:235], v245 offset:57664
	s_waitcnt lgkmcnt(6)
	v_mfma_f32_16x16x32_bf16 v[2:5], v[196:199], v[220:223], v[2:5]
	ds_read_b128 v[236:239], v245 offset:59968
	s_waitcnt lgkmcnt(6)
	v_mfma_f32_16x16x32_bf16 v[6:9], v[196:199], v[224:227], v[6:9]
	ds_read_b128 v[240:243], v245 offset:62272
	ds_read_b128 v[196:199], v244 offset:18496
	s_waitcnt lgkmcnt(7)
	v_mfma_f32_16x16x32_bf16 v[42:45], v[200:203], v[212:215], v[42:45]
	v_mfma_f32_16x16x32_bf16 v[46:49], v[200:203], v[216:219], v[46:49]
	v_mfma_f32_16x16x32_bf16 v[10:13], v[200:203], v[220:223], v[10:13]
	v_mfma_f32_16x16x32_bf16 v[14:17], v[200:203], v[224:227], v[14:17]
	ds_read_b128 v[200:203], v244 offset:20800
	s_waitcnt lgkmcnt(7)
	v_mfma_f32_16x16x32_bf16 v[50:53], v[204:207], v[212:215], v[50:53]
	v_mfma_f32_16x16x32_bf16 v[54:57], v[204:207], v[216:219], v[54:57]
	v_mfma_f32_16x16x32_bf16 v[18:21], v[204:207], v[220:223], v[18:21]
	v_mfma_f32_16x16x32_bf16 v[22:25], v[204:207], v[224:227], v[22:25]
	ds_read_b128 v[204:207], v244 offset:23104
	s_waitcnt vmcnt(15)
	ds_write_b128 v95, v[132:135]
	s_waitcnt vmcnt(14)
	ds_write_b128 v95, v[136:139] offset:4608
	s_waitcnt lgkmcnt(9)
	v_mfma_f32_16x16x32_bf16 v[58:61], v[208:211], v[212:215], v[58:61]
	v_mfma_f32_16x16x32_bf16 v[62:65], v[208:211], v[216:219], v[62:65]
	v_mfma_f32_16x16x32_bf16 v[26:29], v[208:211], v[220:223], v[26:29]
	v_mfma_f32_16x16x32_bf16 v[30:33], v[208:211], v[224:227], v[30:33]
	ds_read_b128 v[208:211], v244 offset:25408
	s_waitcnt vmcnt(13)
	ds_write_b128 v95, v[140:143] offset:9216
	s_waitcnt vmcnt(12)
	ds_write_b128 v95, v[144:147] offset:13824
	s_waitcnt lgkmcnt(7)
	v_mfma_f32_16x16x32_bf16 v[34:37], v[196:199], v[228:231], v[34:37]
	v_mfma_f32_16x16x32_bf16 v[38:41], v[196:199], v[232:235], v[38:41]
	v_mfma_f32_16x16x32_bf16 v[2:5], v[196:199], v[236:239], v[2:5]
	v_mfma_f32_16x16x32_bf16 v[6:9], v[196:199], v[240:243], v[6:9]
	s_waitcnt vmcnt(11)
	ds_write_b128 v95, v[148:151] offset:36864
	s_waitcnt vmcnt(10)
	ds_write_b128 v95, v[152:155] offset:41472
	s_waitcnt lgkmcnt(8)
	v_mfma_f32_16x16x32_bf16 v[42:45], v[200:203], v[228:231], v[42:45]
	v_mfma_f32_16x16x32_bf16 v[46:49], v[200:203], v[232:235], v[46:49]
	v_mfma_f32_16x16x32_bf16 v[10:13], v[200:203], v[236:239], v[10:13]
	v_mfma_f32_16x16x32_bf16 v[14:17], v[200:203], v[240:243], v[14:17]
	s_waitcnt vmcnt(9)
	ds_write_b128 v95, v[156:159] offset:46080
	s_waitcnt vmcnt(8)
	ds_write_b128 v95, v[160:163] offset:50688
	s_waitcnt lgkmcnt(0)
	s_barrier
	ds_read_b128 v[212:215], v245 offset:36864
	ds_read_b128 v[196:199], v244
	ds_read_b128 v[216:219], v245 offset:39168
	ds_read_b128 v[220:223], v245 offset:41472
	ds_read_b128 v[224:227], v245 offset:43776
	ds_read_b128 v[200:203], v244 offset:2304
	v_mfma_f32_16x16x32_bf16 v[50:53], v[204:207], v[228:231], v[50:53]
	v_mfma_f32_16x16x32_bf16 v[54:57], v[204:207], v[232:235], v[54:57]
	v_mfma_f32_16x16x32_bf16 v[18:21], v[204:207], v[236:239], v[18:21]
	v_mfma_f32_16x16x32_bf16 v[22:25], v[204:207], v[240:243], v[22:25]
	ds_read_b128 v[204:207], v244 offset:4608
	v_mfma_f32_16x16x32_bf16 v[58:61], v[208:211], v[228:231], v[58:61]
	v_mfma_f32_16x16x32_bf16 v[62:65], v[208:211], v[232:235], v[62:65]
	v_mfma_f32_16x16x32_bf16 v[26:29], v[208:211], v[236:239], v[26:29]
	v_mfma_f32_16x16x32_bf16 v[30:33], v[208:211], v[240:243], v[30:33]
	ds_read_b128 v[208:211], v244 offset:6912
	global_load_dwordx4 v[132:135], v[72:73], off offset:768
	global_load_dwordx4 v[136:139], v[74:75], off offset:768
	global_load_dwordx4 v[140:143], v[76:77], off offset:768
	global_load_dwordx4 v[144:147], v[78:79], off offset:768
	global_load_dwordx4 v[148:151], v[80:81], off offset:768
	global_load_dwordx4 v[152:155], v[82:83], off offset:768
	global_load_dwordx4 v[156:159], v[84:85], off offset:768
	global_load_dwordx4 v[160:163], v[86:87], off offset:768
	s_waitcnt lgkmcnt(6)
	v_mfma_f32_16x16x32_bf16 v[34:37], v[196:199], v[212:215], v[34:37]
	ds_read_b128 v[228:231], v245 offset:36928
	s_waitcnt lgkmcnt(6)
	v_mfma_f32_16x16x32_bf16 v[38:41], v[196:199], v[216:219], v[38:41]
	ds_read_b128 v[232:235], v245 offset:39232
	s_waitcnt lgkmcnt(6)
	v_mfma_f32_16x16x32_bf16 v[2:5], v[196:199], v[220:223], v[2:5]
	ds_read_b128 v[236:239], v245 offset:41536
	s_waitcnt lgkmcnt(6)
	v_mfma_f32_16x16x32_bf16 v[6:9], v[196:199], v[224:227], v[6:9]
	ds_read_b128 v[240:243], v245 offset:43840
	ds_read_b128 v[196:199], v244 offset:64
	s_waitcnt lgkmcnt(7)
	v_mfma_f32_16x16x32_bf16 v[42:45], v[200:203], v[212:215], v[42:45]
	v_mfma_f32_16x16x32_bf16 v[46:49], v[200:203], v[216:219], v[46:49]
	v_mfma_f32_16x16x32_bf16 v[10:13], v[200:203], v[220:223], v[10:13]
	v_mfma_f32_16x16x32_bf16 v[14:17], v[200:203], v[224:227], v[14:17]
	ds_read_b128 v[200:203], v244 offset:2368
	s_waitcnt lgkmcnt(7)
	v_mfma_f32_16x16x32_bf16 v[50:53], v[204:207], v[212:215], v[50:53]
	v_mfma_f32_16x16x32_bf16 v[54:57], v[204:207], v[216:219], v[54:57]
	v_mfma_f32_16x16x32_bf16 v[18:21], v[204:207], v[220:223], v[18:21]
	v_mfma_f32_16x16x32_bf16 v[22:25], v[204:207], v[224:227], v[22:25]
	ds_read_b128 v[204:207], v244 offset:4672
	s_waitcnt vmcnt(15)
	ds_write_b128 v95, v[98:101] offset:18432
	s_waitcnt vmcnt(14)
	ds_write_b128 v95, v[102:105] offset:23040
	s_waitcnt lgkmcnt(9)
	v_mfma_f32_16x16x32_bf16 v[58:61], v[208:211], v[212:215], v[58:61]
	v_mfma_f32_16x16x32_bf16 v[62:65], v[208:211], v[216:219], v[62:65]
	v_mfma_f32_16x16x32_bf16 v[26:29], v[208:211], v[220:223], v[26:29]
	v_mfma_f32_16x16x32_bf16 v[30:33], v[208:211], v[224:227], v[30:33]
	ds_read_b128 v[208:211], v244 offset:6976
	s_waitcnt vmcnt(13)
	ds_write_b128 v95, v[106:109] offset:27648
	s_waitcnt vmcnt(12)
	ds_write_b128 v95, v[110:113] offset:32256
	s_waitcnt lgkmcnt(7)
	v_mfma_f32_16x16x32_bf16 v[34:37], v[196:199], v[228:231], v[34:37]
	v_mfma_f32_16x16x32_bf16 v[38:41], v[196:199], v[232:235], v[38:41]
	v_mfma_f32_16x16x32_bf16 v[2:5], v[196:199], v[236:239], v[2:5]
	v_mfma_f32_16x16x32_bf16 v[6:9], v[196:199], v[240:243], v[6:9]
	s_waitcnt vmcnt(11)
	ds_write_b128 v95, v[114:117] offset:55296
	s_waitcnt vmcnt(10)
	ds_write_b128 v95, v[118:121] offset:59904
	s_waitcnt lgkmcnt(8)
	v_mfma_f32_16x16x32_bf16 v[42:45], v[200:203], v[228:231], v[42:45]
	v_mfma_f32_16x16x32_bf16 v[46:49], v[200:203], v[232:235], v[46:49]
	v_mfma_f32_16x16x32_bf16 v[10:13], v[200:203], v[236:239], v[10:13]
	v_mfma_f32_16x16x32_bf16 v[14:17], v[200:203], v[240:243], v[14:17]
	s_waitcnt vmcnt(9)
	ds_write_b128 v95, v[122:125] offset:64512
	s_waitcnt vmcnt(8)
	ds_write_b128 v96, v[126:129] offset:32256
	s_waitcnt lgkmcnt(0)
	s_barrier
	ds_read_b128 v[212:215], v245 offset:55296
	ds_read_b128 v[196:199], v244 offset:18432
	ds_read_b128 v[216:219], v245 offset:57600
	ds_read_b128 v[220:223], v245 offset:59904
	ds_read_b128 v[224:227], v245 offset:62208
	ds_read_b128 v[200:203], v244 offset:20736
	v_mfma_f32_16x16x32_bf16 v[50:53], v[204:207], v[228:231], v[50:53]
	v_mfma_f32_16x16x32_bf16 v[54:57], v[204:207], v[232:235], v[54:57]
	v_mfma_f32_16x16x32_bf16 v[18:21], v[204:207], v[236:239], v[18:21]
	v_mfma_f32_16x16x32_bf16 v[22:25], v[204:207], v[240:243], v[22:25]
	ds_read_b128 v[204:207], v244 offset:23040
	v_mfma_f32_16x16x32_bf16 v[58:61], v[208:211], v[228:231], v[58:61]
	v_mfma_f32_16x16x32_bf16 v[62:65], v[208:211], v[232:235], v[62:65]
	v_mfma_f32_16x16x32_bf16 v[26:29], v[208:211], v[236:239], v[26:29]
	v_mfma_f32_16x16x32_bf16 v[30:33], v[208:211], v[240:243], v[30:33]
	ds_read_b128 v[208:211], v244 offset:25344
	global_load_dwordx4 v[98:101], v[72:73], off offset:896
	global_load_dwordx4 v[102:105], v[74:75], off offset:896
	global_load_dwordx4 v[106:109], v[76:77], off offset:896
	global_load_dwordx4 v[110:113], v[78:79], off offset:896
	global_load_dwordx4 v[114:117], v[80:81], off offset:896
	global_load_dwordx4 v[118:121], v[82:83], off offset:896
	global_load_dwordx4 v[122:125], v[84:85], off offset:896
	global_load_dwordx4 v[126:129], v[86:87], off offset:896
	s_waitcnt lgkmcnt(6)
	v_mfma_f32_16x16x32_bf16 v[34:37], v[196:199], v[212:215], v[34:37]
	ds_read_b128 v[228:231], v245 offset:55360
	s_waitcnt lgkmcnt(6)
	v_mfma_f32_16x16x32_bf16 v[38:41], v[196:199], v[216:219], v[38:41]
	ds_read_b128 v[232:235], v245 offset:57664
	s_waitcnt lgkmcnt(6)
	v_mfma_f32_16x16x32_bf16 v[2:5], v[196:199], v[220:223], v[2:5]
	ds_read_b128 v[236:239], v245 offset:59968
	s_waitcnt lgkmcnt(6)
	v_mfma_f32_16x16x32_bf16 v[6:9], v[196:199], v[224:227], v[6:9]
	ds_read_b128 v[240:243], v245 offset:62272
	ds_read_b128 v[196:199], v244 offset:18496
	s_waitcnt lgkmcnt(7)
	v_mfma_f32_16x16x32_bf16 v[42:45], v[200:203], v[212:215], v[42:45]
	v_mfma_f32_16x16x32_bf16 v[46:49], v[200:203], v[216:219], v[46:49]
	v_mfma_f32_16x16x32_bf16 v[10:13], v[200:203], v[220:223], v[10:13]
	v_mfma_f32_16x16x32_bf16 v[14:17], v[200:203], v[224:227], v[14:17]
	ds_read_b128 v[200:203], v244 offset:20800
	s_waitcnt lgkmcnt(7)
	v_mfma_f32_16x16x32_bf16 v[50:53], v[204:207], v[212:215], v[50:53]
	v_mfma_f32_16x16x32_bf16 v[54:57], v[204:207], v[216:219], v[54:57]
	v_mfma_f32_16x16x32_bf16 v[18:21], v[204:207], v[220:223], v[18:21]
	v_mfma_f32_16x16x32_bf16 v[22:25], v[204:207], v[224:227], v[22:25]
	ds_read_b128 v[204:207], v244 offset:23104
	s_waitcnt vmcnt(15)
	ds_write_b128 v95, v[132:135]
	s_waitcnt vmcnt(14)
	ds_write_b128 v95, v[136:139] offset:4608
	s_waitcnt lgkmcnt(9)
	v_mfma_f32_16x16x32_bf16 v[58:61], v[208:211], v[212:215], v[58:61]
	v_mfma_f32_16x16x32_bf16 v[62:65], v[208:211], v[216:219], v[62:65]
	v_mfma_f32_16x16x32_bf16 v[26:29], v[208:211], v[220:223], v[26:29]
	v_mfma_f32_16x16x32_bf16 v[30:33], v[208:211], v[224:227], v[30:33]
	ds_read_b128 v[208:211], v244 offset:25408
	s_waitcnt vmcnt(13)
	ds_write_b128 v95, v[140:143] offset:9216
	s_waitcnt vmcnt(12)
	ds_write_b128 v95, v[144:147] offset:13824
	s_waitcnt lgkmcnt(7)
	v_mfma_f32_16x16x32_bf16 v[34:37], v[196:199], v[228:231], v[34:37]
	v_mfma_f32_16x16x32_bf16 v[38:41], v[196:199], v[232:235], v[38:41]
	v_mfma_f32_16x16x32_bf16 v[2:5], v[196:199], v[236:239], v[2:5]
	v_mfma_f32_16x16x32_bf16 v[6:9], v[196:199], v[240:243], v[6:9]
	s_waitcnt vmcnt(11)
	ds_write_b128 v95, v[148:151] offset:36864
	s_waitcnt vmcnt(10)
	ds_write_b128 v95, v[152:155] offset:41472
	s_waitcnt lgkmcnt(8)
	v_mfma_f32_16x16x32_bf16 v[42:45], v[200:203], v[228:231], v[42:45]
	v_mfma_f32_16x16x32_bf16 v[46:49], v[200:203], v[232:235], v[46:49]
	v_mfma_f32_16x16x32_bf16 v[10:13], v[200:203], v[236:239], v[10:13]
	v_mfma_f32_16x16x32_bf16 v[14:17], v[200:203], v[240:243], v[14:17]
	s_waitcnt vmcnt(9)
	ds_write_b128 v95, v[156:159] offset:46080
	s_waitcnt vmcnt(8)
	ds_write_b128 v95, v[160:163] offset:50688
	s_waitcnt lgkmcnt(0)
	s_barrier
	ds_read_b128 v[212:215], v245 offset:36864
	ds_read_b128 v[196:199], v244
	ds_read_b128 v[216:219], v245 offset:39168
	ds_read_b128 v[220:223], v245 offset:41472
	ds_read_b128 v[224:227], v245 offset:43776
	ds_read_b128 v[200:203], v244 offset:2304
	v_mfma_f32_16x16x32_bf16 v[50:53], v[204:207], v[228:231], v[50:53]
	v_mfma_f32_16x16x32_bf16 v[54:57], v[204:207], v[232:235], v[54:57]
	v_mfma_f32_16x16x32_bf16 v[18:21], v[204:207], v[236:239], v[18:21]
	v_mfma_f32_16x16x32_bf16 v[22:25], v[204:207], v[240:243], v[22:25]
	ds_read_b128 v[204:207], v244 offset:4608
	v_mfma_f32_16x16x32_bf16 v[58:61], v[208:211], v[228:231], v[58:61]
	v_mfma_f32_16x16x32_bf16 v[62:65], v[208:211], v[232:235], v[62:65]
	v_mfma_f32_16x16x32_bf16 v[26:29], v[208:211], v[236:239], v[26:29]
	v_mfma_f32_16x16x32_bf16 v[30:33], v[208:211], v[240:243], v[30:33]
	ds_read_b128 v[208:211], v244 offset:6912
	global_load_dwordx4 v[132:135], v[72:73], off offset:1024
	global_load_dwordx4 v[136:139], v[74:75], off offset:1024
	global_load_dwordx4 v[140:143], v[76:77], off offset:1024
	global_load_dwordx4 v[144:147], v[78:79], off offset:1024
	global_load_dwordx4 v[148:151], v[80:81], off offset:1024
	global_load_dwordx4 v[152:155], v[82:83], off offset:1024
	global_load_dwordx4 v[156:159], v[84:85], off offset:1024
	global_load_dwordx4 v[160:163], v[86:87], off offset:1024
	s_waitcnt lgkmcnt(6)
	v_mfma_f32_16x16x32_bf16 v[34:37], v[196:199], v[212:215], v[34:37]
	ds_read_b128 v[228:231], v245 offset:36928
	s_waitcnt lgkmcnt(6)
	v_mfma_f32_16x16x32_bf16 v[38:41], v[196:199], v[216:219], v[38:41]
	ds_read_b128 v[232:235], v245 offset:39232
	s_waitcnt lgkmcnt(6)
	v_mfma_f32_16x16x32_bf16 v[2:5], v[196:199], v[220:223], v[2:5]
	ds_read_b128 v[236:239], v245 offset:41536
	s_waitcnt lgkmcnt(6)
	v_mfma_f32_16x16x32_bf16 v[6:9], v[196:199], v[224:227], v[6:9]
	ds_read_b128 v[240:243], v245 offset:43840
	ds_read_b128 v[196:199], v244 offset:64
	s_waitcnt lgkmcnt(7)
	v_mfma_f32_16x16x32_bf16 v[42:45], v[200:203], v[212:215], v[42:45]
	v_mfma_f32_16x16x32_bf16 v[46:49], v[200:203], v[216:219], v[46:49]
	v_mfma_f32_16x16x32_bf16 v[10:13], v[200:203], v[220:223], v[10:13]
	v_mfma_f32_16x16x32_bf16 v[14:17], v[200:203], v[224:227], v[14:17]
	ds_read_b128 v[200:203], v244 offset:2368
	s_waitcnt lgkmcnt(7)
	v_mfma_f32_16x16x32_bf16 v[50:53], v[204:207], v[212:215], v[50:53]
	v_mfma_f32_16x16x32_bf16 v[54:57], v[204:207], v[216:219], v[54:57]
	v_mfma_f32_16x16x32_bf16 v[18:21], v[204:207], v[220:223], v[18:21]
	v_mfma_f32_16x16x32_bf16 v[22:25], v[204:207], v[224:227], v[22:25]
	ds_read_b128 v[204:207], v244 offset:4672
	s_waitcnt vmcnt(15)
	ds_write_b128 v95, v[98:101] offset:18432
	s_waitcnt vmcnt(14)
	ds_write_b128 v95, v[102:105] offset:23040
	s_waitcnt lgkmcnt(9)
	v_mfma_f32_16x16x32_bf16 v[58:61], v[208:211], v[212:215], v[58:61]
	v_mfma_f32_16x16x32_bf16 v[62:65], v[208:211], v[216:219], v[62:65]
	v_mfma_f32_16x16x32_bf16 v[26:29], v[208:211], v[220:223], v[26:29]
	v_mfma_f32_16x16x32_bf16 v[30:33], v[208:211], v[224:227], v[30:33]
	ds_read_b128 v[208:211], v244 offset:6976
	s_waitcnt vmcnt(13)
	ds_write_b128 v95, v[106:109] offset:27648
	s_waitcnt vmcnt(12)
	ds_write_b128 v95, v[110:113] offset:32256
	s_waitcnt lgkmcnt(7)
	v_mfma_f32_16x16x32_bf16 v[34:37], v[196:199], v[228:231], v[34:37]
	v_mfma_f32_16x16x32_bf16 v[38:41], v[196:199], v[232:235], v[38:41]
	v_mfma_f32_16x16x32_bf16 v[2:5], v[196:199], v[236:239], v[2:5]
	v_mfma_f32_16x16x32_bf16 v[6:9], v[196:199], v[240:243], v[6:9]
	s_waitcnt vmcnt(11)
	ds_write_b128 v95, v[114:117] offset:55296
	s_waitcnt vmcnt(10)
	ds_write_b128 v95, v[118:121] offset:59904
	s_waitcnt lgkmcnt(8)
	v_mfma_f32_16x16x32_bf16 v[42:45], v[200:203], v[228:231], v[42:45]
	v_mfma_f32_16x16x32_bf16 v[46:49], v[200:203], v[232:235], v[46:49]
	v_mfma_f32_16x16x32_bf16 v[10:13], v[200:203], v[236:239], v[10:13]
	v_mfma_f32_16x16x32_bf16 v[14:17], v[200:203], v[240:243], v[14:17]
	s_waitcnt vmcnt(9)
	ds_write_b128 v95, v[122:125] offset:64512
	s_waitcnt vmcnt(8)
	ds_write_b128 v96, v[126:129] offset:32256
	s_waitcnt lgkmcnt(0)
	s_barrier
	ds_read_b128 v[212:215], v245 offset:55296
	ds_read_b128 v[196:199], v244 offset:18432
	ds_read_b128 v[216:219], v245 offset:57600
	ds_read_b128 v[220:223], v245 offset:59904
	ds_read_b128 v[224:227], v245 offset:62208
	ds_read_b128 v[200:203], v244 offset:20736
	v_mfma_f32_16x16x32_bf16 v[50:53], v[204:207], v[228:231], v[50:53]
	v_mfma_f32_16x16x32_bf16 v[54:57], v[204:207], v[232:235], v[54:57]
	v_mfma_f32_16x16x32_bf16 v[18:21], v[204:207], v[236:239], v[18:21]
	v_mfma_f32_16x16x32_bf16 v[22:25], v[204:207], v[240:243], v[22:25]
	ds_read_b128 v[204:207], v244 offset:23040
	v_mfma_f32_16x16x32_bf16 v[58:61], v[208:211], v[228:231], v[58:61]
	v_mfma_f32_16x16x32_bf16 v[62:65], v[208:211], v[232:235], v[62:65]
	v_mfma_f32_16x16x32_bf16 v[26:29], v[208:211], v[236:239], v[26:29]
	v_mfma_f32_16x16x32_bf16 v[30:33], v[208:211], v[240:243], v[30:33]
	ds_read_b128 v[208:211], v244 offset:25344
	global_load_dwordx4 v[98:101], v[72:73], off offset:1152
	global_load_dwordx4 v[102:105], v[74:75], off offset:1152
	global_load_dwordx4 v[106:109], v[76:77], off offset:1152
	global_load_dwordx4 v[110:113], v[78:79], off offset:1152
	global_load_dwordx4 v[114:117], v[80:81], off offset:1152
	global_load_dwordx4 v[118:121], v[82:83], off offset:1152
	global_load_dwordx4 v[122:125], v[84:85], off offset:1152
	global_load_dwordx4 v[126:129], v[86:87], off offset:1152
	s_waitcnt lgkmcnt(6)
	v_mfma_f32_16x16x32_bf16 v[34:37], v[196:199], v[212:215], v[34:37]
	ds_read_b128 v[228:231], v245 offset:55360
	s_waitcnt lgkmcnt(6)
	v_mfma_f32_16x16x32_bf16 v[38:41], v[196:199], v[216:219], v[38:41]
	ds_read_b128 v[232:235], v245 offset:57664
	s_waitcnt lgkmcnt(6)
	v_mfma_f32_16x16x32_bf16 v[2:5], v[196:199], v[220:223], v[2:5]
	ds_read_b128 v[236:239], v245 offset:59968
	s_waitcnt lgkmcnt(6)
	v_mfma_f32_16x16x32_bf16 v[6:9], v[196:199], v[224:227], v[6:9]
	ds_read_b128 v[240:243], v245 offset:62272
	ds_read_b128 v[196:199], v244 offset:18496
	s_waitcnt lgkmcnt(7)
	v_mfma_f32_16x16x32_bf16 v[42:45], v[200:203], v[212:215], v[42:45]
	v_mfma_f32_16x16x32_bf16 v[46:49], v[200:203], v[216:219], v[46:49]
	v_mfma_f32_16x16x32_bf16 v[10:13], v[200:203], v[220:223], v[10:13]
	v_mfma_f32_16x16x32_bf16 v[14:17], v[200:203], v[224:227], v[14:17]
	ds_read_b128 v[200:203], v244 offset:20800
	s_waitcnt lgkmcnt(7)
	v_mfma_f32_16x16x32_bf16 v[50:53], v[204:207], v[212:215], v[50:53]
	v_mfma_f32_16x16x32_bf16 v[54:57], v[204:207], v[216:219], v[54:57]
	v_mfma_f32_16x16x32_bf16 v[18:21], v[204:207], v[220:223], v[18:21]
	v_mfma_f32_16x16x32_bf16 v[22:25], v[204:207], v[224:227], v[22:25]
	ds_read_b128 v[204:207], v244 offset:23104
	s_waitcnt vmcnt(15)
	ds_write_b128 v95, v[132:135]
	s_waitcnt vmcnt(14)
	ds_write_b128 v95, v[136:139] offset:4608
	s_waitcnt lgkmcnt(9)
	v_mfma_f32_16x16x32_bf16 v[58:61], v[208:211], v[212:215], v[58:61]
	v_mfma_f32_16x16x32_bf16 v[62:65], v[208:211], v[216:219], v[62:65]
	v_mfma_f32_16x16x32_bf16 v[26:29], v[208:211], v[220:223], v[26:29]
	v_mfma_f32_16x16x32_bf16 v[30:33], v[208:211], v[224:227], v[30:33]
	ds_read_b128 v[208:211], v244 offset:25408
	s_waitcnt vmcnt(13)
	ds_write_b128 v95, v[140:143] offset:9216
	s_waitcnt vmcnt(12)
	ds_write_b128 v95, v[144:147] offset:13824
	s_waitcnt lgkmcnt(7)
	v_mfma_f32_16x16x32_bf16 v[34:37], v[196:199], v[228:231], v[34:37]
	v_mfma_f32_16x16x32_bf16 v[38:41], v[196:199], v[232:235], v[38:41]
	v_mfma_f32_16x16x32_bf16 v[2:5], v[196:199], v[236:239], v[2:5]
	v_mfma_f32_16x16x32_bf16 v[6:9], v[196:199], v[240:243], v[6:9]
	s_waitcnt vmcnt(11)
	ds_write_b128 v95, v[148:151] offset:36864
	s_waitcnt vmcnt(10)
	ds_write_b128 v95, v[152:155] offset:41472
	s_waitcnt lgkmcnt(8)
	v_mfma_f32_16x16x32_bf16 v[42:45], v[200:203], v[228:231], v[42:45]
	v_mfma_f32_16x16x32_bf16 v[46:49], v[200:203], v[232:235], v[46:49]
	v_mfma_f32_16x16x32_bf16 v[10:13], v[200:203], v[236:239], v[10:13]
	v_mfma_f32_16x16x32_bf16 v[14:17], v[200:203], v[240:243], v[14:17]
	s_waitcnt vmcnt(9)
	ds_write_b128 v95, v[156:159] offset:46080
	s_waitcnt vmcnt(8)
	ds_write_b128 v95, v[160:163] offset:50688
	s_waitcnt lgkmcnt(0)
	s_barrier
	ds_read_b128 v[212:215], v245 offset:36864
	ds_read_b128 v[196:199], v244
	ds_read_b128 v[216:219], v245 offset:39168
	ds_read_b128 v[220:223], v245 offset:41472
	ds_read_b128 v[224:227], v245 offset:43776
	ds_read_b128 v[200:203], v244 offset:2304
	v_mfma_f32_16x16x32_bf16 v[50:53], v[204:207], v[228:231], v[50:53]
	v_mfma_f32_16x16x32_bf16 v[54:57], v[204:207], v[232:235], v[54:57]
	v_mfma_f32_16x16x32_bf16 v[18:21], v[204:207], v[236:239], v[18:21]
	v_mfma_f32_16x16x32_bf16 v[22:25], v[204:207], v[240:243], v[22:25]
	ds_read_b128 v[204:207], v244 offset:4608
	v_mfma_f32_16x16x32_bf16 v[58:61], v[208:211], v[228:231], v[58:61]
	v_mfma_f32_16x16x32_bf16 v[62:65], v[208:211], v[232:235], v[62:65]
	v_mfma_f32_16x16x32_bf16 v[26:29], v[208:211], v[236:239], v[26:29]
	v_mfma_f32_16x16x32_bf16 v[30:33], v[208:211], v[240:243], v[30:33]
	ds_read_b128 v[208:211], v244 offset:6912
	global_load_dwordx4 v[132:135], v[72:73], off offset:1280
	global_load_dwordx4 v[136:139], v[74:75], off offset:1280
	global_load_dwordx4 v[140:143], v[76:77], off offset:1280
	global_load_dwordx4 v[144:147], v[78:79], off offset:1280
	global_load_dwordx4 v[148:151], v[80:81], off offset:1280
	global_load_dwordx4 v[152:155], v[82:83], off offset:1280
	global_load_dwordx4 v[156:159], v[84:85], off offset:1280
	global_load_dwordx4 v[160:163], v[86:87], off offset:1280
	s_waitcnt lgkmcnt(6)
	v_mfma_f32_16x16x32_bf16 v[34:37], v[196:199], v[212:215], v[34:37]
	ds_read_b128 v[228:231], v245 offset:36928
	s_waitcnt lgkmcnt(6)
	v_mfma_f32_16x16x32_bf16 v[38:41], v[196:199], v[216:219], v[38:41]
	ds_read_b128 v[232:235], v245 offset:39232
	s_waitcnt lgkmcnt(6)
	v_mfma_f32_16x16x32_bf16 v[2:5], v[196:199], v[220:223], v[2:5]
	ds_read_b128 v[236:239], v245 offset:41536
	s_waitcnt lgkmcnt(6)
	v_mfma_f32_16x16x32_bf16 v[6:9], v[196:199], v[224:227], v[6:9]
	ds_read_b128 v[240:243], v245 offset:43840
	ds_read_b128 v[196:199], v244 offset:64
	s_waitcnt lgkmcnt(7)
	v_mfma_f32_16x16x32_bf16 v[42:45], v[200:203], v[212:215], v[42:45]
	v_mfma_f32_16x16x32_bf16 v[46:49], v[200:203], v[216:219], v[46:49]
	v_mfma_f32_16x16x32_bf16 v[10:13], v[200:203], v[220:223], v[10:13]
	v_mfma_f32_16x16x32_bf16 v[14:17], v[200:203], v[224:227], v[14:17]
	ds_read_b128 v[200:203], v244 offset:2368
	s_waitcnt lgkmcnt(7)
	v_mfma_f32_16x16x32_bf16 v[50:53], v[204:207], v[212:215], v[50:53]
	v_mfma_f32_16x16x32_bf16 v[54:57], v[204:207], v[216:219], v[54:57]
	v_mfma_f32_16x16x32_bf16 v[18:21], v[204:207], v[220:223], v[18:21]
	v_mfma_f32_16x16x32_bf16 v[22:25], v[204:207], v[224:227], v[22:25]
	ds_read_b128 v[204:207], v244 offset:4672
	s_waitcnt vmcnt(15)
	ds_write_b128 v95, v[98:101] offset:18432
	s_waitcnt vmcnt(14)
	ds_write_b128 v95, v[102:105] offset:23040
	s_waitcnt lgkmcnt(9)
	v_mfma_f32_16x16x32_bf16 v[58:61], v[208:211], v[212:215], v[58:61]
	v_mfma_f32_16x16x32_bf16 v[62:65], v[208:211], v[216:219], v[62:65]
	v_mfma_f32_16x16x32_bf16 v[26:29], v[208:211], v[220:223], v[26:29]
	v_mfma_f32_16x16x32_bf16 v[30:33], v[208:211], v[224:227], v[30:33]
	ds_read_b128 v[208:211], v244 offset:6976
	s_waitcnt vmcnt(13)
	ds_write_b128 v95, v[106:109] offset:27648
	s_waitcnt vmcnt(12)
	ds_write_b128 v95, v[110:113] offset:32256
	s_waitcnt lgkmcnt(7)
	v_mfma_f32_16x16x32_bf16 v[34:37], v[196:199], v[228:231], v[34:37]
	v_mfma_f32_16x16x32_bf16 v[38:41], v[196:199], v[232:235], v[38:41]
	v_mfma_f32_16x16x32_bf16 v[2:5], v[196:199], v[236:239], v[2:5]
	v_mfma_f32_16x16x32_bf16 v[6:9], v[196:199], v[240:243], v[6:9]
	s_waitcnt vmcnt(11)
	ds_write_b128 v95, v[114:117] offset:55296
	s_waitcnt vmcnt(10)
	ds_write_b128 v95, v[118:121] offset:59904
	s_waitcnt lgkmcnt(8)
	v_mfma_f32_16x16x32_bf16 v[42:45], v[200:203], v[228:231], v[42:45]
	v_mfma_f32_16x16x32_bf16 v[46:49], v[200:203], v[232:235], v[46:49]
	v_mfma_f32_16x16x32_bf16 v[10:13], v[200:203], v[236:239], v[10:13]
	v_mfma_f32_16x16x32_bf16 v[14:17], v[200:203], v[240:243], v[14:17]
	s_waitcnt vmcnt(9)
	ds_write_b128 v95, v[122:125] offset:64512
	s_waitcnt vmcnt(8)
	ds_write_b128 v96, v[126:129] offset:32256
	s_waitcnt lgkmcnt(0)
	s_barrier
	ds_read_b128 v[212:215], v245 offset:55296
	ds_read_b128 v[196:199], v244 offset:18432
	ds_read_b128 v[216:219], v245 offset:57600
	ds_read_b128 v[220:223], v245 offset:59904
	ds_read_b128 v[224:227], v245 offset:62208
	ds_read_b128 v[200:203], v244 offset:20736
	v_mfma_f32_16x16x32_bf16 v[50:53], v[204:207], v[228:231], v[50:53]
	v_mfma_f32_16x16x32_bf16 v[54:57], v[204:207], v[232:235], v[54:57]
	v_mfma_f32_16x16x32_bf16 v[18:21], v[204:207], v[236:239], v[18:21]
	v_mfma_f32_16x16x32_bf16 v[22:25], v[204:207], v[240:243], v[22:25]
	ds_read_b128 v[204:207], v244 offset:23040
	v_mfma_f32_16x16x32_bf16 v[58:61], v[208:211], v[228:231], v[58:61]
	v_mfma_f32_16x16x32_bf16 v[62:65], v[208:211], v[232:235], v[62:65]
	v_mfma_f32_16x16x32_bf16 v[26:29], v[208:211], v[236:239], v[26:29]
	v_mfma_f32_16x16x32_bf16 v[30:33], v[208:211], v[240:243], v[30:33]
	ds_read_b128 v[208:211], v244 offset:25344
	global_load_dwordx4 v[98:101], v[72:73], off offset:1408
	global_load_dwordx4 v[102:105], v[74:75], off offset:1408
	global_load_dwordx4 v[106:109], v[76:77], off offset:1408
	global_load_dwordx4 v[110:113], v[78:79], off offset:1408
	global_load_dwordx4 v[114:117], v[80:81], off offset:1408
	global_load_dwordx4 v[118:121], v[82:83], off offset:1408
	global_load_dwordx4 v[122:125], v[84:85], off offset:1408
	global_load_dwordx4 v[126:129], v[86:87], off offset:1408
	s_waitcnt lgkmcnt(6)
	v_mfma_f32_16x16x32_bf16 v[34:37], v[196:199], v[212:215], v[34:37]
	ds_read_b128 v[228:231], v245 offset:55360
	s_waitcnt lgkmcnt(6)
	v_mfma_f32_16x16x32_bf16 v[38:41], v[196:199], v[216:219], v[38:41]
	ds_read_b128 v[232:235], v245 offset:57664
	s_waitcnt lgkmcnt(6)
	v_mfma_f32_16x16x32_bf16 v[2:5], v[196:199], v[220:223], v[2:5]
	ds_read_b128 v[236:239], v245 offset:59968
	s_waitcnt lgkmcnt(6)
	v_mfma_f32_16x16x32_bf16 v[6:9], v[196:199], v[224:227], v[6:9]
	ds_read_b128 v[240:243], v245 offset:62272
	ds_read_b128 v[196:199], v244 offset:18496
	s_waitcnt lgkmcnt(7)
	v_mfma_f32_16x16x32_bf16 v[42:45], v[200:203], v[212:215], v[42:45]
	v_mfma_f32_16x16x32_bf16 v[46:49], v[200:203], v[216:219], v[46:49]
	v_mfma_f32_16x16x32_bf16 v[10:13], v[200:203], v[220:223], v[10:13]
	v_mfma_f32_16x16x32_bf16 v[14:17], v[200:203], v[224:227], v[14:17]
	ds_read_b128 v[200:203], v244 offset:20800
	s_waitcnt lgkmcnt(7)
	v_mfma_f32_16x16x32_bf16 v[50:53], v[204:207], v[212:215], v[50:53]
	v_mfma_f32_16x16x32_bf16 v[54:57], v[204:207], v[216:219], v[54:57]
	v_mfma_f32_16x16x32_bf16 v[18:21], v[204:207], v[220:223], v[18:21]
	v_mfma_f32_16x16x32_bf16 v[22:25], v[204:207], v[224:227], v[22:25]
	ds_read_b128 v[204:207], v244 offset:23104
	s_waitcnt vmcnt(15)
	ds_write_b128 v95, v[132:135]
	s_waitcnt vmcnt(14)
	ds_write_b128 v95, v[136:139] offset:4608
	s_waitcnt lgkmcnt(9)
	v_mfma_f32_16x16x32_bf16 v[58:61], v[208:211], v[212:215], v[58:61]
	v_mfma_f32_16x16x32_bf16 v[62:65], v[208:211], v[216:219], v[62:65]
	v_mfma_f32_16x16x32_bf16 v[26:29], v[208:211], v[220:223], v[26:29]
	v_mfma_f32_16x16x32_bf16 v[30:33], v[208:211], v[224:227], v[30:33]
	ds_read_b128 v[208:211], v244 offset:25408
	s_waitcnt vmcnt(13)
	ds_write_b128 v95, v[140:143] offset:9216
	s_waitcnt vmcnt(12)
	ds_write_b128 v95, v[144:147] offset:13824
	s_waitcnt lgkmcnt(7)
	v_mfma_f32_16x16x32_bf16 v[34:37], v[196:199], v[228:231], v[34:37]
	v_mfma_f32_16x16x32_bf16 v[38:41], v[196:199], v[232:235], v[38:41]
	v_mfma_f32_16x16x32_bf16 v[2:5], v[196:199], v[236:239], v[2:5]
	v_mfma_f32_16x16x32_bf16 v[6:9], v[196:199], v[240:243], v[6:9]
	s_waitcnt vmcnt(11)
	ds_write_b128 v95, v[148:151] offset:36864
	s_waitcnt vmcnt(10)
	ds_write_b128 v95, v[152:155] offset:41472
	s_waitcnt lgkmcnt(8)
	v_mfma_f32_16x16x32_bf16 v[42:45], v[200:203], v[228:231], v[42:45]
	v_mfma_f32_16x16x32_bf16 v[46:49], v[200:203], v[232:235], v[46:49]
	v_mfma_f32_16x16x32_bf16 v[10:13], v[200:203], v[236:239], v[10:13]
	v_mfma_f32_16x16x32_bf16 v[14:17], v[200:203], v[240:243], v[14:17]
	s_waitcnt vmcnt(9)
	ds_write_b128 v95, v[156:159] offset:46080
	s_waitcnt vmcnt(8)
	ds_write_b128 v95, v[160:163] offset:50688
	s_waitcnt lgkmcnt(0)
	s_barrier
	ds_read_b128 v[212:215], v245 offset:36864
	ds_read_b128 v[196:199], v244
	ds_read_b128 v[216:219], v245 offset:39168
	ds_read_b128 v[220:223], v245 offset:41472
	ds_read_b128 v[224:227], v245 offset:43776
	ds_read_b128 v[200:203], v244 offset:2304
	v_mfma_f32_16x16x32_bf16 v[50:53], v[204:207], v[228:231], v[50:53]
	v_mfma_f32_16x16x32_bf16 v[54:57], v[204:207], v[232:235], v[54:57]
	v_mfma_f32_16x16x32_bf16 v[18:21], v[204:207], v[236:239], v[18:21]
	v_mfma_f32_16x16x32_bf16 v[22:25], v[204:207], v[240:243], v[22:25]
	ds_read_b128 v[204:207], v244 offset:4608
	v_mfma_f32_16x16x32_bf16 v[58:61], v[208:211], v[228:231], v[58:61]
	v_mfma_f32_16x16x32_bf16 v[62:65], v[208:211], v[232:235], v[62:65]
	v_mfma_f32_16x16x32_bf16 v[26:29], v[208:211], v[236:239], v[26:29]
	v_mfma_f32_16x16x32_bf16 v[30:33], v[208:211], v[240:243], v[30:33]
	ds_read_b128 v[208:211], v244 offset:6912
	global_load_dwordx4 v[132:135], v[72:73], off offset:1536
	global_load_dwordx4 v[136:139], v[74:75], off offset:1536
	global_load_dwordx4 v[140:143], v[76:77], off offset:1536
	global_load_dwordx4 v[144:147], v[78:79], off offset:1536
	global_load_dwordx4 v[148:151], v[80:81], off offset:1536
	global_load_dwordx4 v[152:155], v[82:83], off offset:1536
	global_load_dwordx4 v[156:159], v[84:85], off offset:1536
	global_load_dwordx4 v[160:163], v[86:87], off offset:1536
	s_waitcnt lgkmcnt(6)
	v_mfma_f32_16x16x32_bf16 v[34:37], v[196:199], v[212:215], v[34:37]
	ds_read_b128 v[228:231], v245 offset:36928
	s_waitcnt lgkmcnt(6)
	v_mfma_f32_16x16x32_bf16 v[38:41], v[196:199], v[216:219], v[38:41]
	ds_read_b128 v[232:235], v245 offset:39232
	s_waitcnt lgkmcnt(6)
	v_mfma_f32_16x16x32_bf16 v[2:5], v[196:199], v[220:223], v[2:5]
	ds_read_b128 v[236:239], v245 offset:41536
	s_waitcnt lgkmcnt(6)
	v_mfma_f32_16x16x32_bf16 v[6:9], v[196:199], v[224:227], v[6:9]
	ds_read_b128 v[240:243], v245 offset:43840
	ds_read_b128 v[196:199], v244 offset:64
	s_waitcnt lgkmcnt(7)
	v_mfma_f32_16x16x32_bf16 v[42:45], v[200:203], v[212:215], v[42:45]
	v_mfma_f32_16x16x32_bf16 v[46:49], v[200:203], v[216:219], v[46:49]
	v_mfma_f32_16x16x32_bf16 v[10:13], v[200:203], v[220:223], v[10:13]
	v_mfma_f32_16x16x32_bf16 v[14:17], v[200:203], v[224:227], v[14:17]
	ds_read_b128 v[200:203], v244 offset:2368
	s_waitcnt lgkmcnt(7)
	v_mfma_f32_16x16x32_bf16 v[50:53], v[204:207], v[212:215], v[50:53]
	v_mfma_f32_16x16x32_bf16 v[54:57], v[204:207], v[216:219], v[54:57]
	v_mfma_f32_16x16x32_bf16 v[18:21], v[204:207], v[220:223], v[18:21]
	v_mfma_f32_16x16x32_bf16 v[22:25], v[204:207], v[224:227], v[22:25]
	ds_read_b128 v[204:207], v244 offset:4672
	s_waitcnt vmcnt(15)
	ds_write_b128 v95, v[98:101] offset:18432
	s_waitcnt vmcnt(14)
	ds_write_b128 v95, v[102:105] offset:23040
	s_waitcnt lgkmcnt(9)
	v_mfma_f32_16x16x32_bf16 v[58:61], v[208:211], v[212:215], v[58:61]
	v_mfma_f32_16x16x32_bf16 v[62:65], v[208:211], v[216:219], v[62:65]
	v_mfma_f32_16x16x32_bf16 v[26:29], v[208:211], v[220:223], v[26:29]
	v_mfma_f32_16x16x32_bf16 v[30:33], v[208:211], v[224:227], v[30:33]
	ds_read_b128 v[208:211], v244 offset:6976
	s_waitcnt vmcnt(13)
	ds_write_b128 v95, v[106:109] offset:27648
	s_waitcnt vmcnt(12)
	ds_write_b128 v95, v[110:113] offset:32256
	s_waitcnt lgkmcnt(7)
	v_mfma_f32_16x16x32_bf16 v[34:37], v[196:199], v[228:231], v[34:37]
	v_mfma_f32_16x16x32_bf16 v[38:41], v[196:199], v[232:235], v[38:41]
	v_mfma_f32_16x16x32_bf16 v[2:5], v[196:199], v[236:239], v[2:5]
	v_mfma_f32_16x16x32_bf16 v[6:9], v[196:199], v[240:243], v[6:9]
	s_waitcnt vmcnt(11)
	ds_write_b128 v95, v[114:117] offset:55296
	s_waitcnt vmcnt(10)
	ds_write_b128 v95, v[118:121] offset:59904
	s_waitcnt lgkmcnt(8)
	v_mfma_f32_16x16x32_bf16 v[42:45], v[200:203], v[228:231], v[42:45]
	v_mfma_f32_16x16x32_bf16 v[46:49], v[200:203], v[232:235], v[46:49]
	v_mfma_f32_16x16x32_bf16 v[10:13], v[200:203], v[236:239], v[10:13]
	v_mfma_f32_16x16x32_bf16 v[14:17], v[200:203], v[240:243], v[14:17]
	s_waitcnt vmcnt(9)
	ds_write_b128 v95, v[122:125] offset:64512
	s_waitcnt vmcnt(8)
	ds_write_b128 v96, v[126:129] offset:32256
	s_waitcnt lgkmcnt(0)
	s_barrier
	ds_read_b128 v[212:215], v245 offset:55296
	ds_read_b128 v[196:199], v244 offset:18432
	ds_read_b128 v[216:219], v245 offset:57600
	ds_read_b128 v[220:223], v245 offset:59904
	ds_read_b128 v[224:227], v245 offset:62208
	ds_read_b128 v[200:203], v244 offset:20736
	v_mfma_f32_16x16x32_bf16 v[50:53], v[204:207], v[228:231], v[50:53]
	v_mfma_f32_16x16x32_bf16 v[54:57], v[204:207], v[232:235], v[54:57]
	v_mfma_f32_16x16x32_bf16 v[18:21], v[204:207], v[236:239], v[18:21]
	v_mfma_f32_16x16x32_bf16 v[22:25], v[204:207], v[240:243], v[22:25]
	ds_read_b128 v[204:207], v244 offset:23040
	v_mfma_f32_16x16x32_bf16 v[58:61], v[208:211], v[228:231], v[58:61]
	v_mfma_f32_16x16x32_bf16 v[62:65], v[208:211], v[232:235], v[62:65]
	v_mfma_f32_16x16x32_bf16 v[26:29], v[208:211], v[236:239], v[26:29]
	v_mfma_f32_16x16x32_bf16 v[30:33], v[208:211], v[240:243], v[30:33]
	ds_read_b128 v[208:211], v244 offset:25344
	global_load_dwordx4 v[98:101], v[72:73], off offset:1664
	global_load_dwordx4 v[102:105], v[74:75], off offset:1664
	global_load_dwordx4 v[106:109], v[76:77], off offset:1664
	global_load_dwordx4 v[110:113], v[78:79], off offset:1664
	global_load_dwordx4 v[114:117], v[80:81], off offset:1664
	global_load_dwordx4 v[118:121], v[82:83], off offset:1664
	global_load_dwordx4 v[122:125], v[84:85], off offset:1664
	global_load_dwordx4 v[126:129], v[86:87], off offset:1664
	s_waitcnt lgkmcnt(6)
	v_mfma_f32_16x16x32_bf16 v[34:37], v[196:199], v[212:215], v[34:37]
	ds_read_b128 v[228:231], v245 offset:55360
	s_waitcnt lgkmcnt(6)
	v_mfma_f32_16x16x32_bf16 v[38:41], v[196:199], v[216:219], v[38:41]
	ds_read_b128 v[232:235], v245 offset:57664
	s_waitcnt lgkmcnt(6)
	v_mfma_f32_16x16x32_bf16 v[2:5], v[196:199], v[220:223], v[2:5]
	ds_read_b128 v[236:239], v245 offset:59968
	s_waitcnt lgkmcnt(6)
	v_mfma_f32_16x16x32_bf16 v[6:9], v[196:199], v[224:227], v[6:9]
	ds_read_b128 v[240:243], v245 offset:62272
	ds_read_b128 v[196:199], v244 offset:18496
	s_waitcnt lgkmcnt(7)
	v_mfma_f32_16x16x32_bf16 v[42:45], v[200:203], v[212:215], v[42:45]
	v_mfma_f32_16x16x32_bf16 v[46:49], v[200:203], v[216:219], v[46:49]
	v_mfma_f32_16x16x32_bf16 v[10:13], v[200:203], v[220:223], v[10:13]
	v_mfma_f32_16x16x32_bf16 v[14:17], v[200:203], v[224:227], v[14:17]
	ds_read_b128 v[200:203], v244 offset:20800
	s_waitcnt lgkmcnt(7)
	v_mfma_f32_16x16x32_bf16 v[50:53], v[204:207], v[212:215], v[50:53]
	v_mfma_f32_16x16x32_bf16 v[54:57], v[204:207], v[216:219], v[54:57]
	v_mfma_f32_16x16x32_bf16 v[18:21], v[204:207], v[220:223], v[18:21]
	v_mfma_f32_16x16x32_bf16 v[22:25], v[204:207], v[224:227], v[22:25]
	ds_read_b128 v[204:207], v244 offset:23104
	s_waitcnt vmcnt(15)
	ds_write_b128 v95, v[132:135]
	s_waitcnt vmcnt(14)
	ds_write_b128 v95, v[136:139] offset:4608
	s_waitcnt lgkmcnt(9)
	v_mfma_f32_16x16x32_bf16 v[58:61], v[208:211], v[212:215], v[58:61]
	v_mfma_f32_16x16x32_bf16 v[62:65], v[208:211], v[216:219], v[62:65]
	v_mfma_f32_16x16x32_bf16 v[26:29], v[208:211], v[220:223], v[26:29]
	v_mfma_f32_16x16x32_bf16 v[30:33], v[208:211], v[224:227], v[30:33]
	ds_read_b128 v[208:211], v244 offset:25408
	s_waitcnt vmcnt(13)
	ds_write_b128 v95, v[140:143] offset:9216
	s_waitcnt vmcnt(12)
	ds_write_b128 v95, v[144:147] offset:13824
	s_waitcnt lgkmcnt(7)
	v_mfma_f32_16x16x32_bf16 v[34:37], v[196:199], v[228:231], v[34:37]
	v_mfma_f32_16x16x32_bf16 v[38:41], v[196:199], v[232:235], v[38:41]
	v_mfma_f32_16x16x32_bf16 v[2:5], v[196:199], v[236:239], v[2:5]
	v_mfma_f32_16x16x32_bf16 v[6:9], v[196:199], v[240:243], v[6:9]
	s_waitcnt vmcnt(11)
	ds_write_b128 v95, v[148:151] offset:36864
	s_waitcnt vmcnt(10)
	ds_write_b128 v95, v[152:155] offset:41472
	s_waitcnt lgkmcnt(8)
	v_mfma_f32_16x16x32_bf16 v[42:45], v[200:203], v[228:231], v[42:45]
	v_mfma_f32_16x16x32_bf16 v[46:49], v[200:203], v[232:235], v[46:49]
	v_mfma_f32_16x16x32_bf16 v[10:13], v[200:203], v[236:239], v[10:13]
	v_mfma_f32_16x16x32_bf16 v[14:17], v[200:203], v[240:243], v[14:17]
	s_waitcnt vmcnt(9)
	ds_write_b128 v95, v[156:159] offset:46080
	s_waitcnt vmcnt(8)
	ds_write_b128 v95, v[160:163] offset:50688
	s_waitcnt lgkmcnt(0)
	s_barrier
	ds_read_b128 v[212:215], v245 offset:36864
	ds_read_b128 v[196:199], v244
	ds_read_b128 v[216:219], v245 offset:39168
	ds_read_b128 v[220:223], v245 offset:41472
	ds_read_b128 v[224:227], v245 offset:43776
	ds_read_b128 v[200:203], v244 offset:2304
	v_mfma_f32_16x16x32_bf16 v[50:53], v[204:207], v[228:231], v[50:53]
	v_mfma_f32_16x16x32_bf16 v[54:57], v[204:207], v[232:235], v[54:57]
	v_mfma_f32_16x16x32_bf16 v[18:21], v[204:207], v[236:239], v[18:21]
	v_mfma_f32_16x16x32_bf16 v[22:25], v[204:207], v[240:243], v[22:25]
	ds_read_b128 v[204:207], v244 offset:4608
	v_mfma_f32_16x16x32_bf16 v[58:61], v[208:211], v[228:231], v[58:61]
	v_mfma_f32_16x16x32_bf16 v[62:65], v[208:211], v[232:235], v[62:65]
	v_mfma_f32_16x16x32_bf16 v[26:29], v[208:211], v[236:239], v[26:29]
	v_mfma_f32_16x16x32_bf16 v[30:33], v[208:211], v[240:243], v[30:33]
	ds_read_b128 v[208:211], v244 offset:6912
	global_load_dwordx4 v[132:135], v[72:73], off offset:1792
	global_load_dwordx4 v[136:139], v[74:75], off offset:1792
	global_load_dwordx4 v[140:143], v[76:77], off offset:1792
	global_load_dwordx4 v[144:147], v[78:79], off offset:1792
	global_load_dwordx4 v[148:151], v[80:81], off offset:1792
	global_load_dwordx4 v[152:155], v[82:83], off offset:1792
	global_load_dwordx4 v[156:159], v[84:85], off offset:1792
	global_load_dwordx4 v[160:163], v[86:87], off offset:1792
	s_waitcnt lgkmcnt(6)
	v_mfma_f32_16x16x32_bf16 v[34:37], v[196:199], v[212:215], v[34:37]
	ds_read_b128 v[228:231], v245 offset:36928
	s_waitcnt lgkmcnt(6)
	v_mfma_f32_16x16x32_bf16 v[38:41], v[196:199], v[216:219], v[38:41]
	ds_read_b128 v[232:235], v245 offset:39232
	s_waitcnt lgkmcnt(6)
	v_mfma_f32_16x16x32_bf16 v[2:5], v[196:199], v[220:223], v[2:5]
	ds_read_b128 v[236:239], v245 offset:41536
	s_waitcnt lgkmcnt(6)
	v_mfma_f32_16x16x32_bf16 v[6:9], v[196:199], v[224:227], v[6:9]
	ds_read_b128 v[240:243], v245 offset:43840
	ds_read_b128 v[196:199], v244 offset:64
	s_waitcnt lgkmcnt(7)
	v_mfma_f32_16x16x32_bf16 v[42:45], v[200:203], v[212:215], v[42:45]
	v_mfma_f32_16x16x32_bf16 v[46:49], v[200:203], v[216:219], v[46:49]
	v_mfma_f32_16x16x32_bf16 v[10:13], v[200:203], v[220:223], v[10:13]
	v_mfma_f32_16x16x32_bf16 v[14:17], v[200:203], v[224:227], v[14:17]
	ds_read_b128 v[200:203], v244 offset:2368
	s_waitcnt lgkmcnt(7)
	v_mfma_f32_16x16x32_bf16 v[50:53], v[204:207], v[212:215], v[50:53]
	v_mfma_f32_16x16x32_bf16 v[54:57], v[204:207], v[216:219], v[54:57]
	v_mfma_f32_16x16x32_bf16 v[18:21], v[204:207], v[220:223], v[18:21]
	v_mfma_f32_16x16x32_bf16 v[22:25], v[204:207], v[224:227], v[22:25]
	ds_read_b128 v[204:207], v244 offset:4672
	s_waitcnt vmcnt(15)
	ds_write_b128 v95, v[98:101] offset:18432
	s_waitcnt vmcnt(14)
	ds_write_b128 v95, v[102:105] offset:23040
	s_waitcnt lgkmcnt(9)
	v_mfma_f32_16x16x32_bf16 v[58:61], v[208:211], v[212:215], v[58:61]
	v_mfma_f32_16x16x32_bf16 v[62:65], v[208:211], v[216:219], v[62:65]
	v_mfma_f32_16x16x32_bf16 v[26:29], v[208:211], v[220:223], v[26:29]
	v_mfma_f32_16x16x32_bf16 v[30:33], v[208:211], v[224:227], v[30:33]
	ds_read_b128 v[208:211], v244 offset:6976
	s_waitcnt vmcnt(13)
	ds_write_b128 v95, v[106:109] offset:27648
	s_waitcnt vmcnt(12)
	ds_write_b128 v95, v[110:113] offset:32256
	s_waitcnt lgkmcnt(7)
	v_mfma_f32_16x16x32_bf16 v[34:37], v[196:199], v[228:231], v[34:37]
	v_mfma_f32_16x16x32_bf16 v[38:41], v[196:199], v[232:235], v[38:41]
	v_mfma_f32_16x16x32_bf16 v[2:5], v[196:199], v[236:239], v[2:5]
	v_mfma_f32_16x16x32_bf16 v[6:9], v[196:199], v[240:243], v[6:9]
	s_waitcnt vmcnt(11)
	ds_write_b128 v95, v[114:117] offset:55296
	s_waitcnt vmcnt(10)
	ds_write_b128 v95, v[118:121] offset:59904
	s_waitcnt lgkmcnt(8)
	v_mfma_f32_16x16x32_bf16 v[42:45], v[200:203], v[228:231], v[42:45]
	v_mfma_f32_16x16x32_bf16 v[46:49], v[200:203], v[232:235], v[46:49]
	v_mfma_f32_16x16x32_bf16 v[10:13], v[200:203], v[236:239], v[10:13]
	v_mfma_f32_16x16x32_bf16 v[14:17], v[200:203], v[240:243], v[14:17]
	s_waitcnt vmcnt(9)
	ds_write_b128 v95, v[122:125] offset:64512
	s_waitcnt vmcnt(8)
	ds_write_b128 v96, v[126:129] offset:32256
	s_waitcnt lgkmcnt(0)
	s_barrier
	ds_read_b128 v[212:215], v245 offset:55296
	ds_read_b128 v[196:199], v244 offset:18432
	ds_read_b128 v[216:219], v245 offset:57600
	ds_read_b128 v[220:223], v245 offset:59904
	ds_read_b128 v[224:227], v245 offset:62208
	ds_read_b128 v[200:203], v244 offset:20736
	v_mfma_f32_16x16x32_bf16 v[50:53], v[204:207], v[228:231], v[50:53]
	v_mfma_f32_16x16x32_bf16 v[54:57], v[204:207], v[232:235], v[54:57]
	v_mfma_f32_16x16x32_bf16 v[18:21], v[204:207], v[236:239], v[18:21]
	v_mfma_f32_16x16x32_bf16 v[22:25], v[204:207], v[240:243], v[22:25]
	ds_read_b128 v[204:207], v244 offset:23040
	v_mfma_f32_16x16x32_bf16 v[58:61], v[208:211], v[228:231], v[58:61]
	v_mfma_f32_16x16x32_bf16 v[62:65], v[208:211], v[232:235], v[62:65]
	v_mfma_f32_16x16x32_bf16 v[26:29], v[208:211], v[236:239], v[26:29]
	v_mfma_f32_16x16x32_bf16 v[30:33], v[208:211], v[240:243], v[30:33]
	ds_read_b128 v[208:211], v244 offset:25344
	global_load_dwordx4 v[98:101], v[72:73], off offset:1920
	s_nop 0
	global_load_dwordx4 v[72:75], v[74:75], off offset:1920
	s_nop 0
	global_load_dwordx4 v[102:105], v[76:77], off offset:1920
	s_nop 0
	global_load_dwordx4 v[76:79], v[78:79], off offset:1920
	s_nop 0
	global_load_dwordx4 v[106:109], v[80:81], off offset:1920
	s_nop 0
	global_load_dwordx4 v[80:83], v[82:83], off offset:1920
	s_nop 0
	global_load_dwordx4 v[110:113], v[84:85], off offset:1920
	s_nop 0
	global_load_dwordx4 v[84:87], v[86:87], off offset:1920
	s_waitcnt lgkmcnt(6)
	v_mfma_f32_16x16x32_bf16 v[34:37], v[196:199], v[212:215], v[34:37]
	ds_read_b128 v[228:231], v245 offset:55360
	s_waitcnt lgkmcnt(6)
	v_mfma_f32_16x16x32_bf16 v[38:41], v[196:199], v[216:219], v[38:41]
	ds_read_b128 v[232:235], v245 offset:57664
	s_waitcnt lgkmcnt(6)
	v_mfma_f32_16x16x32_bf16 v[2:5], v[196:199], v[220:223], v[2:5]
	ds_read_b128 v[236:239], v245 offset:59968
	s_waitcnt lgkmcnt(6)
	v_mfma_f32_16x16x32_bf16 v[6:9], v[196:199], v[224:227], v[6:9]
	ds_read_b128 v[240:243], v245 offset:62272
	ds_read_b128 v[196:199], v244 offset:18496
	s_waitcnt lgkmcnt(7)
	v_mfma_f32_16x16x32_bf16 v[42:45], v[200:203], v[212:215], v[42:45]
	v_mfma_f32_16x16x32_bf16 v[46:49], v[200:203], v[216:219], v[46:49]
	v_mfma_f32_16x16x32_bf16 v[10:13], v[200:203], v[220:223], v[10:13]
	v_mfma_f32_16x16x32_bf16 v[14:17], v[200:203], v[224:227], v[14:17]
	ds_read_b128 v[200:203], v244 offset:20800
	s_waitcnt lgkmcnt(7)
	v_mfma_f32_16x16x32_bf16 v[50:53], v[204:207], v[212:215], v[50:53]
	v_mfma_f32_16x16x32_bf16 v[54:57], v[204:207], v[216:219], v[54:57]
	v_mfma_f32_16x16x32_bf16 v[18:21], v[204:207], v[220:223], v[18:21]
	v_mfma_f32_16x16x32_bf16 v[22:25], v[204:207], v[224:227], v[22:25]
	ds_read_b128 v[204:207], v244 offset:23104
	s_waitcnt vmcnt(15)
	ds_write_b128 v95, v[132:135]
	s_waitcnt vmcnt(14)
	ds_write_b128 v95, v[136:139] offset:4608
	s_waitcnt lgkmcnt(9)
	v_mfma_f32_16x16x32_bf16 v[58:61], v[208:211], v[212:215], v[58:61]
	v_mfma_f32_16x16x32_bf16 v[62:65], v[208:211], v[216:219], v[62:65]
	v_mfma_f32_16x16x32_bf16 v[26:29], v[208:211], v[220:223], v[26:29]
	v_mfma_f32_16x16x32_bf16 v[30:33], v[208:211], v[224:227], v[30:33]
	ds_read_b128 v[208:211], v244 offset:25408
	s_waitcnt vmcnt(13)
	ds_write_b128 v95, v[140:143] offset:9216
	s_waitcnt vmcnt(12)
	ds_write_b128 v95, v[144:147] offset:13824
	s_waitcnt lgkmcnt(7)
	v_mfma_f32_16x16x32_bf16 v[34:37], v[196:199], v[228:231], v[34:37]
	v_mfma_f32_16x16x32_bf16 v[38:41], v[196:199], v[232:235], v[38:41]
	v_mfma_f32_16x16x32_bf16 v[2:5], v[196:199], v[236:239], v[2:5]
	v_mfma_f32_16x16x32_bf16 v[6:9], v[196:199], v[240:243], v[6:9]
	s_waitcnt vmcnt(11)
	ds_write_b128 v95, v[148:151] offset:36864
	s_waitcnt vmcnt(10)
	ds_write_b128 v95, v[152:155] offset:41472
	s_waitcnt lgkmcnt(8)
	v_mfma_f32_16x16x32_bf16 v[42:45], v[200:203], v[228:231], v[42:45]
	v_mfma_f32_16x16x32_bf16 v[46:49], v[200:203], v[232:235], v[46:49]
	v_mfma_f32_16x16x32_bf16 v[10:13], v[200:203], v[236:239], v[10:13]
	v_mfma_f32_16x16x32_bf16 v[14:17], v[200:203], v[240:243], v[14:17]
	s_waitcnt vmcnt(9)
	ds_write_b128 v95, v[156:159] offset:46080
	s_waitcnt vmcnt(8)
	ds_write_b128 v95, v[160:163] offset:50688
	s_waitcnt lgkmcnt(0)
	s_barrier
	ds_read_b128 v[212:215], v245 offset:36864
	ds_read_b128 v[196:199], v244
	ds_read_b128 v[216:219], v245 offset:39168
	ds_read_b128 v[220:223], v245 offset:41472
	ds_read_b128 v[224:227], v245 offset:43776
	ds_read_b128 v[200:203], v244 offset:2304
	v_mfma_f32_16x16x32_bf16 v[50:53], v[204:207], v[228:231], v[50:53]
	v_mfma_f32_16x16x32_bf16 v[54:57], v[204:207], v[232:235], v[54:57]
	v_mfma_f32_16x16x32_bf16 v[18:21], v[204:207], v[236:239], v[18:21]
	v_mfma_f32_16x16x32_bf16 v[22:25], v[204:207], v[240:243], v[22:25]
	ds_read_b128 v[204:207], v244 offset:4608
	v_mfma_f32_16x16x32_bf16 v[58:61], v[208:211], v[228:231], v[58:61]
	v_mfma_f32_16x16x32_bf16 v[62:65], v[208:211], v[232:235], v[62:65]
	v_mfma_f32_16x16x32_bf16 v[26:29], v[208:211], v[236:239], v[26:29]
	v_mfma_f32_16x16x32_bf16 v[30:33], v[208:211], v[240:243], v[30:33]
	ds_read_b128 v[208:211], v244 offset:6912
	s_waitcnt lgkmcnt(6)
	v_mfma_f32_16x16x32_bf16 v[34:37], v[196:199], v[212:215], v[34:37]
	ds_read_b128 v[228:231], v245 offset:36928
	s_waitcnt lgkmcnt(6)
	v_mfma_f32_16x16x32_bf16 v[38:41], v[196:199], v[216:219], v[38:41]
	ds_read_b128 v[232:235], v245 offset:39232
	s_waitcnt lgkmcnt(6)
	v_mfma_f32_16x16x32_bf16 v[2:5], v[196:199], v[220:223], v[2:5]
	ds_read_b128 v[236:239], v245 offset:41536
	s_waitcnt lgkmcnt(6)
	v_mfma_f32_16x16x32_bf16 v[6:9], v[196:199], v[224:227], v[6:9]
	ds_read_b128 v[240:243], v245 offset:43840
	ds_read_b128 v[196:199], v244 offset:64
	s_waitcnt lgkmcnt(7)
	v_mfma_f32_16x16x32_bf16 v[42:45], v[200:203], v[212:215], v[42:45]
	v_mfma_f32_16x16x32_bf16 v[46:49], v[200:203], v[216:219], v[46:49]
	v_mfma_f32_16x16x32_bf16 v[10:13], v[200:203], v[220:223], v[10:13]
	v_mfma_f32_16x16x32_bf16 v[14:17], v[200:203], v[224:227], v[14:17]
	ds_read_b128 v[200:203], v244 offset:2368
	s_waitcnt lgkmcnt(7)
	v_mfma_f32_16x16x32_bf16 v[50:53], v[204:207], v[212:215], v[50:53]
	v_mfma_f32_16x16x32_bf16 v[54:57], v[204:207], v[216:219], v[54:57]
	v_mfma_f32_16x16x32_bf16 v[18:21], v[204:207], v[220:223], v[18:21]
	v_mfma_f32_16x16x32_bf16 v[22:25], v[204:207], v[224:227], v[22:25]
	ds_read_b128 v[204:207], v244 offset:4672
	s_waitcnt vmcnt(7)
	ds_write_b128 v95, v[98:101] offset:18432
	s_waitcnt vmcnt(6)
	ds_write_b128 v95, v[72:75] offset:23040
	s_waitcnt lgkmcnt(9)
	v_mfma_f32_16x16x32_bf16 v[58:61], v[208:211], v[212:215], v[58:61]
	v_mfma_f32_16x16x32_bf16 v[62:65], v[208:211], v[216:219], v[62:65]
	v_mfma_f32_16x16x32_bf16 v[26:29], v[208:211], v[220:223], v[26:29]
	v_mfma_f32_16x16x32_bf16 v[30:33], v[208:211], v[224:227], v[30:33]
	ds_read_b128 v[208:211], v244 offset:6976
	s_waitcnt vmcnt(5)
	ds_write_b128 v95, v[102:105] offset:27648
	s_waitcnt vmcnt(4)
	ds_write_b128 v95, v[76:79] offset:32256
	s_waitcnt lgkmcnt(7)
	v_mfma_f32_16x16x32_bf16 v[34:37], v[196:199], v[228:231], v[34:37]
	v_mfma_f32_16x16x32_bf16 v[38:41], v[196:199], v[232:235], v[38:41]
	v_mfma_f32_16x16x32_bf16 v[2:5], v[196:199], v[236:239], v[2:5]
	v_mfma_f32_16x16x32_bf16 v[6:9], v[196:199], v[240:243], v[6:9]
	s_waitcnt vmcnt(3)
	ds_write_b128 v95, v[106:109] offset:55296
	s_waitcnt vmcnt(2)
	ds_write_b128 v95, v[80:83] offset:59904
	s_waitcnt lgkmcnt(8)
	v_mfma_f32_16x16x32_bf16 v[42:45], v[200:203], v[228:231], v[42:45]
	v_mfma_f32_16x16x32_bf16 v[46:49], v[200:203], v[232:235], v[46:49]
	v_mfma_f32_16x16x32_bf16 v[10:13], v[200:203], v[236:239], v[10:13]
	v_mfma_f32_16x16x32_bf16 v[14:17], v[200:203], v[240:243], v[14:17]
	s_waitcnt vmcnt(1)
	ds_write_b128 v95, v[110:113] offset:64512
	s_waitcnt vmcnt(0)
	ds_write_b128 v96, v[84:87] offset:32256
	s_waitcnt lgkmcnt(0)
	s_barrier
	ds_read_b128 v[212:215], v245 offset:55296
	ds_read_b128 v[196:199], v244 offset:18432
	ds_read_b128 v[216:219], v245 offset:57600
	ds_read_b128 v[220:223], v245 offset:59904
	ds_read_b128 v[224:227], v245 offset:62208
	ds_read_b128 v[200:203], v244 offset:20736
	v_mfma_f32_16x16x32_bf16 v[50:53], v[204:207], v[228:231], v[50:53]
	v_mfma_f32_16x16x32_bf16 v[54:57], v[204:207], v[232:235], v[54:57]
	v_mfma_f32_16x16x32_bf16 v[18:21], v[204:207], v[236:239], v[18:21]
	v_mfma_f32_16x16x32_bf16 v[22:25], v[204:207], v[240:243], v[22:25]
	ds_read_b128 v[204:207], v244 offset:23040
	v_mfma_f32_16x16x32_bf16 v[58:61], v[208:211], v[228:231], v[58:61]
	v_mfma_f32_16x16x32_bf16 v[62:65], v[208:211], v[232:235], v[62:65]
	v_mfma_f32_16x16x32_bf16 v[26:29], v[208:211], v[236:239], v[26:29]
	v_mfma_f32_16x16x32_bf16 v[30:33], v[208:211], v[240:243], v[30:33]
	ds_read_b128 v[208:211], v244 offset:25344
	s_waitcnt lgkmcnt(6)
	v_mfma_f32_16x16x32_bf16 v[34:37], v[196:199], v[212:215], v[34:37]
	ds_read_b128 v[228:231], v245 offset:55360
	s_waitcnt lgkmcnt(6)
	v_mfma_f32_16x16x32_bf16 v[38:41], v[196:199], v[216:219], v[38:41]
	ds_read_b128 v[232:235], v245 offset:57664
	s_waitcnt lgkmcnt(6)
	v_mfma_f32_16x16x32_bf16 v[2:5], v[196:199], v[220:223], v[2:5]
	ds_read_b128 v[236:239], v245 offset:59968
	s_waitcnt lgkmcnt(6)
	v_mfma_f32_16x16x32_bf16 v[6:9], v[196:199], v[224:227], v[6:9]
	ds_read_b128 v[240:243], v245 offset:62272
	ds_read_b128 v[196:199], v244 offset:18496
	s_waitcnt lgkmcnt(7)
	v_mfma_f32_16x16x32_bf16 v[42:45], v[200:203], v[212:215], v[42:45]
	v_mfma_f32_16x16x32_bf16 v[46:49], v[200:203], v[216:219], v[46:49]
	v_mfma_f32_16x16x32_bf16 v[10:13], v[200:203], v[220:223], v[10:13]
	v_mfma_f32_16x16x32_bf16 v[14:17], v[200:203], v[224:227], v[14:17]
	ds_read_b128 v[200:203], v244 offset:20800
	s_waitcnt lgkmcnt(7)
	v_mfma_f32_16x16x32_bf16 v[50:53], v[204:207], v[212:215], v[50:53]
	v_mfma_f32_16x16x32_bf16 v[54:57], v[204:207], v[216:219], v[54:57]
	v_mfma_f32_16x16x32_bf16 v[18:21], v[204:207], v[220:223], v[18:21]
	v_mfma_f32_16x16x32_bf16 v[22:25], v[204:207], v[224:227], v[22:25]
	ds_read_b128 v[204:207], v244 offset:23104
	s_waitcnt lgkmcnt(7)
	v_mfma_f32_16x16x32_bf16 v[58:61], v[208:211], v[212:215], v[58:61]
	v_mfma_f32_16x16x32_bf16 v[62:65], v[208:211], v[216:219], v[62:65]
	v_mfma_f32_16x16x32_bf16 v[26:29], v[208:211], v[220:223], v[26:29]
	v_mfma_f32_16x16x32_bf16 v[30:33], v[208:211], v[224:227], v[30:33]
	ds_read_b128 v[208:211], v244 offset:25408
	s_waitcnt lgkmcnt(3)
	v_mfma_f32_16x16x32_bf16 v[34:37], v[196:199], v[228:231], v[34:37]
	v_mfma_f32_16x16x32_bf16 v[38:41], v[196:199], v[232:235], v[38:41]
	v_mfma_f32_16x16x32_bf16 v[2:5], v[196:199], v[236:239], v[2:5]
	v_mfma_f32_16x16x32_bf16 v[6:9], v[196:199], v[240:243], v[6:9]
	s_waitcnt lgkmcnt(2)
	v_mfma_f32_16x16x32_bf16 v[42:45], v[200:203], v[228:231], v[42:45]
	v_mfma_f32_16x16x32_bf16 v[46:49], v[200:203], v[232:235], v[46:49]
	v_mfma_f32_16x16x32_bf16 v[10:13], v[200:203], v[236:239], v[10:13]
	v_mfma_f32_16x16x32_bf16 v[14:17], v[200:203], v[240:243], v[14:17]
	v_or_b32_e32 v66, s5, v88
	s_addk_i32 s5, 0xf000
	s_lshr_b32 s5, s5, 12
	s_mulk_i32 s5, 0xc00
	s_addk_i32 s5, 0x3000
	s_cmp_gt_u32 s0, 31
	v_lshlrev_b32_e32 v66, 12, v66
	s_cselect_b32 s0, s5, 0x2400
	v_lshl_add_u64 v[148:149], s[80:81], 0, v[66:67]
	v_add_lshl_u32 v66, s4, v97, 2
	s_lshl_b64 s[4:5], s[0:1], 2
	s_add_u32 s0, s82, s4
	s_addc_u32 s5, s83, s5
	s_add_u32 s4, s0, 0xe958000
	v_lshl_add_u64 v[150:151], v[148:149], 0, v[66:67]
	s_addc_u32 s5, s5, 0
	v_or_b32_e32 v152, 0xe0, v66
	v_or_b32_e32 v154, 32, v66
	v_or_b32_e32 v156, 64, v66
	v_or_b32_e32 v158, 0x60, v66
	v_or_b32_e32 v160, 0x80, v66
	v_or_b32_e32 v162, 0xa0, v66
	v_or_b32_e32 v164, 0xc0, v66
	v_mov_b32_e32 v155, v67
	v_mov_b32_e32 v157, v67
	v_mov_b32_e32 v159, v67
	v_mov_b32_e32 v161, v67
	v_mov_b32_e32 v163, v67
	v_mov_b32_e32 v165, v67
	v_mov_b32_e32 v153, v67
	s_add_i32 s11, s11, 1
	s_mul_i32 s0, s11, s7
	s_add_i32 s10, s10, s7
	s_waitcnt lgkmcnt(0)
	s_barrier
	v_mfma_f32_16x16x32_bf16 v[50:53], v[204:207], v[228:231], v[50:53]
	v_mfma_f32_16x16x32_bf16 v[54:57], v[204:207], v[232:235], v[54:57]
	v_mfma_f32_16x16x32_bf16 v[18:21], v[204:207], v[236:239], v[18:21]
	v_mfma_f32_16x16x32_bf16 v[22:25], v[204:207], v[240:243], v[22:25]
	v_mfma_f32_16x16x32_bf16 v[58:61], v[208:211], v[228:231], v[58:61]
	v_mfma_f32_16x16x32_bf16 v[62:65], v[208:211], v[232:235], v[62:65]
	v_mfma_f32_16x16x32_bf16 v[26:29], v[208:211], v[236:239], v[26:29]
	v_mfma_f32_16x16x32_bf16 v[30:33], v[208:211], v[240:243], v[30:33]
	s_nop 7
	v_permlane16_swap_b32_e32 v34, v38
	v_permlane16_swap_b32_e32 v35, v39
	v_permlane16_swap_b32_e32 v36, v40
	v_permlane16_swap_b32_e32 v37, v41
	v_permlane16_swap_b32_e32 v42, v46
	v_permlane16_swap_b32_e32 v43, v47
	v_permlane16_swap_b32_e32 v44, v48
	v_permlane16_swap_b32_e32 v45, v49
	v_permlane16_swap_b32_e32 v2, v6
	v_permlane16_swap_b32_e32 v3, v7
	v_permlane16_swap_b32_e32 v4, v8
	v_permlane16_swap_b32_e32 v5, v9
	v_permlane16_swap_b32_e32 v10, v14
	v_permlane16_swap_b32_e32 v11, v15
	v_permlane16_swap_b32_e32 v12, v16
	v_permlane16_swap_b32_e32 v13, v17
	v_permlane16_swap_b32_e32 v50, v54
	v_permlane16_swap_b32_e32 v51, v55
	v_permlane16_swap_b32_e32 v52, v56
	v_permlane16_swap_b32_e32 v53, v57
	v_permlane16_swap_b32_e32 v58, v62
	v_permlane16_swap_b32_e32 v59, v63
	v_permlane16_swap_b32_e32 v60, v64
	v_permlane16_swap_b32_e32 v61, v65
	v_permlane16_swap_b32_e32 v18, v22
	v_permlane16_swap_b32_e32 v19, v23
	v_permlane16_swap_b32_e32 v20, v24
	v_permlane16_swap_b32_e32 v21, v25
	v_permlane16_swap_b32_e32 v26, v30
	v_permlane16_swap_b32_e32 v27, v31
	v_permlane16_swap_b32_e32 v28, v32
	v_permlane16_swap_b32_e32 v29, v33
	v_permlane32_swap_b32_e32 v34, v38
	v_permlane32_swap_b32_e32 v35, v39
	v_permlane32_swap_b32_e32 v36, v40
	v_permlane32_swap_b32_e32 v37, v41
	v_permlane32_swap_b32_e32 v42, v46
	v_permlane32_swap_b32_e32 v43, v47
	v_permlane32_swap_b32_e32 v44, v48
	v_permlane32_swap_b32_e32 v45, v49
	v_permlane32_swap_b32_e32 v2, v6
	v_permlane32_swap_b32_e32 v3, v7
	v_permlane32_swap_b32_e32 v4, v8
	v_permlane32_swap_b32_e32 v5, v9
	v_permlane32_swap_b32_e32 v10, v14
	v_permlane32_swap_b32_e32 v11, v15
	v_permlane32_swap_b32_e32 v12, v16
	v_permlane32_swap_b32_e32 v13, v17
	v_permlane32_swap_b32_e32 v50, v54
	v_permlane32_swap_b32_e32 v51, v55
	v_permlane32_swap_b32_e32 v52, v56
	v_permlane32_swap_b32_e32 v53, v57
	v_permlane32_swap_b32_e32 v58, v62
	v_permlane32_swap_b32_e32 v59, v63
	v_permlane32_swap_b32_e32 v60, v64
	v_permlane32_swap_b32_e32 v61, v65
	v_permlane32_swap_b32_e32 v18, v22
	v_permlane32_swap_b32_e32 v19, v23
	v_permlane32_swap_b32_e32 v20, v24
	v_permlane32_swap_b32_e32 v21, v25
	v_permlane32_swap_b32_e32 v26, v30
	v_permlane32_swap_b32_e32 v27, v31
	v_permlane32_swap_b32_e32 v28, v32
	v_permlane32_swap_b32_e32 v29, v33
	global_load_dwordx4 v[76:79], v[150:151], off offset:224
	global_load_dwordx4 v[84:87], v152, s[4:5]
	global_load_dwordx4 v[80:83], v[150:151], off offset:192
	s_waitcnt vmcnt(1)
	v_fma_f32 v62, v62, v84, v76
	v_fma_f32 v63, v63, v85, v77
	global_load_dwordx4 v[72:75], v164, s[4:5]
	global_load_dwordx4 v[98:101], v[150:151], off offset:160
	global_load_dwordx4 v[102:105], v162, s[4:5]
	global_load_dwordx4 v[106:109], v[150:151], off offset:128
	global_load_dwordx4 v[110:113], v160, s[4:5]
	global_load_dwordx4 v[114:117], v[150:151], off offset:96
	global_load_dwordx4 v[118:121], v158, s[4:5]
	global_load_dwordx4 v[122:125], v[150:151], off offset:64
	global_load_dwordx4 v[126:129], v156, s[4:5]
	global_load_dwordx4 v[132:135], v[150:151], off offset:32
	global_load_dwordx4 v[136:139], v154, s[4:5]
	global_load_dwordx4 v[140:143], v[150:151], off
	global_load_dwordx4 v[144:147], v66, s[4:5]
	v_pk_fma_f32 v[64:65], v[64:65], v[86:87], v[78:79]
	global_store_dwordx4 v[150:151], v[62:65], off offset:224
	s_waitcnt vmcnt(13)
	v_pk_fma_f32 v[58:59], v[58:59], v[72:73], v[80:81]
	v_pk_fma_f32 v[60:61], v[60:61], v[74:75], v[82:83]
	s_waitcnt vmcnt(11)
	v_pk_fma_f32 v[54:55], v[54:55], v[102:103], v[98:99]
	v_pk_fma_f32 v[56:57], v[56:57], v[104:105], v[100:101]
	s_waitcnt vmcnt(9)
	v_pk_fma_f32 v[50:51], v[50:51], v[110:111], v[106:107]
	v_pk_fma_f32 v[52:53], v[52:53], v[112:113], v[108:109]
	s_waitcnt vmcnt(7)
	v_pk_fma_f32 v[46:47], v[46:47], v[118:119], v[114:115]
	v_pk_fma_f32 v[48:49], v[48:49], v[120:121], v[116:117]
	s_waitcnt vmcnt(5)
	v_pk_fma_f32 v[42:43], v[42:43], v[126:127], v[122:123]
	v_pk_fma_f32 v[44:45], v[44:45], v[128:129], v[124:125]
	s_waitcnt vmcnt(3)
	v_pk_fma_f32 v[38:39], v[38:39], v[136:137], v[132:133]
	v_pk_fma_f32 v[40:41], v[40:41], v[138:139], v[134:135]
	s_waitcnt vmcnt(1)
	v_pk_fma_f32 v[34:35], v[34:35], v[144:145], v[140:141]
	v_pk_fma_f32 v[36:37], v[36:37], v[146:147], v[142:143]
	global_store_dwordx4 v[150:151], v[34:37], off
	global_store_dwordx4 v[150:151], v[38:41], off offset:32
	global_store_dwordx4 v[150:151], v[42:45], off offset:64
	v_lshl_add_u64 v[34:35], v[148:149], 0, s[2:3]
	global_store_dwordx4 v[150:151], v[46:49], off offset:96
	global_store_dwordx4 v[150:151], v[50:53], off offset:128
	global_store_dwordx4 v[150:151], v[54:57], off offset:160
	global_store_dwordx4 v[150:151], v[58:61], off offset:192
	v_lshl_add_u64 v[114:115], v[34:35], 0, v[66:67]
	v_lshl_add_u64 v[116:117], v[34:35], 0, v[154:155]
	v_lshl_add_u64 v[118:119], v[34:35], 0, v[156:157]
	v_lshl_add_u64 v[120:121], v[34:35], 0, v[158:159]
	v_lshl_add_u64 v[122:123], v[34:35], 0, v[160:161]
	v_lshl_add_u64 v[124:125], v[34:35], 0, v[162:163]
	v_lshl_add_u64 v[126:127], v[34:35], 0, v[164:165]
	v_lshl_add_u64 v[128:129], v[34:35], 0, v[152:153]
	global_load_dwordx4 v[34:37], v[128:129], off
	global_load_dwordx4 v[38:41], v152, s[4:5]
	global_load_dwordx4 v[42:45], v[126:127], off
	global_load_dwordx4 v[46:49], v164, s[4:5]
	global_load_dwordx4 v[50:53], v[124:125], off
	global_load_dwordx4 v[54:57], v162, s[4:5]
	global_load_dwordx4 v[58:61], v[122:123], off
	global_load_dwordx4 v[62:65], v160, s[4:5]
	global_load_dwordx4 v[72:75], v[120:121], off
	global_load_dwordx4 v[76:79], v158, s[4:5]
	global_load_dwordx4 v[80:83], v[118:119], off
	global_load_dwordx4 v[84:87], v156, s[4:5]
	global_load_dwordx4 v[98:101], v[116:117], off
	global_load_dwordx4 v[102:105], v154, s[4:5]
	global_load_dwordx4 v[106:109], v[114:115], off
	global_load_dwordx4 v[110:113], v66, s[4:5]
	s_add_i32 s4, s0, s6
	s_cmpk_lt_u32 s10, 0x60
	s_waitcnt vmcnt(14)
	v_pk_fma_f32 v[30:31], v[30:31], v[38:39], v[34:35]
	v_pk_fma_f32 v[32:33], v[32:33], v[40:41], v[36:37]
	s_waitcnt vmcnt(12)
	v_pk_fma_f32 v[26:27], v[26:27], v[46:47], v[42:43]
	v_pk_fma_f32 v[28:29], v[28:29], v[48:49], v[44:45]
	s_waitcnt vmcnt(10)
	v_pk_fma_f32 v[22:23], v[22:23], v[54:55], v[50:51]
	v_pk_fma_f32 v[24:25], v[24:25], v[56:57], v[52:53]
	s_waitcnt vmcnt(8)
	v_pk_fma_f32 v[18:19], v[18:19], v[62:63], v[58:59]
	v_pk_fma_f32 v[20:21], v[20:21], v[64:65], v[60:61]
	s_waitcnt vmcnt(6)
	v_pk_fma_f32 v[14:15], v[14:15], v[76:77], v[72:73]
	v_pk_fma_f32 v[16:17], v[16:17], v[78:79], v[74:75]
	s_waitcnt vmcnt(4)
	v_pk_fma_f32 v[10:11], v[10:11], v[84:85], v[80:81]
	v_pk_fma_f32 v[12:13], v[12:13], v[86:87], v[82:83]
	s_waitcnt vmcnt(2)
	v_pk_fma_f32 v[6:7], v[6:7], v[102:103], v[98:99]
	v_pk_fma_f32 v[8:9], v[8:9], v[104:105], v[100:101]
	s_waitcnt vmcnt(0)
	v_pk_fma_f32 v[2:3], v[2:3], v[110:111], v[106:107]
	v_pk_fma_f32 v[4:5], v[4:5], v[112:113], v[108:109]
	global_store_dwordx4 v[114:115], v[2:5], off
	global_store_dwordx4 v[116:117], v[6:9], off
	global_store_dwordx4 v[118:119], v[10:13], off
	global_store_dwordx4 v[120:121], v[14:17], off
	global_store_dwordx4 v[122:123], v[18:21], off
	global_store_dwordx4 v[124:125], v[22:25], off
	global_store_dwordx4 v[126:127], v[26:29], off
	global_store_dwordx4 v[128:129], v[30:33], off
	s_cbranch_scc1 .LBB0_1871
